# I-type load blocks issue all 16 LDS reads before their 2 LDS-DMAs (reads first)
# speedup vs baseline: 1.0335x; 1.0016x over previous
; #define PG8_STAGE(bufoff, gbase, voff) do { _Pragma("unroll") for (int _i = 0; _i < 2; ++_i) \
;         __builtin_amdgcn_global_load_lds((const unsigned*)((const char*)(gbase) + (voff)[_i]), (PG8_LAS unsigned*)(lds + (bufoff) + ldsw + _i * 8192), 16, 0, 0); } while (0)
; #define PG8_LDA(dst, b, h) do { _Pragma("unroll") for (int m = 0; m < 4; ++m) _Pragma("unroll") for (int k = 0; k < 2; ++k) dst[m][k] = *(const PG8_LAS bf16x8*)(lds + PG8_SA(b, h) + aoff + m * 2048 + k * 1024); } while (0)
; #define PG8_LDB(dst, b, h) do { _Pragma("unroll") for (int n = 0; n < 2; ++n) _Pragma("unroll") for (int k = 0; k < 2; ++k) dst[n][k] = *(const PG8_LAS bf16x8*)(lds + PG8_SB(b, h) + boff + n * 2048 + k * 1024); } while (0)
; #define PG8_WAIT_V(n) asm volatile("s_waitcnt vmcnt(" #n ")" ::: "memory")
; #define PG8_WAIT_L(n) asm volatile("s_waitcnt lgkmcnt(" #n ")" ::: "memory")
; #define PG8_BAR __builtin_amdgcn_s_barrier()
; #define PG8_SCHED __builtin_amdgcn_sched_barrier(0)
; template <class Epi, class Sched>
; __device__ __forceinline__ void gemm_phase(PG8_LAS unsigned char* lds, const Gemm g, const Sched& S, const Epi& E) {
;     ...
;         const bool has_next = S.next(ui + 1, nxt);
;         const char* nA = has_next ? (const char*)g.A + (size_t)nxt.pm * tstep : cA; const char* nB = has_next ? (const char*)g.Bt + (size_t)nxt.pn * tstep : cB;
;         for (int t = 0; t < nt; t += 2) {
;             const bool last = (t == nt - 2);
;             const char* a1 = cA + (size_t)(t + 1) * kstep;
;             const char* a2 = last ? nA : cA + (size_t)(t + 2) * kstep; const char* b2 = last ? nB : cB + (size_t)(t + 2) * kstep;
;             const char* a3 = a2 + kstep; const char* b3 = b2 + kstep;
;             if (last && has_next) S.a_ready(nxt);
;             PG8_LDB(B0, 0, 0); PG8_SCHED; PG8_LDA(At, 0, 0); PG8_STAGE(PG8_SA(1, 1), a1 + hstep, voffA);
;             PG8_WAIT_L(8); PG8_BAR; PG8_WAIT_L(0); PG8_MMA(0, 0, At, B0); PG8_BAR; PG8_SCHED;
;             PG8_LDB(B1, 0, 1); PG8_STAGE(PG8_SB(0, 0), b2, voffB);
;             PG8_BAR; PG8_WAIT_L(0); PG8_MMA(0, 1, At, B1); PG8_BAR;
;             PG8_LDA(At, 0, 1); PG8_STAGE(PG8_SA(0, 0), a2, voffA);
;             PG8_BAR; PG8_WAIT_L(0); PG8_MMA(1, 0, At, B0); PG8_BAR; PG8_SCHED;
;             PG8_STAGE(PG8_SB(0, 1), b2 + hstep, voffB);
;             PG8_WAIT_V(6); PG8_BAR; PG8_MMA(1, 1, At, B1); PG8_BAR;
.LBB0_194:
	s_ashr_i32 s17, s16, 31
	v_cmp_lt_i64_e32 vcc, s[18:19], v[140:141]
	s_lshl_b64 s[18:19], s[16:17], 19
	s_add_u32 s18, s38, s18
	s_addc_u32 s19, s39, s19
	s_and_b64 s[24:25], vcc, exec
	s_cselect_b32 s17, s19, s29
	s_cselect_b32 s54, s18, s28
	s_ashr_i32 s15, s14, 31
	s_lshl_b64 s[24:25], s[14:15], 19
	s_add_u32 s24, s90, s24
	s_addc_u32 s25, s91, s25
	s_and_b64 s[34:35], vcc, exec
	s_cselect_b32 s15, s25, s31
	s_cselect_b32 s55, s24, s30
	s_add_u32 s28, s28, 0x40080
	s_addc_u32 s29, s29, 0
	s_add_u32 s56, s30, 0x100
	s_addc_u32 s57, s31, 0
	s_mov_b32 s58, -2
	ds_read_b128 v[144:147], v151
	ds_read_b128 v[156:159], v151 offset:1024
	ds_read_b128 v[160:163], v151 offset:2048
	ds_read_b128 v[166:169], v151 offset:3072
	s_add_u32 s30, s28, 0xfffc0080
	s_addc_u32 s31, s29, -1
	s_cmp_eq_u32 s58, 12
	s_cselect_b32 s35, s17, s31
	s_cselect_b32 s34, s54, s30
	s_cselect_b32 s31, s15, s57
	s_cselect_b32 s30, s55, s56
	ds_read_b128 v[170:173], v153
	ds_read_b128 v[182:185], v153 offset:1024
	ds_read_b128 v[190:193], v153 offset:2048
	ds_read_b128 v[194:197], v153 offset:3072
	ds_read_b128 v[198:201], v153 offset:4096
	ds_read_b128 v[202:205], v153 offset:5120
	ds_read_b128 v[206:209], v153 offset:6144
	ds_read_b128 v[210:213], v153 offset:7168
	s_waitcnt lgkmcnt(8)
	ds_read_b128 v[214:217], v154
	ds_read_b128 v[218:221], v154 offset:1024
	ds_read_b128 v[222:225], v154 offset:2048
	ds_read_b128 v[226:229], v154 offset:3072
	s_add_i32 m0, s27, 0xc000
	s_nop 0
	global_load_lds_dwordx4 v136, s[28:29]
	s_nop 1
	s_add_i32 m0, s27, 0xe000
	s_nop 0
	global_load_lds_dwordx4 v138, s[28:29]
	s_waitcnt vmcnt(8) lgkmcnt(0)
	s_barrier
	v_mfma_f32_16x16x32_bf16 v[124:127], v[144:147], v[170:173], 0
	v_mfma_f32_16x16x32_bf16 v[120:123], v[160:163], v[170:173], 0
	v_mfma_f32_16x16x32_bf16 v[108:111], v[144:147], v[190:193], 0
	v_mfma_f32_16x16x32_bf16 v[104:107], v[160:163], v[190:193], 0
	v_mfma_f32_16x16x32_bf16 v[92:95], v[144:147], v[198:201], 0
	v_mfma_f32_16x16x32_bf16 v[88:91], v[160:163], v[198:201], 0
	v_mfma_f32_16x16x32_bf16 v[76:79], v[144:147], v[206:209], 0
	v_mfma_f32_16x16x32_bf16 v[72:75], v[160:163], v[206:209], 0
	v_mfma_f32_16x16x32_bf16 v[124:127], v[156:159], v[182:185], v[124:127]
	v_mfma_f32_16x16x32_bf16 v[120:123], v[166:169], v[182:185], v[120:123]
	v_mfma_f32_16x16x32_bf16 v[108:111], v[156:159], v[194:197], v[108:111]
	v_mfma_f32_16x16x32_bf16 v[104:107], v[166:169], v[194:197], v[104:107]
	v_mfma_f32_16x16x32_bf16 v[92:95], v[156:159], v[202:205], v[92:95]
	v_mfma_f32_16x16x32_bf16 v[88:91], v[166:169], v[202:205], v[88:91]
	v_mfma_f32_16x16x32_bf16 v[76:79], v[156:159], v[210:213], v[76:79]
	v_mfma_f32_16x16x32_bf16 v[72:75], v[166:169], v[210:213], v[72:75]
	v_mfma_f32_16x16x32_bf16 v[116:119], v[214:217], v[170:173], 0
	v_mfma_f32_16x16x32_bf16 v[112:115], v[222:225], v[170:173], 0
	v_mfma_f32_16x16x32_bf16 v[100:103], v[214:217], v[190:193], 0
	v_mfma_f32_16x16x32_bf16 v[96:99], v[222:225], v[190:193], 0
	v_mfma_f32_16x16x32_bf16 v[84:87], v[214:217], v[198:201], 0
	v_mfma_f32_16x16x32_bf16 v[80:83], v[222:225], v[198:201], 0
	v_mfma_f32_16x16x32_bf16 v[68:71], v[214:217], v[206:209], 0
	v_mfma_f32_16x16x32_bf16 v[64:67], v[222:225], v[206:209], 0
	v_mfma_f32_16x16x32_bf16 v[116:119], v[218:221], v[182:185], v[116:119]
	v_mfma_f32_16x16x32_bf16 v[112:115], v[226:229], v[182:185], v[112:115]
	v_mfma_f32_16x16x32_bf16 v[100:103], v[218:221], v[194:197], v[100:103]
	v_mfma_f32_16x16x32_bf16 v[96:99], v[226:229], v[194:197], v[96:99]
	v_mfma_f32_16x16x32_bf16 v[84:87], v[218:221], v[202:205], v[84:87]
	v_mfma_f32_16x16x32_bf16 v[80:83], v[226:229], v[202:205], v[80:83]
	v_mfma_f32_16x16x32_bf16 v[68:71], v[218:221], v[210:213], v[68:71]
	v_mfma_f32_16x16x32_bf16 v[64:67], v[226:229], v[210:213], v[64:67]
	s_barrier
	ds_read_b128 v[170:173], v153 offset:16384
	ds_read_b128 v[182:185], v153 offset:17408
	ds_read_b128 v[190:193], v153 offset:18432
	ds_read_b128 v[194:197], v153 offset:19456
	ds_read_b128 v[198:201], v153 offset:20480
	ds_read_b128 v[202:205], v153 offset:21504
	ds_read_b128 v[206:209], v153 offset:22528
	ds_read_b128 v[210:213], v153 offset:23552
	s_add_i32 s59, s50, s40
	s_add_u32 s98, s30, s10
	s_addc_u32 s99, s31, s11
	s_mov_b32 m0, s59
	s_nop 0
	global_load_lds_dwordx4 v132, s[30:31]
	s_nop 1
	s_add_i32 m0, s59, 0x2000
	s_nop 0
	global_load_lds_dwordx4 v128, s[30:31]
	s_nop 1
	s_mov_b32 m0, s27
	s_add_u32 s100, s34, s10
	s_addc_u32 s101, s35, s11
	global_load_lds_dwordx4 v134, s[34:35]
	s_nop 1
	s_mov_b32 m0, s43
	s_nop 0
	global_load_lds_dwordx4 v130, s[34:35]
	s_add_u32 s60, s30, 0x40000
	s_addc_u32 s61, s31, 0
	s_add_i32 s59, s51, s40
	s_mov_b32 m0, s59
	s_nop 0
	global_load_lds_dwordx4 v132, s[60:61]
	s_nop 1
	s_add_i32 m0, s59, 0x2000
	s_nop 0
	global_load_lds_dwordx4 v128, s[60:61]
	s_waitcnt vmcnt(8) lgkmcnt(0)
	s_barrier
; #define PG8_STAGE(bufoff, gbase, voff) do { _Pragma("unroll") for (int _i = 0; _i < 2; ++_i) \
;         __builtin_amdgcn_global_load_lds((const unsigned*)((const char*)(gbase) + (voff)[_i]), (PG8_LAS unsigned*)(lds + (bufoff) + ldsw + _i * 8192), 16, 0, 0); } while (0)
; #define PG8_LDA(dst, b, h) do { _Pragma("unroll") for (int m = 0; m < 4; ++m) _Pragma("unroll") for (int k = 0; k < 2; ++k) dst[m][k] = *(const PG8_LAS bf16x8*)(lds + PG8_SA(b, h) + aoff + m * 2048 + k * 1024); } while (0)
; #define PG8_LDB(dst, b, h) do { _Pragma("unroll") for (int n = 0; n < 2; ++n) _Pragma("unroll") for (int k = 0; k < 2; ++k) dst[n][k] = *(const PG8_LAS bf16x8*)(lds + PG8_SB(b, h) + boff + n * 2048 + k * 1024); } while (0)
; #define PG8_MMA(ai, bj, At, Bt) do { __builtin_amdgcn_s_setprio(1); _Pragma("unroll") for (int m = 0; m < 4; ++m) _Pragma("unroll") for (int n = 0; n < 2; ++n) _Pragma("unroll") for (int k = 0; k < 2; ++k) \
;         acc[ai][bj][m][n] = __builtin_amdgcn_mfma_f32_16x16x32_bf16(Bt[n][k], At[m][k], acc[ai][bj][m][n], 0, 0, 0); __builtin_amdgcn_s_setprio(0); } while (0)
; #define PG8_WAIT_V(n) asm volatile("s_waitcnt vmcnt(" #n ")" ::: "memory")
; #define PG8_WAIT_L(n) asm volatile("s_waitcnt lgkmcnt(" #n ")" ::: "memory")
; #define PG8_BAR __builtin_amdgcn_s_barrier()
; #define PG8_SCHED __builtin_amdgcn_sched_barrier(0)
; template <class Epi, class Sched>
; __device__ __forceinline__ void gemm_phase(PG8_LAS unsigned char* lds, const Gemm g, const Sched& S, const Epi& E) {
;     ...
;             PG8_LDA(At, 0, 1); PG8_STAGE(PG8_SA(0, 0), a2, voffA);
;             PG8_BAR; PG8_WAIT_L(0); PG8_MMA(1, 0, At, B0); PG8_BAR; PG8_SCHED;
;             PG8_STAGE(PG8_SB(0, 1), b2 + hstep, voffB);
;             PG8_WAIT_V(6); PG8_BAR; PG8_MMA(1, 1, At, B1); PG8_BAR;
;             PG8_LDB(B0, 1, 0); PG8_SCHED; PG8_LDA(At, 1, 0); PG8_STAGE(PG8_SA(0, 1), a2 + hstep, voffA);
;             PG8_WAIT_L(8); PG8_BAR; PG8_WAIT_L(0); PG8_MMA(0, 0, At, B0); PG8_BAR; PG8_SCHED;
	v_mfma_f32_16x16x32_bf16 v[60:63], v[144:147], v[170:173], 0
	v_mfma_f32_16x16x32_bf16 v[56:59], v[160:163], v[170:173], 0
	v_mfma_f32_16x16x32_bf16 v[44:47], v[144:147], v[190:193], 0
	v_mfma_f32_16x16x32_bf16 v[40:43], v[160:163], v[190:193], 0
	v_mfma_f32_16x16x32_bf16 v[28:31], v[144:147], v[198:201], 0
	v_mfma_f32_16x16x32_bf16 v[24:27], v[160:163], v[198:201], 0
	v_mfma_f32_16x16x32_bf16 v[12:15], v[144:147], v[206:209], 0
	v_mfma_f32_16x16x32_bf16 v[8:11], v[160:163], v[206:209], 0
	v_mfma_f32_16x16x32_bf16 v[60:63], v[156:159], v[182:185], v[60:63]
	v_mfma_f32_16x16x32_bf16 v[56:59], v[166:169], v[182:185], v[56:59]
	v_mfma_f32_16x16x32_bf16 v[44:47], v[156:159], v[194:197], v[44:47]
	v_mfma_f32_16x16x32_bf16 v[40:43], v[166:169], v[194:197], v[40:43]
	v_mfma_f32_16x16x32_bf16 v[28:31], v[156:159], v[202:205], v[28:31]
	v_mfma_f32_16x16x32_bf16 v[24:27], v[166:169], v[202:205], v[24:27]
	v_mfma_f32_16x16x32_bf16 v[12:15], v[156:159], v[210:213], v[12:15]
	v_mfma_f32_16x16x32_bf16 v[8:11], v[166:169], v[210:213], v[8:11]
	v_mfma_f32_16x16x32_bf16 v[52:55], v[214:217], v[170:173], 0
	v_mfma_f32_16x16x32_bf16 v[48:51], v[222:225], v[170:173], 0
	v_mfma_f32_16x16x32_bf16 v[36:39], v[214:217], v[190:193], 0
	v_mfma_f32_16x16x32_bf16 v[32:35], v[222:225], v[190:193], 0
	v_mfma_f32_16x16x32_bf16 v[20:23], v[214:217], v[198:201], 0
	v_mfma_f32_16x16x32_bf16 v[16:19], v[222:225], v[198:201], 0
	v_mfma_f32_16x16x32_bf16 v[4:7], v[214:217], v[206:209], 0
	v_mfma_f32_16x16x32_bf16 v[0:3], v[222:225], v[206:209], 0
	v_mfma_f32_16x16x32_bf16 v[52:55], v[218:221], v[182:185], v[52:55]
	v_mfma_f32_16x16x32_bf16 v[48:51], v[226:229], v[182:185], v[48:51]
	v_mfma_f32_16x16x32_bf16 v[36:39], v[218:221], v[194:197], v[36:39]
	v_mfma_f32_16x16x32_bf16 v[32:35], v[226:229], v[194:197], v[32:35]
	v_mfma_f32_16x16x32_bf16 v[20:23], v[218:221], v[202:205], v[20:23]
	v_mfma_f32_16x16x32_bf16 v[16:19], v[226:229], v[202:205], v[16:19]
	v_mfma_f32_16x16x32_bf16 v[4:7], v[218:221], v[210:213], v[4:7]
	v_mfma_f32_16x16x32_bf16 v[0:3], v[226:229], v[210:213], v[0:3]
	s_barrier
	s_add_i32 s59, 0, 0x18000
	v_add_u32_e32 v155, s59, v149
	ds_read_b128 v[144:147], v155
	ds_read_b128 v[156:159], v155 offset:1024
	ds_read_b128 v[160:163], v155 offset:2048
	ds_read_b128 v[166:169], v155 offset:3072
	ds_read_b128 v[170:173], v153 offset:32768
	ds_read_b128 v[182:185], v153 offset:33792
	ds_read_b128 v[190:193], v153 offset:34816
	ds_read_b128 v[194:197], v153 offset:35840
	ds_read_b128 v[198:201], v153 offset:36864
	ds_read_b128 v[202:205], v153 offset:37888
	ds_read_b128 v[206:209], v153 offset:38912
	ds_read_b128 v[210:213], v153 offset:39936
	v_add_u32_e32 v155, 0x1c000, v149
	s_waitcnt lgkmcnt(8)
	ds_read_b128 v[214:217], v155
	ds_read_b128 v[218:221], v155 offset:1024
	ds_read_b128 v[222:225], v155 offset:2048
	ds_read_b128 v[226:229], v155 offset:3072
	s_add_u32 s34, s34, 0x40000
	s_addc_u32 s35, s35, 0
	s_mov_b32 m0, s44
	s_nop 0
	global_load_lds_dwordx4 v134, s[34:35]
	s_nop 1
	s_mov_b32 m0, s45
	s_nop 0
	global_load_lds_dwordx4 v130, s[34:35]
	s_add_i32 s34, 0, 0x1c000
	s_waitcnt vmcnt(8) lgkmcnt(0)
	s_barrier
	v_mfma_f32_16x16x32_bf16 v[124:127], v[144:147], v[170:173], v[124:127]
	v_mfma_f32_16x16x32_bf16 v[120:123], v[160:163], v[170:173], v[120:123]
	v_mfma_f32_16x16x32_bf16 v[108:111], v[144:147], v[190:193], v[108:111]
	v_mfma_f32_16x16x32_bf16 v[104:107], v[160:163], v[190:193], v[104:107]
	v_mfma_f32_16x16x32_bf16 v[92:95], v[144:147], v[198:201], v[92:95]
	v_mfma_f32_16x16x32_bf16 v[88:91], v[160:163], v[198:201], v[88:91]
	v_mfma_f32_16x16x32_bf16 v[76:79], v[144:147], v[206:209], v[76:79]
	v_mfma_f32_16x16x32_bf16 v[72:75], v[160:163], v[206:209], v[72:75]
	v_mfma_f32_16x16x32_bf16 v[124:127], v[156:159], v[182:185], v[124:127]
	v_mfma_f32_16x16x32_bf16 v[120:123], v[166:169], v[182:185], v[120:123]
	v_mfma_f32_16x16x32_bf16 v[108:111], v[156:159], v[194:197], v[108:111]
	v_mfma_f32_16x16x32_bf16 v[104:107], v[166:169], v[194:197], v[104:107]
	v_mfma_f32_16x16x32_bf16 v[92:95], v[156:159], v[202:205], v[92:95]
	v_mfma_f32_16x16x32_bf16 v[88:91], v[166:169], v[202:205], v[88:91]
	v_mfma_f32_16x16x32_bf16 v[76:79], v[156:159], v[210:213], v[76:79]
	v_mfma_f32_16x16x32_bf16 v[72:75], v[166:169], v[210:213], v[72:75]
	v_mfma_f32_16x16x32_bf16 v[116:119], v[214:217], v[170:173], v[116:119]
	v_mfma_f32_16x16x32_bf16 v[112:115], v[222:225], v[170:173], v[112:115]
	v_mfma_f32_16x16x32_bf16 v[100:103], v[214:217], v[190:193], v[100:103]
	v_mfma_f32_16x16x32_bf16 v[96:99], v[222:225], v[190:193], v[96:99]
	v_mfma_f32_16x16x32_bf16 v[84:87], v[214:217], v[198:201], v[84:87]
	v_mfma_f32_16x16x32_bf16 v[80:83], v[222:225], v[198:201], v[80:83]
	v_mfma_f32_16x16x32_bf16 v[68:71], v[214:217], v[206:209], v[68:71]
	v_mfma_f32_16x16x32_bf16 v[64:67], v[222:225], v[206:209], v[64:67]
	v_mfma_f32_16x16x32_bf16 v[116:119], v[218:221], v[182:185], v[116:119]
	v_mfma_f32_16x16x32_bf16 v[112:115], v[226:229], v[182:185], v[112:115]
	v_mfma_f32_16x16x32_bf16 v[100:103], v[218:221], v[194:197], v[100:103]
	v_mfma_f32_16x16x32_bf16 v[96:99], v[226:229], v[194:197], v[96:99]
	v_mfma_f32_16x16x32_bf16 v[84:87], v[218:221], v[202:205], v[84:87]
	v_mfma_f32_16x16x32_bf16 v[80:83], v[226:229], v[202:205], v[80:83]
	v_mfma_f32_16x16x32_bf16 v[68:71], v[218:221], v[210:213], v[68:71]
	v_mfma_f32_16x16x32_bf16 v[64:67], v[226:229], v[210:213], v[64:67]
	s_barrier
; #define PG8_STAGE(bufoff, gbase, voff) do { _Pragma("unroll") for (int _i = 0; _i < 2; ++_i) \
;         __builtin_amdgcn_global_load_lds((const unsigned*)((const char*)(gbase) + (voff)[_i]), (PG8_LAS unsigned*)(lds + (bufoff) + ldsw + _i * 8192), 16, 0, 0); } while (0)
; #define PG8_LDA(dst, b, h) do { _Pragma("unroll") for (int m = 0; m < 4; ++m) _Pragma("unroll") for (int k = 0; k < 2; ++k) dst[m][k] = *(const PG8_LAS bf16x8*)(lds + PG8_SA(b, h) + aoff + m * 2048 + k * 1024); } while (0)
; #define PG8_LDB(dst, b, h) do { _Pragma("unroll") for (int n = 0; n < 2; ++n) _Pragma("unroll") for (int k = 0; k < 2; ++k) dst[n][k] = *(const PG8_LAS bf16x8*)(lds + PG8_SB(b, h) + boff + n * 2048 + k * 1024); } while (0)
; #define PG8_MMA(ai, bj, At, Bt) do { __builtin_amdgcn_s_setprio(1); _Pragma("unroll") for (int m = 0; m < 4; ++m) _Pragma("unroll") for (int n = 0; n < 2; ++n) _Pragma("unroll") for (int k = 0; k < 2; ++k) \
;         acc[ai][bj][m][n] = __builtin_amdgcn_mfma_f32_16x16x32_bf16(Bt[n][k], At[m][k], acc[ai][bj][m][n], 0, 0, 0); __builtin_amdgcn_s_setprio(0); } while (0)
; #define PG8_WAIT_V(n) asm volatile("s_waitcnt vmcnt(" #n ")" ::: "memory")
; #define PG8_WAIT_L(n) asm volatile("s_waitcnt lgkmcnt(" #n ")" ::: "memory")
; #define PG8_BAR __builtin_amdgcn_s_barrier()
; #define PG8_SCHED __builtin_amdgcn_sched_barrier(0)
; template <class Epi, class Sched>
; __device__ __forceinline__ void gemm_phase(PG8_LAS unsigned char* lds, const Gemm g, const Sched& S, const Epi& E) {
;     ...
;             PG8_LDB(B0, 0, 0); PG8_SCHED; PG8_LDA(At, 0, 0); PG8_STAGE(PG8_SA(1, 1), a1 + hstep, voffA);
;             PG8_WAIT_L(8); PG8_BAR; PG8_WAIT_L(0); PG8_MMA(0, 0, At, B0); PG8_BAR; PG8_SCHED;
;             PG8_LDB(B1, 0, 1); PG8_STAGE(PG8_SB(0, 0), b2, voffB);
;             PG8_BAR; PG8_WAIT_L(0); PG8_MMA(0, 1, At, B1); PG8_BAR;
;     ...
;             PG8_LDB(B1, 1, 1); PG8_STAGE(PG8_SB(1, 0), b3, voffB);
;             PG8_BAR; PG8_WAIT_L(0); PG8_MMA(0, 1, At, B1); PG8_BAR;
;             PG8_LDA(At, 1, 1); PG8_STAGE(PG8_SA(1, 0), a3, voffA);
;             PG8_BAR; PG8_WAIT_L(0); PG8_MMA(1, 0, At, B0); PG8_BAR; PG8_SCHED;
;             PG8_STAGE(PG8_SB(1, 1), b3 + hstep, voffB);
;             PG8_WAIT_V(6); PG8_BAR; PG8_MMA(1, 1, At, B1); PG8_BAR;
	ds_read_b128 v[170:173], v153 offset:49152
	ds_read_b128 v[182:185], v153 offset:50176
	ds_read_b128 v[190:193], v153 offset:51200
	ds_read_b128 v[194:197], v153 offset:52224
	ds_read_b128 v[198:201], v153 offset:53248
	ds_read_b128 v[202:205], v153 offset:54272
	ds_read_b128 v[206:209], v153 offset:55296
	ds_read_b128 v[210:213], v153 offset:56320
	s_add_i32 s35, s59, s40
	s_mov_b32 m0, s35
	s_nop 0
	global_load_lds_dwordx4 v132, s[98:99]
	s_nop 1
	s_add_i32 m0, s35, 0x2000
	s_nop 0
	global_load_lds_dwordx4 v128, s[98:99]
	s_nop 1
	s_mov_b32 m0, s47
	s_nop 0
	global_load_lds_dwordx4 v134, s[100:101]
	s_nop 1
	s_mov_b32 m0, s48
	s_nop 0
	global_load_lds_dwordx4 v130, s[100:101]
	s_add_u32 s30, s30, 0x40080
	s_addc_u32 s31, s31, 0
	s_add_i32 s34, s34, s40
	s_mov_b32 m0, s34
	s_nop 0
	global_load_lds_dwordx4 v132, s[30:31]
	s_nop 1
	s_add_i32 m0, s34, 0x2000
	s_nop 0
	global_load_lds_dwordx4 v128, s[30:31]
	s_waitcnt vmcnt(8) lgkmcnt(0)
	s_barrier
	v_mfma_f32_16x16x32_bf16 v[60:63], v[144:147], v[170:173], v[60:63]
	v_mfma_f32_16x16x32_bf16 v[56:59], v[160:163], v[170:173], v[56:59]
	v_mfma_f32_16x16x32_bf16 v[44:47], v[144:147], v[190:193], v[44:47]
	v_mfma_f32_16x16x32_bf16 v[40:43], v[160:163], v[190:193], v[40:43]
	v_mfma_f32_16x16x32_bf16 v[28:31], v[144:147], v[198:201], v[28:31]
	v_mfma_f32_16x16x32_bf16 v[24:27], v[160:163], v[198:201], v[24:27]
	v_mfma_f32_16x16x32_bf16 v[12:15], v[144:147], v[206:209], v[12:15]
	v_mfma_f32_16x16x32_bf16 v[8:11], v[160:163], v[206:209], v[8:11]
	v_mfma_f32_16x16x32_bf16 v[60:63], v[156:159], v[182:185], v[60:63]
	v_mfma_f32_16x16x32_bf16 v[56:59], v[166:169], v[182:185], v[56:59]
	v_mfma_f32_16x16x32_bf16 v[44:47], v[156:159], v[194:197], v[44:47]
	v_mfma_f32_16x16x32_bf16 v[40:43], v[166:169], v[194:197], v[40:43]
	v_mfma_f32_16x16x32_bf16 v[28:31], v[156:159], v[202:205], v[28:31]
	v_mfma_f32_16x16x32_bf16 v[24:27], v[166:169], v[202:205], v[24:27]
	v_mfma_f32_16x16x32_bf16 v[12:15], v[156:159], v[210:213], v[12:15]
	v_mfma_f32_16x16x32_bf16 v[8:11], v[166:169], v[210:213], v[8:11]
	v_mfma_f32_16x16x32_bf16 v[52:55], v[214:217], v[170:173], v[52:55]
	v_mfma_f32_16x16x32_bf16 v[48:51], v[222:225], v[170:173], v[48:51]
	v_mfma_f32_16x16x32_bf16 v[36:39], v[214:217], v[190:193], v[36:39]
	v_mfma_f32_16x16x32_bf16 v[32:35], v[222:225], v[190:193], v[32:35]
	v_mfma_f32_16x16x32_bf16 v[20:23], v[214:217], v[198:201], v[20:23]
	v_mfma_f32_16x16x32_bf16 v[16:19], v[222:225], v[198:201], v[16:19]
	v_mfma_f32_16x16x32_bf16 v[4:7], v[214:217], v[206:209], v[4:7]
	v_mfma_f32_16x16x32_bf16 v[0:3], v[222:225], v[206:209], v[0:3]
	v_mfma_f32_16x16x32_bf16 v[52:55], v[218:221], v[182:185], v[52:55]
	v_mfma_f32_16x16x32_bf16 v[48:51], v[226:229], v[182:185], v[48:51]
	v_mfma_f32_16x16x32_bf16 v[36:39], v[218:221], v[194:197], v[36:39]
	v_mfma_f32_16x16x32_bf16 v[32:35], v[226:229], v[194:197], v[32:35]
	v_mfma_f32_16x16x32_bf16 v[20:23], v[218:221], v[202:205], v[20:23]
	v_mfma_f32_16x16x32_bf16 v[16:19], v[226:229], v[202:205], v[16:19]
	v_mfma_f32_16x16x32_bf16 v[4:7], v[218:221], v[210:213], v[4:7]
	v_mfma_f32_16x16x32_bf16 v[0:3], v[226:229], v[210:213], v[0:3]
	s_barrier
	s_add_i32 s58, s58, 2
	s_add_u32 s28, s28, 0x100
	s_addc_u32 s29, s29, 0
	s_add_u32 s56, s56, 0x100
	s_addc_u32 s57, s57, 0
	s_cmp_gt_u32 s58, 13
.LBB0_195:
	ds_read_b128 v[144:147], v151
	ds_read_b128 v[156:159], v151 offset:1024
	ds_read_b128 v[160:163], v151 offset:2048
	ds_read_b128 v[166:169], v151 offset:3072
	s_add_u32 s30, s28, 0xfffc0080
	s_addc_u32 s31, s29, -1
	s_cmp_eq_u32 s58, 12
	s_cselect_b32 s35, s17, s31
	s_cselect_b32 s34, s54, s30
	s_cselect_b32 s31, s15, s57
	s_cselect_b32 s30, s55, s56
	ds_read_b128 v[170:173], v153
	ds_read_b128 v[182:185], v153 offset:1024
	ds_read_b128 v[190:193], v153 offset:2048
	ds_read_b128 v[194:197], v153 offset:3072
	ds_read_b128 v[198:201], v153 offset:4096
	ds_read_b128 v[202:205], v153 offset:5120
	ds_read_b128 v[206:209], v153 offset:6144
	ds_read_b128 v[210:213], v153 offset:7168
	s_waitcnt lgkmcnt(8)
	ds_read_b128 v[214:217], v154
	ds_read_b128 v[218:221], v154 offset:1024
	ds_read_b128 v[222:225], v154 offset:2048
	ds_read_b128 v[226:229], v154 offset:3072
	s_add_i32 m0, s27, 0xc000
	s_nop 0
	global_load_lds_dwordx4 v136, s[28:29]
	s_nop 1
	s_add_i32 m0, s27, 0xe000
	s_nop 0
	global_load_lds_dwordx4 v138, s[28:29]
	s_waitcnt vmcnt(8) lgkmcnt(0)
	s_barrier
	v_mfma_f32_16x16x32_bf16 v[124:127], v[144:147], v[170:173], v[124:127]
	v_mfma_f32_16x16x32_bf16 v[120:123], v[160:163], v[170:173], v[120:123]
	v_mfma_f32_16x16x32_bf16 v[108:111], v[144:147], v[190:193], v[108:111]
	v_mfma_f32_16x16x32_bf16 v[104:107], v[160:163], v[190:193], v[104:107]
	v_mfma_f32_16x16x32_bf16 v[92:95], v[144:147], v[198:201], v[92:95]
	v_mfma_f32_16x16x32_bf16 v[88:91], v[160:163], v[198:201], v[88:91]
	v_mfma_f32_16x16x32_bf16 v[76:79], v[144:147], v[206:209], v[76:79]
	v_mfma_f32_16x16x32_bf16 v[72:75], v[160:163], v[206:209], v[72:75]
	v_mfma_f32_16x16x32_bf16 v[124:127], v[156:159], v[182:185], v[124:127]
	v_mfma_f32_16x16x32_bf16 v[120:123], v[166:169], v[182:185], v[120:123]
	v_mfma_f32_16x16x32_bf16 v[108:111], v[156:159], v[194:197], v[108:111]
	v_mfma_f32_16x16x32_bf16 v[104:107], v[166:169], v[194:197], v[104:107]
	v_mfma_f32_16x16x32_bf16 v[92:95], v[156:159], v[202:205], v[92:95]
	v_mfma_f32_16x16x32_bf16 v[88:91], v[166:169], v[202:205], v[88:91]
	v_mfma_f32_16x16x32_bf16 v[76:79], v[156:159], v[210:213], v[76:79]
	v_mfma_f32_16x16x32_bf16 v[72:75], v[166:169], v[210:213], v[72:75]
	v_mfma_f32_16x16x32_bf16 v[116:119], v[214:217], v[170:173], v[116:119]
	v_mfma_f32_16x16x32_bf16 v[112:115], v[222:225], v[170:173], v[112:115]
	v_mfma_f32_16x16x32_bf16 v[100:103], v[214:217], v[190:193], v[100:103]
	v_mfma_f32_16x16x32_bf16 v[96:99], v[222:225], v[190:193], v[96:99]
	v_mfma_f32_16x16x32_bf16 v[84:87], v[214:217], v[198:201], v[84:87]
	v_mfma_f32_16x16x32_bf16 v[80:83], v[222:225], v[198:201], v[80:83]
	v_mfma_f32_16x16x32_bf16 v[68:71], v[214:217], v[206:209], v[68:71]
	v_mfma_f32_16x16x32_bf16 v[64:67], v[222:225], v[206:209], v[64:67]
	v_mfma_f32_16x16x32_bf16 v[116:119], v[218:221], v[182:185], v[116:119]
	v_mfma_f32_16x16x32_bf16 v[112:115], v[226:229], v[182:185], v[112:115]
	v_mfma_f32_16x16x32_bf16 v[100:103], v[218:221], v[194:197], v[100:103]
	v_mfma_f32_16x16x32_bf16 v[96:99], v[226:229], v[194:197], v[96:99]
	v_mfma_f32_16x16x32_bf16 v[84:87], v[218:221], v[202:205], v[84:87]
	v_mfma_f32_16x16x32_bf16 v[80:83], v[226:229], v[202:205], v[80:83]
	v_mfma_f32_16x16x32_bf16 v[68:71], v[218:221], v[210:213], v[68:71]
	v_mfma_f32_16x16x32_bf16 v[64:67], v[226:229], v[210:213], v[64:67]
	s_barrier
; #define PG8_STAGE(bufoff, gbase, voff) do { _Pragma("unroll") for (int _i = 0; _i < 2; ++_i) \
;         __builtin_amdgcn_global_load_lds((const unsigned*)((const char*)(gbase) + (voff)[_i]), (PG8_LAS unsigned*)(lds + (bufoff) + ldsw + _i * 8192), 16, 0, 0); } while (0)
; #define PG8_LDA(dst, b, h) do { _Pragma("unroll") for (int m = 0; m < 4; ++m) _Pragma("unroll") for (int k = 0; k < 2; ++k) dst[m][k] = *(const PG8_LAS bf16x8*)(lds + PG8_SA(b, h) + aoff + m * 2048 + k * 1024); } while (0)
; #define PG8_LDB(dst, b, h) do { _Pragma("unroll") for (int n = 0; n < 2; ++n) _Pragma("unroll") for (int k = 0; k < 2; ++k) dst[n][k] = *(const PG8_LAS bf16x8*)(lds + PG8_SB(b, h) + boff + n * 2048 + k * 1024); } while (0)
; #define PG8_MMA(ai, bj, At, Bt) do { __builtin_amdgcn_s_setprio(1); _Pragma("unroll") for (int m = 0; m < 4; ++m) _Pragma("unroll") for (int n = 0; n < 2; ++n) _Pragma("unroll") for (int k = 0; k < 2; ++k) \
;         acc[ai][bj][m][n] = __builtin_amdgcn_mfma_f32_16x16x32_bf16(Bt[n][k], At[m][k], acc[ai][bj][m][n], 0, 0, 0); __builtin_amdgcn_s_setprio(0); } while (0)
; #define PG8_WAIT_V(n) asm volatile("s_waitcnt vmcnt(" #n ")" ::: "memory")
; #define PG8_WAIT_L(n) asm volatile("s_waitcnt lgkmcnt(" #n ")" ::: "memory")
; #define PG8_BAR __builtin_amdgcn_s_barrier()
; #define PG8_SCHED __builtin_amdgcn_sched_barrier(0)
; template <class Epi, class Sched>
; __device__ __forceinline__ void gemm_phase(PG8_LAS unsigned char* lds, const Gemm g, const Sched& S, const Epi& E) {
;     ...
;             PG8_LDA(At, 0, 1); PG8_STAGE(PG8_SA(0, 0), a2, voffA);
;             PG8_BAR; PG8_WAIT_L(0); PG8_MMA(1, 0, At, B0); PG8_BAR; PG8_SCHED;
;             PG8_STAGE(PG8_SB(0, 1), b2 + hstep, voffB);
;             PG8_WAIT_V(6); PG8_BAR; PG8_MMA(1, 1, At, B1); PG8_BAR;
;             PG8_LDB(B0, 1, 0); PG8_SCHED; PG8_LDA(At, 1, 0); PG8_STAGE(PG8_SA(0, 1), a2 + hstep, voffA);
;             PG8_WAIT_L(8); PG8_BAR; PG8_WAIT_L(0); PG8_MMA(0, 0, At, B0); PG8_BAR; PG8_SCHED;
;             PG8_LDB(B1, 1, 1); PG8_STAGE(PG8_SB(1, 0), b3, voffB);
;             PG8_BAR; PG8_WAIT_L(0); PG8_MMA(0, 1, At, B1); PG8_BAR;
;             PG8_LDA(At, 1, 1); PG8_STAGE(PG8_SA(1, 0), a3, voffA);
;             PG8_BAR; PG8_WAIT_L(0); PG8_MMA(1, 0, At, B0); PG8_BAR; PG8_SCHED;
	ds_read_b128 v[170:173], v153 offset:16384
	ds_read_b128 v[182:185], v153 offset:17408
	ds_read_b128 v[190:193], v153 offset:18432
	ds_read_b128 v[194:197], v153 offset:19456
	ds_read_b128 v[198:201], v153 offset:20480
	ds_read_b128 v[202:205], v153 offset:21504
	ds_read_b128 v[206:209], v153 offset:22528
	ds_read_b128 v[210:213], v153 offset:23552
	s_add_i32 s59, s50, s40
	s_add_u32 s98, s30, s10
	s_addc_u32 s99, s31, s11
	s_mov_b32 m0, s59
	s_nop 0
	global_load_lds_dwordx4 v132, s[30:31]
	s_nop 1
	s_add_i32 m0, s59, 0x2000
	s_nop 0
	global_load_lds_dwordx4 v128, s[30:31]
	s_nop 1
	s_mov_b32 m0, s27
	s_add_u32 s100, s34, s10
	s_addc_u32 s101, s35, s11
	global_load_lds_dwordx4 v134, s[34:35]
	s_nop 1
	s_mov_b32 m0, s43
	s_nop 0
	global_load_lds_dwordx4 v130, s[34:35]
	s_add_u32 s60, s30, 0x40000
	s_addc_u32 s61, s31, 0
	s_add_i32 s59, s51, s40
	s_mov_b32 m0, s59
	s_nop 0
	global_load_lds_dwordx4 v132, s[60:61]
	s_nop 1
	s_add_i32 m0, s59, 0x2000
	s_nop 0
	global_load_lds_dwordx4 v128, s[60:61]
	s_waitcnt vmcnt(8) lgkmcnt(0)
	s_barrier
	v_mfma_f32_16x16x32_bf16 v[60:63], v[144:147], v[170:173], v[60:63]
	v_mfma_f32_16x16x32_bf16 v[56:59], v[160:163], v[170:173], v[56:59]
	v_mfma_f32_16x16x32_bf16 v[44:47], v[144:147], v[190:193], v[44:47]
	v_mfma_f32_16x16x32_bf16 v[40:43], v[160:163], v[190:193], v[40:43]
	v_mfma_f32_16x16x32_bf16 v[28:31], v[144:147], v[198:201], v[28:31]
	v_mfma_f32_16x16x32_bf16 v[24:27], v[160:163], v[198:201], v[24:27]
	v_mfma_f32_16x16x32_bf16 v[12:15], v[144:147], v[206:209], v[12:15]
	v_mfma_f32_16x16x32_bf16 v[8:11], v[160:163], v[206:209], v[8:11]
	v_mfma_f32_16x16x32_bf16 v[60:63], v[156:159], v[182:185], v[60:63]
	v_mfma_f32_16x16x32_bf16 v[56:59], v[166:169], v[182:185], v[56:59]
	v_mfma_f32_16x16x32_bf16 v[44:47], v[156:159], v[194:197], v[44:47]
	v_mfma_f32_16x16x32_bf16 v[40:43], v[166:169], v[194:197], v[40:43]
	v_mfma_f32_16x16x32_bf16 v[28:31], v[156:159], v[202:205], v[28:31]
	v_mfma_f32_16x16x32_bf16 v[24:27], v[166:169], v[202:205], v[24:27]
	v_mfma_f32_16x16x32_bf16 v[12:15], v[156:159], v[210:213], v[12:15]
	v_mfma_f32_16x16x32_bf16 v[8:11], v[166:169], v[210:213], v[8:11]
	v_mfma_f32_16x16x32_bf16 v[52:55], v[214:217], v[170:173], v[52:55]
	v_mfma_f32_16x16x32_bf16 v[48:51], v[222:225], v[170:173], v[48:51]
	v_mfma_f32_16x16x32_bf16 v[36:39], v[214:217], v[190:193], v[36:39]
	v_mfma_f32_16x16x32_bf16 v[32:35], v[222:225], v[190:193], v[32:35]
	v_mfma_f32_16x16x32_bf16 v[20:23], v[214:217], v[198:201], v[20:23]
	v_mfma_f32_16x16x32_bf16 v[16:19], v[222:225], v[198:201], v[16:19]
	v_mfma_f32_16x16x32_bf16 v[4:7], v[214:217], v[206:209], v[4:7]
	v_mfma_f32_16x16x32_bf16 v[0:3], v[222:225], v[206:209], v[0:3]
	v_mfma_f32_16x16x32_bf16 v[52:55], v[218:221], v[182:185], v[52:55]
	v_mfma_f32_16x16x32_bf16 v[48:51], v[226:229], v[182:185], v[48:51]
	v_mfma_f32_16x16x32_bf16 v[36:39], v[218:221], v[194:197], v[36:39]
	v_mfma_f32_16x16x32_bf16 v[32:35], v[226:229], v[194:197], v[32:35]
	v_mfma_f32_16x16x32_bf16 v[20:23], v[218:221], v[202:205], v[20:23]
	v_mfma_f32_16x16x32_bf16 v[16:19], v[226:229], v[202:205], v[16:19]
	v_mfma_f32_16x16x32_bf16 v[4:7], v[218:221], v[210:213], v[4:7]
	v_mfma_f32_16x16x32_bf16 v[0:3], v[226:229], v[210:213], v[0:3]
	s_barrier
	s_add_i32 s59, 0, 0x18000
	v_add_u32_e32 v155, s59, v149
	ds_read_b128 v[144:147], v155
	ds_read_b128 v[156:159], v155 offset:1024
	ds_read_b128 v[160:163], v155 offset:2048
	ds_read_b128 v[166:169], v155 offset:3072
	ds_read_b128 v[170:173], v153 offset:32768
	ds_read_b128 v[182:185], v153 offset:33792
	ds_read_b128 v[190:193], v153 offset:34816
	ds_read_b128 v[194:197], v153 offset:35840
	ds_read_b128 v[198:201], v153 offset:36864
	ds_read_b128 v[202:205], v153 offset:37888
	ds_read_b128 v[206:209], v153 offset:38912
	ds_read_b128 v[210:213], v153 offset:39936
	v_add_u32_e32 v155, 0x1c000, v149
	s_waitcnt lgkmcnt(8)
	ds_read_b128 v[214:217], v155
	ds_read_b128 v[218:221], v155 offset:1024
	ds_read_b128 v[222:225], v155 offset:2048
	ds_read_b128 v[226:229], v155 offset:3072
	s_add_u32 s34, s34, 0x40000
	s_addc_u32 s35, s35, 0
	s_mov_b32 m0, s44
	s_nop 0
	global_load_lds_dwordx4 v134, s[34:35]
	s_nop 1
	s_mov_b32 m0, s45
	s_nop 0
	global_load_lds_dwordx4 v130, s[34:35]
	s_add_i32 s34, 0, 0x1c000
	s_waitcnt vmcnt(8) lgkmcnt(0)
	s_barrier
	v_mfma_f32_16x16x32_bf16 v[124:127], v[144:147], v[170:173], v[124:127]
	v_mfma_f32_16x16x32_bf16 v[120:123], v[160:163], v[170:173], v[120:123]
	v_mfma_f32_16x16x32_bf16 v[108:111], v[144:147], v[190:193], v[108:111]
	v_mfma_f32_16x16x32_bf16 v[104:107], v[160:163], v[190:193], v[104:107]
	v_mfma_f32_16x16x32_bf16 v[92:95], v[144:147], v[198:201], v[92:95]
	v_mfma_f32_16x16x32_bf16 v[88:91], v[160:163], v[198:201], v[88:91]
	v_mfma_f32_16x16x32_bf16 v[76:79], v[144:147], v[206:209], v[76:79]
	v_mfma_f32_16x16x32_bf16 v[72:75], v[160:163], v[206:209], v[72:75]
	v_mfma_f32_16x16x32_bf16 v[124:127], v[156:159], v[182:185], v[124:127]
	v_mfma_f32_16x16x32_bf16 v[120:123], v[166:169], v[182:185], v[120:123]
	v_mfma_f32_16x16x32_bf16 v[108:111], v[156:159], v[194:197], v[108:111]
	v_mfma_f32_16x16x32_bf16 v[104:107], v[166:169], v[194:197], v[104:107]
	v_mfma_f32_16x16x32_bf16 v[92:95], v[156:159], v[202:205], v[92:95]
	v_mfma_f32_16x16x32_bf16 v[88:91], v[166:169], v[202:205], v[88:91]
	v_mfma_f32_16x16x32_bf16 v[76:79], v[156:159], v[210:213], v[76:79]
	v_mfma_f32_16x16x32_bf16 v[72:75], v[166:169], v[210:213], v[72:75]
	v_mfma_f32_16x16x32_bf16 v[116:119], v[214:217], v[170:173], v[116:119]
	v_mfma_f32_16x16x32_bf16 v[112:115], v[222:225], v[170:173], v[112:115]
	v_mfma_f32_16x16x32_bf16 v[100:103], v[214:217], v[190:193], v[100:103]
	v_mfma_f32_16x16x32_bf16 v[96:99], v[222:225], v[190:193], v[96:99]
	v_mfma_f32_16x16x32_bf16 v[84:87], v[214:217], v[198:201], v[84:87]
	v_mfma_f32_16x16x32_bf16 v[80:83], v[222:225], v[198:201], v[80:83]
	v_mfma_f32_16x16x32_bf16 v[68:71], v[214:217], v[206:209], v[68:71]
	v_mfma_f32_16x16x32_bf16 v[64:67], v[222:225], v[206:209], v[64:67]
	v_mfma_f32_16x16x32_bf16 v[116:119], v[218:221], v[182:185], v[116:119]
	v_mfma_f32_16x16x32_bf16 v[112:115], v[226:229], v[182:185], v[112:115]
	v_mfma_f32_16x16x32_bf16 v[100:103], v[218:221], v[194:197], v[100:103]
	v_mfma_f32_16x16x32_bf16 v[96:99], v[226:229], v[194:197], v[96:99]
	v_mfma_f32_16x16x32_bf16 v[84:87], v[218:221], v[202:205], v[84:87]
	v_mfma_f32_16x16x32_bf16 v[80:83], v[226:229], v[202:205], v[80:83]
	v_mfma_f32_16x16x32_bf16 v[68:71], v[218:221], v[210:213], v[68:71]
	v_mfma_f32_16x16x32_bf16 v[64:67], v[226:229], v[210:213], v[64:67]
	s_barrier
; #define PG8_STAGE(bufoff, gbase, voff) do { _Pragma("unroll") for (int _i = 0; _i < 2; ++_i) \
;         __builtin_amdgcn_global_load_lds((const unsigned*)((const char*)(gbase) + (voff)[_i]), (PG8_LAS unsigned*)(lds + (bufoff) + ldsw + _i * 8192), 16, 0, 0); } while (0)
; #define PG8_LDA(dst, b, h) do { _Pragma("unroll") for (int m = 0; m < 4; ++m) _Pragma("unroll") for (int k = 0; k < 2; ++k) dst[m][k] = *(const PG8_LAS bf16x8*)(lds + PG8_SA(b, h) + aoff + m * 2048 + k * 1024); } while (0)
; #define PG8_LDB(dst, b, h) do { _Pragma("unroll") for (int n = 0; n < 2; ++n) _Pragma("unroll") for (int k = 0; k < 2; ++k) dst[n][k] = *(const PG8_LAS bf16x8*)(lds + PG8_SB(b, h) + boff + n * 2048 + k * 1024); } while (0)
; #define PG8_MMA(ai, bj, At, Bt) do { __builtin_amdgcn_s_setprio(1); _Pragma("unroll") for (int m = 0; m < 4; ++m) _Pragma("unroll") for (int n = 0; n < 2; ++n) _Pragma("unroll") for (int k = 0; k < 2; ++k) \
;         acc[ai][bj][m][n] = __builtin_amdgcn_mfma_f32_16x16x32_bf16(Bt[n][k], At[m][k], acc[ai][bj][m][n], 0, 0, 0); __builtin_amdgcn_s_setprio(0); } while (0)
; #define PG8_BAR __builtin_amdgcn_s_barrier()
;     __device__ __forceinline__ void operator()(const f32x4 (&acc)[2][2][4][2], const Unit& u, int wr, int wc, int fr, int fq) const {
;         const int row0 = u.pm * BM + wr * 64 + fr, col0 = u.pn * HALF + wc * 32 + 8 * fq;
; #pragma unroll
;         for (int ai = 0; ai < 2; ++ai)
; #pragma unroll
;             for (int m = 0; m < 4; ++m) { bf16_t* rowp = O + (size_t)(row0 + ai * HALF + m * 16) * ldc + col0;
;                 f32x4 v0, v1;
; #pragma unroll
;                 for (int j = 0; j < 1; ++j) { v0 = acc[ai][0][m][0] * sigmoid4(acc[ai][0][m][0]) * acc[ai][1][m][0]; v1 = acc[ai][0][m][1] * sigmoid4(acc[ai][0][m][1]) * acc[ai][1][m][1]; }
; template <class Epi, class Sched>
; __device__ __forceinline__ void gemm_phase(PG8_LAS unsigned char* lds, const Gemm g, const Sched& S, const Epi& E) {
;     ...
;             PG8_LDB(B1, 1, 1); PG8_STAGE(PG8_SB(1, 0), b3, voffB);
;             PG8_BAR; PG8_WAIT_L(0); PG8_MMA(0, 1, At, B1); PG8_BAR;
;             PG8_LDA(At, 1, 1); PG8_STAGE(PG8_SA(1, 0), a3, voffA);
;             PG8_BAR; PG8_WAIT_L(0); PG8_MMA(1, 0, At, B0); PG8_BAR; PG8_SCHED;
;             PG8_STAGE(PG8_SB(1, 1), b3 + hstep, voffB);
;             PG8_WAIT_V(6); PG8_BAR; PG8_MMA(1, 1, At, B1); PG8_BAR;
;         }
	ds_read_b128 v[170:173], v153 offset:49152
	ds_read_b128 v[182:185], v153 offset:50176
	ds_read_b128 v[190:193], v153 offset:51200
	ds_read_b128 v[194:197], v153 offset:52224
	ds_read_b128 v[198:201], v153 offset:53248
	ds_read_b128 v[202:205], v153 offset:54272
	ds_read_b128 v[206:209], v153 offset:55296
	ds_read_b128 v[210:213], v153 offset:56320
	s_add_i32 s35, s59, s40
	s_mov_b32 m0, s35
	s_nop 0
	global_load_lds_dwordx4 v132, s[98:99]
	s_nop 1
	s_add_i32 m0, s35, 0x2000
	s_nop 0
	global_load_lds_dwordx4 v128, s[98:99]
	s_nop 1
	s_mov_b32 m0, s47
	s_nop 0
	global_load_lds_dwordx4 v134, s[100:101]
	s_nop 1
	s_mov_b32 m0, s48
	s_nop 0
	global_load_lds_dwordx4 v130, s[100:101]
	s_add_u32 s30, s30, 0x40080
	s_addc_u32 s31, s31, 0
	s_add_i32 s34, s34, s40
	s_mov_b32 m0, s34
	s_nop 0
	global_load_lds_dwordx4 v132, s[30:31]
	s_nop 1
	s_add_i32 m0, s34, 0x2000
	s_nop 0
	global_load_lds_dwordx4 v128, s[30:31]
	s_waitcnt vmcnt(8) lgkmcnt(0)
	s_barrier
	v_mfma_f32_16x16x32_bf16 v[60:63], v[144:147], v[170:173], v[60:63]
	v_mfma_f32_16x16x32_bf16 v[56:59], v[160:163], v[170:173], v[56:59]
	v_mfma_f32_16x16x32_bf16 v[44:47], v[144:147], v[190:193], v[44:47]
	v_mfma_f32_16x16x32_bf16 v[40:43], v[160:163], v[190:193], v[40:43]
	v_mfma_f32_16x16x32_bf16 v[28:31], v[144:147], v[198:201], v[28:31]
	v_mfma_f32_16x16x32_bf16 v[24:27], v[160:163], v[198:201], v[24:27]
	v_mfma_f32_16x16x32_bf16 v[12:15], v[144:147], v[206:209], v[12:15]
	v_mfma_f32_16x16x32_bf16 v[8:11], v[160:163], v[206:209], v[8:11]
	v_mfma_f32_16x16x32_bf16 v[60:63], v[156:159], v[182:185], v[60:63]
	v_mfma_f32_16x16x32_bf16 v[56:59], v[166:169], v[182:185], v[56:59]
	v_mfma_f32_16x16x32_bf16 v[44:47], v[156:159], v[194:197], v[44:47]
	v_mfma_f32_16x16x32_bf16 v[40:43], v[166:169], v[194:197], v[40:43]
	v_mfma_f32_16x16x32_bf16 v[28:31], v[156:159], v[202:205], v[28:31]
	v_mfma_f32_16x16x32_bf16 v[24:27], v[166:169], v[202:205], v[24:27]
	v_mfma_f32_16x16x32_bf16 v[12:15], v[156:159], v[210:213], v[12:15]
	v_mfma_f32_16x16x32_bf16 v[8:11], v[166:169], v[210:213], v[8:11]
	v_mfma_f32_16x16x32_bf16 v[52:55], v[214:217], v[170:173], v[52:55]
	v_mfma_f32_16x16x32_bf16 v[48:51], v[222:225], v[170:173], v[48:51]
	v_mfma_f32_16x16x32_bf16 v[36:39], v[214:217], v[190:193], v[36:39]
	v_mfma_f32_16x16x32_bf16 v[32:35], v[222:225], v[190:193], v[32:35]
	v_mfma_f32_16x16x32_bf16 v[20:23], v[214:217], v[198:201], v[20:23]
	v_mfma_f32_16x16x32_bf16 v[16:19], v[222:225], v[198:201], v[16:19]
	v_mfma_f32_16x16x32_bf16 v[4:7], v[214:217], v[206:209], v[4:7]
	v_mfma_f32_16x16x32_bf16 v[0:3], v[222:225], v[206:209], v[0:3]
	v_mfma_f32_16x16x32_bf16 v[52:55], v[218:221], v[182:185], v[52:55]
	v_mfma_f32_16x16x32_bf16 v[48:51], v[226:229], v[182:185], v[48:51]
	v_mfma_f32_16x16x32_bf16 v[36:39], v[218:221], v[194:197], v[36:39]
	v_mfma_f32_16x16x32_bf16 v[32:35], v[226:229], v[194:197], v[32:35]
	v_mfma_f32_16x16x32_bf16 v[20:23], v[218:221], v[202:205], v[20:23]
	v_mfma_f32_16x16x32_bf16 v[16:19], v[226:229], v[202:205], v[16:19]
	v_mfma_f32_16x16x32_bf16 v[4:7], v[218:221], v[210:213], v[4:7]
	v_mfma_f32_16x16x32_bf16 v[0:3], v[226:229], v[210:213], v[0:3]
	s_barrier
	s_add_i32 s58, s58, 2
	s_add_u32 s28, s28, 0x100
	s_addc_u32 s29, s29, 0
	s_add_u32 s56, s56, 0x100
	s_addc_u32 s57, s57, 0
	s_cmp_gt_u32 s58, 13
	s_cbranch_scc0 .LBB0_195
	v_max_f32_e32 v144, 0xc1a00000, v124
	v_mul_f32_e32 v144, 0xbfb8aa3b, v144
	v_exp_f32_e32 v157, v144
	v_max_f32_e32 v144, 0xc1a00000, v125
	v_mul_f32_e32 v144, 0xbfb8aa3b, v144
	v_exp_f32_e32 v156, v144
	v_max_f32_e32 v144, 0xc1a00000, v126
	v_mul_f32_e32 v144, 0xbfb8aa3b, v144
	v_exp_f32_e32 v159, v144
	v_max_f32_e32 v144, 0xc1a00000, v127
	v_mul_f32_e32 v144, 0xbfb8aa3b, v144
	v_exp_f32_e32 v158, v144
	v_pk_add_f32 v[156:157], v[156:157], 1.0 op_sel_hi:[1,0]
	v_lshl_or_b32 v146, s53, 7, v150
	v_mov_b32_e32 v160, v157
	v_pk_add_f32 v[158:159], v[158:159], 1.0 op_sel_hi:[1,0]
	v_mov_b32_e32 v162, v156
	v_mov_b32_e32 v161, v159
	v_mov_b32_e32 v163, v158
	v_pk_mul_f32 v[160:161], v[160:161], v[162:163]
	v_lshl_add_u32 v155, s26, 8, v148
	v_mul_f32_e32 v162, v160, v161
	v_rcp_f32_e32 v166, v162
	v_ashrrev_i32_e32 v147, 31, v146
	v_mov_b64_e32 v[144:145], s[4:5]
	v_mad_i64_i32 v[162:163], s[28:29], v155, s52, v[144:145]
	v_mul_f32_e32 v160, v160, v166
	v_mul_f32_e32 v164, v161, v166
	v_pk_mul_f32 v[158:159], v[158:159], v[160:161] op_sel_hi:[1,0]
	v_max_f32_e32 v160, 0xc1a00000, v120
	v_max_f32_e32 v166, 0xc1a00000, v122
	v_mul_f32_e32 v160, 0xbfb8aa3b, v160
	v_mul_f32_e32 v166, 0xbfb8aa3b, v166
	v_exp_f32_e32 v161, v160
	v_exp_f32_e32 v167, v166
	v_max_f32_e32 v160, 0xc1a00000, v121
	v_max_f32_e32 v166, 0xc1a00000, v123
	v_mul_f32_e32 v160, 0xbfb8aa3b, v160
	v_mul_f32_e32 v166, 0xbfb8aa3b, v166
	v_exp_f32_e32 v160, v160
	v_exp_f32_e32 v166, v166
	v_pk_mul_f32 v[156:157], v[156:157], v[164:165] op_sel_hi:[1,0]
	v_pk_mul_f32 v[126:127], v[126:127], v[158:159]
	v_pk_mul_f32 v[124:125], v[124:125], v[156:157]
	v_pk_add_f32 v[156:157], v[160:161], 1.0 op_sel_hi:[1,0]
	v_pk_add_f32 v[160:161], v[166:167], 1.0 op_sel_hi:[1,0]
	v_mov_b32_e32 v166, v157
	v_mov_b32_e32 v167, v161
	v_mov_b32_e32 v168, v156
	v_mov_b32_e32 v169, v160
	v_pk_mul_f32 v[166:167], v[166:167], v[168:169]
	v_pk_mul_f32 v[118:119], v[126:127], v[118:119]
	v_mul_f32_e32 v164, v166, v167
	v_rcp_f32_e32 v164, v164
	v_pk_mul_f32 v[116:117], v[124:125], v[116:117]
	v_lshlrev_b64 v[146:147], 1, v[146:147]
	v_lshl_add_u64 v[162:163], v[162:163], 0, v[146:147]
	v_mul_f32_e32 v124, v167, v164
	v_mul_f32_e32 v126, v166, v164
	v_pk_mul_f32 v[126:127], v[160:161], v[126:127] op_sel_hi:[1,0]
; __device__ __forceinline__ unsigned cvt_pk_bf16(float lo, float hi) { unsigned r; asm volatile("v_cvt_pk_bf16_f32 %0, %1, %2" : "=v"(r) : "v"(lo), "v"(hi)); return r; }
; __device__ __forceinline__ f32x4 sigmoid4(f32x4 x) {
;     f32x4 d;
; #pragma unroll
;     for (int j = 0; j < 4; ++j) d[j] = 1.0f + __expf(-fmaxf(x[j], -20.0f));
;     const float p01 = d[0] * d[1], p23 = d[2] * d[3], r = __builtin_amdgcn_rcpf(p01 * p23), r01 = r * p23, r23 = r * p01;
;     return (f32x4){r01 * d[1], r01 * d[0], r23 * d[3], r23 * d[2]};
; }
;     __device__ __forceinline__ void operator()(const f32x4 (&acc)[2][2][4][2], const Unit& u, int wr, int wc, int fr, int fq) const {
;         const int row0 = u.pm * BM + wr * 64 + fr, col0 = u.pn * HALF + wc * 32 + 8 * fq;
; #pragma unroll
;         for (int ai = 0; ai < 2; ++ai)
; #pragma unroll
;             for (int m = 0; m < 4; ++m) { bf16_t* rowp = O + (size_t)(row0 + ai * HALF + m * 16) * ldc + col0;
;                 f32x4 v0, v1;
; #pragma unroll
;                 for (int j = 0; j < 1; ++j) { v0 = acc[ai][0][m][0] * sigmoid4(acc[ai][0][m][0]) * acc[ai][1][m][0]; v1 = acc[ai][0][m][1] * sigmoid4(acc[ai][0][m][1]) * acc[ai][1][m][1]; }
;                 u32x4 w; w.x = cvt_pk_bf16(v0[0], v0[1]); w.y = cvt_pk_bf16(v0[2], v0[3]); w.z = cvt_pk_bf16(v1[0], v1[1]); w.w = cvt_pk_bf16(v1[2], v1[3]);
;                 *(u32x4*)rowp = w; }
	v_pk_mul_f32 v[124:125], v[156:157], v[124:125] op_sel_hi:[1,0]
	v_pk_mul_f32 v[122:123], v[122:123], v[126:127]
	v_pk_mul_f32 v[120:121], v[120:121], v[124:125]
	v_pk_mul_f32 v[122:123], v[122:123], v[114:115]
	v_pk_mul_f32 v[114:115], v[120:121], v[112:113]
	v_cvt_pk_bf16_f32 v112, v116, v117
	v_cvt_pk_bf16_f32 v113, v118, v119
	v_max_f32_e32 v116, 0xc1a00000, v108
	v_max_f32_e32 v118, 0xc1a00000, v110
	v_mul_f32_e32 v116, 0xbfb8aa3b, v116
	v_mul_f32_e32 v118, 0xbfb8aa3b, v118
	v_exp_f32_e32 v117, v116
	v_exp_f32_e32 v119, v118
	v_max_f32_e32 v116, 0xc1a00000, v109
	v_max_f32_e32 v118, 0xc1a00000, v111
	v_mul_f32_e32 v116, 0xbfb8aa3b, v116
	v_mul_f32_e32 v118, 0xbfb8aa3b, v118
	v_exp_f32_e32 v116, v116
	v_exp_f32_e32 v118, v118
	v_cvt_pk_bf16_f32 v114, v114, v115
	v_cvt_pk_bf16_f32 v115, v122, v123
	global_store_dwordx4 v[162:163], v[112:115], off
	v_or_b32_e32 v120, 16, v155
	s_and_b64 vcc, exec, s[2:3]
	v_pk_add_f32 v[112:113], v[116:117], 1.0 op_sel_hi:[1,0]
	v_pk_add_f32 v[114:115], v[118:119], 1.0 op_sel_hi:[1,0]
	v_mov_b32_e32 v116, v113
	v_mov_b32_e32 v117, v115
	v_mov_b32_e32 v118, v112
	v_mov_b32_e32 v119, v114
	v_pk_mul_f32 v[116:117], v[116:117], v[118:119]
	s_mov_b32 s53, s14
	v_mul_f32_e32 v118, v116, v117
	v_rcp_f32_e32 v121, v118
	v_mad_i64_i32 v[118:119], s[28:29], v120, s52, v[144:145]
	v_lshl_add_u64 v[118:119], v[118:119], 0, v[146:147]
	v_mul_f32_e32 v116, v116, v121
	v_mul_f32_e32 v120, v117, v121
	v_pk_mul_f32 v[114:115], v[114:115], v[116:117] op_sel_hi:[1,0]
	v_max_f32_e32 v116, 0xc1a00000, v104
	v_max_f32_e32 v121, 0xc1a00000, v106
	v_mul_f32_e32 v116, 0xbfb8aa3b, v116
	v_mul_f32_e32 v121, 0xbfb8aa3b, v121
	v_exp_f32_e32 v117, v116
	v_exp_f32_e32 v123, v121
	v_max_f32_e32 v116, 0xc1a00000, v105
	v_max_f32_e32 v121, 0xc1a00000, v107
	v_mul_f32_e32 v116, 0xbfb8aa3b, v116
	v_mul_f32_e32 v121, 0xbfb8aa3b, v121
	v_exp_f32_e32 v116, v116
	v_exp_f32_e32 v122, v121
	v_pk_mul_f32 v[112:113], v[112:113], v[120:121] op_sel_hi:[1,0]
	v_pk_mul_f32 v[110:111], v[110:111], v[114:115]
	v_pk_mul_f32 v[108:109], v[108:109], v[112:113]
	v_pk_add_f32 v[112:113], v[116:117], 1.0 op_sel_hi:[1,0]
	v_pk_add_f32 v[116:117], v[122:123], 1.0 op_sel_hi:[1,0]
	v_mov_b32_e32 v120, v113
	v_mov_b32_e32 v121, v117
	v_mov_b32_e32 v122, v112
	v_mov_b32_e32 v123, v116
	v_pk_mul_f32 v[120:121], v[120:121], v[122:123]
	v_pk_mul_f32 v[102:103], v[110:111], v[102:103]
	v_mul_f32_e32 v122, v120, v121
	v_rcp_f32_e32 v122, v122
	v_pk_mul_f32 v[100:101], v[108:109], v[100:101]
	s_mov_b32 s26, s16
	s_mov_b64 s[30:31], s[24:25]
	v_mul_f32_e32 v108, v121, v122
	v_mul_f32_e32 v110, v120, v122
	v_pk_mul_f32 v[110:111], v[116:117], v[110:111] op_sel_hi:[1,0]
	v_pk_mul_f32 v[108:109], v[112:113], v[108:109] op_sel_hi:[1,0]
	v_pk_mul_f32 v[106:107], v[106:107], v[110:111]
	v_pk_mul_f32 v[104:105], v[104:105], v[108:109]
	v_pk_mul_f32 v[106:107], v[106:107], v[98:99]
	v_pk_mul_f32 v[98:99], v[104:105], v[96:97]
	v_cvt_pk_bf16_f32 v96, v100, v101
	v_cvt_pk_bf16_f32 v97, v102, v103
	v_max_f32_e32 v100, 0xc1a00000, v92
	v_max_f32_e32 v102, 0xc1a00000, v94
	v_mul_f32_e32 v100, 0xbfb8aa3b, v100
	v_mul_f32_e32 v102, 0xbfb8aa3b, v102
	v_exp_f32_e32 v101, v100
	v_exp_f32_e32 v103, v102
	v_max_f32_e32 v100, 0xc1a00000, v93
	v_max_f32_e32 v102, 0xc1a00000, v95
	v_mul_f32_e32 v100, 0xbfb8aa3b, v100
	v_mul_f32_e32 v102, 0xbfb8aa3b, v102
	v_exp_f32_e32 v100, v100
	v_exp_f32_e32 v102, v102
	v_cvt_pk_bf16_f32 v98, v98, v99
	v_cvt_pk_bf16_f32 v99, v106, v107
	global_store_dwordx4 v[118:119], v[96:99], off
	v_or_b32_e32 v104, 32, v155
	s_nop 0
	v_pk_add_f32 v[96:97], v[100:101], 1.0 op_sel_hi:[1,0]
	v_pk_add_f32 v[98:99], v[102:103], 1.0 op_sel_hi:[1,0]
	v_mov_b32_e32 v100, v97
	v_mov_b32_e32 v101, v99
	v_mov_b32_e32 v102, v96
	v_mov_b32_e32 v103, v98
	v_pk_mul_f32 v[100:101], v[100:101], v[102:103]
	s_nop 0
	v_mul_f32_e32 v102, v100, v101
	v_rcp_f32_e32 v105, v102
	v_mad_i64_i32 v[102:103], s[28:29], v104, s52, v[144:145]
	v_lshl_add_u64 v[102:103], v[102:103], 0, v[146:147]
	v_mul_f32_e32 v100, v100, v105
	v_mul_f32_e32 v104, v101, v105
	v_pk_mul_f32 v[98:99], v[98:99], v[100:101] op_sel_hi:[1,0]
	v_max_f32_e32 v100, 0xc1a00000, v88
	v_max_f32_e32 v105, 0xc1a00000, v90
	v_mul_f32_e32 v100, 0xbfb8aa3b, v100
	v_mul_f32_e32 v105, 0xbfb8aa3b, v105
	v_exp_f32_e32 v101, v100
	v_exp_f32_e32 v107, v105
	v_max_f32_e32 v100, 0xc1a00000, v89
	v_max_f32_e32 v105, 0xc1a00000, v91
	v_mul_f32_e32 v100, 0xbfb8aa3b, v100
	v_mul_f32_e32 v105, 0xbfb8aa3b, v105
	v_exp_f32_e32 v100, v100
	v_exp_f32_e32 v106, v105
	v_pk_mul_f32 v[96:97], v[96:97], v[104:105] op_sel_hi:[1,0]
	v_pk_mul_f32 v[94:95], v[94:95], v[98:99]
	v_pk_mul_f32 v[92:93], v[92:93], v[96:97]
	v_pk_add_f32 v[96:97], v[100:101], 1.0 op_sel_hi:[1,0]
	v_pk_add_f32 v[100:101], v[106:107], 1.0 op_sel_hi:[1,0]
	v_mov_b32_e32 v104, v97
	v_mov_b32_e32 v105, v101
	v_mov_b32_e32 v106, v96
	v_mov_b32_e32 v107, v100
	v_pk_mul_f32 v[104:105], v[104:105], v[106:107]
	v_pk_mul_f32 v[86:87], v[94:95], v[86:87]
	v_mul_f32_e32 v106, v104, v105
	v_rcp_f32_e32 v106, v106
	v_pk_mul_f32 v[84:85], v[92:93], v[84:85]
	v_mul_f32_e32 v92, v105, v106
	v_mul_f32_e32 v94, v104, v106
	v_pk_mul_f32 v[94:95], v[100:101], v[94:95] op_sel_hi:[1,0]
	v_pk_mul_f32 v[92:93], v[96:97], v[92:93] op_sel_hi:[1,0]
	v_pk_mul_f32 v[90:91], v[90:91], v[94:95]
	v_pk_mul_f32 v[88:89], v[88:89], v[92:93]
	v_pk_mul_f32 v[90:91], v[90:91], v[82:83]
	v_pk_mul_f32 v[82:83], v[88:89], v[80:81]
	v_cvt_pk_bf16_f32 v80, v84, v85
	v_cvt_pk_bf16_f32 v81, v86, v87
	v_max_f32_e32 v84, 0xc1a00000, v76
	v_max_f32_e32 v86, 0xc1a00000, v78
	v_mul_f32_e32 v84, 0xbfb8aa3b, v84
; __device__ __forceinline__ unsigned cvt_pk_bf16(float lo, float hi) { unsigned r; asm volatile("v_cvt_pk_bf16_f32 %0, %1, %2" : "=v"(r) : "v"(lo), "v"(hi)); return r; }
; __device__ __forceinline__ f32x4 sigmoid4(f32x4 x) {
;     f32x4 d;
; #pragma unroll
;     for (int j = 0; j < 4; ++j) d[j] = 1.0f + __expf(-fmaxf(x[j], -20.0f));
;     const float p01 = d[0] * d[1], p23 = d[2] * d[3], r = __builtin_amdgcn_rcpf(p01 * p23), r01 = r * p23, r23 = r * p01;
;     return (f32x4){r01 * d[1], r01 * d[0], r23 * d[3], r23 * d[2]};
; }
;     __device__ __forceinline__ void operator()(const f32x4 (&acc)[2][2][4][2], const Unit& u, int wr, int wc, int fr, int fq) const {
;         const int row0 = u.pm * BM + wr * 64 + fr, col0 = u.pn * HALF + wc * 32 + 8 * fq;
; #pragma unroll
;         for (int ai = 0; ai < 2; ++ai)
; #pragma unroll
;             for (int m = 0; m < 4; ++m) { bf16_t* rowp = O + (size_t)(row0 + ai * HALF + m * 16) * ldc + col0;
;                 f32x4 v0, v1;
; #pragma unroll
;                 for (int j = 0; j < 1; ++j) { v0 = acc[ai][0][m][0] * sigmoid4(acc[ai][0][m][0]) * acc[ai][1][m][0]; v1 = acc[ai][0][m][1] * sigmoid4(acc[ai][0][m][1]) * acc[ai][1][m][1]; }
;                 u32x4 w; w.x = cvt_pk_bf16(v0[0], v0[1]); w.y = cvt_pk_bf16(v0[2], v0[3]); w.z = cvt_pk_bf16(v1[0], v1[1]); w.w = cvt_pk_bf16(v1[2], v1[3]);
;                 *(u32x4*)rowp = w; }
	v_mul_f32_e32 v86, 0xbfb8aa3b, v86
	v_exp_f32_e32 v85, v84
	v_exp_f32_e32 v87, v86
	v_max_f32_e32 v84, 0xc1a00000, v77
	v_max_f32_e32 v86, 0xc1a00000, v79
	v_mul_f32_e32 v84, 0xbfb8aa3b, v84
	v_mul_f32_e32 v86, 0xbfb8aa3b, v86
	v_exp_f32_e32 v84, v84
	v_exp_f32_e32 v86, v86
	v_cvt_pk_bf16_f32 v82, v82, v83
	v_cvt_pk_bf16_f32 v83, v90, v91
	global_store_dwordx4 v[102:103], v[80:83], off
	v_or_b32_e32 v88, 48, v155
	s_nop 0
	v_pk_add_f32 v[80:81], v[84:85], 1.0 op_sel_hi:[1,0]
	v_pk_add_f32 v[82:83], v[86:87], 1.0 op_sel_hi:[1,0]
	v_mov_b32_e32 v84, v81
	v_mov_b32_e32 v85, v83
	v_mov_b32_e32 v86, v80
	v_mov_b32_e32 v87, v82
	v_pk_mul_f32 v[84:85], v[84:85], v[86:87]
	s_nop 0
	v_mul_f32_e32 v86, v84, v85
	v_rcp_f32_e32 v89, v86
	v_mad_i64_i32 v[86:87], s[28:29], v88, s52, v[144:145]
	v_lshl_add_u64 v[86:87], v[86:87], 0, v[146:147]
	v_mul_f32_e32 v84, v84, v89
	v_mul_f32_e32 v88, v85, v89
	v_pk_mul_f32 v[82:83], v[82:83], v[84:85] op_sel_hi:[1,0]
	v_max_f32_e32 v84, 0xc1a00000, v72
	v_max_f32_e32 v89, 0xc1a00000, v74
	v_mul_f32_e32 v84, 0xbfb8aa3b, v84
	v_mul_f32_e32 v89, 0xbfb8aa3b, v89
	v_exp_f32_e32 v85, v84
	v_exp_f32_e32 v91, v89
	v_max_f32_e32 v84, 0xc1a00000, v73
	v_max_f32_e32 v89, 0xc1a00000, v75
	v_mul_f32_e32 v84, 0xbfb8aa3b, v84
	v_mul_f32_e32 v89, 0xbfb8aa3b, v89
	v_exp_f32_e32 v84, v84
	v_exp_f32_e32 v90, v89
	v_pk_mul_f32 v[80:81], v[80:81], v[88:89] op_sel_hi:[1,0]
	v_pk_mul_f32 v[78:79], v[78:79], v[82:83]
	v_pk_mul_f32 v[76:77], v[76:77], v[80:81]
	v_pk_add_f32 v[80:81], v[84:85], 1.0 op_sel_hi:[1,0]
	v_pk_add_f32 v[84:85], v[90:91], 1.0 op_sel_hi:[1,0]
	v_mov_b32_e32 v88, v81
	v_mov_b32_e32 v89, v85
	v_mov_b32_e32 v90, v80
	v_mov_b32_e32 v91, v84
	v_pk_mul_f32 v[88:89], v[88:89], v[90:91]
	v_pk_mul_f32 v[70:71], v[78:79], v[70:71]
	v_mul_f32_e32 v90, v88, v89
	v_rcp_f32_e32 v90, v90
	v_pk_mul_f32 v[68:69], v[76:77], v[68:69]
	v_mul_f32_e32 v76, v89, v90
	v_mul_f32_e32 v78, v88, v90
	v_pk_mul_f32 v[78:79], v[84:85], v[78:79] op_sel_hi:[1,0]
	v_pk_mul_f32 v[76:77], v[80:81], v[76:77] op_sel_hi:[1,0]
	v_pk_mul_f32 v[74:75], v[74:75], v[78:79]
	v_pk_mul_f32 v[72:73], v[72:73], v[76:77]
	v_pk_mul_f32 v[74:75], v[74:75], v[66:67]
	v_pk_mul_f32 v[66:67], v[72:73], v[64:65]
	v_cvt_pk_bf16_f32 v64, v68, v69
	v_cvt_pk_bf16_f32 v65, v70, v71
	v_max_f32_e32 v68, 0xc1a00000, v60
	v_max_f32_e32 v70, 0xc1a00000, v62
	v_mul_f32_e32 v68, 0xbfb8aa3b, v68
	v_mul_f32_e32 v70, 0xbfb8aa3b, v70
	v_exp_f32_e32 v69, v68
	v_exp_f32_e32 v71, v70
	v_max_f32_e32 v68, 0xc1a00000, v61
	v_max_f32_e32 v70, 0xc1a00000, v63
	v_mul_f32_e32 v68, 0xbfb8aa3b, v68
	v_mul_f32_e32 v70, 0xbfb8aa3b, v70
	v_exp_f32_e32 v68, v68
	v_exp_f32_e32 v70, v70
	v_cvt_pk_bf16_f32 v66, v66, v67
	v_cvt_pk_bf16_f32 v67, v74, v75
	global_store_dwordx4 v[86:87], v[64:67], off
	v_add_u32_e32 v72, 0x80, v155
	s_nop 0
	v_pk_add_f32 v[64:65], v[68:69], 1.0 op_sel_hi:[1,0]
	v_pk_add_f32 v[66:67], v[70:71], 1.0 op_sel_hi:[1,0]
	v_mov_b32_e32 v68, v65
	v_mov_b32_e32 v69, v67
	v_mov_b32_e32 v70, v64
	v_mov_b32_e32 v71, v66
	v_pk_mul_f32 v[68:69], v[68:69], v[70:71]
	s_nop 0
	v_mul_f32_e32 v70, v68, v69
	v_rcp_f32_e32 v73, v70
	v_mad_i64_i32 v[70:71], s[28:29], v72, s52, v[144:145]
	v_lshl_add_u64 v[70:71], v[70:71], 0, v[146:147]
	v_mul_f32_e32 v68, v68, v73
	v_mul_f32_e32 v72, v69, v73
	v_pk_mul_f32 v[66:67], v[66:67], v[68:69] op_sel_hi:[1,0]
	v_max_f32_e32 v68, 0xc1a00000, v56
	v_max_f32_e32 v73, 0xc1a00000, v58
	v_mul_f32_e32 v68, 0xbfb8aa3b, v68
	v_mul_f32_e32 v73, 0xbfb8aa3b, v73
	v_exp_f32_e32 v69, v68
	v_exp_f32_e32 v75, v73
	v_max_f32_e32 v68, 0xc1a00000, v57
	v_max_f32_e32 v73, 0xc1a00000, v59
	v_mul_f32_e32 v68, 0xbfb8aa3b, v68
	v_mul_f32_e32 v73, 0xbfb8aa3b, v73
	v_exp_f32_e32 v68, v68
	v_exp_f32_e32 v74, v73
	v_pk_mul_f32 v[64:65], v[64:65], v[72:73] op_sel_hi:[1,0]
	v_pk_mul_f32 v[62:63], v[62:63], v[66:67]
	v_pk_mul_f32 v[60:61], v[60:61], v[64:65]
	v_pk_add_f32 v[64:65], v[68:69], 1.0 op_sel_hi:[1,0]
	v_pk_add_f32 v[68:69], v[74:75], 1.0 op_sel_hi:[1,0]
	v_mov_b32_e32 v72, v65
	v_mov_b32_e32 v73, v69
	v_mov_b32_e32 v74, v64
	v_mov_b32_e32 v75, v68
	v_pk_mul_f32 v[72:73], v[72:73], v[74:75]
	v_pk_mul_f32 v[54:55], v[62:63], v[54:55]
	v_mul_f32_e32 v74, v72, v73
	v_rcp_f32_e32 v74, v74
	v_pk_mul_f32 v[52:53], v[60:61], v[52:53]
	v_mul_f32_e32 v60, v73, v74
	v_mul_f32_e32 v62, v72, v74
	v_pk_mul_f32 v[62:63], v[68:69], v[62:63] op_sel_hi:[1,0]
	v_pk_mul_f32 v[60:61], v[64:65], v[60:61] op_sel_hi:[1,0]
	v_pk_mul_f32 v[58:59], v[58:59], v[62:63]
	v_pk_mul_f32 v[56:57], v[56:57], v[60:61]
	v_pk_mul_f32 v[58:59], v[58:59], v[50:51]
	v_pk_mul_f32 v[50:51], v[56:57], v[48:49]
	v_cvt_pk_bf16_f32 v48, v52, v53
	v_cvt_pk_bf16_f32 v49, v54, v55
	v_max_f32_e32 v52, 0xc1a00000, v44
	v_max_f32_e32 v54, 0xc1a00000, v46
	v_mul_f32_e32 v52, 0xbfb8aa3b, v52
	v_mul_f32_e32 v54, 0xbfb8aa3b, v54
	v_exp_f32_e32 v53, v52
	v_exp_f32_e32 v55, v54
	v_max_f32_e32 v52, 0xc1a00000, v45
	v_max_f32_e32 v54, 0xc1a00000, v47
	v_mul_f32_e32 v52, 0xbfb8aa3b, v52
	v_mul_f32_e32 v54, 0xbfb8aa3b, v54
	v_exp_f32_e32 v52, v52
	v_exp_f32_e32 v54, v54
	v_cvt_pk_bf16_f32 v50, v50, v51
	v_cvt_pk_bf16_f32 v51, v58, v59
	global_store_dwordx4 v[70:71], v[48:51], off
	v_add_u32_e32 v56, 0x90, v155
	s_nop 0
	v_pk_add_f32 v[48:49], v[52:53], 1.0 op_sel_hi:[1,0]
	v_pk_add_f32 v[50:51], v[54:55], 1.0 op_sel_hi:[1,0]
	v_mov_b32_e32 v52, v49
	v_mov_b32_e32 v53, v51
	v_mov_b32_e32 v54, v48
	v_mov_b32_e32 v55, v50
	v_pk_mul_f32 v[52:53], v[52:53], v[54:55]
	s_nop 0
	v_mul_f32_e32 v54, v52, v53
	v_rcp_f32_e32 v57, v54
	v_mad_i64_i32 v[54:55], s[28:29], v56, s52, v[144:145]
	v_lshl_add_u64 v[54:55], v[54:55], 0, v[146:147]
; __device__ __forceinline__ unsigned cvt_pk_bf16(float lo, float hi) { unsigned r; asm volatile("v_cvt_pk_bf16_f32 %0, %1, %2" : "=v"(r) : "v"(lo), "v"(hi)); return r; }
; __device__ __forceinline__ f32x4 sigmoid4(f32x4 x) {
;     f32x4 d;
; #pragma unroll
;     for (int j = 0; j < 4; ++j) d[j] = 1.0f + __expf(-fmaxf(x[j], -20.0f));
;     const float p01 = d[0] * d[1], p23 = d[2] * d[3], r = __builtin_amdgcn_rcpf(p01 * p23), r01 = r * p23, r23 = r * p01;
;     return (f32x4){r01 * d[1], r01 * d[0], r23 * d[3], r23 * d[2]};
; }
;     __device__ __forceinline__ void operator()(const f32x4 (&acc)[2][2][4][2], const Unit& u, int wr, int wc, int fr, int fq) const {
;         const int row0 = u.pm * BM + wr * 64 + fr, col0 = u.pn * HALF + wc * 32 + 8 * fq;
; #pragma unroll
;         for (int ai = 0; ai < 2; ++ai)
; #pragma unroll
;             for (int m = 0; m < 4; ++m) { bf16_t* rowp = O + (size_t)(row0 + ai * HALF + m * 16) * ldc + col0;
;                 f32x4 v0, v1;
; #pragma unroll
;                 for (int j = 0; j < 1; ++j) { v0 = acc[ai][0][m][0] * sigmoid4(acc[ai][0][m][0]) * acc[ai][1][m][0]; v1 = acc[ai][0][m][1] * sigmoid4(acc[ai][0][m][1]) * acc[ai][1][m][1]; }
;                 u32x4 w; w.x = cvt_pk_bf16(v0[0], v0[1]); w.y = cvt_pk_bf16(v0[2], v0[3]); w.z = cvt_pk_bf16(v1[0], v1[1]); w.w = cvt_pk_bf16(v1[2], v1[3]);
;                 *(u32x4*)rowp = w; }
	v_mul_f32_e32 v52, v52, v57
	v_mul_f32_e32 v56, v53, v57
	v_pk_mul_f32 v[50:51], v[50:51], v[52:53] op_sel_hi:[1,0]
	v_max_f32_e32 v52, 0xc1a00000, v40
	v_max_f32_e32 v57, 0xc1a00000, v42
	v_mul_f32_e32 v52, 0xbfb8aa3b, v52
	v_mul_f32_e32 v57, 0xbfb8aa3b, v57
	v_exp_f32_e32 v53, v52
	v_exp_f32_e32 v59, v57
	v_max_f32_e32 v52, 0xc1a00000, v41
	v_max_f32_e32 v57, 0xc1a00000, v43
	v_mul_f32_e32 v52, 0xbfb8aa3b, v52
	v_mul_f32_e32 v57, 0xbfb8aa3b, v57
	v_exp_f32_e32 v52, v52
	v_exp_f32_e32 v58, v57
	v_pk_mul_f32 v[48:49], v[48:49], v[56:57] op_sel_hi:[1,0]
	v_pk_mul_f32 v[46:47], v[46:47], v[50:51]
	v_pk_mul_f32 v[44:45], v[44:45], v[48:49]
	v_pk_add_f32 v[48:49], v[52:53], 1.0 op_sel_hi:[1,0]
	v_pk_add_f32 v[52:53], v[58:59], 1.0 op_sel_hi:[1,0]
	v_mov_b32_e32 v56, v49
	v_mov_b32_e32 v57, v53
	v_mov_b32_e32 v58, v48
	v_mov_b32_e32 v59, v52
	v_pk_mul_f32 v[56:57], v[56:57], v[58:59]
	v_pk_mul_f32 v[38:39], v[46:47], v[38:39]
	v_mul_f32_e32 v58, v56, v57
	v_rcp_f32_e32 v58, v58
	v_pk_mul_f32 v[36:37], v[44:45], v[36:37]
	v_mul_f32_e32 v44, v57, v58
	v_mul_f32_e32 v46, v56, v58
	v_pk_mul_f32 v[46:47], v[52:53], v[46:47] op_sel_hi:[1,0]
	v_pk_mul_f32 v[44:45], v[48:49], v[44:45] op_sel_hi:[1,0]
	v_pk_mul_f32 v[42:43], v[42:43], v[46:47]
	v_pk_mul_f32 v[40:41], v[40:41], v[44:45]
	v_pk_mul_f32 v[42:43], v[42:43], v[34:35]
	v_pk_mul_f32 v[34:35], v[40:41], v[32:33]
	v_cvt_pk_bf16_f32 v32, v36, v37
	v_cvt_pk_bf16_f32 v33, v38, v39
	v_max_f32_e32 v36, 0xc1a00000, v28
	v_max_f32_e32 v38, 0xc1a00000, v30
	v_mul_f32_e32 v36, 0xbfb8aa3b, v36
	v_mul_f32_e32 v38, 0xbfb8aa3b, v38
	v_exp_f32_e32 v37, v36
	v_exp_f32_e32 v39, v38
	v_max_f32_e32 v36, 0xc1a00000, v29
	v_max_f32_e32 v38, 0xc1a00000, v31
	v_mul_f32_e32 v36, 0xbfb8aa3b, v36
	v_mul_f32_e32 v38, 0xbfb8aa3b, v38
	v_exp_f32_e32 v36, v36
	v_exp_f32_e32 v38, v38
	v_cvt_pk_bf16_f32 v34, v34, v35
	v_cvt_pk_bf16_f32 v35, v42, v43
	global_store_dwordx4 v[54:55], v[32:35], off
	v_add_u32_e32 v40, 0xa0, v155
	s_nop 0
	v_pk_add_f32 v[32:33], v[36:37], 1.0 op_sel_hi:[1,0]
	v_pk_add_f32 v[34:35], v[38:39], 1.0 op_sel_hi:[1,0]
	v_mov_b32_e32 v36, v33
	v_mov_b32_e32 v37, v35
	v_mov_b32_e32 v38, v32
	v_mov_b32_e32 v39, v34
	v_pk_mul_f32 v[36:37], v[36:37], v[38:39]
	s_nop 0
	v_mul_f32_e32 v38, v36, v37
	v_rcp_f32_e32 v41, v38
	v_mad_i64_i32 v[38:39], s[28:29], v40, s52, v[144:145]
	v_lshl_add_u64 v[38:39], v[38:39], 0, v[146:147]
	v_mul_f32_e32 v36, v36, v41
	v_mul_f32_e32 v40, v37, v41
	v_pk_mul_f32 v[34:35], v[34:35], v[36:37] op_sel_hi:[1,0]
	v_max_f32_e32 v36, 0xc1a00000, v24
	v_max_f32_e32 v41, 0xc1a00000, v26
	v_mul_f32_e32 v36, 0xbfb8aa3b, v36
	v_mul_f32_e32 v41, 0xbfb8aa3b, v41
	v_exp_f32_e32 v37, v36
	v_exp_f32_e32 v43, v41
	v_max_f32_e32 v36, 0xc1a00000, v25
	v_max_f32_e32 v41, 0xc1a00000, v27
	v_mul_f32_e32 v36, 0xbfb8aa3b, v36
	v_mul_f32_e32 v41, 0xbfb8aa3b, v41
	v_exp_f32_e32 v36, v36
	v_exp_f32_e32 v42, v41
	v_pk_mul_f32 v[32:33], v[32:33], v[40:41] op_sel_hi:[1,0]
	v_pk_mul_f32 v[30:31], v[30:31], v[34:35]
	v_pk_mul_f32 v[28:29], v[28:29], v[32:33]
	v_pk_add_f32 v[32:33], v[36:37], 1.0 op_sel_hi:[1,0]
	v_pk_add_f32 v[36:37], v[42:43], 1.0 op_sel_hi:[1,0]
	v_mov_b32_e32 v40, v33
	v_mov_b32_e32 v41, v37
	v_mov_b32_e32 v42, v32
	v_mov_b32_e32 v43, v36
	v_pk_mul_f32 v[40:41], v[40:41], v[42:43]
	v_pk_mul_f32 v[22:23], v[30:31], v[22:23]
	v_mul_f32_e32 v42, v40, v41
	v_rcp_f32_e32 v42, v42
	v_pk_mul_f32 v[20:21], v[28:29], v[20:21]
	v_mul_f32_e32 v28, v41, v42
	v_mul_f32_e32 v30, v40, v42
	v_pk_mul_f32 v[30:31], v[36:37], v[30:31] op_sel_hi:[1,0]
	v_pk_mul_f32 v[28:29], v[32:33], v[28:29] op_sel_hi:[1,0]
	v_pk_mul_f32 v[26:27], v[26:27], v[30:31]
	v_pk_mul_f32 v[24:25], v[24:25], v[28:29]
	v_pk_mul_f32 v[26:27], v[26:27], v[18:19]
	v_pk_mul_f32 v[18:19], v[24:25], v[16:17]
	v_cvt_pk_bf16_f32 v16, v20, v21
	v_cvt_pk_bf16_f32 v17, v22, v23
	v_max_f32_e32 v20, 0xc1a00000, v12
	v_max_f32_e32 v22, 0xc1a00000, v14
	v_mul_f32_e32 v20, 0xbfb8aa3b, v20
	v_mul_f32_e32 v22, 0xbfb8aa3b, v22
	v_exp_f32_e32 v21, v20
	v_exp_f32_e32 v23, v22
	v_max_f32_e32 v20, 0xc1a00000, v13
	v_max_f32_e32 v22, 0xc1a00000, v15
	v_mul_f32_e32 v20, 0xbfb8aa3b, v20
	v_mul_f32_e32 v22, 0xbfb8aa3b, v22
	v_exp_f32_e32 v20, v20
	v_exp_f32_e32 v22, v22
	v_cvt_pk_bf16_f32 v18, v18, v19
	v_cvt_pk_bf16_f32 v19, v26, v27
	global_store_dwordx4 v[38:39], v[16:19], off
	v_add_u32_e32 v24, 0xb0, v155
	s_nop 0
	v_pk_add_f32 v[16:17], v[20:21], 1.0 op_sel_hi:[1,0]
	v_pk_add_f32 v[18:19], v[22:23], 1.0 op_sel_hi:[1,0]
	v_mov_b32_e32 v20, v17
	v_mov_b32_e32 v21, v19
	v_mov_b32_e32 v22, v16
	v_mov_b32_e32 v23, v18
	v_pk_mul_f32 v[20:21], v[20:21], v[22:23]
	s_nop 0
	v_mul_f32_e32 v22, v20, v21
	v_rcp_f32_e32 v25, v22
	v_mad_i64_i32 v[22:23], s[28:29], v24, s52, v[144:145]
	v_lshl_add_u64 v[22:23], v[22:23], 0, v[146:147]
	v_mul_f32_e32 v20, v20, v25
	v_mul_f32_e32 v24, v21, v25
	v_pk_mul_f32 v[18:19], v[18:19], v[20:21] op_sel_hi:[1,0]
	v_max_f32_e32 v20, 0xc1a00000, v8
	v_max_f32_e32 v25, 0xc1a00000, v10
	v_mul_f32_e32 v20, 0xbfb8aa3b, v20
	v_mul_f32_e32 v25, 0xbfb8aa3b, v25
	v_exp_f32_e32 v21, v20
	v_exp_f32_e32 v27, v25
	v_max_f32_e32 v20, 0xc1a00000, v9
	v_max_f32_e32 v25, 0xc1a00000, v11
	v_mul_f32_e32 v20, 0xbfb8aa3b, v20
	v_mul_f32_e32 v25, 0xbfb8aa3b, v25
	v_exp_f32_e32 v20, v20
	v_exp_f32_e32 v26, v25
	v_pk_mul_f32 v[16:17], v[16:17], v[24:25] op_sel_hi:[1,0]
	v_pk_mul_f32 v[14:15], v[14:15], v[18:19]
	v_pk_mul_f32 v[12:13], v[12:13], v[16:17]
	v_pk_add_f32 v[16:17], v[20:21], 1.0 op_sel_hi:[1,0]
	v_pk_add_f32 v[20:21], v[26:27], 1.0 op_sel_hi:[1,0]
	v_mov_b32_e32 v24, v17
	v_mov_b32_e32 v25, v21
	v_mov_b32_e32 v26, v16
	v_mov_b32_e32 v27, v20
	v_pk_mul_f32 v[24:25], v[24:25], v[26:27]
	v_pk_mul_f32 v[6:7], v[14:15], v[6:7]
	v_mul_f32_e32 v26, v24, v25
	v_rcp_f32_e32 v26, v26
	v_pk_mul_f32 v[4:5], v[12:13], v[4:5]
	s_mov_b64 s[28:29], s[18:19]
	v_mul_f32_e32 v12, v25, v26
	v_mul_f32_e32 v14, v24, v26
	v_pk_mul_f32 v[14:15], v[20:21], v[14:15] op_sel_hi:[1,0]
	v_pk_mul_f32 v[12:13], v[16:17], v[12:13] op_sel_hi:[1,0]
	v_pk_mul_f32 v[10:11], v[10:11], v[14:15]
	v_pk_mul_f32 v[8:9], v[8:9], v[12:13]
	v_pk_mul_f32 v[10:11], v[10:11], v[2:3]
	v_pk_mul_f32 v[2:3], v[8:9], v[0:1]
	v_cvt_pk_bf16_f32 v0, v4, v5
	v_cvt_pk_bf16_f32 v1, v6, v7
	s_nop 0
	v_cvt_pk_bf16_f32 v2, v2, v3
	v_cvt_pk_bf16_f32 v3, v10, v11
	global_store_dwordx4 v[22:23], v[0:3], off
	s_cbranch_vccz .LBB0_192
	s_waitcnt vmcnt(0)
	s_cmpk_gt_u32 s37, 0xff
	s_cbranch_scc1 .LBB0_199
	s_barrier

; #define PG8_STAGE(bufoff, gbase, voff) do { _Pragma("unroll") for (int _i = 0; _i < 2; ++_i) \
;         __builtin_amdgcn_global_load_lds((const unsigned*)((const char*)(gbase) + (voff)[_i]), (PG8_LAS unsigned*)(lds + (bufoff) + ldsw + _i * 8192), 16, 0, 0); } while (0)
; #define PG8_LDA(dst, b, h) do { _Pragma("unroll") for (int m = 0; m < 4; ++m) _Pragma("unroll") for (int k = 0; k < 2; ++k) dst[m][k] = *(const PG8_LAS bf16x8*)(lds + PG8_SA(b, h) + aoff + m * 2048 + k * 1024); } while (0)
; #define PG8_LDB(dst, b, h) do { _Pragma("unroll") for (int n = 0; n < 2; ++n) _Pragma("unroll") for (int k = 0; k < 2; ++k) dst[n][k] = *(const PG8_LAS bf16x8*)(lds + PG8_SB(b, h) + boff + n * 2048 + k * 1024); } while (0)
; #define PG8_MMA(ai, bj, At, Bt) do { __builtin_amdgcn_s_setprio(1); _Pragma("unroll") for (int m = 0; m < 4; ++m) _Pragma("unroll") for (int n = 0; n < 2; ++n) _Pragma("unroll") for (int k = 0; k < 2; ++k) \
;         acc[ai][bj][m][n] = __builtin_amdgcn_mfma_f32_16x16x32_bf16(Bt[n][k], At[m][k], acc[ai][bj][m][n], 0, 0, 0); __builtin_amdgcn_s_setprio(0); } while (0)
; #define PG8_WAIT_V(n) asm volatile("s_waitcnt vmcnt(" #n ")" ::: "memory")
; #define PG8_WAIT_L(n) asm volatile("s_waitcnt lgkmcnt(" #n ")" ::: "memory")
; #define PG8_BAR __builtin_amdgcn_s_barrier()
; #define PG8_SCHED __builtin_amdgcn_sched_barrier(0)
; template <class Epi, class Sched>
; __device__ __forceinline__ void gemm_phase(PG8_LAS unsigned char* lds, const Gemm g, const Sched& S, const Epi& E) {
;     ...
;             PG8_LDB(B0, 0, 0); PG8_SCHED; PG8_LDA(At, 0, 0); PG8_STAGE(PG8_SA(1, 1), a1 + hstep, voffA);
;             PG8_WAIT_L(8); PG8_BAR; PG8_WAIT_L(0); PG8_MMA(0, 0, At, B0); PG8_BAR; PG8_SCHED;
;             PG8_LDB(B1, 0, 1); PG8_STAGE(PG8_SB(0, 0), b2, voffB);
;             PG8_BAR; PG8_WAIT_L(0); PG8_MMA(0, 1, At, B1); PG8_BAR;
;             PG8_LDA(At, 0, 1); PG8_STAGE(PG8_SA(0, 0), a2, voffA);
;             PG8_BAR; PG8_WAIT_L(0); PG8_MMA(1, 0, At, B0); PG8_BAR; PG8_SCHED;
;             PG8_STAGE(PG8_SB(0, 1), b2 + hstep, voffB);
;             PG8_WAIT_V(6); PG8_BAR; PG8_MMA(1, 1, At, B1); PG8_BAR;
.LBB0_285:
	s_add_u32 s55, s24, 0x100
	s_addc_u32 s56, s25, 0
	s_mov_b32 s57, -2
	ds_read_b128 v[154:157], v149
	ds_read_b128 v[158:161], v149 offset:1024
	ds_read_b128 v[166:169], v149 offset:2048
	ds_read_b128 v[170:173], v149 offset:3072
	s_add_u32 s24, s22, 0x100
	s_addc_u32 s25, s23, 0
	s_cmp_eq_u32 s57, 40
	s_cselect_b32 s29, s1, s25
	s_cselect_b32 s28, s0, s24
	s_cselect_b32 s27, s5, s56
	s_cselect_b32 s26, s4, s55
	ds_read_b128 v[182:185], v150
	ds_read_b128 v[190:193], v150 offset:1024
	ds_read_b128 v[194:197], v150 offset:2048
	ds_read_b128 v[198:201], v150 offset:3072
	ds_read_b128 v[202:205], v150 offset:4096
	ds_read_b128 v[206:209], v150 offset:5120
	ds_read_b128 v[210:213], v150 offset:6144
	ds_read_b128 v[214:217], v150 offset:7168
	s_waitcnt lgkmcnt(8)
	ds_read_b128 v[218:221], v151
	ds_read_b128 v[222:225], v151 offset:1024
	ds_read_b128 v[226:229], v151 offset:2048
	ds_read_b128 v[230:233], v151 offset:3072
	s_add_i32 m0, s38, 0xc000
	s_nop 0
	global_load_lds_dwordx4 v136, s[22:23]
	s_nop 1
	s_add_i32 m0, s38, 0xe000
	s_nop 0
	global_load_lds_dwordx4 v138, s[22:23]
	s_waitcnt vmcnt(8) lgkmcnt(0)
	s_barrier
	v_mfma_f32_16x16x32_bf16 v[124:127], v[154:157], v[182:185], 0
	v_mfma_f32_16x16x32_bf16 v[120:123], v[166:169], v[182:185], 0
	v_mfma_f32_16x16x32_bf16 v[108:111], v[154:157], v[194:197], 0
	v_mfma_f32_16x16x32_bf16 v[104:107], v[166:169], v[194:197], 0
	v_mfma_f32_16x16x32_bf16 v[92:95], v[154:157], v[202:205], 0
	v_mfma_f32_16x16x32_bf16 v[88:91], v[166:169], v[202:205], 0
	v_mfma_f32_16x16x32_bf16 v[76:79], v[154:157], v[210:213], 0
	v_mfma_f32_16x16x32_bf16 v[72:75], v[166:169], v[210:213], 0
	v_mfma_f32_16x16x32_bf16 v[124:127], v[158:161], v[190:193], v[124:127]
	v_mfma_f32_16x16x32_bf16 v[120:123], v[170:173], v[190:193], v[120:123]
	v_mfma_f32_16x16x32_bf16 v[108:111], v[158:161], v[198:201], v[108:111]
	v_mfma_f32_16x16x32_bf16 v[104:107], v[170:173], v[198:201], v[104:107]
	v_mfma_f32_16x16x32_bf16 v[92:95], v[158:161], v[206:209], v[92:95]
	v_mfma_f32_16x16x32_bf16 v[88:91], v[170:173], v[206:209], v[88:91]
	v_mfma_f32_16x16x32_bf16 v[76:79], v[158:161], v[214:217], v[76:79]
	v_mfma_f32_16x16x32_bf16 v[72:75], v[170:173], v[214:217], v[72:75]
	v_mfma_f32_16x16x32_bf16 v[116:119], v[218:221], v[182:185], 0
	v_mfma_f32_16x16x32_bf16 v[112:115], v[226:229], v[182:185], 0
	v_mfma_f32_16x16x32_bf16 v[100:103], v[218:221], v[194:197], 0
	v_mfma_f32_16x16x32_bf16 v[96:99], v[226:229], v[194:197], 0
	v_mfma_f32_16x16x32_bf16 v[84:87], v[218:221], v[202:205], 0
	v_mfma_f32_16x16x32_bf16 v[80:83], v[226:229], v[202:205], 0
	v_mfma_f32_16x16x32_bf16 v[68:71], v[218:221], v[210:213], 0
	v_mfma_f32_16x16x32_bf16 v[64:67], v[226:229], v[210:213], 0
	v_mfma_f32_16x16x32_bf16 v[116:119], v[222:225], v[190:193], v[116:119]
	v_mfma_f32_16x16x32_bf16 v[112:115], v[230:233], v[190:193], v[112:115]
	v_mfma_f32_16x16x32_bf16 v[100:103], v[222:225], v[198:201], v[100:103]
	v_mfma_f32_16x16x32_bf16 v[96:99], v[230:233], v[198:201], v[96:99]
	v_mfma_f32_16x16x32_bf16 v[84:87], v[222:225], v[206:209], v[84:87]
	v_mfma_f32_16x16x32_bf16 v[80:83], v[230:233], v[206:209], v[80:83]
	v_mfma_f32_16x16x32_bf16 v[68:71], v[222:225], v[214:217], v[68:71]
	v_mfma_f32_16x16x32_bf16 v[64:67], v[230:233], v[214:217], v[64:67]
	s_barrier
	ds_read_b128 v[182:185], v150 offset:16384
	ds_read_b128 v[190:193], v150 offset:17408
	ds_read_b128 v[194:197], v150 offset:18432
	ds_read_b128 v[198:201], v150 offset:19456
	ds_read_b128 v[202:205], v150 offset:20480
	ds_read_b128 v[206:209], v150 offset:21504
	ds_read_b128 v[210:213], v150 offset:22528
	ds_read_b128 v[214:217], v150 offset:23552
	s_add_i32 s22, s46, s37
	s_add_u32 s98, s26, s14
	s_addc_u32 s99, s27, s15
	s_mov_b32 m0, s22
	s_nop 0
	global_load_lds_dwordx4 v130, s[26:27]
	s_nop 1
	s_add_i32 m0, s22, 0x2000
	s_nop 0
	global_load_lds_dwordx4 v134, s[26:27]
	s_nop 1
	s_mov_b32 m0, s38
	s_add_u32 s100, s28, s14
	s_addc_u32 s101, s29, s15
	global_load_lds_dwordx4 v128, s[28:29]
	s_nop 1
	s_mov_b32 m0, s39
	s_nop 0
	global_load_lds_dwordx4 v132, s[28:29]
	s_add_u32 s22, s26, 0xb0000
	s_addc_u32 s23, s27, 0
	s_add_i32 s58, s47, s37
	s_mov_b32 m0, s58
	s_nop 0
	global_load_lds_dwordx4 v130, s[22:23]
	s_nop 1
	s_add_i32 m0, s58, 0x2000
	s_nop 0
	global_load_lds_dwordx4 v134, s[22:23]
	s_waitcnt vmcnt(8) lgkmcnt(0)
	s_barrier
	v_mfma_f32_16x16x32_bf16 v[60:63], v[154:157], v[182:185], 0
	v_mfma_f32_16x16x32_bf16 v[56:59], v[166:169], v[182:185], 0
	v_mfma_f32_16x16x32_bf16 v[48:51], v[154:157], v[194:197], 0
	v_mfma_f32_16x16x32_bf16 v[40:43], v[166:169], v[194:197], 0
	v_mfma_f32_16x16x32_bf16 v[32:35], v[154:157], v[202:205], 0
	v_mfma_f32_16x16x32_bf16 v[24:27], v[166:169], v[202:205], 0
	v_mfma_f32_16x16x32_bf16 v[16:19], v[154:157], v[210:213], 0
	v_mfma_f32_16x16x32_bf16 v[8:11], v[166:169], v[210:213], 0
	v_mfma_f32_16x16x32_bf16 v[60:63], v[158:161], v[190:193], v[60:63]
	v_mfma_f32_16x16x32_bf16 v[56:59], v[170:173], v[190:193], v[56:59]
	v_mfma_f32_16x16x32_bf16 v[48:51], v[158:161], v[198:201], v[48:51]
	v_mfma_f32_16x16x32_bf16 v[40:43], v[170:173], v[198:201], v[40:43]
	v_mfma_f32_16x16x32_bf16 v[32:35], v[158:161], v[206:209], v[32:35]
	v_mfma_f32_16x16x32_bf16 v[24:27], v[170:173], v[206:209], v[24:27]
	v_mfma_f32_16x16x32_bf16 v[16:19], v[158:161], v[214:217], v[16:19]
	v_mfma_f32_16x16x32_bf16 v[8:11], v[170:173], v[214:217], v[8:11]
	v_mfma_f32_16x16x32_bf16 v[52:55], v[218:221], v[182:185], 0
	v_mfma_f32_16x16x32_bf16 v[44:47], v[226:229], v[182:185], 0
	v_mfma_f32_16x16x32_bf16 v[36:39], v[218:221], v[194:197], 0
	v_mfma_f32_16x16x32_bf16 v[28:31], v[226:229], v[194:197], 0
	v_mfma_f32_16x16x32_bf16 v[20:23], v[218:221], v[202:205], 0
	v_mfma_f32_16x16x32_bf16 v[12:15], v[226:229], v[202:205], 0
	v_mfma_f32_16x16x32_bf16 v[4:7], v[218:221], v[210:213], 0
	v_mfma_f32_16x16x32_bf16 v[0:3], v[226:229], v[210:213], 0
	v_mfma_f32_16x16x32_bf16 v[52:55], v[222:225], v[190:193], v[52:55]
	v_mfma_f32_16x16x32_bf16 v[44:47], v[230:233], v[190:193], v[44:47]
	v_mfma_f32_16x16x32_bf16 v[36:39], v[222:225], v[198:201], v[36:39]
	v_mfma_f32_16x16x32_bf16 v[28:31], v[230:233], v[198:201], v[28:31]
	v_mfma_f32_16x16x32_bf16 v[20:23], v[222:225], v[206:209], v[20:23]
	v_mfma_f32_16x16x32_bf16 v[12:15], v[230:233], v[206:209], v[12:15]
	v_mfma_f32_16x16x32_bf16 v[4:7], v[222:225], v[214:217], v[4:7]
	v_mfma_f32_16x16x32_bf16 v[0:3], v[230:233], v[214:217], v[0:3]
	s_barrier
; #define PG8_STAGE(bufoff, gbase, voff) do { _Pragma("unroll") for (int _i = 0; _i < 2; ++_i) \
;         __builtin_amdgcn_global_load_lds((const unsigned*)((const char*)(gbase) + (voff)[_i]), (PG8_LAS unsigned*)(lds + (bufoff) + ldsw + _i * 8192), 16, 0, 0); } while (0)
; #define PG8_LDA(dst, b, h) do { _Pragma("unroll") for (int m = 0; m < 4; ++m) _Pragma("unroll") for (int k = 0; k < 2; ++k) dst[m][k] = *(const PG8_LAS bf16x8*)(lds + PG8_SA(b, h) + aoff + m * 2048 + k * 1024); } while (0)
; #define PG8_LDB(dst, b, h) do { _Pragma("unroll") for (int n = 0; n < 2; ++n) _Pragma("unroll") for (int k = 0; k < 2; ++k) dst[n][k] = *(const PG8_LAS bf16x8*)(lds + PG8_SB(b, h) + boff + n * 2048 + k * 1024); } while (0)
; #define PG8_MMA(ai, bj, At, Bt) do { __builtin_amdgcn_s_setprio(1); _Pragma("unroll") for (int m = 0; m < 4; ++m) _Pragma("unroll") for (int n = 0; n < 2; ++n) _Pragma("unroll") for (int k = 0; k < 2; ++k) \
;         acc[ai][bj][m][n] = __builtin_amdgcn_mfma_f32_16x16x32_bf16(Bt[n][k], At[m][k], acc[ai][bj][m][n], 0, 0, 0); __builtin_amdgcn_s_setprio(0); } while (0)
; #define PG8_WAIT_V(n) asm volatile("s_waitcnt vmcnt(" #n ")" ::: "memory")
; #define PG8_WAIT_L(n) asm volatile("s_waitcnt lgkmcnt(" #n ")" ::: "memory")
; #define PG8_BAR __builtin_amdgcn_s_barrier()
; #define PG8_SCHED __builtin_amdgcn_sched_barrier(0)
; template <class Epi, class Sched>
; __device__ __forceinline__ void gemm_phase(PG8_LAS unsigned char* lds, const Gemm g, const Sched& S, const Epi& E) {
;     ...
;             PG8_LDB(B0, 1, 0); PG8_SCHED; PG8_LDA(At, 1, 0); PG8_STAGE(PG8_SA(0, 1), a2 + hstep, voffA);
;             PG8_WAIT_L(8); PG8_BAR; PG8_WAIT_L(0); PG8_MMA(0, 0, At, B0); PG8_BAR; PG8_SCHED;
;             PG8_LDB(B1, 1, 1); PG8_STAGE(PG8_SB(1, 0), b3, voffB);
;             PG8_BAR; PG8_WAIT_L(0); PG8_MMA(0, 1, At, B1); PG8_BAR;
;             PG8_LDA(At, 1, 1); PG8_STAGE(PG8_SA(1, 0), a3, voffA);
;             PG8_BAR; PG8_WAIT_L(0); PG8_MMA(1, 0, At, B0); PG8_BAR; PG8_SCHED;
;             PG8_STAGE(PG8_SB(1, 1), b3 + hstep, voffB);
;             PG8_WAIT_V(6); PG8_BAR; PG8_MMA(1, 1, At, B1); PG8_BAR;
	s_add_i32 s58, 0, 0x18000
	v_add_u32_e32 v153, s58, v147
	ds_read_b128 v[154:157], v153
	ds_read_b128 v[158:161], v153 offset:1024
	ds_read_b128 v[166:169], v153 offset:2048
	ds_read_b128 v[170:173], v153 offset:3072
	ds_read_b128 v[182:185], v150 offset:32768
	ds_read_b128 v[190:193], v150 offset:33792
	ds_read_b128 v[194:197], v150 offset:34816
	ds_read_b128 v[198:201], v150 offset:35840
	ds_read_b128 v[202:205], v150 offset:36864
	ds_read_b128 v[206:209], v150 offset:37888
	ds_read_b128 v[210:213], v150 offset:38912
	ds_read_b128 v[214:217], v150 offset:39936
	v_add_u32_e32 v153, 0x1c000, v147
	s_waitcnt lgkmcnt(8)
	ds_read_b128 v[218:221], v153
	ds_read_b128 v[222:225], v153 offset:1024
	ds_read_b128 v[226:229], v153 offset:2048
	ds_read_b128 v[230:233], v153 offset:3072
	s_add_u32 s22, s28, 0xb0000
	s_addc_u32 s23, s29, 0
	s_mov_b32 m0, s40
	s_nop 0
	global_load_lds_dwordx4 v128, s[22:23]
	s_nop 1
	s_mov_b32 m0, s41
	s_nop 0
	global_load_lds_dwordx4 v132, s[22:23]
	s_add_i32 s28, 0, 0x1c000
	s_waitcnt vmcnt(8) lgkmcnt(0)
	s_barrier
	v_mfma_f32_16x16x32_bf16 v[124:127], v[154:157], v[182:185], v[124:127]
	v_mfma_f32_16x16x32_bf16 v[120:123], v[166:169], v[182:185], v[120:123]
	v_mfma_f32_16x16x32_bf16 v[108:111], v[154:157], v[194:197], v[108:111]
	v_mfma_f32_16x16x32_bf16 v[104:107], v[166:169], v[194:197], v[104:107]
	v_mfma_f32_16x16x32_bf16 v[92:95], v[154:157], v[202:205], v[92:95]
	v_mfma_f32_16x16x32_bf16 v[88:91], v[166:169], v[202:205], v[88:91]
	v_mfma_f32_16x16x32_bf16 v[76:79], v[154:157], v[210:213], v[76:79]
	v_mfma_f32_16x16x32_bf16 v[72:75], v[166:169], v[210:213], v[72:75]
	v_mfma_f32_16x16x32_bf16 v[124:127], v[158:161], v[190:193], v[124:127]
	v_mfma_f32_16x16x32_bf16 v[120:123], v[170:173], v[190:193], v[120:123]
	v_mfma_f32_16x16x32_bf16 v[108:111], v[158:161], v[198:201], v[108:111]
	v_mfma_f32_16x16x32_bf16 v[104:107], v[170:173], v[198:201], v[104:107]
	v_mfma_f32_16x16x32_bf16 v[92:95], v[158:161], v[206:209], v[92:95]
	v_mfma_f32_16x16x32_bf16 v[88:91], v[170:173], v[206:209], v[88:91]
	v_mfma_f32_16x16x32_bf16 v[76:79], v[158:161], v[214:217], v[76:79]
	v_mfma_f32_16x16x32_bf16 v[72:75], v[170:173], v[214:217], v[72:75]
	v_mfma_f32_16x16x32_bf16 v[116:119], v[218:221], v[182:185], v[116:119]
	v_mfma_f32_16x16x32_bf16 v[112:115], v[226:229], v[182:185], v[112:115]
	v_mfma_f32_16x16x32_bf16 v[100:103], v[218:221], v[194:197], v[100:103]
	v_mfma_f32_16x16x32_bf16 v[96:99], v[226:229], v[194:197], v[96:99]
	v_mfma_f32_16x16x32_bf16 v[84:87], v[218:221], v[202:205], v[84:87]
	v_mfma_f32_16x16x32_bf16 v[80:83], v[226:229], v[202:205], v[80:83]
	v_mfma_f32_16x16x32_bf16 v[68:71], v[218:221], v[210:213], v[68:71]
	v_mfma_f32_16x16x32_bf16 v[64:67], v[226:229], v[210:213], v[64:67]
	v_mfma_f32_16x16x32_bf16 v[116:119], v[222:225], v[190:193], v[116:119]
	v_mfma_f32_16x16x32_bf16 v[112:115], v[230:233], v[190:193], v[112:115]
	v_mfma_f32_16x16x32_bf16 v[100:103], v[222:225], v[198:201], v[100:103]
	v_mfma_f32_16x16x32_bf16 v[96:99], v[230:233], v[198:201], v[96:99]
	v_mfma_f32_16x16x32_bf16 v[84:87], v[222:225], v[206:209], v[84:87]
	v_mfma_f32_16x16x32_bf16 v[80:83], v[230:233], v[206:209], v[80:83]
	v_mfma_f32_16x16x32_bf16 v[68:71], v[222:225], v[214:217], v[68:71]
	v_mfma_f32_16x16x32_bf16 v[64:67], v[230:233], v[214:217], v[64:67]
	s_barrier
	ds_read_b128 v[182:185], v150 offset:49152
	ds_read_b128 v[190:193], v150 offset:50176
	ds_read_b128 v[194:197], v150 offset:51200
	ds_read_b128 v[198:201], v150 offset:52224
	ds_read_b128 v[202:205], v150 offset:53248
	ds_read_b128 v[206:209], v150 offset:54272
	ds_read_b128 v[210:213], v150 offset:55296
	ds_read_b128 v[214:217], v150 offset:56320
	s_add_i32 s22, s58, s37
	s_mov_b32 m0, s22
	s_nop 0
	global_load_lds_dwordx4 v130, s[98:99]
	s_nop 1
	s_add_i32 m0, s22, 0x2000
	s_nop 0
	global_load_lds_dwordx4 v134, s[98:99]
	s_nop 1
	s_mov_b32 m0, s43
	s_nop 0
	global_load_lds_dwordx4 v128, s[100:101]
	s_nop 1
	s_mov_b32 m0, s44
	s_nop 0
	global_load_lds_dwordx4 v132, s[100:101]
	s_add_u32 s22, s26, 0xb0080
	s_addc_u32 s23, s27, 0
	s_add_i32 s26, s28, s37
	s_mov_b32 m0, s26
	s_nop 0
	global_load_lds_dwordx4 v130, s[22:23]
	s_nop 1
	s_add_i32 m0, s26, 0x2000
	s_nop 0
	global_load_lds_dwordx4 v134, s[22:23]
	s_waitcnt vmcnt(8) lgkmcnt(0)
	s_barrier
	v_mfma_f32_16x16x32_bf16 v[60:63], v[154:157], v[182:185], v[60:63]
	v_mfma_f32_16x16x32_bf16 v[56:59], v[166:169], v[182:185], v[56:59]
	v_mfma_f32_16x16x32_bf16 v[48:51], v[154:157], v[194:197], v[48:51]
	v_mfma_f32_16x16x32_bf16 v[40:43], v[166:169], v[194:197], v[40:43]
	v_mfma_f32_16x16x32_bf16 v[32:35], v[154:157], v[202:205], v[32:35]
	v_mfma_f32_16x16x32_bf16 v[24:27], v[166:169], v[202:205], v[24:27]
	v_mfma_f32_16x16x32_bf16 v[16:19], v[154:157], v[210:213], v[16:19]
	v_mfma_f32_16x16x32_bf16 v[8:11], v[166:169], v[210:213], v[8:11]
	v_mfma_f32_16x16x32_bf16 v[60:63], v[158:161], v[190:193], v[60:63]
	v_mfma_f32_16x16x32_bf16 v[56:59], v[170:173], v[190:193], v[56:59]
	v_mfma_f32_16x16x32_bf16 v[48:51], v[158:161], v[198:201], v[48:51]
	v_mfma_f32_16x16x32_bf16 v[40:43], v[170:173], v[198:201], v[40:43]
	v_mfma_f32_16x16x32_bf16 v[32:35], v[158:161], v[206:209], v[32:35]
	v_mfma_f32_16x16x32_bf16 v[24:27], v[170:173], v[206:209], v[24:27]
	v_mfma_f32_16x16x32_bf16 v[16:19], v[158:161], v[214:217], v[16:19]
	v_mfma_f32_16x16x32_bf16 v[8:11], v[170:173], v[214:217], v[8:11]
	v_mfma_f32_16x16x32_bf16 v[52:55], v[218:221], v[182:185], v[52:55]
	v_mfma_f32_16x16x32_bf16 v[44:47], v[226:229], v[182:185], v[44:47]
	v_mfma_f32_16x16x32_bf16 v[36:39], v[218:221], v[194:197], v[36:39]
	v_mfma_f32_16x16x32_bf16 v[28:31], v[226:229], v[194:197], v[28:31]
	v_mfma_f32_16x16x32_bf16 v[20:23], v[218:221], v[202:205], v[20:23]
	v_mfma_f32_16x16x32_bf16 v[12:15], v[226:229], v[202:205], v[12:15]
	v_mfma_f32_16x16x32_bf16 v[4:7], v[218:221], v[210:213], v[4:7]
	v_mfma_f32_16x16x32_bf16 v[0:3], v[226:229], v[210:213], v[0:3]
	v_mfma_f32_16x16x32_bf16 v[52:55], v[222:225], v[190:193], v[52:55]
	v_mfma_f32_16x16x32_bf16 v[44:47], v[230:233], v[190:193], v[44:47]
	v_mfma_f32_16x16x32_bf16 v[36:39], v[222:225], v[198:201], v[36:39]
	v_mfma_f32_16x16x32_bf16 v[28:31], v[230:233], v[198:201], v[28:31]
	v_mfma_f32_16x16x32_bf16 v[20:23], v[222:225], v[206:209], v[20:23]
	v_mfma_f32_16x16x32_bf16 v[12:15], v[230:233], v[206:209], v[12:15]
	v_mfma_f32_16x16x32_bf16 v[4:7], v[222:225], v[214:217], v[4:7]
	v_mfma_f32_16x16x32_bf16 v[0:3], v[230:233], v[214:217], v[0:3]
	s_barrier
	s_add_i32 s57, s57, 2
	s_add_u32 s55, s55, 0x100
	s_addc_u32 s56, s56, 0
	s_cmp_gt_u32 s57, 41
	s_mov_b64 s[22:23], s[24:25]
; #define PG8_STAGE(bufoff, gbase, voff) do { _Pragma("unroll") for (int _i = 0; _i < 2; ++_i) \
;         __builtin_amdgcn_global_load_lds((const unsigned*)((const char*)(gbase) + (voff)[_i]), (PG8_LAS unsigned*)(lds + (bufoff) + ldsw + _i * 8192), 16, 0, 0); } while (0)
; #define PG8_LDA(dst, b, h) do { _Pragma("unroll") for (int m = 0; m < 4; ++m) _Pragma("unroll") for (int k = 0; k < 2; ++k) dst[m][k] = *(const PG8_LAS bf16x8*)(lds + PG8_SA(b, h) + aoff + m * 2048 + k * 1024); } while (0)
; #define PG8_WAIT_V(n) asm volatile("s_waitcnt vmcnt(" #n ")" ::: "memory")
; template <class Epi, class Sched>
; __device__ __forceinline__ void gemm_phase(PG8_LAS unsigned char* lds, const Gemm g, const Sched& S, const Epi& E) {
;     ...
;         for (int t = 0; t < nt; t += 2) {
;             const bool last = (t == nt - 2);
;             const char* a1 = cA + (size_t)(t + 1) * kstep;
;             const char* a2 = last ? nA : cA + (size_t)(t + 2) * kstep; const char* b2 = last ? nB : cB + (size_t)(t + 2) * kstep;
;             const char* a3 = a2 + kstep; const char* b3 = b2 + kstep;
;             if (last && has_next) S.a_ready(nxt);
;             PG8_LDB(B0, 0, 0); PG8_SCHED; PG8_LDA(At, 0, 0); PG8_STAGE(PG8_SA(1, 1), a1 + hstep, voffA);
;             PG8_WAIT_L(8); PG8_BAR; PG8_WAIT_L(0); PG8_MMA(0, 0, At, B0); PG8_BAR; PG8_SCHED;
;             PG8_LDB(B1, 0, 1); PG8_STAGE(PG8_SB(0, 0), b2, voffB);
;             PG8_BAR; PG8_WAIT_L(0); PG8_MMA(0, 1, At, B1); PG8_BAR;
;             PG8_LDA(At, 0, 1); PG8_STAGE(PG8_SA(0, 0), a2, voffA);
;             PG8_BAR; PG8_WAIT_L(0); PG8_MMA(1, 0, At, B0); PG8_BAR; PG8_SCHED;
;             PG8_STAGE(PG8_SB(0, 1), b2 + hstep, voffB);
;             PG8_WAIT_V(6); PG8_BAR; PG8_MMA(1, 1, At, B1); PG8_BAR;
;             PG8_LDB(B0, 1, 0); PG8_SCHED; PG8_LDA(At, 1, 0); PG8_STAGE(PG8_SA(0, 1), a2 + hstep, voffA);
;             PG8_WAIT_L(8); PG8_BAR; PG8_WAIT_L(0); PG8_MMA(0, 0, At, B0); PG8_BAR; PG8_SCHED;
;             PG8_LDB(B1, 1, 1); PG8_STAGE(PG8_SB(1, 0), b3, voffB);
;             PG8_BAR; PG8_WAIT_L(0); PG8_MMA(0, 1, At, B1); PG8_BAR;
;             PG8_LDA(At, 1, 1); PG8_STAGE(PG8_SA(1, 0), a3, voffA);
;             PG8_BAR; PG8_WAIT_L(0); PG8_MMA(1, 0, At, B0); PG8_BAR; PG8_SCHED;
;             PG8_STAGE(PG8_SB(1, 1), b3 + hstep, voffB);
;             PG8_WAIT_V(6); PG8_BAR; PG8_MMA(1, 1, At, B1); PG8_BAR;
.LBB0_286:
	ds_read_b128 v[154:157], v149
	ds_read_b128 v[158:161], v149 offset:1024
	ds_read_b128 v[166:169], v149 offset:2048
	ds_read_b128 v[170:173], v149 offset:3072
	s_add_u32 s24, s22, 0x100
	s_addc_u32 s25, s23, 0
	s_cmp_eq_u32 s57, 40
	s_cselect_b32 s29, s1, s25
	s_cselect_b32 s28, s0, s24
	s_cselect_b32 s27, s5, s56
	s_cselect_b32 s26, s4, s55
	ds_read_b128 v[182:185], v150
	ds_read_b128 v[190:193], v150 offset:1024
	ds_read_b128 v[194:197], v150 offset:2048
	ds_read_b128 v[198:201], v150 offset:3072
	ds_read_b128 v[202:205], v150 offset:4096
	ds_read_b128 v[206:209], v150 offset:5120
	ds_read_b128 v[210:213], v150 offset:6144
	ds_read_b128 v[214:217], v150 offset:7168
	s_waitcnt lgkmcnt(8)
	ds_read_b128 v[218:221], v151
	ds_read_b128 v[222:225], v151 offset:1024
	ds_read_b128 v[226:229], v151 offset:2048
	ds_read_b128 v[230:233], v151 offset:3072
	s_add_i32 m0, s38, 0xc000
	s_nop 0
	global_load_lds_dwordx4 v136, s[22:23]
	s_nop 1
	s_add_i32 m0, s38, 0xe000
	s_nop 0
	global_load_lds_dwordx4 v138, s[22:23]
	s_waitcnt vmcnt(8) lgkmcnt(0)
	s_barrier
	v_mfma_f32_16x16x32_bf16 v[124:127], v[154:157], v[182:185], v[124:127]
	v_mfma_f32_16x16x32_bf16 v[120:123], v[166:169], v[182:185], v[120:123]
	v_mfma_f32_16x16x32_bf16 v[108:111], v[154:157], v[194:197], v[108:111]
	v_mfma_f32_16x16x32_bf16 v[104:107], v[166:169], v[194:197], v[104:107]
	v_mfma_f32_16x16x32_bf16 v[92:95], v[154:157], v[202:205], v[92:95]
	v_mfma_f32_16x16x32_bf16 v[88:91], v[166:169], v[202:205], v[88:91]
	v_mfma_f32_16x16x32_bf16 v[76:79], v[154:157], v[210:213], v[76:79]
	v_mfma_f32_16x16x32_bf16 v[72:75], v[166:169], v[210:213], v[72:75]
	v_mfma_f32_16x16x32_bf16 v[124:127], v[158:161], v[190:193], v[124:127]
	v_mfma_f32_16x16x32_bf16 v[120:123], v[170:173], v[190:193], v[120:123]
	v_mfma_f32_16x16x32_bf16 v[108:111], v[158:161], v[198:201], v[108:111]
	v_mfma_f32_16x16x32_bf16 v[104:107], v[170:173], v[198:201], v[104:107]
	v_mfma_f32_16x16x32_bf16 v[92:95], v[158:161], v[206:209], v[92:95]
	v_mfma_f32_16x16x32_bf16 v[88:91], v[170:173], v[206:209], v[88:91]
	v_mfma_f32_16x16x32_bf16 v[76:79], v[158:161], v[214:217], v[76:79]
	v_mfma_f32_16x16x32_bf16 v[72:75], v[170:173], v[214:217], v[72:75]
	v_mfma_f32_16x16x32_bf16 v[116:119], v[218:221], v[182:185], v[116:119]
	v_mfma_f32_16x16x32_bf16 v[112:115], v[226:229], v[182:185], v[112:115]
	v_mfma_f32_16x16x32_bf16 v[100:103], v[218:221], v[194:197], v[100:103]
	v_mfma_f32_16x16x32_bf16 v[96:99], v[226:229], v[194:197], v[96:99]
	v_mfma_f32_16x16x32_bf16 v[84:87], v[218:221], v[202:205], v[84:87]
	v_mfma_f32_16x16x32_bf16 v[80:83], v[226:229], v[202:205], v[80:83]
	v_mfma_f32_16x16x32_bf16 v[68:71], v[218:221], v[210:213], v[68:71]
	v_mfma_f32_16x16x32_bf16 v[64:67], v[226:229], v[210:213], v[64:67]
	v_mfma_f32_16x16x32_bf16 v[116:119], v[222:225], v[190:193], v[116:119]
	v_mfma_f32_16x16x32_bf16 v[112:115], v[230:233], v[190:193], v[112:115]
	v_mfma_f32_16x16x32_bf16 v[100:103], v[222:225], v[198:201], v[100:103]
	v_mfma_f32_16x16x32_bf16 v[96:99], v[230:233], v[198:201], v[96:99]
	v_mfma_f32_16x16x32_bf16 v[84:87], v[222:225], v[206:209], v[84:87]
	v_mfma_f32_16x16x32_bf16 v[80:83], v[230:233], v[206:209], v[80:83]
	v_mfma_f32_16x16x32_bf16 v[68:71], v[222:225], v[214:217], v[68:71]
	v_mfma_f32_16x16x32_bf16 v[64:67], v[230:233], v[214:217], v[64:67]
	s_barrier
	ds_read_b128 v[182:185], v150 offset:16384
	ds_read_b128 v[190:193], v150 offset:17408
	ds_read_b128 v[194:197], v150 offset:18432
	ds_read_b128 v[198:201], v150 offset:19456
	ds_read_b128 v[202:205], v150 offset:20480
	ds_read_b128 v[206:209], v150 offset:21504
	ds_read_b128 v[210:213], v150 offset:22528
	ds_read_b128 v[214:217], v150 offset:23552
	s_add_i32 s22, s46, s37
	s_add_u32 s98, s26, s14
	s_addc_u32 s99, s27, s15
	s_mov_b32 m0, s22
	s_nop 0
	global_load_lds_dwordx4 v130, s[26:27]
	s_nop 1
	s_add_i32 m0, s22, 0x2000
	s_nop 0
	global_load_lds_dwordx4 v134, s[26:27]
	s_nop 1
	s_mov_b32 m0, s38
	s_add_u32 s100, s28, s14
	s_addc_u32 s101, s29, s15
	global_load_lds_dwordx4 v128, s[28:29]
	s_nop 1
	s_mov_b32 m0, s39
	s_nop 0
	global_load_lds_dwordx4 v132, s[28:29]
	s_add_u32 s22, s26, 0xb0000
	s_addc_u32 s23, s27, 0
	s_add_i32 s58, s47, s37
	s_mov_b32 m0, s58
	s_nop 0
	global_load_lds_dwordx4 v130, s[22:23]
	s_nop 1
	s_add_i32 m0, s58, 0x2000
	s_nop 0
	global_load_lds_dwordx4 v134, s[22:23]
	s_waitcnt vmcnt(8) lgkmcnt(0)
	s_barrier
	v_mfma_f32_16x16x32_bf16 v[60:63], v[154:157], v[182:185], v[60:63]
	v_mfma_f32_16x16x32_bf16 v[56:59], v[166:169], v[182:185], v[56:59]
	v_mfma_f32_16x16x32_bf16 v[48:51], v[154:157], v[194:197], v[48:51]
	v_mfma_f32_16x16x32_bf16 v[40:43], v[166:169], v[194:197], v[40:43]
	v_mfma_f32_16x16x32_bf16 v[32:35], v[154:157], v[202:205], v[32:35]
	v_mfma_f32_16x16x32_bf16 v[24:27], v[166:169], v[202:205], v[24:27]
	v_mfma_f32_16x16x32_bf16 v[16:19], v[154:157], v[210:213], v[16:19]
	v_mfma_f32_16x16x32_bf16 v[8:11], v[166:169], v[210:213], v[8:11]
	v_mfma_f32_16x16x32_bf16 v[60:63], v[158:161], v[190:193], v[60:63]
	v_mfma_f32_16x16x32_bf16 v[56:59], v[170:173], v[190:193], v[56:59]
	v_mfma_f32_16x16x32_bf16 v[48:51], v[158:161], v[198:201], v[48:51]
	v_mfma_f32_16x16x32_bf16 v[40:43], v[170:173], v[198:201], v[40:43]
	v_mfma_f32_16x16x32_bf16 v[32:35], v[158:161], v[206:209], v[32:35]
	v_mfma_f32_16x16x32_bf16 v[24:27], v[170:173], v[206:209], v[24:27]
	v_mfma_f32_16x16x32_bf16 v[16:19], v[158:161], v[214:217], v[16:19]
	v_mfma_f32_16x16x32_bf16 v[8:11], v[170:173], v[214:217], v[8:11]
	v_mfma_f32_16x16x32_bf16 v[52:55], v[218:221], v[182:185], v[52:55]
	v_mfma_f32_16x16x32_bf16 v[44:47], v[226:229], v[182:185], v[44:47]
	v_mfma_f32_16x16x32_bf16 v[36:39], v[218:221], v[194:197], v[36:39]
	v_mfma_f32_16x16x32_bf16 v[28:31], v[226:229], v[194:197], v[28:31]
	v_mfma_f32_16x16x32_bf16 v[20:23], v[218:221], v[202:205], v[20:23]
	v_mfma_f32_16x16x32_bf16 v[12:15], v[226:229], v[202:205], v[12:15]
	v_mfma_f32_16x16x32_bf16 v[4:7], v[218:221], v[210:213], v[4:7]
	v_mfma_f32_16x16x32_bf16 v[0:3], v[226:229], v[210:213], v[0:3]
	v_mfma_f32_16x16x32_bf16 v[52:55], v[222:225], v[190:193], v[52:55]
	v_mfma_f32_16x16x32_bf16 v[44:47], v[230:233], v[190:193], v[44:47]
	v_mfma_f32_16x16x32_bf16 v[36:39], v[222:225], v[198:201], v[36:39]
	v_mfma_f32_16x16x32_bf16 v[28:31], v[230:233], v[198:201], v[28:31]
	v_mfma_f32_16x16x32_bf16 v[20:23], v[222:225], v[206:209], v[20:23]
	v_mfma_f32_16x16x32_bf16 v[12:15], v[230:233], v[206:209], v[12:15]
	v_mfma_f32_16x16x32_bf16 v[4:7], v[222:225], v[214:217], v[4:7]
	v_mfma_f32_16x16x32_bf16 v[0:3], v[230:233], v[214:217], v[0:3]
	s_barrier
; #define PG8_STAGE(bufoff, gbase, voff) do { _Pragma("unroll") for (int _i = 0; _i < 2; ++_i) \
;         __builtin_amdgcn_global_load_lds((const unsigned*)((const char*)(gbase) + (voff)[_i]), (PG8_LAS unsigned*)(lds + (bufoff) + ldsw + _i * 8192), 16, 0, 0); } while (0)
; #define PG8_LDA(dst, b, h) do { _Pragma("unroll") for (int m = 0; m < 4; ++m) _Pragma("unroll") for (int k = 0; k < 2; ++k) dst[m][k] = *(const PG8_LAS bf16x8*)(lds + PG8_SA(b, h) + aoff + m * 2048 + k * 1024); } while (0)
; #define PG8_LDB(dst, b, h) do { _Pragma("unroll") for (int n = 0; n < 2; ++n) _Pragma("unroll") for (int k = 0; k < 2; ++k) dst[n][k] = *(const PG8_LAS bf16x8*)(lds + PG8_SB(b, h) + boff + n * 2048 + k * 1024); } while (0)
; #define PG8_WAIT_V(n) asm volatile("s_waitcnt vmcnt(" #n ")" ::: "memory")
; #define PG8_WAIT_L(n) asm volatile("s_waitcnt lgkmcnt(" #n ")" ::: "memory")
; #define PG8_BAR __builtin_amdgcn_s_barrier()
; #define PG8_SCHED __builtin_amdgcn_sched_barrier(0)
; template <class Epi, class Sched>
; __device__ __forceinline__ void gemm_phase(PG8_LAS unsigned char* lds, const Gemm g, const Sched& S, const Epi& E) {
;     ...
;             PG8_LDB(B0, 0, 0); PG8_SCHED; PG8_LDA(At, 0, 0); PG8_STAGE(PG8_SA(1, 1), a1 + hstep, voffA);
;             PG8_WAIT_L(8); PG8_BAR; PG8_WAIT_L(0); PG8_MMA(0, 0, At, B0); PG8_BAR; PG8_SCHED;
;             PG8_LDB(B1, 0, 1); PG8_STAGE(PG8_SB(0, 0), b2, voffB);
;             PG8_BAR; PG8_WAIT_L(0); PG8_MMA(0, 1, At, B1); PG8_BAR;
;             PG8_LDA(At, 0, 1); PG8_STAGE(PG8_SA(0, 0), a2, voffA);
;             PG8_BAR; PG8_WAIT_L(0); PG8_MMA(1, 0, At, B0); PG8_BAR; PG8_SCHED;
;             PG8_STAGE(PG8_SB(0, 1), b2 + hstep, voffB);
;             PG8_WAIT_V(6); PG8_BAR; PG8_MMA(1, 1, At, B1); PG8_BAR;
;             PG8_LDB(B0, 1, 0); PG8_SCHED; PG8_LDA(At, 1, 0); PG8_STAGE(PG8_SA(0, 1), a2 + hstep, voffA);
;             PG8_WAIT_L(8); PG8_BAR; PG8_WAIT_L(0); PG8_MMA(0, 0, At, B0); PG8_BAR; PG8_SCHED;
;             PG8_LDB(B1, 1, 1); PG8_STAGE(PG8_SB(1, 0), b3, voffB);
;             PG8_BAR; PG8_WAIT_L(0); PG8_MMA(0, 1, At, B1); PG8_BAR;
;             PG8_LDA(At, 1, 1); PG8_STAGE(PG8_SA(1, 0), a3, voffA);
;             PG8_BAR; PG8_WAIT_L(0); PG8_MMA(1, 0, At, B0); PG8_BAR; PG8_SCHED;
;             PG8_STAGE(PG8_SB(1, 1), b3 + hstep, voffB);
;             PG8_WAIT_V(6); PG8_BAR; PG8_MMA(1, 1, At, B1); PG8_BAR;
	s_add_i32 s58, 0, 0x18000
	v_add_u32_e32 v153, s58, v147
	ds_read_b128 v[154:157], v153
	ds_read_b128 v[158:161], v153 offset:1024
	ds_read_b128 v[166:169], v153 offset:2048
	ds_read_b128 v[170:173], v153 offset:3072
	ds_read_b128 v[182:185], v150 offset:32768
	ds_read_b128 v[190:193], v150 offset:33792
	ds_read_b128 v[194:197], v150 offset:34816
	ds_read_b128 v[198:201], v150 offset:35840
	ds_read_b128 v[202:205], v150 offset:36864
	ds_read_b128 v[206:209], v150 offset:37888
	ds_read_b128 v[210:213], v150 offset:38912
	ds_read_b128 v[214:217], v150 offset:39936
	v_add_u32_e32 v153, 0x1c000, v147
	s_waitcnt lgkmcnt(8)
	ds_read_b128 v[218:221], v153
	ds_read_b128 v[222:225], v153 offset:1024
	ds_read_b128 v[226:229], v153 offset:2048
	ds_read_b128 v[230:233], v153 offset:3072
	s_add_u32 s22, s28, 0xb0000
	s_addc_u32 s23, s29, 0
	s_mov_b32 m0, s40
	s_nop 0
	global_load_lds_dwordx4 v128, s[22:23]
	s_nop 1
	s_mov_b32 m0, s41
	s_nop 0
	global_load_lds_dwordx4 v132, s[22:23]
	s_add_i32 s28, 0, 0x1c000
	s_waitcnt vmcnt(8) lgkmcnt(0)
	s_barrier
	v_mfma_f32_16x16x32_bf16 v[124:127], v[154:157], v[182:185], v[124:127]
	v_mfma_f32_16x16x32_bf16 v[120:123], v[166:169], v[182:185], v[120:123]
	v_mfma_f32_16x16x32_bf16 v[108:111], v[154:157], v[194:197], v[108:111]
	v_mfma_f32_16x16x32_bf16 v[104:107], v[166:169], v[194:197], v[104:107]
	v_mfma_f32_16x16x32_bf16 v[92:95], v[154:157], v[202:205], v[92:95]
	v_mfma_f32_16x16x32_bf16 v[88:91], v[166:169], v[202:205], v[88:91]
	v_mfma_f32_16x16x32_bf16 v[76:79], v[154:157], v[210:213], v[76:79]
	v_mfma_f32_16x16x32_bf16 v[72:75], v[166:169], v[210:213], v[72:75]
	v_mfma_f32_16x16x32_bf16 v[124:127], v[158:161], v[190:193], v[124:127]
	v_mfma_f32_16x16x32_bf16 v[120:123], v[170:173], v[190:193], v[120:123]
	v_mfma_f32_16x16x32_bf16 v[108:111], v[158:161], v[198:201], v[108:111]
	v_mfma_f32_16x16x32_bf16 v[104:107], v[170:173], v[198:201], v[104:107]
	v_mfma_f32_16x16x32_bf16 v[92:95], v[158:161], v[206:209], v[92:95]
	v_mfma_f32_16x16x32_bf16 v[88:91], v[170:173], v[206:209], v[88:91]
	v_mfma_f32_16x16x32_bf16 v[76:79], v[158:161], v[214:217], v[76:79]
	v_mfma_f32_16x16x32_bf16 v[72:75], v[170:173], v[214:217], v[72:75]
	v_mfma_f32_16x16x32_bf16 v[116:119], v[218:221], v[182:185], v[116:119]
	v_mfma_f32_16x16x32_bf16 v[112:115], v[226:229], v[182:185], v[112:115]
	v_mfma_f32_16x16x32_bf16 v[100:103], v[218:221], v[194:197], v[100:103]
	v_mfma_f32_16x16x32_bf16 v[96:99], v[226:229], v[194:197], v[96:99]
	v_mfma_f32_16x16x32_bf16 v[84:87], v[218:221], v[202:205], v[84:87]
	v_mfma_f32_16x16x32_bf16 v[80:83], v[226:229], v[202:205], v[80:83]
	v_mfma_f32_16x16x32_bf16 v[68:71], v[218:221], v[210:213], v[68:71]
	v_mfma_f32_16x16x32_bf16 v[64:67], v[226:229], v[210:213], v[64:67]
	v_mfma_f32_16x16x32_bf16 v[116:119], v[222:225], v[190:193], v[116:119]
	v_mfma_f32_16x16x32_bf16 v[112:115], v[230:233], v[190:193], v[112:115]
	v_mfma_f32_16x16x32_bf16 v[100:103], v[222:225], v[198:201], v[100:103]
	v_mfma_f32_16x16x32_bf16 v[96:99], v[230:233], v[198:201], v[96:99]
	v_mfma_f32_16x16x32_bf16 v[84:87], v[222:225], v[206:209], v[84:87]
	v_mfma_f32_16x16x32_bf16 v[80:83], v[230:233], v[206:209], v[80:83]
	v_mfma_f32_16x16x32_bf16 v[68:71], v[222:225], v[214:217], v[68:71]
	v_mfma_f32_16x16x32_bf16 v[64:67], v[230:233], v[214:217], v[64:67]
	s_barrier
	ds_read_b128 v[182:185], v150 offset:49152
	ds_read_b128 v[190:193], v150 offset:50176
	ds_read_b128 v[194:197], v150 offset:51200
	ds_read_b128 v[198:201], v150 offset:52224
	ds_read_b128 v[202:205], v150 offset:53248
	ds_read_b128 v[206:209], v150 offset:54272
	ds_read_b128 v[210:213], v150 offset:55296
	ds_read_b128 v[214:217], v150 offset:56320
	s_add_i32 s22, s58, s37
	s_mov_b32 m0, s22
	s_nop 0
	global_load_lds_dwordx4 v130, s[98:99]
	s_nop 1
	s_add_i32 m0, s22, 0x2000
	s_nop 0
	global_load_lds_dwordx4 v134, s[98:99]
	s_nop 1
	s_mov_b32 m0, s43
	s_nop 0
	global_load_lds_dwordx4 v128, s[100:101]
	s_nop 1
	s_mov_b32 m0, s44
	s_nop 0
	global_load_lds_dwordx4 v132, s[100:101]
	s_add_u32 s22, s26, 0xb0080
	s_addc_u32 s23, s27, 0
	s_add_i32 s26, s28, s37
	s_mov_b32 m0, s26
	s_nop 0
	global_load_lds_dwordx4 v130, s[22:23]
	s_nop 1
	s_add_i32 m0, s26, 0x2000
	s_nop 0
	global_load_lds_dwordx4 v134, s[22:23]
	s_waitcnt vmcnt(8) lgkmcnt(0)
	s_barrier
	v_mfma_f32_16x16x32_bf16 v[60:63], v[154:157], v[182:185], v[60:63]
	v_mfma_f32_16x16x32_bf16 v[56:59], v[166:169], v[182:185], v[56:59]
	v_mfma_f32_16x16x32_bf16 v[48:51], v[154:157], v[194:197], v[48:51]
	v_mfma_f32_16x16x32_bf16 v[40:43], v[166:169], v[194:197], v[40:43]
	v_mfma_f32_16x16x32_bf16 v[32:35], v[154:157], v[202:205], v[32:35]
	v_mfma_f32_16x16x32_bf16 v[24:27], v[166:169], v[202:205], v[24:27]
	v_mfma_f32_16x16x32_bf16 v[16:19], v[154:157], v[210:213], v[16:19]
	v_mfma_f32_16x16x32_bf16 v[8:11], v[166:169], v[210:213], v[8:11]
	v_mfma_f32_16x16x32_bf16 v[60:63], v[158:161], v[190:193], v[60:63]
	v_mfma_f32_16x16x32_bf16 v[56:59], v[170:173], v[190:193], v[56:59]
	v_mfma_f32_16x16x32_bf16 v[48:51], v[158:161], v[198:201], v[48:51]
	v_mfma_f32_16x16x32_bf16 v[40:43], v[170:173], v[198:201], v[40:43]
	v_mfma_f32_16x16x32_bf16 v[32:35], v[158:161], v[206:209], v[32:35]
	v_mfma_f32_16x16x32_bf16 v[24:27], v[170:173], v[206:209], v[24:27]
	v_mfma_f32_16x16x32_bf16 v[16:19], v[158:161], v[214:217], v[16:19]
	v_mfma_f32_16x16x32_bf16 v[8:11], v[170:173], v[214:217], v[8:11]
	v_mfma_f32_16x16x32_bf16 v[52:55], v[218:221], v[182:185], v[52:55]
	v_mfma_f32_16x16x32_bf16 v[44:47], v[226:229], v[182:185], v[44:47]
	v_mfma_f32_16x16x32_bf16 v[36:39], v[218:221], v[194:197], v[36:39]
	v_mfma_f32_16x16x32_bf16 v[28:31], v[226:229], v[194:197], v[28:31]
	v_mfma_f32_16x16x32_bf16 v[20:23], v[218:221], v[202:205], v[20:23]
	v_mfma_f32_16x16x32_bf16 v[12:15], v[226:229], v[202:205], v[12:15]
	v_mfma_f32_16x16x32_bf16 v[4:7], v[218:221], v[210:213], v[4:7]
	v_mfma_f32_16x16x32_bf16 v[0:3], v[226:229], v[210:213], v[0:3]
	v_mfma_f32_16x16x32_bf16 v[52:55], v[222:225], v[190:193], v[52:55]
	v_mfma_f32_16x16x32_bf16 v[44:47], v[230:233], v[190:193], v[44:47]
	v_mfma_f32_16x16x32_bf16 v[36:39], v[222:225], v[198:201], v[36:39]
	v_mfma_f32_16x16x32_bf16 v[28:31], v[230:233], v[198:201], v[28:31]
	v_mfma_f32_16x16x32_bf16 v[20:23], v[222:225], v[206:209], v[20:23]
	v_mfma_f32_16x16x32_bf16 v[12:15], v[230:233], v[206:209], v[12:15]
	v_mfma_f32_16x16x32_bf16 v[4:7], v[222:225], v[214:217], v[4:7]
	v_mfma_f32_16x16x32_bf16 v[0:3], v[230:233], v[214:217], v[0:3]
	s_barrier
; __device__ __forceinline__ unsigned cvt_pk_bf16(float lo, float hi) { unsigned r; asm volatile("v_cvt_pk_bf16_f32 %0, %1, %2" : "=v"(r) : "v"(lo), "v"(hi)); return r; }
; __device__ __forceinline__ float flogsig16(float x) { return (fminf(x, 0.f) - __logf(1.0f + __expf(-fabsf(x)))) * 0.0625f; }
; #define PG8_MMA(ai, bj, At, Bt) do { __builtin_amdgcn_s_setprio(1); _Pragma("unroll") for (int m = 0; m < 4; ++m) _Pragma("unroll") for (int n = 0; n < 2; ++n) _Pragma("unroll") for (int k = 0; k < 2; ++k) \
;         acc[ai][bj][m][n] = __builtin_amdgcn_mfma_f32_16x16x32_bf16(Bt[n][k], At[m][k], acc[ai][bj][m][n], 0, 0, 0); __builtin_amdgcn_s_setprio(0); } while (0)
; #define PG8_WAIT_V(n) asm volatile("s_waitcnt vmcnt(" #n ")" ::: "memory")
; #define PG8_BAR __builtin_amdgcn_s_barrier()
;     __device__ __forceinline__ void operator()(const f32x4 (&acc)[2][2][4][2], const Unit& u, int wr, int wc, int fr, int fq) const {
;     ...
;             for (int m = 0; m < 4; ++m) { bf16_t* rowp = O + (size_t)(row0 + ai * HALF + m * 16) * ldc + col0;
; #pragma unroll
;                 for (int bj = 0; bj < 2; ++bj) { f32x4 v0 = acc[ai][bj][m][0] + bv[bj][0], v1 = acc[ai][bj][m][1] + bv[bj][1];
;                     if (act == 1) {
; #pragma unroll
;                         for (int j = 0; j < 1; ++j) { v0 = v0 * sigmoid4(v0); v1 = v1 * sigmoid4(v1); } }
;                     else if (act == 2) {
; #pragma unroll
;                         for (int j = 0; j < 1; ++j) { v0 = sigmoid4(v0); v1 = sigmoid4(v1); } }
;                     else if (act == 3) {
; #pragma unroll
;                         for (int j = 0; j < 4; ++j) { v0[j] = flogsig16(v0[j]); v1[j] = flogsig16(v1[j]); } }
;                     u32x4 w; w.x = cvt_pk_bf16(v0[0], v0[1]); w.y = cvt_pk_bf16(v0[2], v0[3]); w.z = cvt_pk_bf16(v1[0], v1[1]); w.w = cvt_pk_bf16(v1[2], v1[3]);
;                     *(u32x4*)(rowp + bj * HALF) = w; } }
; template <class Epi, class Sched>
; __device__ __forceinline__ void gemm_phase(PG8_LAS unsigned char* lds, const Gemm g, const Sched& S, const Epi& E) {
;     ...
;             PG8_WAIT_V(6); PG8_BAR; PG8_MMA(1, 1, At, B1); PG8_BAR;
;         }
;         if constexpr (!Epi::AFTER_DRAIN) { E(acc, cur, wr, wc, fr, fq); S.done(cur); }
	s_add_i32 s57, s57, 2
	s_add_u32 s55, s55, 0x100
	s_addc_u32 s56, s56, 0
	s_cmp_gt_u32 s57, 41
	s_mov_b64 s[22:23], s[24:25]
	s_cbranch_scc0 .LBB0_286
	v_lshl_add_u32 v154, s53, 8, v146
	v_lshl_or_b32 v144, s54, 8, v148
	v_ashrrev_i32_e32 v155, 31, v154
	v_ashrrev_i32_e32 v145, 31, v144
	v_lshlrev_b64 v[156:157], 11, v[154:155]
	v_lshl_add_u64 v[156:157], s[10:11], 0, v[156:157]
	v_lshlrev_b64 v[158:159], 1, v[144:145]
	v_lshl_add_u64 v[144:145], v[156:157], 0, v[158:159]
	v_pk_add_f32 v[126:127], v[126:127], 0 op_sel_hi:[1,0]
	v_pk_add_f32 v[124:125], v[124:125], 0 op_sel_hi:[1,0]
	v_pk_add_f32 v[156:157], v[122:123], 0 op_sel_hi:[1,0]
	v_pk_add_f32 v[122:123], v[120:121], 0 op_sel_hi:[1,0]
	v_cvt_pk_bf16_f32 v120, v124, v125
	v_cvt_pk_bf16_f32 v121, v126, v127
	v_pk_add_f32 v[116:117], v[116:117], 0 op_sel_hi:[1,0]
	v_cvt_pk_bf16_f32 v122, v122, v123
	v_cvt_pk_bf16_f32 v123, v156, v157
	global_store_dwordx4 v[144:145], v[120:123], off
	v_pk_add_f32 v[118:119], v[118:119], 0 op_sel_hi:[1,0]
	v_pk_add_f32 v[110:111], v[110:111], 0 op_sel_hi:[1,0]
	v_pk_add_f32 v[120:121], v[114:115], 0 op_sel_hi:[1,0]
	v_pk_add_f32 v[114:115], v[112:113], 0 op_sel_hi:[1,0]
	v_cvt_pk_bf16_f32 v112, v116, v117
	v_cvt_pk_bf16_f32 v113, v118, v119
	v_pk_add_f32 v[108:109], v[108:109], 0 op_sel_hi:[1,0]
	v_cvt_pk_bf16_f32 v114, v114, v115
	v_cvt_pk_bf16_f32 v115, v120, v121
	global_store_dwordx4 v[144:145], v[112:115], off offset:256
	v_pk_add_f32 v[100:101], v[100:101], 0 op_sel_hi:[1,0]
	v_pk_add_f32 v[102:103], v[102:103], 0 op_sel_hi:[1,0]
	v_or_b32_e32 v112, 16, v154
	v_ashrrev_i32_e32 v113, 31, v112
	v_lshlrev_b64 v[112:113], 11, v[112:113]
	v_lshl_add_u64 v[112:113], s[10:11], 0, v[112:113]
	v_lshl_add_u64 v[112:113], v[112:113], 0, v[158:159]
	v_pk_add_f32 v[114:115], v[106:107], 0 op_sel_hi:[1,0]
	v_pk_add_f32 v[106:107], v[104:105], 0 op_sel_hi:[1,0]
	v_cvt_pk_bf16_f32 v104, v108, v109
	v_cvt_pk_bf16_f32 v105, v110, v111
	v_pk_add_f32 v[94:95], v[94:95], 0 op_sel_hi:[1,0]
	v_cvt_pk_bf16_f32 v106, v106, v107
	v_cvt_pk_bf16_f32 v107, v114, v115
	global_store_dwordx4 v[112:113], v[104:107], off
	v_pk_add_f32 v[92:93], v[92:93], 0 op_sel_hi:[1,0]
	v_pk_add_f32 v[84:85], v[84:85], 0 op_sel_hi:[1,0]
	v_pk_add_f32 v[104:105], v[98:99], 0 op_sel_hi:[1,0]
	v_pk_add_f32 v[98:99], v[96:97], 0 op_sel_hi:[1,0]
	v_cvt_pk_bf16_f32 v96, v100, v101
	v_cvt_pk_bf16_f32 v97, v102, v103
	v_pk_add_f32 v[86:87], v[86:87], 0 op_sel_hi:[1,0]
	v_cvt_pk_bf16_f32 v98, v98, v99
	v_cvt_pk_bf16_f32 v99, v104, v105
	global_store_dwordx4 v[112:113], v[96:99], off offset:256
	v_pk_add_f32 v[78:79], v[78:79], 0 op_sel_hi:[1,0]
	v_pk_add_f32 v[76:77], v[76:77], 0 op_sel_hi:[1,0]
	v_or_b32_e32 v96, 32, v154
	v_ashrrev_i32_e32 v97, 31, v96
	v_lshlrev_b64 v[96:97], 11, v[96:97]
	v_lshl_add_u64 v[96:97], s[10:11], 0, v[96:97]
	v_lshl_add_u64 v[96:97], v[96:97], 0, v[158:159]
	v_pk_add_f32 v[98:99], v[90:91], 0 op_sel_hi:[1,0]
	v_pk_add_f32 v[90:91], v[88:89], 0 op_sel_hi:[1,0]
	v_cvt_pk_bf16_f32 v88, v92, v93
	v_cvt_pk_bf16_f32 v89, v94, v95
	v_pk_add_f32 v[70:71], v[70:71], 0 op_sel_hi:[1,0]
	v_cvt_pk_bf16_f32 v90, v90, v91
	v_cvt_pk_bf16_f32 v91, v98, v99
	global_store_dwordx4 v[96:97], v[88:91], off
	v_pk_add_f32 v[68:69], v[68:69], 0 op_sel_hi:[1,0]
	s_mov_b64 s[22:23], 0x40000
	v_pk_add_f32 v[88:89], v[82:83], 0 op_sel_hi:[1,0]
	v_pk_add_f32 v[82:83], v[80:81], 0 op_sel_hi:[1,0]
	v_cvt_pk_bf16_f32 v80, v84, v85
	v_cvt_pk_bf16_f32 v81, v86, v87
	v_pk_add_f32 v[60:61], v[60:61], 0 op_sel_hi:[1,0]
	v_cvt_pk_bf16_f32 v82, v82, v83
	v_cvt_pk_bf16_f32 v83, v88, v89
	global_store_dwordx4 v[96:97], v[80:83], off offset:256
	v_pk_add_f32 v[62:63], v[62:63], 0 op_sel_hi:[1,0]
	v_pk_add_f32 v[54:55], v[54:55], 0 op_sel_hi:[1,0]
	v_or_b32_e32 v80, 48, v154
	v_ashrrev_i32_e32 v81, 31, v80
	v_lshlrev_b64 v[80:81], 11, v[80:81]
	v_lshl_add_u64 v[80:81], s[10:11], 0, v[80:81]
	v_lshl_add_u64 v[80:81], v[80:81], 0, v[158:159]
	v_pk_add_f32 v[82:83], v[74:75], 0 op_sel_hi:[1,0]
	v_pk_add_f32 v[74:75], v[72:73], 0 op_sel_hi:[1,0]
	v_cvt_pk_bf16_f32 v72, v76, v77
	v_cvt_pk_bf16_f32 v73, v78, v79
	v_pk_add_f32 v[52:53], v[52:53], 0 op_sel_hi:[1,0]
; __device__ __forceinline__ unsigned cvt_pk_bf16(float lo, float hi) { unsigned r; asm volatile("v_cvt_pk_bf16_f32 %0, %1, %2" : "=v"(r) : "v"(lo), "v"(hi)); return r; }
; __device__ __forceinline__ float flogsig16(float x) { return (fminf(x, 0.f) - __logf(1.0f + __expf(-fabsf(x)))) * 0.0625f; }
; #define PG8_WAIT_V(n) asm volatile("s_waitcnt vmcnt(" #n ")" ::: "memory")
; #define PG8_BAR __builtin_amdgcn_s_barrier()
;     __device__ __forceinline__ void operator()(const f32x4 (&acc)[2][2][4][2], const Unit& u, int wr, int wc, int fr, int fq) const {
;     ...
;             for (int m = 0; m < 4; ++m) { bf16_t* rowp = O + (size_t)(row0 + ai * HALF + m * 16) * ldc + col0;
; #pragma unroll
;                 for (int bj = 0; bj < 2; ++bj) { f32x4 v0 = acc[ai][bj][m][0] + bv[bj][0], v1 = acc[ai][bj][m][1] + bv[bj][1];
;                     if (act == 1) {
; #pragma unroll
;                         for (int j = 0; j < 1; ++j) { v0 = v0 * sigmoid4(v0); v1 = v1 * sigmoid4(v1); } }
;                     else if (act == 2) {
; #pragma unroll
;                         for (int j = 0; j < 1; ++j) { v0 = sigmoid4(v0); v1 = sigmoid4(v1); } }
;                     else if (act == 3) {
; #pragma unroll
;                         for (int j = 0; j < 4; ++j) { v0[j] = flogsig16(v0[j]); v1[j] = flogsig16(v1[j]); } }
;                     u32x4 w; w.x = cvt_pk_bf16(v0[0], v0[1]); w.y = cvt_pk_bf16(v0[2], v0[3]); w.z = cvt_pk_bf16(v1[0], v1[1]); w.w = cvt_pk_bf16(v1[2], v1[3]);
;                     *(u32x4*)(rowp + bj * HALF) = w; } }
; template <class Epi, class Sched>
; __device__ __forceinline__ void gemm_phase(PG8_LAS unsigned char* lds, const Gemm g, const Sched& S, const Epi& E) {
;     ...
;         if constexpr (!Epi::AFTER_DRAIN) { E(acc, cur, wr, wc, fr, fq); S.done(cur); }
;         if (!has_next) break;
; #pragma unroll
;         for (int a = 0; a < 2; ++a)
; #pragma unroll
;             for (int b = 0; b < 2; ++b)
; #pragma unroll
;                 for (int m = 0; m < 4; ++m)
; #pragma unroll
;                     for (int n = 0; n < 2; ++n) acc[a][b][m][n] = (f32x4){0.f, 0.f, 0.f, 0.f};
;         cur = nxt; cA = nA; cB = nB; ++ui;
;     }
;     PG8_WAIT_V(0);
;     if (wr == 0) PG8_BAR;
;     PG8_BAR;
	v_cvt_pk_bf16_f32 v74, v74, v75
	v_cvt_pk_bf16_f32 v75, v82, v83
	global_store_dwordx4 v[80:81], v[72:75], off
	v_pk_add_f32 v[48:49], v[48:49], 0 op_sel_hi:[1,0]
	v_pk_add_f32 v[38:39], v[38:39], 0 op_sel_hi:[1,0]
	v_pk_add_f32 v[72:73], v[66:67], 0 op_sel_hi:[1,0]
	v_pk_add_f32 v[66:67], v[64:65], 0 op_sel_hi:[1,0]
	v_cvt_pk_bf16_f32 v64, v68, v69
	v_cvt_pk_bf16_f32 v65, v70, v71
	v_pk_add_f32 v[36:37], v[36:37], 0 op_sel_hi:[1,0]
	v_cvt_pk_bf16_f32 v66, v66, v67
	v_cvt_pk_bf16_f32 v67, v72, v73
	global_store_dwordx4 v[80:81], v[64:67], off offset:256
	v_pk_add_f32 v[32:33], v[32:33], 0 op_sel_hi:[1,0]
	v_pk_add_f32 v[22:23], v[22:23], 0 op_sel_hi:[1,0]
	v_lshl_add_u64 v[64:65], v[144:145], 0, s[22:23]
	s_mov_b32 s22, 0x40000
	v_pk_add_f32 v[66:67], v[58:59], 0 op_sel_hi:[1,0]
	v_pk_add_f32 v[58:59], v[56:57], 0 op_sel_hi:[1,0]
	v_cvt_pk_bf16_f32 v56, v60, v61
	v_add_co_u32_e32 v60, vcc, s22, v144
	v_cvt_pk_bf16_f32 v57, v62, v63
	v_cvt_pk_bf16_f32 v58, v58, v59
	v_cvt_pk_bf16_f32 v59, v66, v67
	s_mov_b64 s[22:23], 0x48000
	s_nop 0
	v_addc_co_u32_e32 v61, vcc, 0, v145, vcc
	global_store_dwordx4 v[60:61], v[56:59], off
	v_pk_add_f32 v[20:21], v[20:21], 0 op_sel_hi:[1,0]
	v_pk_add_f32 v[16:17], v[16:17], 0 op_sel_hi:[1,0]
	v_pk_add_f32 v[56:57], v[46:47], 0 op_sel_hi:[1,0]
	v_pk_add_f32 v[46:47], v[44:45], 0 op_sel_hi:[1,0]
	v_cvt_pk_bf16_f32 v44, v52, v53
	v_cvt_pk_bf16_f32 v45, v54, v55
	s_mov_b32 s54, s51
	v_cvt_pk_bf16_f32 v46, v46, v47
	v_cvt_pk_bf16_f32 v47, v56, v57
	global_store_dwordx4 v[64:65], v[44:47], off offset:256
	s_mov_b32 s53, s52
	s_mov_b64 s[24:25], s[4:5]
	v_pk_add_f32 v[46:47], v[50:51], 0 op_sel_hi:[1,0]
	v_pk_add_f32 v[50:51], v[42:43], 0 op_sel_hi:[1,0]
	v_pk_add_f32 v[42:43], v[40:41], 0 op_sel_hi:[1,0]
	v_cvt_pk_bf16_f32 v40, v48, v49
	v_cvt_pk_bf16_f32 v41, v46, v47
	v_add_co_u32_e32 v46, vcc, s48, v144
	v_cvt_pk_bf16_f32 v42, v42, v43
	v_cvt_pk_bf16_f32 v43, v50, v51
	v_lshl_add_u64 v[44:45], v[144:145], 0, s[22:23]
	s_nop 0
	v_addc_co_u32_e32 v47, vcc, 0, v145, vcc
	global_store_dwordx4 v[46:47], v[40:43], off
	s_mov_b64 s[22:23], s[0:1]
	v_pk_add_f32 v[6:7], v[6:7], 0 op_sel_hi:[1,0]
	v_pk_add_f32 v[40:41], v[30:31], 0 op_sel_hi:[1,0]
	v_pk_add_f32 v[30:31], v[28:29], 0 op_sel_hi:[1,0]
	v_cvt_pk_bf16_f32 v28, v36, v37
	v_cvt_pk_bf16_f32 v29, v38, v39
	v_pk_add_f32 v[4:5], v[4:5], 0 op_sel_hi:[1,0]
	v_cvt_pk_bf16_f32 v30, v30, v31
	v_cvt_pk_bf16_f32 v31, v40, v41
	global_store_dwordx4 v[44:45], v[28:31], off offset:256
	s_nop 1
	v_pk_add_f32 v[30:31], v[34:35], 0 op_sel_hi:[1,0]
	v_pk_add_f32 v[34:35], v[26:27], 0 op_sel_hi:[1,0]
	v_pk_add_f32 v[26:27], v[24:25], 0 op_sel_hi:[1,0]
	v_cvt_pk_bf16_f32 v24, v32, v33
	v_cvt_pk_bf16_f32 v25, v30, v31
	v_add_co_u32_e32 v30, vcc, s49, v144
	v_cvt_pk_bf16_f32 v26, v26, v27
	v_cvt_pk_bf16_f32 v27, v34, v35
	v_lshl_add_u64 v[28:29], v[144:145], 0, s[16:17]
	s_nop 0
	v_addc_co_u32_e32 v31, vcc, 0, v145, vcc
	global_store_dwordx4 v[30:31], v[24:27], off
	s_nop 1
	v_pk_add_f32 v[24:25], v[14:15], 0 op_sel_hi:[1,0]
	v_pk_add_f32 v[14:15], v[12:13], 0 op_sel_hi:[1,0]
	v_cvt_pk_bf16_f32 v12, v20, v21
	v_cvt_pk_bf16_f32 v13, v22, v23
	s_nop 0
	v_cvt_pk_bf16_f32 v14, v14, v15
	v_cvt_pk_bf16_f32 v15, v24, v25
	global_store_dwordx4 v[28:29], v[12:15], off offset:256
	s_nop 1
	v_pk_add_f32 v[14:15], v[18:19], 0 op_sel_hi:[1,0]
	v_pk_add_f32 v[18:19], v[10:11], 0 op_sel_hi:[1,0]
	v_pk_add_f32 v[10:11], v[8:9], 0 op_sel_hi:[1,0]
	v_cvt_pk_bf16_f32 v8, v16, v17
	v_cvt_pk_bf16_f32 v9, v14, v15
	v_add_co_u32_e32 v14, vcc, s50, v144
	v_lshl_add_u64 v[12:13], v[144:145], 0, s[18:19]
	s_nop 0
	v_addc_co_u32_e32 v15, vcc, 0, v145, vcc
	v_cvt_pk_bf16_f32 v10, v10, v11
	v_cvt_pk_bf16_f32 v11, v18, v19
	global_store_dwordx4 v[14:15], v[8:11], off
	s_and_b64 vcc, exec, s[2:3]
	s_nop 0
	v_pk_add_f32 v[8:9], v[2:3], 0 op_sel_hi:[1,0]
	v_pk_add_f32 v[2:3], v[0:1], 0 op_sel_hi:[1,0]
	v_cvt_pk_bf16_f32 v0, v4, v5
	v_cvt_pk_bf16_f32 v1, v6, v7
	s_nop 0
	v_cvt_pk_bf16_f32 v2, v2, v3
	v_cvt_pk_bf16_f32 v3, v8, v9
	global_store_dwordx4 v[12:13], v[0:3], off offset:256
	s_cbranch_vccz .LBB0_275
	s_waitcnt vmcnt(0)
	s_cmpk_gt_u32 s31, 0xff
	s_cbranch_scc1 .LBB0_290
	s_barrier

; #define PG8_STAGE(bufoff, gbase, voff) do { _Pragma("unroll") for (int _i = 0; _i < 2; ++_i) \
;         __builtin_amdgcn_global_load_lds((const unsigned*)((const char*)(gbase) + (voff)[_i]), (PG8_LAS unsigned*)(lds + (bufoff) + ldsw + _i * 8192), 16, 0, 0); } while (0)
; #define PG8_LDA(dst, b, h) do { _Pragma("unroll") for (int m = 0; m < 4; ++m) _Pragma("unroll") for (int k = 0; k < 2; ++k) dst[m][k] = *(const PG8_LAS bf16x8*)(lds + PG8_SA(b, h) + aoff + m * 2048 + k * 1024); } while (0)
; #define PG8_LDB(dst, b, h) do { _Pragma("unroll") for (int n = 0; n < 2; ++n) _Pragma("unroll") for (int k = 0; k < 2; ++k) dst[n][k] = *(const PG8_LAS bf16x8*)(lds + PG8_SB(b, h) + boff + n * 2048 + k * 1024); } while (0)
; #define PG8_BAR __builtin_amdgcn_s_barrier()
; template <class Epi, class Sched>
; __device__ __forceinline__ void gemm_phase(PG8_LAS unsigned char* lds, const Gemm g, const Sched& S, const Epi& E) {
;     ...
;         const bool has_next = S.next(ui + 1, nxt);
;         const char* nA = has_next ? (const char*)g.A + (size_t)nxt.pm * tstep : cA; const char* nB = has_next ? (const char*)g.Bt + (size_t)nxt.pn * tstep : cB;
;         for (int t = 0; t < nt; t += 2) {
;             const bool last = (t == nt - 2);
;             const char* a1 = cA + (size_t)(t + 1) * kstep;
;             const char* a2 = last ? nA : cA + (size_t)(t + 2) * kstep; const char* b2 = last ? nB : cB + (size_t)(t + 2) * kstep;
;             const char* a3 = a2 + kstep; const char* b3 = b2 + kstep;
;             if (last && has_next) S.a_ready(nxt);
;             PG8_LDB(B0, 0, 0); PG8_SCHED; PG8_LDA(At, 0, 0); PG8_STAGE(PG8_SA(1, 1), a1 + hstep, voffA);
;             PG8_WAIT_L(8); PG8_BAR; PG8_WAIT_L(0); PG8_MMA(0, 0, At, B0); PG8_BAR; PG8_SCHED;
;             PG8_LDB(B1, 0, 1); PG8_STAGE(PG8_SB(0, 0), b2, voffB);
;             PG8_BAR; PG8_WAIT_L(0); PG8_MMA(0, 1, At, B1); PG8_BAR;
;             PG8_LDA(At, 0, 1); PG8_STAGE(PG8_SA(0, 0), a2, voffA);
;             PG8_BAR; PG8_WAIT_L(0); PG8_MMA(1, 0, At, B0); PG8_BAR; PG8_SCHED;
;             PG8_STAGE(PG8_SB(0, 1), b2 + hstep, voffB);
;             PG8_WAIT_V(6); PG8_BAR; PG8_MMA(1, 1, At, B1); PG8_BAR;
;             PG8_LDB(B0, 1, 0); PG8_SCHED; PG8_LDA(At, 1, 0); PG8_STAGE(PG8_SA(0, 1), a2 + hstep, voffA);
;             PG8_WAIT_L(8); PG8_BAR; PG8_WAIT_L(0); PG8_MMA(0, 0, At, B0); PG8_BAR; PG8_SCHED;
.LBB0_415:
	s_ashr_i32 s21, s20, 31
	v_cmp_lt_i64_e32 vcc, s[22:23], v[170:171]
	s_lshl_b64 s[22:23], s[20:21], 19
	s_add_u32 s22, s31, s22
	s_addc_u32 s23, s34, s23
	s_and_b64 s[24:25], vcc, exec
	s_cselect_b32 s7, s23, s1
	s_cselect_b32 s10, s22, s0
	s_ashr_i32 s19, s18, 31
	s_lshl_b64 s[24:25], s[18:19], 19
	s_add_u32 s24, s8, s24
	s_addc_u32 s25, s9, s25
	s_and_b64 s[28:29], vcc, exec
	s_cselect_b32 s19, s25, s5
	s_cselect_b32 s21, s24, s4
	s_add_u32 s0, s0, 0x40080
	s_addc_u32 s1, s1, 0
	s_add_u32 s51, s4, 0x100
	s_addc_u32 s52, s5, 0
	s_mov_b32 s53, -2
	ds_read_b128 v[24:27], v186
	ds_read_b128 v[28:31], v186 offset:1024
	ds_read_b128 v[40:43], v186 offset:2048
	ds_read_b128 v[44:47], v186 offset:3072
	s_add_u32 s4, s0, 0xfffc0080
	s_addc_u32 s5, s1, -1
	s_cmp_eq_u32 s53, 12
	s_cselect_b32 s29, s7, s5
	s_cselect_b32 s28, s10, s4
	s_cselect_b32 s5, s19, s52
	s_cselect_b32 s4, s21, s51
	ds_read_b128 v[144:147], v187
	ds_read_b128 v[148:151], v187 offset:1024
	ds_read_b128 v[182:185], v187 offset:2048
	ds_read_b128 v[192:195], v187 offset:3072
	ds_read_b128 v[196:199], v187 offset:4096
	ds_read_b128 v[200:203], v187 offset:5120
	ds_read_b128 v[204:207], v187 offset:6144
	ds_read_b128 v[208:211], v187 offset:7168
	s_waitcnt lgkmcnt(8)
	ds_read_b128 v[212:215], v189
	ds_read_b128 v[216:219], v189 offset:1024
	ds_read_b128 v[220:223], v189 offset:2048
	ds_read_b128 v[224:227], v189 offset:3072
	s_add_i32 m0, s27, 0xc000
	s_nop 0
	global_load_lds_dwordx4 v166, s[0:1]
	s_nop 1
	s_add_i32 m0, s27, 0xe000
	s_nop 0
	global_load_lds_dwordx4 v168, s[0:1]
	s_waitcnt vmcnt(8) lgkmcnt(0)
	s_barrier
	v_mfma_f32_16x16x32_bf16 v[140:143], v[24:27], v[144:147], 0
	v_mfma_f32_16x16x32_bf16 v[136:139], v[40:43], v[144:147], 0
	v_mfma_f32_16x16x32_bf16 v[124:127], v[24:27], v[182:185], 0
	v_mfma_f32_16x16x32_bf16 v[120:123], v[40:43], v[182:185], 0
	v_mfma_f32_16x16x32_bf16 v[108:111], v[24:27], v[196:199], 0
	v_mfma_f32_16x16x32_bf16 v[104:107], v[40:43], v[196:199], 0
	v_mfma_f32_16x16x32_bf16 v[92:95], v[24:27], v[204:207], 0
	v_mfma_f32_16x16x32_bf16 v[88:91], v[40:43], v[204:207], 0
	v_mfma_f32_16x16x32_bf16 v[140:143], v[28:31], v[148:151], v[140:143]
	v_mfma_f32_16x16x32_bf16 v[136:139], v[44:47], v[148:151], v[136:139]
	v_mfma_f32_16x16x32_bf16 v[124:127], v[28:31], v[192:195], v[124:127]
	v_mfma_f32_16x16x32_bf16 v[120:123], v[44:47], v[192:195], v[120:123]
	v_mfma_f32_16x16x32_bf16 v[108:111], v[28:31], v[200:203], v[108:111]
	v_mfma_f32_16x16x32_bf16 v[104:107], v[44:47], v[200:203], v[104:107]
	v_mfma_f32_16x16x32_bf16 v[92:95], v[28:31], v[208:211], v[92:95]
	v_mfma_f32_16x16x32_bf16 v[88:91], v[44:47], v[208:211], v[88:91]
	v_mfma_f32_16x16x32_bf16 v[132:135], v[212:215], v[144:147], 0
	v_mfma_f32_16x16x32_bf16 v[128:131], v[220:223], v[144:147], 0
	v_mfma_f32_16x16x32_bf16 v[116:119], v[212:215], v[182:185], 0
	v_mfma_f32_16x16x32_bf16 v[112:115], v[220:223], v[182:185], 0
	v_mfma_f32_16x16x32_bf16 v[100:103], v[212:215], v[196:199], 0
	v_mfma_f32_16x16x32_bf16 v[96:99], v[220:223], v[196:199], 0
	v_mfma_f32_16x16x32_bf16 v[84:87], v[212:215], v[204:207], 0
	v_mfma_f32_16x16x32_bf16 v[80:83], v[220:223], v[204:207], 0
	v_mfma_f32_16x16x32_bf16 v[132:135], v[216:219], v[148:151], v[132:135]
	v_mfma_f32_16x16x32_bf16 v[128:131], v[224:227], v[148:151], v[128:131]
	v_mfma_f32_16x16x32_bf16 v[116:119], v[216:219], v[192:195], v[116:119]
	v_mfma_f32_16x16x32_bf16 v[112:115], v[224:227], v[192:195], v[112:115]
	v_mfma_f32_16x16x32_bf16 v[100:103], v[216:219], v[200:203], v[100:103]
	v_mfma_f32_16x16x32_bf16 v[96:99], v[224:227], v[200:203], v[96:99]
	v_mfma_f32_16x16x32_bf16 v[84:87], v[216:219], v[208:211], v[84:87]
	v_mfma_f32_16x16x32_bf16 v[80:83], v[224:227], v[208:211], v[80:83]
	s_barrier
	ds_read_b128 v[144:147], v187 offset:16384
	ds_read_b128 v[148:151], v187 offset:17408
	ds_read_b128 v[182:185], v187 offset:18432
	ds_read_b128 v[192:195], v187 offset:19456
	ds_read_b128 v[196:199], v187 offset:20480
	ds_read_b128 v[200:203], v187 offset:21504
	ds_read_b128 v[204:207], v187 offset:22528
	ds_read_b128 v[208:211], v187 offset:23552
	s_add_i32 s54, s43, s35
	s_add_u32 s98, s4, s14
	s_addc_u32 s99, s5, s15
	s_mov_b32 m0, s54
	s_nop 0
	global_load_lds_dwordx4 v156, s[4:5]
	s_nop 1
	s_add_i32 m0, s54, 0x2000
	s_nop 0
	global_load_lds_dwordx4 v160, s[4:5]
	s_nop 1
	s_mov_b32 m0, s27
	s_add_u32 s100, s28, s14
	s_addc_u32 s101, s29, s15
	global_load_lds_dwordx4 v154, s[28:29]
	s_nop 1
	s_mov_b32 m0, s36
	s_nop 0
	global_load_lds_dwordx4 v158, s[28:29]
	s_add_u32 s54, s4, 0x40000
	s_addc_u32 s55, s5, 0
	s_add_i32 s56, s44, s35
	s_mov_b32 m0, s56
	s_nop 0
	global_load_lds_dwordx4 v156, s[54:55]
	s_nop 1
	s_add_i32 m0, s56, 0x2000
	s_nop 0
	global_load_lds_dwordx4 v160, s[54:55]
	s_waitcnt vmcnt(8) lgkmcnt(0)
	s_barrier
; #define PG8_STAGE(bufoff, gbase, voff) do { _Pragma("unroll") for (int _i = 0; _i < 2; ++_i) \
;         __builtin_amdgcn_global_load_lds((const unsigned*)((const char*)(gbase) + (voff)[_i]), (PG8_LAS unsigned*)(lds + (bufoff) + ldsw + _i * 8192), 16, 0, 0); } while (0)
; #define PG8_LDA(dst, b, h) do { _Pragma("unroll") for (int m = 0; m < 4; ++m) _Pragma("unroll") for (int k = 0; k < 2; ++k) dst[m][k] = *(const PG8_LAS bf16x8*)(lds + PG8_SA(b, h) + aoff + m * 2048 + k * 1024); } while (0)
; #define PG8_LDB(dst, b, h) do { _Pragma("unroll") for (int n = 0; n < 2; ++n) _Pragma("unroll") for (int k = 0; k < 2; ++k) dst[n][k] = *(const PG8_LAS bf16x8*)(lds + PG8_SB(b, h) + boff + n * 2048 + k * 1024); } while (0)
; #define PG8_WAIT_V(n) asm volatile("s_waitcnt vmcnt(" #n ")" ::: "memory")
; #define PG8_WAIT_L(n) asm volatile("s_waitcnt lgkmcnt(" #n ")" ::: "memory")
; #define PG8_BAR __builtin_amdgcn_s_barrier()
; #define PG8_SCHED __builtin_amdgcn_sched_barrier(0)
; template <class Epi, class Sched>
; __device__ __forceinline__ void gemm_phase(PG8_LAS unsigned char* lds, const Gemm g, const Sched& S, const Epi& E) {
;     ...
;             PG8_LDB(B0, 0, 0); PG8_SCHED; PG8_LDA(At, 0, 0); PG8_STAGE(PG8_SA(1, 1), a1 + hstep, voffA);
;             PG8_WAIT_L(8); PG8_BAR; PG8_WAIT_L(0); PG8_MMA(0, 0, At, B0); PG8_BAR; PG8_SCHED;
;             PG8_LDB(B1, 0, 1); PG8_STAGE(PG8_SB(0, 0), b2, voffB);
;             PG8_BAR; PG8_WAIT_L(0); PG8_MMA(0, 1, At, B1); PG8_BAR;
;             PG8_LDA(At, 0, 1); PG8_STAGE(PG8_SA(0, 0), a2, voffA);
;             PG8_BAR; PG8_WAIT_L(0); PG8_MMA(1, 0, At, B0); PG8_BAR; PG8_SCHED;
;             PG8_STAGE(PG8_SB(0, 1), b2 + hstep, voffB);
;             PG8_WAIT_V(6); PG8_BAR; PG8_MMA(1, 1, At, B1); PG8_BAR;
;             PG8_LDB(B0, 1, 0); PG8_SCHED; PG8_LDA(At, 1, 0); PG8_STAGE(PG8_SA(0, 1), a2 + hstep, voffA);
;             PG8_WAIT_L(8); PG8_BAR; PG8_WAIT_L(0); PG8_MMA(0, 0, At, B0); PG8_BAR; PG8_SCHED;
;             PG8_LDB(B1, 1, 1); PG8_STAGE(PG8_SB(1, 0), b3, voffB);
;             PG8_BAR; PG8_WAIT_L(0); PG8_MMA(0, 1, At, B1); PG8_BAR;
;             PG8_LDA(At, 1, 1); PG8_STAGE(PG8_SA(1, 0), a3, voffA);
;             PG8_BAR; PG8_WAIT_L(0); PG8_MMA(1, 0, At, B0); PG8_BAR; PG8_SCHED;
;             PG8_STAGE(PG8_SB(1, 1), b3 + hstep, voffB);
;             PG8_WAIT_V(6); PG8_BAR; PG8_MMA(1, 1, At, B1); PG8_BAR;
	v_mfma_f32_16x16x32_bf16 v[76:79], v[24:27], v[144:147], 0
	v_mfma_f32_16x16x32_bf16 v[72:75], v[40:43], v[144:147], 0
	v_mfma_f32_16x16x32_bf16 v[60:63], v[24:27], v[182:185], 0
	v_mfma_f32_16x16x32_bf16 v[56:59], v[40:43], v[182:185], 0
	v_mfma_f32_16x16x32_bf16 v[36:39], v[24:27], v[196:199], 0
	v_mfma_f32_16x16x32_bf16 v[32:35], v[40:43], v[196:199], 0
	v_mfma_f32_16x16x32_bf16 v[12:15], v[24:27], v[204:207], 0
	v_mfma_f32_16x16x32_bf16 v[8:11], v[40:43], v[204:207], 0
	v_mfma_f32_16x16x32_bf16 v[76:79], v[28:31], v[148:151], v[76:79]
	v_mfma_f32_16x16x32_bf16 v[72:75], v[44:47], v[148:151], v[72:75]
	v_mfma_f32_16x16x32_bf16 v[60:63], v[28:31], v[192:195], v[60:63]
	v_mfma_f32_16x16x32_bf16 v[56:59], v[44:47], v[192:195], v[56:59]
	v_mfma_f32_16x16x32_bf16 v[36:39], v[28:31], v[200:203], v[36:39]
	v_mfma_f32_16x16x32_bf16 v[32:35], v[44:47], v[200:203], v[32:35]
	v_mfma_f32_16x16x32_bf16 v[12:15], v[28:31], v[208:211], v[12:15]
	v_mfma_f32_16x16x32_bf16 v[8:11], v[44:47], v[208:211], v[8:11]
	v_mfma_f32_16x16x32_bf16 v[20:23], v[212:215], v[196:199], 0
	v_mfma_f32_16x16x32_bf16 v[16:19], v[220:223], v[196:199], 0
	v_mfma_f32_16x16x32_bf16 v[4:7], v[212:215], v[204:207], 0
	v_mfma_f32_16x16x32_bf16 v[0:3], v[220:223], v[204:207], 0
	v_mfma_f32_16x16x32_bf16 v[24:27], v[212:215], v[144:147], 0
	v_mfma_f32_16x16x32_bf16 v[28:31], v[220:223], v[144:147], 0
	v_mfma_f32_16x16x32_bf16 v[40:43], v[212:215], v[182:185], 0
	v_mfma_f32_16x16x32_bf16 v[44:47], v[220:223], v[182:185], 0
	v_mfma_f32_16x16x32_bf16 v[20:23], v[216:219], v[200:203], v[20:23]
	v_mfma_f32_16x16x32_bf16 v[16:19], v[224:227], v[200:203], v[16:19]
	v_mfma_f32_16x16x32_bf16 v[4:7], v[216:219], v[208:211], v[4:7]
	v_mfma_f32_16x16x32_bf16 v[0:3], v[224:227], v[208:211], v[0:3]
	v_mfma_f32_16x16x32_bf16 v[24:27], v[216:219], v[148:151], v[24:27]
	v_mfma_f32_16x16x32_bf16 v[28:31], v[224:227], v[148:151], v[28:31]
	v_mfma_f32_16x16x32_bf16 v[40:43], v[216:219], v[192:195], v[40:43]
	v_mfma_f32_16x16x32_bf16 v[44:47], v[224:227], v[192:195], v[44:47]
	s_barrier
	s_add_i32 s54, 0, 0x18000
	v_add_u32_e32 v68, s54, v179
	ds_read_b128 v[48:51], v68
	ds_read_b128 v[52:55], v68 offset:1024
	ds_read_b128 v[64:67], v68 offset:2048
	ds_read_b128 v[68:71], v68 offset:3072
	ds_read_b128 v[144:147], v187 offset:32768
	ds_read_b128 v[148:151], v187 offset:33792
	ds_read_b128 v[182:185], v187 offset:34816
	ds_read_b128 v[192:195], v187 offset:35840
	ds_read_b128 v[196:199], v187 offset:36864
	ds_read_b128 v[200:203], v187 offset:37888
	ds_read_b128 v[204:207], v187 offset:38912
	ds_read_b128 v[208:211], v187 offset:39936
	v_add_u32_e32 v162, 0x1c000, v179
	s_waitcnt lgkmcnt(8)
	ds_read_b128 v[212:215], v162
	ds_read_b128 v[216:219], v162 offset:1024
	ds_read_b128 v[220:223], v162 offset:2048
	ds_read_b128 v[224:227], v162 offset:3072
	s_add_u32 s28, s28, 0x40000
	s_addc_u32 s29, s29, 0
	s_mov_b32 m0, s37
	s_nop 0
	global_load_lds_dwordx4 v154, s[28:29]
	s_nop 1
	s_mov_b32 m0, s38
	s_nop 0
	global_load_lds_dwordx4 v158, s[28:29]
	s_add_i32 s28, 0, 0x1c000
	s_waitcnt vmcnt(8) lgkmcnt(0)
	s_barrier
	v_mfma_f32_16x16x32_bf16 v[140:143], v[48:51], v[144:147], v[140:143]
	v_mfma_f32_16x16x32_bf16 v[136:139], v[64:67], v[144:147], v[136:139]
	v_mfma_f32_16x16x32_bf16 v[124:127], v[48:51], v[182:185], v[124:127]
	v_mfma_f32_16x16x32_bf16 v[120:123], v[64:67], v[182:185], v[120:123]
	v_mfma_f32_16x16x32_bf16 v[108:111], v[48:51], v[196:199], v[108:111]
	v_mfma_f32_16x16x32_bf16 v[104:107], v[64:67], v[196:199], v[104:107]
	v_mfma_f32_16x16x32_bf16 v[92:95], v[48:51], v[204:207], v[92:95]
	v_mfma_f32_16x16x32_bf16 v[88:91], v[64:67], v[204:207], v[88:91]
	v_mfma_f32_16x16x32_bf16 v[140:143], v[52:55], v[148:151], v[140:143]
	v_mfma_f32_16x16x32_bf16 v[136:139], v[68:71], v[148:151], v[136:139]
	v_mfma_f32_16x16x32_bf16 v[124:127], v[52:55], v[192:195], v[124:127]
	v_mfma_f32_16x16x32_bf16 v[120:123], v[68:71], v[192:195], v[120:123]
	v_mfma_f32_16x16x32_bf16 v[108:111], v[52:55], v[200:203], v[108:111]
	v_mfma_f32_16x16x32_bf16 v[104:107], v[68:71], v[200:203], v[104:107]
	v_mfma_f32_16x16x32_bf16 v[92:95], v[52:55], v[208:211], v[92:95]
	v_mfma_f32_16x16x32_bf16 v[88:91], v[68:71], v[208:211], v[88:91]
	v_mfma_f32_16x16x32_bf16 v[132:135], v[212:215], v[144:147], v[132:135]
	v_mfma_f32_16x16x32_bf16 v[128:131], v[220:223], v[144:147], v[128:131]
	v_mfma_f32_16x16x32_bf16 v[116:119], v[212:215], v[182:185], v[116:119]
	v_mfma_f32_16x16x32_bf16 v[112:115], v[220:223], v[182:185], v[112:115]
	v_mfma_f32_16x16x32_bf16 v[100:103], v[212:215], v[196:199], v[100:103]
	v_mfma_f32_16x16x32_bf16 v[96:99], v[220:223], v[196:199], v[96:99]
	v_mfma_f32_16x16x32_bf16 v[84:87], v[212:215], v[204:207], v[84:87]
	v_mfma_f32_16x16x32_bf16 v[80:83], v[220:223], v[204:207], v[80:83]
	v_mfma_f32_16x16x32_bf16 v[132:135], v[216:219], v[148:151], v[132:135]
	v_mfma_f32_16x16x32_bf16 v[128:131], v[224:227], v[148:151], v[128:131]
	v_mfma_f32_16x16x32_bf16 v[116:119], v[216:219], v[192:195], v[116:119]
	v_mfma_f32_16x16x32_bf16 v[112:115], v[224:227], v[192:195], v[112:115]
	v_mfma_f32_16x16x32_bf16 v[100:103], v[216:219], v[200:203], v[100:103]
	v_mfma_f32_16x16x32_bf16 v[96:99], v[224:227], v[200:203], v[96:99]
	v_mfma_f32_16x16x32_bf16 v[84:87], v[216:219], v[208:211], v[84:87]
	v_mfma_f32_16x16x32_bf16 v[80:83], v[224:227], v[208:211], v[80:83]
	s_barrier
; #define PG8_STAGE(bufoff, gbase, voff) do { _Pragma("unroll") for (int _i = 0; _i < 2; ++_i) \
;         __builtin_amdgcn_global_load_lds((const unsigned*)((const char*)(gbase) + (voff)[_i]), (PG8_LAS unsigned*)(lds + (bufoff) + ldsw + _i * 8192), 16, 0, 0); } while (0)
; #define PG8_LDA(dst, b, h) do { _Pragma("unroll") for (int m = 0; m < 4; ++m) _Pragma("unroll") for (int k = 0; k < 2; ++k) dst[m][k] = *(const PG8_LAS bf16x8*)(lds + PG8_SA(b, h) + aoff + m * 2048 + k * 1024); } while (0)
; #define PG8_WAIT_V(n) asm volatile("s_waitcnt vmcnt(" #n ")" ::: "memory")
; template <class Epi, class Sched>
; __device__ __forceinline__ void gemm_phase(PG8_LAS unsigned char* lds, const Gemm g, const Sched& S, const Epi& E) {
;     ...
;         for (int t = 0; t < nt; t += 2) {
;             const bool last = (t == nt - 2);
;             const char* a1 = cA + (size_t)(t + 1) * kstep;
;             const char* a2 = last ? nA : cA + (size_t)(t + 2) * kstep; const char* b2 = last ? nB : cB + (size_t)(t + 2) * kstep;
;             const char* a3 = a2 + kstep; const char* b3 = b2 + kstep;
;             if (last && has_next) S.a_ready(nxt);
;             PG8_LDB(B0, 0, 0); PG8_SCHED; PG8_LDA(At, 0, 0); PG8_STAGE(PG8_SA(1, 1), a1 + hstep, voffA);
;             PG8_WAIT_L(8); PG8_BAR; PG8_WAIT_L(0); PG8_MMA(0, 0, At, B0); PG8_BAR; PG8_SCHED;
;             PG8_LDB(B1, 0, 1); PG8_STAGE(PG8_SB(0, 0), b2, voffB);
;             PG8_BAR; PG8_WAIT_L(0); PG8_MMA(0, 1, At, B1); PG8_BAR;
;             PG8_LDA(At, 0, 1); PG8_STAGE(PG8_SA(0, 0), a2, voffA);
;             PG8_BAR; PG8_WAIT_L(0); PG8_MMA(1, 0, At, B0); PG8_BAR; PG8_SCHED;
;             PG8_STAGE(PG8_SB(0, 1), b2 + hstep, voffB);
;             PG8_WAIT_V(6); PG8_BAR; PG8_MMA(1, 1, At, B1); PG8_BAR;
;             PG8_LDB(B0, 1, 0); PG8_SCHED; PG8_LDA(At, 1, 0); PG8_STAGE(PG8_SA(0, 1), a2 + hstep, voffA);
;             PG8_WAIT_L(8); PG8_BAR; PG8_WAIT_L(0); PG8_MMA(0, 0, At, B0); PG8_BAR; PG8_SCHED;
;             PG8_LDB(B1, 1, 1); PG8_STAGE(PG8_SB(1, 0), b3, voffB);
;             PG8_BAR; PG8_WAIT_L(0); PG8_MMA(0, 1, At, B1); PG8_BAR;
;             PG8_LDA(At, 1, 1); PG8_STAGE(PG8_SA(1, 0), a3, voffA);
;             PG8_BAR; PG8_WAIT_L(0); PG8_MMA(1, 0, At, B0); PG8_BAR; PG8_SCHED;
;             PG8_STAGE(PG8_SB(1, 1), b3 + hstep, voffB);
;             PG8_WAIT_V(6); PG8_BAR; PG8_MMA(1, 1, At, B1); PG8_BAR;
	ds_read_b128 v[144:147], v187 offset:49152
	ds_read_b128 v[148:151], v187 offset:50176
	ds_read_b128 v[182:185], v187 offset:51200
	ds_read_b128 v[192:195], v187 offset:52224
	ds_read_b128 v[196:199], v187 offset:53248
	ds_read_b128 v[200:203], v187 offset:54272
	ds_read_b128 v[204:207], v187 offset:55296
	ds_read_b128 v[208:211], v187 offset:56320
	s_add_i32 s29, s54, s35
	s_mov_b32 m0, s29
	s_nop 0
	global_load_lds_dwordx4 v156, s[98:99]
	s_nop 1
	s_add_i32 m0, s29, 0x2000
	s_nop 0
	global_load_lds_dwordx4 v160, s[98:99]
	s_nop 1
	s_mov_b32 m0, s39
	s_nop 0
	global_load_lds_dwordx4 v154, s[100:101]
	s_nop 1
	s_mov_b32 m0, s40
	s_nop 0
	global_load_lds_dwordx4 v158, s[100:101]
	s_add_u32 s4, s4, 0x40080
	s_addc_u32 s5, s5, 0
	s_add_i32 s28, s28, s35
	s_mov_b32 m0, s28
	s_nop 0
	global_load_lds_dwordx4 v156, s[4:5]
	s_nop 1
	s_add_i32 m0, s28, 0x2000
	s_nop 0
	global_load_lds_dwordx4 v160, s[4:5]
	s_waitcnt vmcnt(8) lgkmcnt(0)
	s_barrier
	v_mfma_f32_16x16x32_bf16 v[76:79], v[48:51], v[144:147], v[76:79]
	v_mfma_f32_16x16x32_bf16 v[72:75], v[64:67], v[144:147], v[72:75]
	v_mfma_f32_16x16x32_bf16 v[60:63], v[48:51], v[182:185], v[60:63]
	v_mfma_f32_16x16x32_bf16 v[56:59], v[64:67], v[182:185], v[56:59]
	v_mfma_f32_16x16x32_bf16 v[36:39], v[48:51], v[196:199], v[36:39]
	v_mfma_f32_16x16x32_bf16 v[32:35], v[64:67], v[196:199], v[32:35]
	v_mfma_f32_16x16x32_bf16 v[12:15], v[48:51], v[204:207], v[12:15]
	v_mfma_f32_16x16x32_bf16 v[8:11], v[64:67], v[204:207], v[8:11]
	v_mfma_f32_16x16x32_bf16 v[76:79], v[52:55], v[148:151], v[76:79]
	v_mfma_f32_16x16x32_bf16 v[72:75], v[68:71], v[148:151], v[72:75]
	v_mfma_f32_16x16x32_bf16 v[60:63], v[52:55], v[192:195], v[60:63]
	v_mfma_f32_16x16x32_bf16 v[56:59], v[68:71], v[192:195], v[56:59]
	v_mfma_f32_16x16x32_bf16 v[36:39], v[52:55], v[200:203], v[36:39]
	v_mfma_f32_16x16x32_bf16 v[32:35], v[68:71], v[200:203], v[32:35]
	v_mfma_f32_16x16x32_bf16 v[12:15], v[52:55], v[208:211], v[12:15]
	v_mfma_f32_16x16x32_bf16 v[8:11], v[68:71], v[208:211], v[8:11]
	v_mfma_f32_16x16x32_bf16 v[24:27], v[212:215], v[144:147], v[24:27]
	v_mfma_f32_16x16x32_bf16 v[68:71], v[216:219], v[148:151], v[24:27]
	v_mfma_f32_16x16x32_bf16 v[24:27], v[220:223], v[144:147], v[28:31]
	v_mfma_f32_16x16x32_bf16 v[64:67], v[224:227], v[148:151], v[24:27]
	v_mfma_f32_16x16x32_bf16 v[24:27], v[212:215], v[182:185], v[40:43]
	v_mfma_f32_16x16x32_bf16 v[52:55], v[216:219], v[192:195], v[24:27]
	v_mfma_f32_16x16x32_bf16 v[24:27], v[220:223], v[182:185], v[44:47]
	v_mfma_f32_16x16x32_bf16 v[20:23], v[212:215], v[196:199], v[20:23]
	v_mfma_f32_16x16x32_bf16 v[16:19], v[220:223], v[196:199], v[16:19]
	v_mfma_f32_16x16x32_bf16 v[4:7], v[212:215], v[204:207], v[4:7]
	v_mfma_f32_16x16x32_bf16 v[0:3], v[220:223], v[204:207], v[0:3]
	v_mfma_f32_16x16x32_bf16 v[48:51], v[224:227], v[192:195], v[24:27]
	v_mfma_f32_16x16x32_bf16 v[20:23], v[216:219], v[200:203], v[20:23]
	v_mfma_f32_16x16x32_bf16 v[16:19], v[224:227], v[200:203], v[16:19]
	v_mfma_f32_16x16x32_bf16 v[4:7], v[216:219], v[208:211], v[4:7]
	v_mfma_f32_16x16x32_bf16 v[0:3], v[224:227], v[208:211], v[0:3]
	s_barrier
	s_add_i32 s53, s53, 2
	s_add_u32 s0, s0, 0x100
	s_addc_u32 s1, s1, 0
	s_add_u32 s51, s51, 0x100
	s_addc_u32 s52, s52, 0
	s_cmp_gt_u32 s53, 13
.LBB0_416:
	ds_read_b128 v[24:27], v186
	ds_read_b128 v[28:31], v186 offset:1024
	ds_read_b128 v[40:43], v186 offset:2048
	ds_read_b128 v[44:47], v186 offset:3072
	s_add_u32 s4, s0, 0xfffc0080
	s_addc_u32 s5, s1, -1
	s_cmp_eq_u32 s53, 12
	s_cselect_b32 s29, s7, s5
	s_cselect_b32 s28, s10, s4
	s_cselect_b32 s5, s19, s52
	s_cselect_b32 s4, s21, s51
	ds_read_b128 v[144:147], v187
	ds_read_b128 v[148:151], v187 offset:1024
	ds_read_b128 v[182:185], v187 offset:2048
	ds_read_b128 v[192:195], v187 offset:3072
	ds_read_b128 v[196:199], v187 offset:4096
	ds_read_b128 v[200:203], v187 offset:5120
	ds_read_b128 v[204:207], v187 offset:6144
	ds_read_b128 v[208:211], v187 offset:7168
	s_waitcnt lgkmcnt(8)
	ds_read_b128 v[212:215], v189
	ds_read_b128 v[216:219], v189 offset:1024
	ds_read_b128 v[220:223], v189 offset:2048
	ds_read_b128 v[224:227], v189 offset:3072
	s_add_i32 m0, s27, 0xc000
	s_nop 0
	global_load_lds_dwordx4 v166, s[0:1]
	s_nop 1
	s_add_i32 m0, s27, 0xe000
	s_nop 0
	global_load_lds_dwordx4 v168, s[0:1]
	s_waitcnt vmcnt(8) lgkmcnt(0)
	s_barrier
	v_mfma_f32_16x16x32_bf16 v[140:143], v[24:27], v[144:147], v[140:143]
	v_mfma_f32_16x16x32_bf16 v[136:139], v[40:43], v[144:147], v[136:139]
	v_mfma_f32_16x16x32_bf16 v[124:127], v[24:27], v[182:185], v[124:127]
	v_mfma_f32_16x16x32_bf16 v[120:123], v[40:43], v[182:185], v[120:123]
	v_mfma_f32_16x16x32_bf16 v[108:111], v[24:27], v[196:199], v[108:111]
	v_mfma_f32_16x16x32_bf16 v[104:107], v[40:43], v[196:199], v[104:107]
	v_mfma_f32_16x16x32_bf16 v[92:95], v[24:27], v[204:207], v[92:95]
	v_mfma_f32_16x16x32_bf16 v[88:91], v[40:43], v[204:207], v[88:91]
	v_mfma_f32_16x16x32_bf16 v[140:143], v[28:31], v[148:151], v[140:143]
	v_mfma_f32_16x16x32_bf16 v[136:139], v[44:47], v[148:151], v[136:139]
	v_mfma_f32_16x16x32_bf16 v[124:127], v[28:31], v[192:195], v[124:127]
	v_mfma_f32_16x16x32_bf16 v[120:123], v[44:47], v[192:195], v[120:123]
	v_mfma_f32_16x16x32_bf16 v[108:111], v[28:31], v[200:203], v[108:111]
	v_mfma_f32_16x16x32_bf16 v[104:107], v[44:47], v[200:203], v[104:107]
	v_mfma_f32_16x16x32_bf16 v[92:95], v[28:31], v[208:211], v[92:95]
	v_mfma_f32_16x16x32_bf16 v[88:91], v[44:47], v[208:211], v[88:91]
	v_mfma_f32_16x16x32_bf16 v[132:135], v[212:215], v[144:147], v[132:135]
	v_mfma_f32_16x16x32_bf16 v[128:131], v[220:223], v[144:147], v[128:131]
	v_mfma_f32_16x16x32_bf16 v[116:119], v[212:215], v[182:185], v[116:119]
	v_mfma_f32_16x16x32_bf16 v[112:115], v[220:223], v[182:185], v[112:115]
	v_mfma_f32_16x16x32_bf16 v[100:103], v[212:215], v[196:199], v[100:103]
	v_mfma_f32_16x16x32_bf16 v[96:99], v[220:223], v[196:199], v[96:99]
	v_mfma_f32_16x16x32_bf16 v[84:87], v[212:215], v[204:207], v[84:87]
	v_mfma_f32_16x16x32_bf16 v[80:83], v[220:223], v[204:207], v[80:83]
	v_mfma_f32_16x16x32_bf16 v[132:135], v[216:219], v[148:151], v[132:135]
	v_mfma_f32_16x16x32_bf16 v[128:131], v[224:227], v[148:151], v[128:131]
	v_mfma_f32_16x16x32_bf16 v[116:119], v[216:219], v[192:195], v[116:119]
	v_mfma_f32_16x16x32_bf16 v[112:115], v[224:227], v[192:195], v[112:115]
	v_mfma_f32_16x16x32_bf16 v[100:103], v[216:219], v[200:203], v[100:103]
	v_mfma_f32_16x16x32_bf16 v[96:99], v[224:227], v[200:203], v[96:99]
	v_mfma_f32_16x16x32_bf16 v[84:87], v[216:219], v[208:211], v[84:87]
	v_mfma_f32_16x16x32_bf16 v[80:83], v[224:227], v[208:211], v[80:83]
	s_barrier
; #define PG8_STAGE(bufoff, gbase, voff) do { _Pragma("unroll") for (int _i = 0; _i < 2; ++_i) \
;         __builtin_amdgcn_global_load_lds((const unsigned*)((const char*)(gbase) + (voff)[_i]), (PG8_LAS unsigned*)(lds + (bufoff) + ldsw + _i * 8192), 16, 0, 0); } while (0)
; #define PG8_LDA(dst, b, h) do { _Pragma("unroll") for (int m = 0; m < 4; ++m) _Pragma("unroll") for (int k = 0; k < 2; ++k) dst[m][k] = *(const PG8_LAS bf16x8*)(lds + PG8_SA(b, h) + aoff + m * 2048 + k * 1024); } while (0)
; #define PG8_LDB(dst, b, h) do { _Pragma("unroll") for (int n = 0; n < 2; ++n) _Pragma("unroll") for (int k = 0; k < 2; ++k) dst[n][k] = *(const PG8_LAS bf16x8*)(lds + PG8_SB(b, h) + boff + n * 2048 + k * 1024); } while (0)
; #define PG8_MMA(ai, bj, At, Bt) do { __builtin_amdgcn_s_setprio(1); _Pragma("unroll") for (int m = 0; m < 4; ++m) _Pragma("unroll") for (int n = 0; n < 2; ++n) _Pragma("unroll") for (int k = 0; k < 2; ++k) \
;         acc[ai][bj][m][n] = __builtin_amdgcn_mfma_f32_16x16x32_bf16(Bt[n][k], At[m][k], acc[ai][bj][m][n], 0, 0, 0); __builtin_amdgcn_s_setprio(0); } while (0)
; template <class Epi, class Sched>
; __device__ __forceinline__ void gemm_phase(PG8_LAS unsigned char* lds, const Gemm g, const Sched& S, const Epi& E) {
;     ...
;             PG8_LDB(B0, 0, 0); PG8_SCHED; PG8_LDA(At, 0, 0); PG8_STAGE(PG8_SA(1, 1), a1 + hstep, voffA);
;             PG8_WAIT_L(8); PG8_BAR; PG8_WAIT_L(0); PG8_MMA(0, 0, At, B0); PG8_BAR; PG8_SCHED;
;             PG8_LDB(B1, 0, 1); PG8_STAGE(PG8_SB(0, 0), b2, voffB);
;             PG8_BAR; PG8_WAIT_L(0); PG8_MMA(0, 1, At, B1); PG8_BAR;
;             PG8_LDA(At, 0, 1); PG8_STAGE(PG8_SA(0, 0), a2, voffA);
;             PG8_BAR; PG8_WAIT_L(0); PG8_MMA(1, 0, At, B0); PG8_BAR; PG8_SCHED;
;             PG8_STAGE(PG8_SB(0, 1), b2 + hstep, voffB);
;             PG8_WAIT_V(6); PG8_BAR; PG8_MMA(1, 1, At, B1); PG8_BAR;
;             PG8_LDB(B0, 1, 0); PG8_SCHED; PG8_LDA(At, 1, 0); PG8_STAGE(PG8_SA(0, 1), a2 + hstep, voffA);
;             PG8_WAIT_L(8); PG8_BAR; PG8_WAIT_L(0); PG8_MMA(0, 0, At, B0); PG8_BAR; PG8_SCHED;
;             PG8_LDB(B1, 1, 1); PG8_STAGE(PG8_SB(1, 0), b3, voffB);
;             PG8_BAR; PG8_WAIT_L(0); PG8_MMA(0, 1, At, B1); PG8_BAR;
;             PG8_LDA(At, 1, 1); PG8_STAGE(PG8_SA(1, 0), a3, voffA);
;             PG8_BAR; PG8_WAIT_L(0); PG8_MMA(1, 0, At, B0); PG8_BAR; PG8_SCHED;
	ds_read_b128 v[144:147], v187 offset:16384
	ds_read_b128 v[148:151], v187 offset:17408
	ds_read_b128 v[182:185], v187 offset:18432
	ds_read_b128 v[192:195], v187 offset:19456
	ds_read_b128 v[196:199], v187 offset:20480
	ds_read_b128 v[200:203], v187 offset:21504
	ds_read_b128 v[204:207], v187 offset:22528
	ds_read_b128 v[208:211], v187 offset:23552
	s_add_i32 s54, s43, s35
	s_add_u32 s98, s4, s14
	s_addc_u32 s99, s5, s15
	s_mov_b32 m0, s54
	s_nop 0
	global_load_lds_dwordx4 v156, s[4:5]
	s_nop 1
	s_add_i32 m0, s54, 0x2000
	s_nop 0
	global_load_lds_dwordx4 v160, s[4:5]
	s_nop 1
	s_mov_b32 m0, s27
	s_add_u32 s100, s28, s14
	s_addc_u32 s101, s29, s15
	global_load_lds_dwordx4 v154, s[28:29]
	s_nop 1
	s_mov_b32 m0, s36
	s_nop 0
	global_load_lds_dwordx4 v158, s[28:29]
	s_add_u32 s54, s4, 0x40000
	s_addc_u32 s55, s5, 0
	s_add_i32 s56, s44, s35
	s_mov_b32 m0, s56
	s_nop 0
	global_load_lds_dwordx4 v156, s[54:55]
	s_nop 1
	s_add_i32 m0, s56, 0x2000
	s_nop 0
	global_load_lds_dwordx4 v160, s[54:55]
	s_waitcnt vmcnt(8) lgkmcnt(0)
	s_barrier
	v_mfma_f32_16x16x32_bf16 v[76:79], v[24:27], v[144:147], v[76:79]
	v_mfma_f32_16x16x32_bf16 v[72:75], v[40:43], v[144:147], v[72:75]
	v_mfma_f32_16x16x32_bf16 v[60:63], v[24:27], v[182:185], v[60:63]
	v_mfma_f32_16x16x32_bf16 v[56:59], v[40:43], v[182:185], v[56:59]
	v_mfma_f32_16x16x32_bf16 v[36:39], v[24:27], v[196:199], v[36:39]
	v_mfma_f32_16x16x32_bf16 v[32:35], v[40:43], v[196:199], v[32:35]
	v_mfma_f32_16x16x32_bf16 v[12:15], v[24:27], v[204:207], v[12:15]
	v_mfma_f32_16x16x32_bf16 v[8:11], v[40:43], v[204:207], v[8:11]
	v_mfma_f32_16x16x32_bf16 v[76:79], v[28:31], v[148:151], v[76:79]
	v_mfma_f32_16x16x32_bf16 v[72:75], v[44:47], v[148:151], v[72:75]
	v_mfma_f32_16x16x32_bf16 v[60:63], v[28:31], v[192:195], v[60:63]
	v_mfma_f32_16x16x32_bf16 v[56:59], v[44:47], v[192:195], v[56:59]
	v_mfma_f32_16x16x32_bf16 v[36:39], v[28:31], v[200:203], v[36:39]
	v_mfma_f32_16x16x32_bf16 v[32:35], v[44:47], v[200:203], v[32:35]
	v_mfma_f32_16x16x32_bf16 v[12:15], v[28:31], v[208:211], v[12:15]
	v_mfma_f32_16x16x32_bf16 v[8:11], v[44:47], v[208:211], v[8:11]
	v_mfma_f32_16x16x32_bf16 v[20:23], v[212:215], v[196:199], v[20:23]
	v_mfma_f32_16x16x32_bf16 v[16:19], v[220:223], v[196:199], v[16:19]
	v_mfma_f32_16x16x32_bf16 v[4:7], v[212:215], v[204:207], v[4:7]
	v_mfma_f32_16x16x32_bf16 v[0:3], v[220:223], v[204:207], v[0:3]
	v_mfma_f32_16x16x32_bf16 v[24:27], v[212:215], v[144:147], v[68:71]
	v_mfma_f32_16x16x32_bf16 v[28:31], v[220:223], v[144:147], v[64:67]
	v_mfma_f32_16x16x32_bf16 v[40:43], v[212:215], v[182:185], v[52:55]
	v_mfma_f32_16x16x32_bf16 v[44:47], v[220:223], v[182:185], v[48:51]
	v_mfma_f32_16x16x32_bf16 v[20:23], v[216:219], v[200:203], v[20:23]
	v_mfma_f32_16x16x32_bf16 v[16:19], v[224:227], v[200:203], v[16:19]
	v_mfma_f32_16x16x32_bf16 v[4:7], v[216:219], v[208:211], v[4:7]
	v_mfma_f32_16x16x32_bf16 v[0:3], v[224:227], v[208:211], v[0:3]
	v_mfma_f32_16x16x32_bf16 v[24:27], v[216:219], v[148:151], v[24:27]
	v_mfma_f32_16x16x32_bf16 v[28:31], v[224:227], v[148:151], v[28:31]
	v_mfma_f32_16x16x32_bf16 v[40:43], v[216:219], v[192:195], v[40:43]
	v_mfma_f32_16x16x32_bf16 v[44:47], v[224:227], v[192:195], v[44:47]
	s_barrier
	s_add_i32 s54, 0, 0x18000
	v_add_u32_e32 v68, s54, v179
	ds_read_b128 v[48:51], v68
	ds_read_b128 v[52:55], v68 offset:1024
	ds_read_b128 v[64:67], v68 offset:2048
	ds_read_b128 v[68:71], v68 offset:3072
	ds_read_b128 v[144:147], v187 offset:32768
	ds_read_b128 v[148:151], v187 offset:33792
	ds_read_b128 v[182:185], v187 offset:34816
	ds_read_b128 v[192:195], v187 offset:35840
	ds_read_b128 v[196:199], v187 offset:36864
	ds_read_b128 v[200:203], v187 offset:37888
	ds_read_b128 v[204:207], v187 offset:38912
	ds_read_b128 v[208:211], v187 offset:39936
	v_add_u32_e32 v162, 0x1c000, v179
	s_waitcnt lgkmcnt(8)
	ds_read_b128 v[212:215], v162
	ds_read_b128 v[216:219], v162 offset:1024
	ds_read_b128 v[220:223], v162 offset:2048
	ds_read_b128 v[224:227], v162 offset:3072
	s_add_u32 s28, s28, 0x40000
	s_addc_u32 s29, s29, 0
	s_mov_b32 m0, s37
	s_nop 0
	global_load_lds_dwordx4 v154, s[28:29]
	s_nop 1
	s_mov_b32 m0, s38
	s_nop 0
	global_load_lds_dwordx4 v158, s[28:29]
	s_add_i32 s28, 0, 0x1c000
	s_waitcnt vmcnt(8) lgkmcnt(0)
	s_barrier
; #define PG8_STAGE(bufoff, gbase, voff) do { _Pragma("unroll") for (int _i = 0; _i < 2; ++_i) \
;         __builtin_amdgcn_global_load_lds((const unsigned*)((const char*)(gbase) + (voff)[_i]), (PG8_LAS unsigned*)(lds + (bufoff) + ldsw + _i * 8192), 16, 0, 0); } while (0)
; #define PG8_LDA(dst, b, h) do { _Pragma("unroll") for (int m = 0; m < 4; ++m) _Pragma("unroll") for (int k = 0; k < 2; ++k) dst[m][k] = *(const PG8_LAS bf16x8*)(lds + PG8_SA(b, h) + aoff + m * 2048 + k * 1024); } while (0)
; #define PG8_LDB(dst, b, h) do { _Pragma("unroll") for (int n = 0; n < 2; ++n) _Pragma("unroll") for (int k = 0; k < 2; ++k) dst[n][k] = *(const PG8_LAS bf16x8*)(lds + PG8_SB(b, h) + boff + n * 2048 + k * 1024); } while (0)
; #define PG8_MMA(ai, bj, At, Bt) do { __builtin_amdgcn_s_setprio(1); _Pragma("unroll") for (int m = 0; m < 4; ++m) _Pragma("unroll") for (int n = 0; n < 2; ++n) _Pragma("unroll") for (int k = 0; k < 2; ++k) \
;         acc[ai][bj][m][n] = __builtin_amdgcn_mfma_f32_16x16x32_bf16(Bt[n][k], At[m][k], acc[ai][bj][m][n], 0, 0, 0); __builtin_amdgcn_s_setprio(0); } while (0)
; #define PG8_BAR __builtin_amdgcn_s_barrier()
;     __device__ __forceinline__ void operator()(const f32x4 (&acc)[2][2][4][2], const Unit& u, int wr, int wc, int fr, int fq) const {
;         int act = 0; const float* bias = nullptr;
;         if (mode == 1) { if (u.pn >= 8 && u.pn < 12) act = 1; else if (u.pn >= 12) { act = 3; bias = (u.pn >= 14) ? bias_b + (u.pn - 14) * 256 : bias_f + (u.pn - 12) * 256; } }
; template <class Epi, class Sched>
; __device__ __forceinline__ void gemm_phase(PG8_LAS unsigned char* lds, const Gemm g, const Sched& S, const Epi& E) {
;     ...
;             PG8_LDB(B0, 1, 0); PG8_SCHED; PG8_LDA(At, 1, 0); PG8_STAGE(PG8_SA(0, 1), a2 + hstep, voffA);
;             PG8_WAIT_L(8); PG8_BAR; PG8_WAIT_L(0); PG8_MMA(0, 0, At, B0); PG8_BAR; PG8_SCHED;
;             PG8_LDB(B1, 1, 1); PG8_STAGE(PG8_SB(1, 0), b3, voffB);
;             PG8_BAR; PG8_WAIT_L(0); PG8_MMA(0, 1, At, B1); PG8_BAR;
;             PG8_LDA(At, 1, 1); PG8_STAGE(PG8_SA(1, 0), a3, voffA);
;             PG8_BAR; PG8_WAIT_L(0); PG8_MMA(1, 0, At, B0); PG8_BAR; PG8_SCHED;
;             PG8_STAGE(PG8_SB(1, 1), b3 + hstep, voffB);
;             PG8_WAIT_V(6); PG8_BAR; PG8_MMA(1, 1, At, B1); PG8_BAR;
;         }
;         if constexpr (!Epi::AFTER_DRAIN) { E(acc, cur, wr, wc, fr, fq); S.done(cur); }
	v_mfma_f32_16x16x32_bf16 v[140:143], v[48:51], v[144:147], v[140:143]
	v_mfma_f32_16x16x32_bf16 v[136:139], v[64:67], v[144:147], v[136:139]
	v_mfma_f32_16x16x32_bf16 v[124:127], v[48:51], v[182:185], v[124:127]
	v_mfma_f32_16x16x32_bf16 v[120:123], v[64:67], v[182:185], v[120:123]
	v_mfma_f32_16x16x32_bf16 v[108:111], v[48:51], v[196:199], v[108:111]
	v_mfma_f32_16x16x32_bf16 v[104:107], v[64:67], v[196:199], v[104:107]
	v_mfma_f32_16x16x32_bf16 v[92:95], v[48:51], v[204:207], v[92:95]
	v_mfma_f32_16x16x32_bf16 v[88:91], v[64:67], v[204:207], v[88:91]
	v_mfma_f32_16x16x32_bf16 v[140:143], v[52:55], v[148:151], v[140:143]
	v_mfma_f32_16x16x32_bf16 v[136:139], v[68:71], v[148:151], v[136:139]
	v_mfma_f32_16x16x32_bf16 v[124:127], v[52:55], v[192:195], v[124:127]
	v_mfma_f32_16x16x32_bf16 v[120:123], v[68:71], v[192:195], v[120:123]
	v_mfma_f32_16x16x32_bf16 v[108:111], v[52:55], v[200:203], v[108:111]
	v_mfma_f32_16x16x32_bf16 v[104:107], v[68:71], v[200:203], v[104:107]
	v_mfma_f32_16x16x32_bf16 v[92:95], v[52:55], v[208:211], v[92:95]
	v_mfma_f32_16x16x32_bf16 v[88:91], v[68:71], v[208:211], v[88:91]
	v_mfma_f32_16x16x32_bf16 v[132:135], v[212:215], v[144:147], v[132:135]
	v_mfma_f32_16x16x32_bf16 v[128:131], v[220:223], v[144:147], v[128:131]
	v_mfma_f32_16x16x32_bf16 v[116:119], v[212:215], v[182:185], v[116:119]
	v_mfma_f32_16x16x32_bf16 v[112:115], v[220:223], v[182:185], v[112:115]
	v_mfma_f32_16x16x32_bf16 v[100:103], v[212:215], v[196:199], v[100:103]
	v_mfma_f32_16x16x32_bf16 v[96:99], v[220:223], v[196:199], v[96:99]
	v_mfma_f32_16x16x32_bf16 v[84:87], v[212:215], v[204:207], v[84:87]
	v_mfma_f32_16x16x32_bf16 v[80:83], v[220:223], v[204:207], v[80:83]
	v_mfma_f32_16x16x32_bf16 v[132:135], v[216:219], v[148:151], v[132:135]
	v_mfma_f32_16x16x32_bf16 v[128:131], v[224:227], v[148:151], v[128:131]
	v_mfma_f32_16x16x32_bf16 v[116:119], v[216:219], v[192:195], v[116:119]
	v_mfma_f32_16x16x32_bf16 v[112:115], v[224:227], v[192:195], v[112:115]
	v_mfma_f32_16x16x32_bf16 v[100:103], v[216:219], v[200:203], v[100:103]
	v_mfma_f32_16x16x32_bf16 v[96:99], v[224:227], v[200:203], v[96:99]
	v_mfma_f32_16x16x32_bf16 v[84:87], v[216:219], v[208:211], v[84:87]
	v_mfma_f32_16x16x32_bf16 v[80:83], v[224:227], v[208:211], v[80:83]
	s_barrier
	ds_read_b128 v[144:147], v187 offset:49152
	ds_read_b128 v[148:151], v187 offset:50176
	ds_read_b128 v[182:185], v187 offset:51200
	ds_read_b128 v[192:195], v187 offset:52224
	ds_read_b128 v[196:199], v187 offset:53248
	ds_read_b128 v[200:203], v187 offset:54272
	ds_read_b128 v[204:207], v187 offset:55296
	ds_read_b128 v[208:211], v187 offset:56320
	s_add_i32 s29, s54, s35
	s_mov_b32 m0, s29
	s_nop 0
	global_load_lds_dwordx4 v156, s[98:99]
	s_nop 1
	s_add_i32 m0, s29, 0x2000
	s_nop 0
	global_load_lds_dwordx4 v160, s[98:99]
	s_nop 1
	s_mov_b32 m0, s39
	s_nop 0
	global_load_lds_dwordx4 v154, s[100:101]
	s_nop 1
	s_mov_b32 m0, s40
	s_nop 0
	global_load_lds_dwordx4 v158, s[100:101]
	s_add_u32 s4, s4, 0x40080
	s_addc_u32 s5, s5, 0
	s_add_i32 s28, s28, s35
	s_mov_b32 m0, s28
	s_nop 0
	global_load_lds_dwordx4 v156, s[4:5]
	s_nop 1
	s_add_i32 m0, s28, 0x2000
	s_nop 0
	global_load_lds_dwordx4 v160, s[4:5]
	s_waitcnt vmcnt(8) lgkmcnt(0)
	s_barrier
	v_mfma_f32_16x16x32_bf16 v[76:79], v[48:51], v[144:147], v[76:79]
	v_mfma_f32_16x16x32_bf16 v[72:75], v[64:67], v[144:147], v[72:75]
	v_mfma_f32_16x16x32_bf16 v[60:63], v[48:51], v[182:185], v[60:63]
	v_mfma_f32_16x16x32_bf16 v[56:59], v[64:67], v[182:185], v[56:59]
	v_mfma_f32_16x16x32_bf16 v[36:39], v[48:51], v[196:199], v[36:39]
	v_mfma_f32_16x16x32_bf16 v[32:35], v[64:67], v[196:199], v[32:35]
	v_mfma_f32_16x16x32_bf16 v[12:15], v[48:51], v[204:207], v[12:15]
	v_mfma_f32_16x16x32_bf16 v[8:11], v[64:67], v[204:207], v[8:11]
	v_mfma_f32_16x16x32_bf16 v[76:79], v[52:55], v[148:151], v[76:79]
	v_mfma_f32_16x16x32_bf16 v[72:75], v[68:71], v[148:151], v[72:75]
	v_mfma_f32_16x16x32_bf16 v[60:63], v[52:55], v[192:195], v[60:63]
	v_mfma_f32_16x16x32_bf16 v[56:59], v[68:71], v[192:195], v[56:59]
	v_mfma_f32_16x16x32_bf16 v[36:39], v[52:55], v[200:203], v[36:39]
	v_mfma_f32_16x16x32_bf16 v[32:35], v[68:71], v[200:203], v[32:35]
	v_mfma_f32_16x16x32_bf16 v[12:15], v[52:55], v[208:211], v[12:15]
	v_mfma_f32_16x16x32_bf16 v[8:11], v[68:71], v[208:211], v[8:11]
	v_mfma_f32_16x16x32_bf16 v[24:27], v[212:215], v[144:147], v[24:27]
	v_mfma_f32_16x16x32_bf16 v[68:71], v[216:219], v[148:151], v[24:27]
	v_mfma_f32_16x16x32_bf16 v[24:27], v[220:223], v[144:147], v[28:31]
	v_mfma_f32_16x16x32_bf16 v[64:67], v[224:227], v[148:151], v[24:27]
	v_mfma_f32_16x16x32_bf16 v[24:27], v[212:215], v[182:185], v[40:43]
	v_mfma_f32_16x16x32_bf16 v[52:55], v[216:219], v[192:195], v[24:27]
	v_mfma_f32_16x16x32_bf16 v[24:27], v[220:223], v[182:185], v[44:47]
	v_mfma_f32_16x16x32_bf16 v[20:23], v[212:215], v[196:199], v[20:23]
	v_mfma_f32_16x16x32_bf16 v[16:19], v[220:223], v[196:199], v[16:19]
	v_mfma_f32_16x16x32_bf16 v[4:7], v[212:215], v[204:207], v[4:7]
	v_mfma_f32_16x16x32_bf16 v[0:3], v[220:223], v[204:207], v[0:3]
	v_mfma_f32_16x16x32_bf16 v[48:51], v[224:227], v[192:195], v[24:27]
	v_mfma_f32_16x16x32_bf16 v[20:23], v[216:219], v[200:203], v[20:23]
	v_mfma_f32_16x16x32_bf16 v[16:19], v[224:227], v[200:203], v[16:19]
	v_mfma_f32_16x16x32_bf16 v[4:7], v[216:219], v[208:211], v[4:7]
	v_mfma_f32_16x16x32_bf16 v[0:3], v[224:227], v[208:211], v[0:3]
	s_barrier
	s_add_i32 s53, s53, 2
	s_add_u32 s0, s0, 0x100
	s_addc_u32 s1, s1, 0
	s_add_u32 s51, s51, 0x100
	s_addc_u32 s52, s52, 0
	s_cmp_gt_u32 s53, 13
	s_cbranch_scc0 .LBB0_416
	s_cmp_gt_i32 s26, 11
	s_cselect_b64 s[4:5], -1, 0
	s_cmp_lt_i32 s26, 12
	s_mov_b64 s[0:1], 0
	s_cbranch_scc1 .LBB0_422
	s_lshl_b32 s10, s26, 8
	s_cmp_lt_u32 s26, 14
	s_mov_b64 s[28:29], -1
	s_cbranch_scc0 .LBB0_420
	s_lshl_b64 s[0:1], s[10:11], 2
	v_readlane_b32 s52, v245, 0
	v_readlane_b32 s53, v245, 1
	s_add_u32 s0, s52, s0
	s_addc_u32 s1, s53, s1
	s_add_u32 s0, s0, 0xffffd000
	v_readlane_b32 s54, v245, 2
	v_readlane_b32 s55, v245, 3
	v_readlane_b32 s56, v245, 4
	v_readlane_b32 s57, v245, 5
	v_readlane_b32 s58, v245, 6
	v_readlane_b32 s59, v245, 7
	v_readlane_b32 s60, v245, 8
	v_readlane_b32 s61, v245, 9
	v_readlane_b32 s62, v245, 10
	v_readlane_b32 s63, v245, 11
	v_readlane_b32 s64, v245, 12
	v_readlane_b32 s65, v245, 13
	v_readlane_b32 s66, v245, 14
	v_readlane_b32 s67, v245, 15
	s_addc_u32 s1, s1, -1
	s_mov_b64 s[28:29], 0

; #define PG8_STAGE(bufoff, gbase, voff) do { _Pragma("unroll") for (int _i = 0; _i < 2; ++_i) \
;         __builtin_amdgcn_global_load_lds((const unsigned*)((const char*)(gbase) + (voff)[_i]), (PG8_LAS unsigned*)(lds + (bufoff) + ldsw + _i * 8192), 16, 0, 0); } while (0)
; #define PG8_LDA(dst, b, h) do { _Pragma("unroll") for (int m = 0; m < 4; ++m) _Pragma("unroll") for (int k = 0; k < 2; ++k) dst[m][k] = *(const PG8_LAS bf16x8*)(lds + PG8_SA(b, h) + aoff + m * 2048 + k * 1024); } while (0)
; #define PG8_LDB(dst, b, h) do { _Pragma("unroll") for (int n = 0; n < 2; ++n) _Pragma("unroll") for (int k = 0; k < 2; ++k) dst[n][k] = *(const PG8_LAS bf16x8*)(lds + PG8_SB(b, h) + boff + n * 2048 + k * 1024); } while (0)
; #define PG8_BAR __builtin_amdgcn_s_barrier()
; template <class Epi, class Sched>
; __device__ __forceinline__ void gemm_phase(PG8_LAS unsigned char* lds, const Gemm g, const Sched& S, const Epi& E) {
;     ...
;         const bool has_next = S.next(ui + 1, nxt);
;         const char* nA = has_next ? (const char*)g.A + (size_t)nxt.pm * tstep : cA; const char* nB = has_next ? (const char*)g.Bt + (size_t)nxt.pn * tstep : cB;
;         for (int t = 0; t < nt; t += 2) {
;             const bool last = (t == nt - 2);
;             const char* a1 = cA + (size_t)(t + 1) * kstep;
;             const char* a2 = last ? nA : cA + (size_t)(t + 2) * kstep; const char* b2 = last ? nB : cB + (size_t)(t + 2) * kstep;
;             const char* a3 = a2 + kstep; const char* b3 = b2 + kstep;
;             if (last && has_next) S.a_ready(nxt);
;             PG8_LDB(B0, 0, 0); PG8_SCHED; PG8_LDA(At, 0, 0); PG8_STAGE(PG8_SA(1, 1), a1 + hstep, voffA);
;             PG8_WAIT_L(8); PG8_BAR; PG8_WAIT_L(0); PG8_MMA(0, 0, At, B0); PG8_BAR; PG8_SCHED;
;             PG8_LDB(B1, 0, 1); PG8_STAGE(PG8_SB(0, 0), b2, voffB);
;             PG8_BAR; PG8_WAIT_L(0); PG8_MMA(0, 1, At, B1); PG8_BAR;
;             PG8_LDA(At, 0, 1); PG8_STAGE(PG8_SA(0, 0), a2, voffA);
;             PG8_BAR; PG8_WAIT_L(0); PG8_MMA(1, 0, At, B0); PG8_BAR; PG8_SCHED;
;             PG8_STAGE(PG8_SB(0, 1), b2 + hstep, voffB);
;             PG8_WAIT_V(6); PG8_BAR; PG8_MMA(1, 1, At, B1); PG8_BAR;
;             PG8_LDB(B0, 1, 0); PG8_SCHED; PG8_LDA(At, 1, 0); PG8_STAGE(PG8_SA(0, 1), a2 + hstep, voffA);
;             PG8_WAIT_L(8); PG8_BAR; PG8_WAIT_L(0); PG8_MMA(0, 0, At, B0); PG8_BAR; PG8_SCHED;
.LBB0_723:
	s_ashr_i32 s11, s10, 31
	v_cmp_lt_i64_e32 vcc, s[12:13], v[140:141]
	s_lshl_b64 s[12:13], s[10:11], 19
	s_add_u32 s12, s26, s12
	s_addc_u32 s13, s27, s13
	s_and_b64 s[14:15], vcc, exec
	s_cselect_b32 s5, s13, s19
	s_cselect_b32 s11, s12, s18
	s_ashr_i32 s9, s8, 31
	s_lshl_b64 s[14:15], s[8:9], 19
	s_add_u32 s14, s28, s14
	s_addc_u32 s15, s29, s15
	s_and_b64 s[22:23], vcc, exec
	s_cselect_b32 s9, s15, s21
	s_cselect_b32 s45, s14, s20
	s_add_u32 s18, s18, 0x40080
	s_addc_u32 s19, s19, 0
	s_add_u32 s46, s20, 0x100
	s_addc_u32 s47, s21, 0
	s_mov_b32 s48, -2
	ds_read_b128 v[144:147], v151
	ds_read_b128 v[156:159], v151 offset:1024
	ds_read_b128 v[160:163], v151 offset:2048
	ds_read_b128 v[166:169], v151 offset:3072
	s_add_u32 s20, s18, 0xfffc0080
	s_addc_u32 s21, s19, -1
	s_cmp_eq_u32 s48, 12
	s_cselect_b32 s23, s5, s21
	s_cselect_b32 s22, s11, s20
	s_cselect_b32 s21, s9, s47
	s_cselect_b32 s20, s45, s46
	ds_read_b128 v[170:173], v153
	ds_read_b128 v[182:185], v153 offset:1024
	ds_read_b128 v[190:193], v153 offset:2048
	ds_read_b128 v[194:197], v153 offset:3072
	ds_read_b128 v[198:201], v153 offset:4096
	ds_read_b128 v[202:205], v153 offset:5120
	ds_read_b128 v[206:209], v153 offset:6144
	ds_read_b128 v[210:213], v153 offset:7168
	s_waitcnt lgkmcnt(8)
	ds_read_b128 v[214:217], v154
	ds_read_b128 v[218:221], v154 offset:1024
	ds_read_b128 v[222:225], v154 offset:2048
	ds_read_b128 v[226:229], v154 offset:3072
	s_add_i32 m0, s17, 0xc000
	s_nop 0
	global_load_lds_dwordx4 v136, s[18:19]
	s_nop 1
	s_add_i32 m0, s17, 0xe000
	s_nop 0
	global_load_lds_dwordx4 v138, s[18:19]
	s_waitcnt vmcnt(8) lgkmcnt(0)
	s_barrier
	v_mfma_f32_16x16x32_bf16 v[124:127], v[144:147], v[170:173], 0
	v_mfma_f32_16x16x32_bf16 v[120:123], v[160:163], v[170:173], 0
	v_mfma_f32_16x16x32_bf16 v[108:111], v[144:147], v[190:193], 0
	v_mfma_f32_16x16x32_bf16 v[104:107], v[160:163], v[190:193], 0
	v_mfma_f32_16x16x32_bf16 v[92:95], v[144:147], v[198:201], 0
	v_mfma_f32_16x16x32_bf16 v[88:91], v[160:163], v[198:201], 0
	v_mfma_f32_16x16x32_bf16 v[76:79], v[144:147], v[206:209], 0
	v_mfma_f32_16x16x32_bf16 v[72:75], v[160:163], v[206:209], 0
	v_mfma_f32_16x16x32_bf16 v[124:127], v[156:159], v[182:185], v[124:127]
	v_mfma_f32_16x16x32_bf16 v[120:123], v[166:169], v[182:185], v[120:123]
	v_mfma_f32_16x16x32_bf16 v[108:111], v[156:159], v[194:197], v[108:111]
	v_mfma_f32_16x16x32_bf16 v[104:107], v[166:169], v[194:197], v[104:107]
	v_mfma_f32_16x16x32_bf16 v[92:95], v[156:159], v[202:205], v[92:95]
	v_mfma_f32_16x16x32_bf16 v[88:91], v[166:169], v[202:205], v[88:91]
	v_mfma_f32_16x16x32_bf16 v[76:79], v[156:159], v[210:213], v[76:79]
	v_mfma_f32_16x16x32_bf16 v[72:75], v[166:169], v[210:213], v[72:75]
	v_mfma_f32_16x16x32_bf16 v[116:119], v[214:217], v[170:173], 0
	v_mfma_f32_16x16x32_bf16 v[112:115], v[222:225], v[170:173], 0
	v_mfma_f32_16x16x32_bf16 v[100:103], v[214:217], v[190:193], 0
	v_mfma_f32_16x16x32_bf16 v[96:99], v[222:225], v[190:193], 0
	v_mfma_f32_16x16x32_bf16 v[84:87], v[214:217], v[198:201], 0
	v_mfma_f32_16x16x32_bf16 v[80:83], v[222:225], v[198:201], 0
	v_mfma_f32_16x16x32_bf16 v[68:71], v[214:217], v[206:209], 0
	v_mfma_f32_16x16x32_bf16 v[64:67], v[222:225], v[206:209], 0
	v_mfma_f32_16x16x32_bf16 v[116:119], v[218:221], v[182:185], v[116:119]
	v_mfma_f32_16x16x32_bf16 v[112:115], v[226:229], v[182:185], v[112:115]
	v_mfma_f32_16x16x32_bf16 v[100:103], v[218:221], v[194:197], v[100:103]
	v_mfma_f32_16x16x32_bf16 v[96:99], v[226:229], v[194:197], v[96:99]
	v_mfma_f32_16x16x32_bf16 v[84:87], v[218:221], v[202:205], v[84:87]
	v_mfma_f32_16x16x32_bf16 v[80:83], v[226:229], v[202:205], v[80:83]
	v_mfma_f32_16x16x32_bf16 v[68:71], v[218:221], v[210:213], v[68:71]
	v_mfma_f32_16x16x32_bf16 v[64:67], v[226:229], v[210:213], v[64:67]
	s_barrier
	ds_read_b128 v[170:173], v153 offset:16384
	ds_read_b128 v[182:185], v153 offset:17408
	ds_read_b128 v[190:193], v153 offset:18432
	ds_read_b128 v[194:197], v153 offset:19456
	ds_read_b128 v[198:201], v153 offset:20480
	ds_read_b128 v[202:205], v153 offset:21504
	ds_read_b128 v[206:209], v153 offset:22528
	ds_read_b128 v[210:213], v153 offset:23552
	s_add_i32 s49, s42, s30
	s_add_u32 s98, s20, s6
	s_addc_u32 s99, s21, s7
	s_mov_b32 m0, s49
	s_nop 0
	global_load_lds_dwordx4 v130, s[20:21]
	s_nop 1
	s_add_i32 m0, s49, 0x2000
	s_nop 0
	global_load_lds_dwordx4 v134, s[20:21]
	s_nop 1
	s_mov_b32 m0, s17
	s_add_u32 s100, s22, s6
	s_addc_u32 s101, s23, s7
	global_load_lds_dwordx4 v128, s[22:23]
	s_nop 1
	s_mov_b32 m0, s31
	s_nop 0
	global_load_lds_dwordx4 v132, s[22:23]
	s_add_u32 s50, s20, 0x40000
	s_addc_u32 s51, s21, 0
	s_add_i32 s49, s43, s30
	s_mov_b32 m0, s49
	s_nop 0
	global_load_lds_dwordx4 v130, s[50:51]
	s_nop 1
	s_add_i32 m0, s49, 0x2000
	s_nop 0
	global_load_lds_dwordx4 v134, s[50:51]
	s_waitcnt vmcnt(8) lgkmcnt(0)
	s_barrier
; #define PG8_STAGE(bufoff, gbase, voff) do { _Pragma("unroll") for (int _i = 0; _i < 2; ++_i) \
;         __builtin_amdgcn_global_load_lds((const unsigned*)((const char*)(gbase) + (voff)[_i]), (PG8_LAS unsigned*)(lds + (bufoff) + ldsw + _i * 8192), 16, 0, 0); } while (0)
; #define PG8_LDA(dst, b, h) do { _Pragma("unroll") for (int m = 0; m < 4; ++m) _Pragma("unroll") for (int k = 0; k < 2; ++k) dst[m][k] = *(const PG8_LAS bf16x8*)(lds + PG8_SA(b, h) + aoff + m * 2048 + k * 1024); } while (0)
; #define PG8_LDB(dst, b, h) do { _Pragma("unroll") for (int n = 0; n < 2; ++n) _Pragma("unroll") for (int k = 0; k < 2; ++k) dst[n][k] = *(const PG8_LAS bf16x8*)(lds + PG8_SB(b, h) + boff + n * 2048 + k * 1024); } while (0)
; #define PG8_MMA(ai, bj, At, Bt) do { __builtin_amdgcn_s_setprio(1); _Pragma("unroll") for (int m = 0; m < 4; ++m) _Pragma("unroll") for (int n = 0; n < 2; ++n) _Pragma("unroll") for (int k = 0; k < 2; ++k) \
;         acc[ai][bj][m][n] = __builtin_amdgcn_mfma_f32_16x16x32_bf16(Bt[n][k], At[m][k], acc[ai][bj][m][n], 0, 0, 0); __builtin_amdgcn_s_setprio(0); } while (0)
; #define PG8_WAIT_V(n) asm volatile("s_waitcnt vmcnt(" #n ")" ::: "memory")
; #define PG8_WAIT_L(n) asm volatile("s_waitcnt lgkmcnt(" #n ")" ::: "memory")
; #define PG8_BAR __builtin_amdgcn_s_barrier()
; #define PG8_SCHED __builtin_amdgcn_sched_barrier(0)
; template <class Epi, class Sched>
; __device__ __forceinline__ void gemm_phase(PG8_LAS unsigned char* lds, const Gemm g, const Sched& S, const Epi& E) {
;     ...
;             PG8_BAR; PG8_WAIT_L(0); PG8_MMA(1, 0, At, B0); PG8_BAR; PG8_SCHED;
;             PG8_STAGE(PG8_SB(0, 1), b2 + hstep, voffB);
;             PG8_WAIT_V(6); PG8_BAR; PG8_MMA(1, 1, At, B1); PG8_BAR;
;             PG8_LDB(B0, 1, 0); PG8_SCHED; PG8_LDA(At, 1, 0); PG8_STAGE(PG8_SA(0, 1), a2 + hstep, voffA);
;             PG8_WAIT_L(8); PG8_BAR; PG8_WAIT_L(0); PG8_MMA(0, 0, At, B0); PG8_BAR; PG8_SCHED;
;             PG8_LDB(B1, 1, 1); PG8_STAGE(PG8_SB(1, 0), b3, voffB);
;             PG8_BAR; PG8_WAIT_L(0); PG8_MMA(0, 1, At, B1); PG8_BAR;
;             PG8_LDA(At, 1, 1); PG8_STAGE(PG8_SA(1, 0), a3, voffA);
;             PG8_BAR; PG8_WAIT_L(0); PG8_MMA(1, 0, At, B0); PG8_BAR; PG8_SCHED;
	v_mfma_f32_16x16x32_bf16 v[60:63], v[144:147], v[170:173], 0
	v_mfma_f32_16x16x32_bf16 v[56:59], v[160:163], v[170:173], 0
	v_mfma_f32_16x16x32_bf16 v[44:47], v[144:147], v[190:193], 0
	v_mfma_f32_16x16x32_bf16 v[40:43], v[160:163], v[190:193], 0
	v_mfma_f32_16x16x32_bf16 v[28:31], v[144:147], v[198:201], 0
	v_mfma_f32_16x16x32_bf16 v[24:27], v[160:163], v[198:201], 0
	v_mfma_f32_16x16x32_bf16 v[12:15], v[144:147], v[206:209], 0
	v_mfma_f32_16x16x32_bf16 v[8:11], v[160:163], v[206:209], 0
	v_mfma_f32_16x16x32_bf16 v[60:63], v[156:159], v[182:185], v[60:63]
	v_mfma_f32_16x16x32_bf16 v[56:59], v[166:169], v[182:185], v[56:59]
	v_mfma_f32_16x16x32_bf16 v[44:47], v[156:159], v[194:197], v[44:47]
	v_mfma_f32_16x16x32_bf16 v[40:43], v[166:169], v[194:197], v[40:43]
	v_mfma_f32_16x16x32_bf16 v[28:31], v[156:159], v[202:205], v[28:31]
	v_mfma_f32_16x16x32_bf16 v[24:27], v[166:169], v[202:205], v[24:27]
	v_mfma_f32_16x16x32_bf16 v[12:15], v[156:159], v[210:213], v[12:15]
	v_mfma_f32_16x16x32_bf16 v[8:11], v[166:169], v[210:213], v[8:11]
	v_mfma_f32_16x16x32_bf16 v[52:55], v[214:217], v[170:173], 0
	v_mfma_f32_16x16x32_bf16 v[48:51], v[222:225], v[170:173], 0
	v_mfma_f32_16x16x32_bf16 v[36:39], v[214:217], v[190:193], 0
	v_mfma_f32_16x16x32_bf16 v[32:35], v[222:225], v[190:193], 0
	v_mfma_f32_16x16x32_bf16 v[20:23], v[214:217], v[198:201], 0
	v_mfma_f32_16x16x32_bf16 v[16:19], v[222:225], v[198:201], 0
	v_mfma_f32_16x16x32_bf16 v[4:7], v[214:217], v[206:209], 0
	v_mfma_f32_16x16x32_bf16 v[0:3], v[222:225], v[206:209], 0
	v_mfma_f32_16x16x32_bf16 v[52:55], v[218:221], v[182:185], v[52:55]
	v_mfma_f32_16x16x32_bf16 v[48:51], v[226:229], v[182:185], v[48:51]
	v_mfma_f32_16x16x32_bf16 v[36:39], v[218:221], v[194:197], v[36:39]
	v_mfma_f32_16x16x32_bf16 v[32:35], v[226:229], v[194:197], v[32:35]
	v_mfma_f32_16x16x32_bf16 v[20:23], v[218:221], v[202:205], v[20:23]
	v_mfma_f32_16x16x32_bf16 v[16:19], v[226:229], v[202:205], v[16:19]
	v_mfma_f32_16x16x32_bf16 v[4:7], v[218:221], v[210:213], v[4:7]
	v_mfma_f32_16x16x32_bf16 v[0:3], v[226:229], v[210:213], v[0:3]
	s_barrier
	s_add_i32 s49, 0, 0x18000
	v_add_u32_e32 v155, s49, v149
	ds_read_b128 v[144:147], v155
	ds_read_b128 v[156:159], v155 offset:1024
	ds_read_b128 v[160:163], v155 offset:2048
	ds_read_b128 v[166:169], v155 offset:3072
	ds_read_b128 v[170:173], v153 offset:32768
	ds_read_b128 v[182:185], v153 offset:33792
	ds_read_b128 v[190:193], v153 offset:34816
	ds_read_b128 v[194:197], v153 offset:35840
	ds_read_b128 v[198:201], v153 offset:36864
	ds_read_b128 v[202:205], v153 offset:37888
	ds_read_b128 v[206:209], v153 offset:38912
	ds_read_b128 v[210:213], v153 offset:39936
	v_add_u32_e32 v155, 0x1c000, v149
	s_waitcnt lgkmcnt(8)
	ds_read_b128 v[214:217], v155
	ds_read_b128 v[218:221], v155 offset:1024
	ds_read_b128 v[222:225], v155 offset:2048
	ds_read_b128 v[226:229], v155 offset:3072
	s_add_u32 s22, s22, 0x40000
	s_addc_u32 s23, s23, 0
	s_mov_b32 m0, s34
	s_nop 0
	global_load_lds_dwordx4 v128, s[22:23]
	s_nop 1
	s_mov_b32 m0, s35
	s_nop 0
	global_load_lds_dwordx4 v132, s[22:23]
	s_add_i32 s22, 0, 0x1c000
	s_waitcnt vmcnt(8) lgkmcnt(0)
	s_barrier
	v_mfma_f32_16x16x32_bf16 v[124:127], v[144:147], v[170:173], v[124:127]
	v_mfma_f32_16x16x32_bf16 v[120:123], v[160:163], v[170:173], v[120:123]
	v_mfma_f32_16x16x32_bf16 v[108:111], v[144:147], v[190:193], v[108:111]
	v_mfma_f32_16x16x32_bf16 v[104:107], v[160:163], v[190:193], v[104:107]
	v_mfma_f32_16x16x32_bf16 v[92:95], v[144:147], v[198:201], v[92:95]
	v_mfma_f32_16x16x32_bf16 v[88:91], v[160:163], v[198:201], v[88:91]
	v_mfma_f32_16x16x32_bf16 v[76:79], v[144:147], v[206:209], v[76:79]
	v_mfma_f32_16x16x32_bf16 v[72:75], v[160:163], v[206:209], v[72:75]
	v_mfma_f32_16x16x32_bf16 v[124:127], v[156:159], v[182:185], v[124:127]
	v_mfma_f32_16x16x32_bf16 v[120:123], v[166:169], v[182:185], v[120:123]
	v_mfma_f32_16x16x32_bf16 v[108:111], v[156:159], v[194:197], v[108:111]
	v_mfma_f32_16x16x32_bf16 v[104:107], v[166:169], v[194:197], v[104:107]
	v_mfma_f32_16x16x32_bf16 v[92:95], v[156:159], v[202:205], v[92:95]
	v_mfma_f32_16x16x32_bf16 v[88:91], v[166:169], v[202:205], v[88:91]
	v_mfma_f32_16x16x32_bf16 v[76:79], v[156:159], v[210:213], v[76:79]
	v_mfma_f32_16x16x32_bf16 v[72:75], v[166:169], v[210:213], v[72:75]
	v_mfma_f32_16x16x32_bf16 v[116:119], v[214:217], v[170:173], v[116:119]
	v_mfma_f32_16x16x32_bf16 v[112:115], v[222:225], v[170:173], v[112:115]
	v_mfma_f32_16x16x32_bf16 v[100:103], v[214:217], v[190:193], v[100:103]
	v_mfma_f32_16x16x32_bf16 v[96:99], v[222:225], v[190:193], v[96:99]
	v_mfma_f32_16x16x32_bf16 v[84:87], v[214:217], v[198:201], v[84:87]
	v_mfma_f32_16x16x32_bf16 v[80:83], v[222:225], v[198:201], v[80:83]
	v_mfma_f32_16x16x32_bf16 v[68:71], v[214:217], v[206:209], v[68:71]
	v_mfma_f32_16x16x32_bf16 v[64:67], v[222:225], v[206:209], v[64:67]
	v_mfma_f32_16x16x32_bf16 v[116:119], v[218:221], v[182:185], v[116:119]
	v_mfma_f32_16x16x32_bf16 v[112:115], v[226:229], v[182:185], v[112:115]
	v_mfma_f32_16x16x32_bf16 v[100:103], v[218:221], v[194:197], v[100:103]
	v_mfma_f32_16x16x32_bf16 v[96:99], v[226:229], v[194:197], v[96:99]
	v_mfma_f32_16x16x32_bf16 v[84:87], v[218:221], v[202:205], v[84:87]
	v_mfma_f32_16x16x32_bf16 v[80:83], v[226:229], v[202:205], v[80:83]
	v_mfma_f32_16x16x32_bf16 v[68:71], v[218:221], v[210:213], v[68:71]
	v_mfma_f32_16x16x32_bf16 v[64:67], v[226:229], v[210:213], v[64:67]
	s_barrier
; #define PG8_STAGE(bufoff, gbase, voff) do { _Pragma("unroll") for (int _i = 0; _i < 2; ++_i) \
;         __builtin_amdgcn_global_load_lds((const unsigned*)((const char*)(gbase) + (voff)[_i]), (PG8_LAS unsigned*)(lds + (bufoff) + ldsw + _i * 8192), 16, 0, 0); } while (0)
; #define PG8_LDA(dst, b, h) do { _Pragma("unroll") for (int m = 0; m < 4; ++m) _Pragma("unroll") for (int k = 0; k < 2; ++k) dst[m][k] = *(const PG8_LAS bf16x8*)(lds + PG8_SA(b, h) + aoff + m * 2048 + k * 1024); } while (0)
; #define PG8_WAIT_V(n) asm volatile("s_waitcnt vmcnt(" #n ")" ::: "memory")
; template <class Epi, class Sched>
; __device__ __forceinline__ void gemm_phase(PG8_LAS unsigned char* lds, const Gemm g, const Sched& S, const Epi& E) {
;     ...
;         for (int t = 0; t < nt; t += 2) {
;             const bool last = (t == nt - 2);
;             const char* a1 = cA + (size_t)(t + 1) * kstep;
;             const char* a2 = last ? nA : cA + (size_t)(t + 2) * kstep; const char* b2 = last ? nB : cB + (size_t)(t + 2) * kstep;
;             const char* a3 = a2 + kstep; const char* b3 = b2 + kstep;
;             if (last && has_next) S.a_ready(nxt);
;             PG8_LDB(B0, 0, 0); PG8_SCHED; PG8_LDA(At, 0, 0); PG8_STAGE(PG8_SA(1, 1), a1 + hstep, voffA);
;             PG8_WAIT_L(8); PG8_BAR; PG8_WAIT_L(0); PG8_MMA(0, 0, At, B0); PG8_BAR; PG8_SCHED;
;             PG8_LDB(B1, 0, 1); PG8_STAGE(PG8_SB(0, 0), b2, voffB);
;             PG8_BAR; PG8_WAIT_L(0); PG8_MMA(0, 1, At, B1); PG8_BAR;
;             PG8_LDA(At, 0, 1); PG8_STAGE(PG8_SA(0, 0), a2, voffA);
;             PG8_BAR; PG8_WAIT_L(0); PG8_MMA(1, 0, At, B0); PG8_BAR; PG8_SCHED;
;             PG8_STAGE(PG8_SB(0, 1), b2 + hstep, voffB);
;             PG8_WAIT_V(6); PG8_BAR; PG8_MMA(1, 1, At, B1); PG8_BAR;
;             PG8_LDB(B0, 1, 0); PG8_SCHED; PG8_LDA(At, 1, 0); PG8_STAGE(PG8_SA(0, 1), a2 + hstep, voffA);
;             PG8_WAIT_L(8); PG8_BAR; PG8_WAIT_L(0); PG8_MMA(0, 0, At, B0); PG8_BAR; PG8_SCHED;
;             PG8_LDB(B1, 1, 1); PG8_STAGE(PG8_SB(1, 0), b3, voffB);
;             PG8_BAR; PG8_WAIT_L(0); PG8_MMA(0, 1, At, B1); PG8_BAR;
;             PG8_LDA(At, 1, 1); PG8_STAGE(PG8_SA(1, 0), a3, voffA);
;             PG8_BAR; PG8_WAIT_L(0); PG8_MMA(1, 0, At, B0); PG8_BAR; PG8_SCHED;
;             PG8_STAGE(PG8_SB(1, 1), b3 + hstep, voffB);
;             PG8_WAIT_V(6); PG8_BAR; PG8_MMA(1, 1, At, B1); PG8_BAR;
	ds_read_b128 v[170:173], v153 offset:49152
	ds_read_b128 v[182:185], v153 offset:50176
	ds_read_b128 v[190:193], v153 offset:51200
	ds_read_b128 v[194:197], v153 offset:52224
	ds_read_b128 v[198:201], v153 offset:53248
	ds_read_b128 v[202:205], v153 offset:54272
	ds_read_b128 v[206:209], v153 offset:55296
	ds_read_b128 v[210:213], v153 offset:56320
	s_add_i32 s23, s49, s30
	s_mov_b32 m0, s23
	s_nop 0
	global_load_lds_dwordx4 v130, s[98:99]
	s_nop 1
	s_add_i32 m0, s23, 0x2000
	s_nop 0
	global_load_lds_dwordx4 v134, s[98:99]
	s_nop 1
	s_mov_b32 m0, s37
	s_nop 0
	global_load_lds_dwordx4 v128, s[100:101]
	s_nop 1
	s_mov_b32 m0, s38
	s_nop 0
	global_load_lds_dwordx4 v132, s[100:101]
	s_add_u32 s20, s20, 0x40080
	s_addc_u32 s21, s21, 0
	s_add_i32 s22, s22, s30
	s_mov_b32 m0, s22
	s_nop 0
	global_load_lds_dwordx4 v130, s[20:21]
	s_nop 1
	s_add_i32 m0, s22, 0x2000
	s_nop 0
	global_load_lds_dwordx4 v134, s[20:21]
	s_waitcnt vmcnt(8) lgkmcnt(0)
	s_barrier
	v_mfma_f32_16x16x32_bf16 v[60:63], v[144:147], v[170:173], v[60:63]
	v_mfma_f32_16x16x32_bf16 v[56:59], v[160:163], v[170:173], v[56:59]
	v_mfma_f32_16x16x32_bf16 v[44:47], v[144:147], v[190:193], v[44:47]
	v_mfma_f32_16x16x32_bf16 v[40:43], v[160:163], v[190:193], v[40:43]
	v_mfma_f32_16x16x32_bf16 v[28:31], v[144:147], v[198:201], v[28:31]
	v_mfma_f32_16x16x32_bf16 v[24:27], v[160:163], v[198:201], v[24:27]
	v_mfma_f32_16x16x32_bf16 v[12:15], v[144:147], v[206:209], v[12:15]
	v_mfma_f32_16x16x32_bf16 v[8:11], v[160:163], v[206:209], v[8:11]
	v_mfma_f32_16x16x32_bf16 v[60:63], v[156:159], v[182:185], v[60:63]
	v_mfma_f32_16x16x32_bf16 v[56:59], v[166:169], v[182:185], v[56:59]
	v_mfma_f32_16x16x32_bf16 v[44:47], v[156:159], v[194:197], v[44:47]
	v_mfma_f32_16x16x32_bf16 v[40:43], v[166:169], v[194:197], v[40:43]
	v_mfma_f32_16x16x32_bf16 v[28:31], v[156:159], v[202:205], v[28:31]
	v_mfma_f32_16x16x32_bf16 v[24:27], v[166:169], v[202:205], v[24:27]
	v_mfma_f32_16x16x32_bf16 v[12:15], v[156:159], v[210:213], v[12:15]
	v_mfma_f32_16x16x32_bf16 v[8:11], v[166:169], v[210:213], v[8:11]
	v_mfma_f32_16x16x32_bf16 v[52:55], v[214:217], v[170:173], v[52:55]
	v_mfma_f32_16x16x32_bf16 v[48:51], v[222:225], v[170:173], v[48:51]
	v_mfma_f32_16x16x32_bf16 v[36:39], v[214:217], v[190:193], v[36:39]
	v_mfma_f32_16x16x32_bf16 v[32:35], v[222:225], v[190:193], v[32:35]
	v_mfma_f32_16x16x32_bf16 v[20:23], v[214:217], v[198:201], v[20:23]
	v_mfma_f32_16x16x32_bf16 v[16:19], v[222:225], v[198:201], v[16:19]
	v_mfma_f32_16x16x32_bf16 v[4:7], v[214:217], v[206:209], v[4:7]
	v_mfma_f32_16x16x32_bf16 v[0:3], v[222:225], v[206:209], v[0:3]
	v_mfma_f32_16x16x32_bf16 v[52:55], v[218:221], v[182:185], v[52:55]
	v_mfma_f32_16x16x32_bf16 v[48:51], v[226:229], v[182:185], v[48:51]
	v_mfma_f32_16x16x32_bf16 v[36:39], v[218:221], v[194:197], v[36:39]
	v_mfma_f32_16x16x32_bf16 v[32:35], v[226:229], v[194:197], v[32:35]
	v_mfma_f32_16x16x32_bf16 v[20:23], v[218:221], v[202:205], v[20:23]
	v_mfma_f32_16x16x32_bf16 v[16:19], v[226:229], v[202:205], v[16:19]
	v_mfma_f32_16x16x32_bf16 v[4:7], v[218:221], v[210:213], v[4:7]
	v_mfma_f32_16x16x32_bf16 v[0:3], v[226:229], v[210:213], v[0:3]
	s_barrier
	s_add_i32 s48, s48, 2
	s_add_u32 s18, s18, 0x100
	s_addc_u32 s19, s19, 0
	s_add_u32 s46, s46, 0x100
	s_addc_u32 s47, s47, 0
	s_cmp_gt_u32 s48, 13
.LBB0_724:
	ds_read_b128 v[144:147], v151
	ds_read_b128 v[156:159], v151 offset:1024
	ds_read_b128 v[160:163], v151 offset:2048
	ds_read_b128 v[166:169], v151 offset:3072
	s_add_u32 s20, s18, 0xfffc0080
	s_addc_u32 s21, s19, -1
	s_cmp_eq_u32 s48, 12
	s_cselect_b32 s23, s5, s21
	s_cselect_b32 s22, s11, s20
	s_cselect_b32 s21, s9, s47
	s_cselect_b32 s20, s45, s46
	ds_read_b128 v[170:173], v153
	ds_read_b128 v[182:185], v153 offset:1024
	ds_read_b128 v[190:193], v153 offset:2048
	ds_read_b128 v[194:197], v153 offset:3072
	ds_read_b128 v[198:201], v153 offset:4096
	ds_read_b128 v[202:205], v153 offset:5120
	ds_read_b128 v[206:209], v153 offset:6144
	ds_read_b128 v[210:213], v153 offset:7168
	s_waitcnt lgkmcnt(8)
	ds_read_b128 v[214:217], v154
	ds_read_b128 v[218:221], v154 offset:1024
	ds_read_b128 v[222:225], v154 offset:2048
	ds_read_b128 v[226:229], v154 offset:3072
	s_add_i32 m0, s17, 0xc000
	s_nop 0
	global_load_lds_dwordx4 v136, s[18:19]
	s_nop 1
	s_add_i32 m0, s17, 0xe000
	s_nop 0
	global_load_lds_dwordx4 v138, s[18:19]
	s_waitcnt vmcnt(8) lgkmcnt(0)
	s_barrier
	v_mfma_f32_16x16x32_bf16 v[124:127], v[144:147], v[170:173], v[124:127]
	v_mfma_f32_16x16x32_bf16 v[120:123], v[160:163], v[170:173], v[120:123]
	v_mfma_f32_16x16x32_bf16 v[108:111], v[144:147], v[190:193], v[108:111]
	v_mfma_f32_16x16x32_bf16 v[104:107], v[160:163], v[190:193], v[104:107]
	v_mfma_f32_16x16x32_bf16 v[92:95], v[144:147], v[198:201], v[92:95]
	v_mfma_f32_16x16x32_bf16 v[88:91], v[160:163], v[198:201], v[88:91]
	v_mfma_f32_16x16x32_bf16 v[76:79], v[144:147], v[206:209], v[76:79]
	v_mfma_f32_16x16x32_bf16 v[72:75], v[160:163], v[206:209], v[72:75]
	v_mfma_f32_16x16x32_bf16 v[124:127], v[156:159], v[182:185], v[124:127]
	v_mfma_f32_16x16x32_bf16 v[120:123], v[166:169], v[182:185], v[120:123]
	v_mfma_f32_16x16x32_bf16 v[108:111], v[156:159], v[194:197], v[108:111]
	v_mfma_f32_16x16x32_bf16 v[104:107], v[166:169], v[194:197], v[104:107]
	v_mfma_f32_16x16x32_bf16 v[92:95], v[156:159], v[202:205], v[92:95]
	v_mfma_f32_16x16x32_bf16 v[88:91], v[166:169], v[202:205], v[88:91]
	v_mfma_f32_16x16x32_bf16 v[76:79], v[156:159], v[210:213], v[76:79]
	v_mfma_f32_16x16x32_bf16 v[72:75], v[166:169], v[210:213], v[72:75]
	v_mfma_f32_16x16x32_bf16 v[116:119], v[214:217], v[170:173], v[116:119]
	v_mfma_f32_16x16x32_bf16 v[112:115], v[222:225], v[170:173], v[112:115]
	v_mfma_f32_16x16x32_bf16 v[100:103], v[214:217], v[190:193], v[100:103]
	v_mfma_f32_16x16x32_bf16 v[96:99], v[222:225], v[190:193], v[96:99]
	v_mfma_f32_16x16x32_bf16 v[84:87], v[214:217], v[198:201], v[84:87]
	v_mfma_f32_16x16x32_bf16 v[80:83], v[222:225], v[198:201], v[80:83]
	v_mfma_f32_16x16x32_bf16 v[68:71], v[214:217], v[206:209], v[68:71]
	v_mfma_f32_16x16x32_bf16 v[64:67], v[222:225], v[206:209], v[64:67]
	v_mfma_f32_16x16x32_bf16 v[116:119], v[218:221], v[182:185], v[116:119]
	v_mfma_f32_16x16x32_bf16 v[112:115], v[226:229], v[182:185], v[112:115]
	v_mfma_f32_16x16x32_bf16 v[100:103], v[218:221], v[194:197], v[100:103]
	v_mfma_f32_16x16x32_bf16 v[96:99], v[226:229], v[194:197], v[96:99]
	v_mfma_f32_16x16x32_bf16 v[84:87], v[218:221], v[202:205], v[84:87]
	v_mfma_f32_16x16x32_bf16 v[80:83], v[226:229], v[202:205], v[80:83]
	v_mfma_f32_16x16x32_bf16 v[68:71], v[218:221], v[210:213], v[68:71]
	v_mfma_f32_16x16x32_bf16 v[64:67], v[226:229], v[210:213], v[64:67]
	s_barrier
; #define PG8_STAGE(bufoff, gbase, voff) do { _Pragma("unroll") for (int _i = 0; _i < 2; ++_i) \
;         __builtin_amdgcn_global_load_lds((const unsigned*)((const char*)(gbase) + (voff)[_i]), (PG8_LAS unsigned*)(lds + (bufoff) + ldsw + _i * 8192), 16, 0, 0); } while (0)
; #define PG8_LDA(dst, b, h) do { _Pragma("unroll") for (int m = 0; m < 4; ++m) _Pragma("unroll") for (int k = 0; k < 2; ++k) dst[m][k] = *(const PG8_LAS bf16x8*)(lds + PG8_SA(b, h) + aoff + m * 2048 + k * 1024); } while (0)
; #define PG8_LDB(dst, b, h) do { _Pragma("unroll") for (int n = 0; n < 2; ++n) _Pragma("unroll") for (int k = 0; k < 2; ++k) dst[n][k] = *(const PG8_LAS bf16x8*)(lds + PG8_SB(b, h) + boff + n * 2048 + k * 1024); } while (0)
; #define PG8_WAIT_V(n) asm volatile("s_waitcnt vmcnt(" #n ")" ::: "memory")
; #define PG8_WAIT_L(n) asm volatile("s_waitcnt lgkmcnt(" #n ")" ::: "memory")
; #define PG8_BAR __builtin_amdgcn_s_barrier()
; #define PG8_SCHED __builtin_amdgcn_sched_barrier(0)
; template <class Epi, class Sched>
; __device__ __forceinline__ void gemm_phase(PG8_LAS unsigned char* lds, const Gemm g, const Sched& S, const Epi& E) {
;     ...
;             PG8_LDB(B0, 0, 0); PG8_SCHED; PG8_LDA(At, 0, 0); PG8_STAGE(PG8_SA(1, 1), a1 + hstep, voffA);
;             PG8_WAIT_L(8); PG8_BAR; PG8_WAIT_L(0); PG8_MMA(0, 0, At, B0); PG8_BAR; PG8_SCHED;
;             PG8_LDB(B1, 0, 1); PG8_STAGE(PG8_SB(0, 0), b2, voffB);
;             PG8_BAR; PG8_WAIT_L(0); PG8_MMA(0, 1, At, B1); PG8_BAR;
;             PG8_LDA(At, 0, 1); PG8_STAGE(PG8_SA(0, 0), a2, voffA);
;             PG8_BAR; PG8_WAIT_L(0); PG8_MMA(1, 0, At, B0); PG8_BAR; PG8_SCHED;
;             PG8_STAGE(PG8_SB(0, 1), b2 + hstep, voffB);
;             PG8_WAIT_V(6); PG8_BAR; PG8_MMA(1, 1, At, B1); PG8_BAR;
;             PG8_LDB(B0, 1, 0); PG8_SCHED; PG8_LDA(At, 1, 0); PG8_STAGE(PG8_SA(0, 1), a2 + hstep, voffA);
;             PG8_WAIT_L(8); PG8_BAR; PG8_WAIT_L(0); PG8_MMA(0, 0, At, B0); PG8_BAR; PG8_SCHED;
;             PG8_LDB(B1, 1, 1); PG8_STAGE(PG8_SB(1, 0), b3, voffB);
;             PG8_BAR; PG8_WAIT_L(0); PG8_MMA(0, 1, At, B1); PG8_BAR;
;             PG8_LDA(At, 1, 1); PG8_STAGE(PG8_SA(1, 0), a3, voffA);
;             PG8_BAR; PG8_WAIT_L(0); PG8_MMA(1, 0, At, B0); PG8_BAR; PG8_SCHED;
;             PG8_STAGE(PG8_SB(1, 1), b3 + hstep, voffB);
;             PG8_WAIT_V(6); PG8_BAR; PG8_MMA(1, 1, At, B1); PG8_BAR;
	ds_read_b128 v[170:173], v153 offset:16384
	ds_read_b128 v[182:185], v153 offset:17408
	ds_read_b128 v[190:193], v153 offset:18432
	ds_read_b128 v[194:197], v153 offset:19456
	ds_read_b128 v[198:201], v153 offset:20480
	ds_read_b128 v[202:205], v153 offset:21504
	ds_read_b128 v[206:209], v153 offset:22528
	ds_read_b128 v[210:213], v153 offset:23552
	s_add_i32 s49, s42, s30
	s_add_u32 s98, s20, s6
	s_addc_u32 s99, s21, s7
	s_mov_b32 m0, s49
	s_nop 0
	global_load_lds_dwordx4 v130, s[20:21]
	s_nop 1
	s_add_i32 m0, s49, 0x2000
	s_nop 0
	global_load_lds_dwordx4 v134, s[20:21]
	s_nop 1
	s_mov_b32 m0, s17
	s_add_u32 s100, s22, s6
	s_addc_u32 s101, s23, s7
	global_load_lds_dwordx4 v128, s[22:23]
	s_nop 1
	s_mov_b32 m0, s31
	s_nop 0
	global_load_lds_dwordx4 v132, s[22:23]
	s_add_u32 s50, s20, 0x40000
	s_addc_u32 s51, s21, 0
	s_add_i32 s49, s43, s30
	s_mov_b32 m0, s49
	s_nop 0
	global_load_lds_dwordx4 v130, s[50:51]
	s_nop 1
	s_add_i32 m0, s49, 0x2000
	s_nop 0
	global_load_lds_dwordx4 v134, s[50:51]
	s_waitcnt vmcnt(8) lgkmcnt(0)
	s_barrier
	v_mfma_f32_16x16x32_bf16 v[60:63], v[144:147], v[170:173], v[60:63]
	v_mfma_f32_16x16x32_bf16 v[56:59], v[160:163], v[170:173], v[56:59]
	v_mfma_f32_16x16x32_bf16 v[44:47], v[144:147], v[190:193], v[44:47]
	v_mfma_f32_16x16x32_bf16 v[40:43], v[160:163], v[190:193], v[40:43]
	v_mfma_f32_16x16x32_bf16 v[28:31], v[144:147], v[198:201], v[28:31]
	v_mfma_f32_16x16x32_bf16 v[24:27], v[160:163], v[198:201], v[24:27]
	v_mfma_f32_16x16x32_bf16 v[12:15], v[144:147], v[206:209], v[12:15]
	v_mfma_f32_16x16x32_bf16 v[8:11], v[160:163], v[206:209], v[8:11]
	v_mfma_f32_16x16x32_bf16 v[60:63], v[156:159], v[182:185], v[60:63]
	v_mfma_f32_16x16x32_bf16 v[56:59], v[166:169], v[182:185], v[56:59]
	v_mfma_f32_16x16x32_bf16 v[44:47], v[156:159], v[194:197], v[44:47]
	v_mfma_f32_16x16x32_bf16 v[40:43], v[166:169], v[194:197], v[40:43]
	v_mfma_f32_16x16x32_bf16 v[28:31], v[156:159], v[202:205], v[28:31]
	v_mfma_f32_16x16x32_bf16 v[24:27], v[166:169], v[202:205], v[24:27]
	v_mfma_f32_16x16x32_bf16 v[12:15], v[156:159], v[210:213], v[12:15]
	v_mfma_f32_16x16x32_bf16 v[8:11], v[166:169], v[210:213], v[8:11]
	v_mfma_f32_16x16x32_bf16 v[52:55], v[214:217], v[170:173], v[52:55]
	v_mfma_f32_16x16x32_bf16 v[48:51], v[222:225], v[170:173], v[48:51]
	v_mfma_f32_16x16x32_bf16 v[36:39], v[214:217], v[190:193], v[36:39]
	v_mfma_f32_16x16x32_bf16 v[32:35], v[222:225], v[190:193], v[32:35]
	v_mfma_f32_16x16x32_bf16 v[20:23], v[214:217], v[198:201], v[20:23]
	v_mfma_f32_16x16x32_bf16 v[16:19], v[222:225], v[198:201], v[16:19]
	v_mfma_f32_16x16x32_bf16 v[4:7], v[214:217], v[206:209], v[4:7]
	v_mfma_f32_16x16x32_bf16 v[0:3], v[222:225], v[206:209], v[0:3]
	v_mfma_f32_16x16x32_bf16 v[52:55], v[218:221], v[182:185], v[52:55]
	v_mfma_f32_16x16x32_bf16 v[48:51], v[226:229], v[182:185], v[48:51]
	v_mfma_f32_16x16x32_bf16 v[36:39], v[218:221], v[194:197], v[36:39]
	v_mfma_f32_16x16x32_bf16 v[32:35], v[226:229], v[194:197], v[32:35]
	v_mfma_f32_16x16x32_bf16 v[20:23], v[218:221], v[202:205], v[20:23]
	v_mfma_f32_16x16x32_bf16 v[16:19], v[226:229], v[202:205], v[16:19]
	v_mfma_f32_16x16x32_bf16 v[4:7], v[218:221], v[210:213], v[4:7]
	v_mfma_f32_16x16x32_bf16 v[0:3], v[226:229], v[210:213], v[0:3]
	s_barrier
	s_add_i32 s49, 0, 0x18000
	v_add_u32_e32 v155, s49, v149
	ds_read_b128 v[144:147], v155
	ds_read_b128 v[156:159], v155 offset:1024
	ds_read_b128 v[160:163], v155 offset:2048
	ds_read_b128 v[166:169], v155 offset:3072
	ds_read_b128 v[170:173], v153 offset:32768
	ds_read_b128 v[182:185], v153 offset:33792
	ds_read_b128 v[190:193], v153 offset:34816
	ds_read_b128 v[194:197], v153 offset:35840
	ds_read_b128 v[198:201], v153 offset:36864
	ds_read_b128 v[202:205], v153 offset:37888
	ds_read_b128 v[206:209], v153 offset:38912
	ds_read_b128 v[210:213], v153 offset:39936
	v_add_u32_e32 v155, 0x1c000, v149
	s_waitcnt lgkmcnt(8)
	ds_read_b128 v[214:217], v155
	ds_read_b128 v[218:221], v155 offset:1024
	ds_read_b128 v[222:225], v155 offset:2048
	ds_read_b128 v[226:229], v155 offset:3072
	s_add_u32 s22, s22, 0x40000
	s_addc_u32 s23, s23, 0
	s_mov_b32 m0, s34
	s_nop 0
	global_load_lds_dwordx4 v128, s[22:23]
	s_nop 1
	s_mov_b32 m0, s35
	s_nop 0
	global_load_lds_dwordx4 v132, s[22:23]
	s_add_i32 s22, 0, 0x1c000
	s_waitcnt vmcnt(8) lgkmcnt(0)
	s_barrier
	v_mfma_f32_16x16x32_bf16 v[124:127], v[144:147], v[170:173], v[124:127]
	v_mfma_f32_16x16x32_bf16 v[120:123], v[160:163], v[170:173], v[120:123]
	v_mfma_f32_16x16x32_bf16 v[108:111], v[144:147], v[190:193], v[108:111]
	v_mfma_f32_16x16x32_bf16 v[104:107], v[160:163], v[190:193], v[104:107]
	v_mfma_f32_16x16x32_bf16 v[92:95], v[144:147], v[198:201], v[92:95]
	v_mfma_f32_16x16x32_bf16 v[88:91], v[160:163], v[198:201], v[88:91]
	v_mfma_f32_16x16x32_bf16 v[76:79], v[144:147], v[206:209], v[76:79]
	v_mfma_f32_16x16x32_bf16 v[72:75], v[160:163], v[206:209], v[72:75]
	v_mfma_f32_16x16x32_bf16 v[124:127], v[156:159], v[182:185], v[124:127]
	v_mfma_f32_16x16x32_bf16 v[120:123], v[166:169], v[182:185], v[120:123]
	v_mfma_f32_16x16x32_bf16 v[108:111], v[156:159], v[194:197], v[108:111]
	v_mfma_f32_16x16x32_bf16 v[104:107], v[166:169], v[194:197], v[104:107]
	v_mfma_f32_16x16x32_bf16 v[92:95], v[156:159], v[202:205], v[92:95]
	v_mfma_f32_16x16x32_bf16 v[88:91], v[166:169], v[202:205], v[88:91]
	v_mfma_f32_16x16x32_bf16 v[76:79], v[156:159], v[210:213], v[76:79]
	v_mfma_f32_16x16x32_bf16 v[72:75], v[166:169], v[210:213], v[72:75]
	v_mfma_f32_16x16x32_bf16 v[116:119], v[214:217], v[170:173], v[116:119]
	v_mfma_f32_16x16x32_bf16 v[112:115], v[222:225], v[170:173], v[112:115]
	v_mfma_f32_16x16x32_bf16 v[100:103], v[214:217], v[190:193], v[100:103]
	v_mfma_f32_16x16x32_bf16 v[96:99], v[222:225], v[190:193], v[96:99]
	v_mfma_f32_16x16x32_bf16 v[84:87], v[214:217], v[198:201], v[84:87]
	v_mfma_f32_16x16x32_bf16 v[80:83], v[222:225], v[198:201], v[80:83]
	v_mfma_f32_16x16x32_bf16 v[68:71], v[214:217], v[206:209], v[68:71]
	v_mfma_f32_16x16x32_bf16 v[64:67], v[222:225], v[206:209], v[64:67]
	v_mfma_f32_16x16x32_bf16 v[116:119], v[218:221], v[182:185], v[116:119]
	v_mfma_f32_16x16x32_bf16 v[112:115], v[226:229], v[182:185], v[112:115]
	v_mfma_f32_16x16x32_bf16 v[100:103], v[218:221], v[194:197], v[100:103]
	v_mfma_f32_16x16x32_bf16 v[96:99], v[226:229], v[194:197], v[96:99]
	v_mfma_f32_16x16x32_bf16 v[84:87], v[218:221], v[202:205], v[84:87]
	v_mfma_f32_16x16x32_bf16 v[80:83], v[226:229], v[202:205], v[80:83]
	v_mfma_f32_16x16x32_bf16 v[68:71], v[218:221], v[210:213], v[68:71]
	v_mfma_f32_16x16x32_bf16 v[64:67], v[226:229], v[210:213], v[64:67]
	s_barrier
; #define PG8_STAGE(bufoff, gbase, voff) do { _Pragma("unroll") for (int _i = 0; _i < 2; ++_i) \
;         __builtin_amdgcn_global_load_lds((const unsigned*)((const char*)(gbase) + (voff)[_i]), (PG8_LAS unsigned*)(lds + (bufoff) + ldsw + _i * 8192), 16, 0, 0); } while (0)
; #define PG8_LDA(dst, b, h) do { _Pragma("unroll") for (int m = 0; m < 4; ++m) _Pragma("unroll") for (int k = 0; k < 2; ++k) dst[m][k] = *(const PG8_LAS bf16x8*)(lds + PG8_SA(b, h) + aoff + m * 2048 + k * 1024); } while (0)
; #define PG8_MMA(ai, bj, At, Bt) do { __builtin_amdgcn_s_setprio(1); _Pragma("unroll") for (int m = 0; m < 4; ++m) _Pragma("unroll") for (int n = 0; n < 2; ++n) _Pragma("unroll") for (int k = 0; k < 2; ++k) \
;         acc[ai][bj][m][n] = __builtin_amdgcn_mfma_f32_16x16x32_bf16(Bt[n][k], At[m][k], acc[ai][bj][m][n], 0, 0, 0); __builtin_amdgcn_s_setprio(0); } while (0)
; #define PG8_WAIT_V(n) asm volatile("s_waitcnt vmcnt(" #n ")" ::: "memory")
; #define PG8_WAIT_L(n) asm volatile("s_waitcnt lgkmcnt(" #n ")" ::: "memory")
; #define PG8_BAR __builtin_amdgcn_s_barrier()
; #define PG8_SCHED __builtin_amdgcn_sched_barrier(0)
; __device__ __forceinline__ f32x4 sigmoid4(f32x4 x) {
;     f32x4 d;
; #pragma unroll
;     for (int j = 0; j < 4; ++j) d[j] = 1.0f + __expf(-fmaxf(x[j], -20.0f));
;     const float p01 = d[0] * d[1], p23 = d[2] * d[3], r = __builtin_amdgcn_rcpf(p01 * p23), r01 = r * p23, r23 = r * p01;
;     return (f32x4){r01 * d[1], r01 * d[0], r23 * d[3], r23 * d[2]};
; }
; template <class Epi, class Sched>
; __device__ __forceinline__ void gemm_phase(PG8_LAS unsigned char* lds, const Gemm g, const Sched& S, const Epi& E) {
;     ...
;             PG8_LDA(At, 1, 1); PG8_STAGE(PG8_SA(1, 0), a3, voffA);
;             PG8_BAR; PG8_WAIT_L(0); PG8_MMA(1, 0, At, B0); PG8_BAR; PG8_SCHED;
;             PG8_STAGE(PG8_SB(1, 1), b3 + hstep, voffB);
;             PG8_WAIT_V(6); PG8_BAR; PG8_MMA(1, 1, At, B1); PG8_BAR;
;         }
;         if constexpr (!Epi::AFTER_DRAIN) { E(acc, cur, wr, wc, fr, fq); S.done(cur); }
	ds_read_b128 v[170:173], v153 offset:49152
	ds_read_b128 v[182:185], v153 offset:50176
	ds_read_b128 v[190:193], v153 offset:51200
	ds_read_b128 v[194:197], v153 offset:52224
	ds_read_b128 v[198:201], v153 offset:53248
	ds_read_b128 v[202:205], v153 offset:54272
	ds_read_b128 v[206:209], v153 offset:55296
	ds_read_b128 v[210:213], v153 offset:56320
	s_add_i32 s23, s49, s30
	s_mov_b32 m0, s23
	s_nop 0
	global_load_lds_dwordx4 v130, s[98:99]
	s_nop 1
	s_add_i32 m0, s23, 0x2000
	s_nop 0
	global_load_lds_dwordx4 v134, s[98:99]
	s_nop 1
	s_mov_b32 m0, s37
	s_nop 0
	global_load_lds_dwordx4 v128, s[100:101]
	s_nop 1
	s_mov_b32 m0, s38
	s_nop 0
	global_load_lds_dwordx4 v132, s[100:101]
	s_add_u32 s20, s20, 0x40080
	s_addc_u32 s21, s21, 0
	s_add_i32 s22, s22, s30
	s_mov_b32 m0, s22
	s_nop 0
	global_load_lds_dwordx4 v130, s[20:21]
	s_nop 1
	s_add_i32 m0, s22, 0x2000
	s_nop 0
	global_load_lds_dwordx4 v134, s[20:21]
	s_waitcnt vmcnt(8) lgkmcnt(0)
	s_barrier
	v_mfma_f32_16x16x32_bf16 v[60:63], v[144:147], v[170:173], v[60:63]
	v_mfma_f32_16x16x32_bf16 v[56:59], v[160:163], v[170:173], v[56:59]
	v_mfma_f32_16x16x32_bf16 v[44:47], v[144:147], v[190:193], v[44:47]
	v_mfma_f32_16x16x32_bf16 v[40:43], v[160:163], v[190:193], v[40:43]
	v_mfma_f32_16x16x32_bf16 v[28:31], v[144:147], v[198:201], v[28:31]
	v_mfma_f32_16x16x32_bf16 v[24:27], v[160:163], v[198:201], v[24:27]
	v_mfma_f32_16x16x32_bf16 v[12:15], v[144:147], v[206:209], v[12:15]
	v_mfma_f32_16x16x32_bf16 v[8:11], v[160:163], v[206:209], v[8:11]
	v_mfma_f32_16x16x32_bf16 v[60:63], v[156:159], v[182:185], v[60:63]
	v_mfma_f32_16x16x32_bf16 v[56:59], v[166:169], v[182:185], v[56:59]
	v_mfma_f32_16x16x32_bf16 v[44:47], v[156:159], v[194:197], v[44:47]
	v_mfma_f32_16x16x32_bf16 v[40:43], v[166:169], v[194:197], v[40:43]
	v_mfma_f32_16x16x32_bf16 v[28:31], v[156:159], v[202:205], v[28:31]
	v_mfma_f32_16x16x32_bf16 v[24:27], v[166:169], v[202:205], v[24:27]
	v_mfma_f32_16x16x32_bf16 v[12:15], v[156:159], v[210:213], v[12:15]
	v_mfma_f32_16x16x32_bf16 v[8:11], v[166:169], v[210:213], v[8:11]
	v_mfma_f32_16x16x32_bf16 v[52:55], v[214:217], v[170:173], v[52:55]
	v_mfma_f32_16x16x32_bf16 v[48:51], v[222:225], v[170:173], v[48:51]
	v_mfma_f32_16x16x32_bf16 v[36:39], v[214:217], v[190:193], v[36:39]
	v_mfma_f32_16x16x32_bf16 v[32:35], v[222:225], v[190:193], v[32:35]
	v_mfma_f32_16x16x32_bf16 v[20:23], v[214:217], v[198:201], v[20:23]
	v_mfma_f32_16x16x32_bf16 v[16:19], v[222:225], v[198:201], v[16:19]
	v_mfma_f32_16x16x32_bf16 v[4:7], v[214:217], v[206:209], v[4:7]
	v_mfma_f32_16x16x32_bf16 v[0:3], v[222:225], v[206:209], v[0:3]
	v_mfma_f32_16x16x32_bf16 v[52:55], v[218:221], v[182:185], v[52:55]
	v_mfma_f32_16x16x32_bf16 v[48:51], v[226:229], v[182:185], v[48:51]
	v_mfma_f32_16x16x32_bf16 v[36:39], v[218:221], v[194:197], v[36:39]
	v_mfma_f32_16x16x32_bf16 v[32:35], v[226:229], v[194:197], v[32:35]
	v_mfma_f32_16x16x32_bf16 v[20:23], v[218:221], v[202:205], v[20:23]
	v_mfma_f32_16x16x32_bf16 v[16:19], v[226:229], v[202:205], v[16:19]
	v_mfma_f32_16x16x32_bf16 v[4:7], v[218:221], v[210:213], v[4:7]
	v_mfma_f32_16x16x32_bf16 v[0:3], v[226:229], v[210:213], v[0:3]
	s_barrier
	s_add_i32 s48, s48, 2
	s_add_u32 s18, s18, 0x100
	s_addc_u32 s19, s19, 0
	s_add_u32 s46, s46, 0x100
	s_addc_u32 s47, s47, 0
	s_cmp_gt_u32 s48, 13
	s_cbranch_scc0 .LBB0_724
	s_cmp_gt_i32 s4, 5
	s_cselect_b64 s[18:19], -1, 0
	s_cmp_lt_i32 s4, 6
	v_pk_add_f32 v[144:145], v[126:127], 0 op_sel_hi:[1,0]
	v_pk_add_f32 v[146:147], v[124:125], 0 op_sel_hi:[1,0]
	v_pk_add_f32 v[124:125], v[122:123], 0 op_sel_hi:[1,0]
	v_pk_add_f32 v[126:127], v[120:121], 0 op_sel_hi:[1,0]
	s_cbranch_scc1 .LBB0_727
	v_max_f32_e32 v122, 0xc1a00000, v144
	v_mul_f32_e32 v122, 0xbfb8aa3b, v122
	v_exp_f32_e32 v123, v122
	v_max_f32_e32 v120, 0xc1a00000, v146
	v_max_f32_e32 v121, 0xc1a00000, v147
	v_max_f32_e32 v122, 0xc1a00000, v145
	v_mul_f32_e32 v120, 0xbfb8aa3b, v120
	v_mul_f32_e32 v121, 0xbfb8aa3b, v121
	v_mul_f32_e32 v122, 0xbfb8aa3b, v122
	v_exp_f32_e32 v120, v120
	v_exp_f32_e32 v121, v121
	v_exp_f32_e32 v122, v122
	v_max_f32_e32 v124, 0xc1a00000, v124
	v_pk_add_f32 v[120:121], v[120:121], 1.0 op_sel_hi:[1,0]
	v_pk_add_f32 v[122:123], v[122:123], 1.0 op_sel_hi:[1,0]
	v_mov_b32_e32 v144, v120
	v_mov_b32_e32 v145, v123
	v_pk_mov_b32 v[146:147], v[120:121], v[122:123] op_sel:[1,0]
	v_mul_f32_e32 v124, 0xbfb8aa3b, v124
	v_pk_mul_f32 v[144:145], v[144:145], v[146:147]
	v_exp_f32_e32 v147, v124
	v_max_f32_e32 v126, 0xc1a00000, v126
	v_max_f32_e32 v127, 0xc1a00000, v127
	v_max_f32_e32 v124, 0xc1a00000, v125
	v_mul_f32_e32 v146, v144, v145
	v_mul_f32_e32 v126, 0xbfb8aa3b, v126
	v_mul_f32_e32 v127, 0xbfb8aa3b, v127
	v_mul_f32_e32 v124, 0xbfb8aa3b, v124
	v_rcp_f32_e32 v155, v146
	v_exp_f32_e32 v126, v126
	v_exp_f32_e32 v127, v127
	v_exp_f32_e32 v146, v124
	v_mul_f32_e32 v124, v145, v155
	v_mul_f32_e32 v144, v144, v155
	v_pk_add_f32 v[126:127], v[126:127], 1.0 op_sel_hi:[1,0]
	v_pk_add_f32 v[156:157], v[146:147], 1.0 op_sel_hi:[1,0]
	v_mov_b32_e32 v146, v126
	v_mov_b32_e32 v147, v157
	v_pk_mov_b32 v[158:159], v[126:127], v[156:157] op_sel:[1,0]
	v_pk_mul_f32 v[144:145], v[122:123], v[144:145] op_sel_hi:[1,0]
	v_pk_mul_f32 v[158:159], v[146:147], v[158:159]
	s_nop 0
	v_mul_f32_e32 v125, v158, v159
	v_rcp_f32_e32 v125, v125
	s_nop 0
	v_pk_mul_f32 v[146:147], v[120:121], v[124:125] op_sel:[1,0] op_sel_hi:[0,0]
	v_mul_f32_e32 v120, v159, v125
	v_mul_f32_e32 v122, v158, v125
	v_pk_mul_f32 v[124:125], v[156:157], v[122:123] op_sel_hi:[1,0]
	v_pk_mul_f32 v[126:127], v[126:127], v[120:121] op_sel:[1,0] op_sel_hi:[0,0]

; #define PG8_STAGE(bufoff, gbase, voff) do { _Pragma("unroll") for (int _i = 0; _i < 2; ++_i) \
;         __builtin_amdgcn_global_load_lds((const unsigned*)((const char*)(gbase) + (voff)[_i]), (PG8_LAS unsigned*)(lds + (bufoff) + ldsw + _i * 8192), 16, 0, 0); } while (0)
; #define PG8_LDA(dst, b, h) do { _Pragma("unroll") for (int m = 0; m < 4; ++m) _Pragma("unroll") for (int k = 0; k < 2; ++k) dst[m][k] = *(const PG8_LAS bf16x8*)(lds + PG8_SA(b, h) + aoff + m * 2048 + k * 1024); } while (0)
; #define PG8_LDB(dst, b, h) do { _Pragma("unroll") for (int n = 0; n < 2; ++n) _Pragma("unroll") for (int k = 0; k < 2; ++k) dst[n][k] = *(const PG8_LAS bf16x8*)(lds + PG8_SB(b, h) + boff + n * 2048 + k * 1024); } while (0)
; #define PG8_BAR __builtin_amdgcn_s_barrier()
; template <class Epi, class Sched>
; __device__ __forceinline__ void gemm_phase(PG8_LAS unsigned char* lds, const Gemm g, const Sched& S, const Epi& E) {
;     ...
;         const bool has_next = S.next(ui + 1, nxt);
;         const char* nA = has_next ? (const char*)g.A + (size_t)nxt.pm * tstep : cA; const char* nB = has_next ? (const char*)g.Bt + (size_t)nxt.pn * tstep : cB;
;         for (int t = 0; t < nt; t += 2) {
;             const bool last = (t == nt - 2);
;             const char* a1 = cA + (size_t)(t + 1) * kstep;
;             const char* a2 = last ? nA : cA + (size_t)(t + 2) * kstep; const char* b2 = last ? nB : cB + (size_t)(t + 2) * kstep;
;             const char* a3 = a2 + kstep; const char* b3 = b2 + kstep;
;             if (last && has_next) S.a_ready(nxt);
;             PG8_LDB(B0, 0, 0); PG8_SCHED; PG8_LDA(At, 0, 0); PG8_STAGE(PG8_SA(1, 1), a1 + hstep, voffA);
;             PG8_WAIT_L(8); PG8_BAR; PG8_WAIT_L(0); PG8_MMA(0, 0, At, B0); PG8_BAR; PG8_SCHED;
;             PG8_LDB(B1, 0, 1); PG8_STAGE(PG8_SB(0, 0), b2, voffB);
;             PG8_BAR; PG8_WAIT_L(0); PG8_MMA(0, 1, At, B1); PG8_BAR;
;             PG8_LDA(At, 0, 1); PG8_STAGE(PG8_SA(0, 0), a2, voffA);
;             PG8_BAR; PG8_WAIT_L(0); PG8_MMA(1, 0, At, B0); PG8_BAR; PG8_SCHED;
;             PG8_STAGE(PG8_SB(0, 1), b2 + hstep, voffB);
;             PG8_WAIT_V(6); PG8_BAR; PG8_MMA(1, 1, At, B1); PG8_BAR;
;             PG8_LDB(B0, 1, 0); PG8_SCHED; PG8_LDA(At, 1, 0); PG8_STAGE(PG8_SA(0, 1), a2 + hstep, voffA);
;             PG8_WAIT_L(8); PG8_BAR; PG8_WAIT_L(0); PG8_MMA(0, 0, At, B0); PG8_BAR; PG8_SCHED;
.LBB0_990:
	s_ashr_i32 s11, s10, 31
	v_cmp_lt_i64_e32 vcc, s[12:13], v[140:141]
	s_lshl_b64 s[12:13], s[10:11], 19
	s_add_u32 s12, s27, s12
	s_addc_u32 s13, s28, s13
	s_and_b64 s[14:15], vcc, exec
	s_cselect_b32 s11, s13, s19
	s_cselect_b32 s43, s12, s18
	s_ashr_i32 s9, s8, 31
	s_lshl_b64 s[14:15], s[8:9], 19
	s_add_u32 s14, s96, s14
	s_addc_u32 s15, s97, s15
	s_and_b64 s[22:23], vcc, exec
	s_cselect_b32 s9, s15, s21
	s_cselect_b32 s44, s14, s20
	s_add_u32 s18, s18, 0x40080
	s_addc_u32 s19, s19, 0
	s_add_u32 s45, s20, 0x100
	s_addc_u32 s46, s21, 0
	s_mov_b32 s47, -2
	ds_read_b128 v[144:147], v153
	ds_read_b128 v[156:159], v153 offset:1024
	ds_read_b128 v[160:163], v153 offset:2048
	ds_read_b128 v[164:167], v153 offset:3072
	s_add_u32 s20, s18, 0xfffc0080
	s_addc_u32 s21, s19, -1
	s_cmp_eq_u32 s47, 12
	s_cselect_b32 s23, s11, s21
	s_cselect_b32 s22, s43, s20
	s_cselect_b32 s21, s9, s46
	s_cselect_b32 s20, s44, s45
	ds_read_b128 v[168:171], v154
	ds_read_b128 v[172:175], v154 offset:1024
	ds_read_b128 v[182:185], v154 offset:2048
	ds_read_b128 v[190:193], v154 offset:3072
	ds_read_b128 v[194:197], v154 offset:4096
	ds_read_b128 v[198:201], v154 offset:5120
	ds_read_b128 v[202:205], v154 offset:6144
	ds_read_b128 v[206:209], v154 offset:7168
	s_waitcnt lgkmcnt(8)
	ds_read_b128 v[210:213], v155
	ds_read_b128 v[214:217], v155 offset:1024
	ds_read_b128 v[218:221], v155 offset:2048
	ds_read_b128 v[222:225], v155 offset:3072
	s_add_i32 m0, s17, 0xc000
	s_nop 0
	global_load_lds_dwordx4 v136, s[18:19]
	s_nop 1
	s_add_i32 m0, s17, 0xe000
	s_nop 0
	global_load_lds_dwordx4 v138, s[18:19]
	s_waitcnt vmcnt(8) lgkmcnt(0)
	s_barrier
	v_mfma_f32_16x16x32_bf16 v[124:127], v[144:147], v[168:171], 0
	v_mfma_f32_16x16x32_bf16 v[120:123], v[160:163], v[168:171], 0
	v_mfma_f32_16x16x32_bf16 v[112:115], v[144:147], v[182:185], 0
	v_mfma_f32_16x16x32_bf16 v[104:107], v[160:163], v[182:185], 0
	v_mfma_f32_16x16x32_bf16 v[96:99], v[144:147], v[194:197], 0
	v_mfma_f32_16x16x32_bf16 v[88:91], v[160:163], v[194:197], 0
	v_mfma_f32_16x16x32_bf16 v[80:83], v[144:147], v[202:205], 0
	v_mfma_f32_16x16x32_bf16 v[72:75], v[160:163], v[202:205], 0
	v_mfma_f32_16x16x32_bf16 v[124:127], v[156:159], v[172:175], v[124:127]
	v_mfma_f32_16x16x32_bf16 v[120:123], v[164:167], v[172:175], v[120:123]
	v_mfma_f32_16x16x32_bf16 v[112:115], v[156:159], v[190:193], v[112:115]
	v_mfma_f32_16x16x32_bf16 v[104:107], v[164:167], v[190:193], v[104:107]
	v_mfma_f32_16x16x32_bf16 v[96:99], v[156:159], v[198:201], v[96:99]
	v_mfma_f32_16x16x32_bf16 v[88:91], v[164:167], v[198:201], v[88:91]
	v_mfma_f32_16x16x32_bf16 v[80:83], v[156:159], v[206:209], v[80:83]
	v_mfma_f32_16x16x32_bf16 v[72:75], v[164:167], v[206:209], v[72:75]
	v_mfma_f32_16x16x32_bf16 v[116:119], v[210:213], v[168:171], 0
	v_mfma_f32_16x16x32_bf16 v[108:111], v[218:221], v[168:171], 0
	v_mfma_f32_16x16x32_bf16 v[100:103], v[210:213], v[182:185], 0
	v_mfma_f32_16x16x32_bf16 v[92:95], v[218:221], v[182:185], 0
	v_mfma_f32_16x16x32_bf16 v[84:87], v[210:213], v[194:197], 0
	v_mfma_f32_16x16x32_bf16 v[76:79], v[218:221], v[194:197], 0
	v_mfma_f32_16x16x32_bf16 v[68:71], v[210:213], v[202:205], 0
	v_mfma_f32_16x16x32_bf16 v[64:67], v[218:221], v[202:205], 0
	v_mfma_f32_16x16x32_bf16 v[116:119], v[214:217], v[172:175], v[116:119]
	v_mfma_f32_16x16x32_bf16 v[108:111], v[222:225], v[172:175], v[108:111]
	v_mfma_f32_16x16x32_bf16 v[100:103], v[214:217], v[190:193], v[100:103]
	v_mfma_f32_16x16x32_bf16 v[92:95], v[222:225], v[190:193], v[92:95]
	v_mfma_f32_16x16x32_bf16 v[84:87], v[214:217], v[198:201], v[84:87]
	v_mfma_f32_16x16x32_bf16 v[76:79], v[222:225], v[198:201], v[76:79]
	v_mfma_f32_16x16x32_bf16 v[68:71], v[214:217], v[206:209], v[68:71]
	v_mfma_f32_16x16x32_bf16 v[64:67], v[222:225], v[206:209], v[64:67]
	s_barrier
	ds_read_b128 v[168:171], v154 offset:16384
	ds_read_b128 v[172:175], v154 offset:17408
	ds_read_b128 v[182:185], v154 offset:18432
	ds_read_b128 v[190:193], v154 offset:19456
	ds_read_b128 v[194:197], v154 offset:20480
	ds_read_b128 v[198:201], v154 offset:21504
	ds_read_b128 v[202:205], v154 offset:22528
	ds_read_b128 v[206:209], v154 offset:23552
	s_add_i32 s48, s39, s29
	s_add_u32 s98, s20, s6
	s_addc_u32 s99, s21, s7
	s_mov_b32 m0, s48
	s_nop 0
	global_load_lds_dwordx4 v130, s[20:21]
	s_nop 1
	s_add_i32 m0, s48, 0x2000
	s_nop 0
	global_load_lds_dwordx4 v134, s[20:21]
	s_nop 1
	s_mov_b32 m0, s17
	s_add_u32 s100, s22, s6
	s_addc_u32 s101, s23, s7
	global_load_lds_dwordx4 v128, s[22:23]
	s_nop 1
	s_mov_b32 m0, s30
	s_nop 0
	global_load_lds_dwordx4 v132, s[22:23]
	s_add_u32 s48, s20, 0x40000
	s_addc_u32 s49, s21, 0
	s_add_i32 s50, s40, s29
	s_mov_b32 m0, s50
	s_nop 0
	global_load_lds_dwordx4 v130, s[48:49]
	s_nop 1
	s_add_i32 m0, s50, 0x2000
	s_nop 0
	global_load_lds_dwordx4 v134, s[48:49]
	s_waitcnt vmcnt(8) lgkmcnt(0)
	s_barrier
; #define PG8_STAGE(bufoff, gbase, voff) do { _Pragma("unroll") for (int _i = 0; _i < 2; ++_i) \
;         __builtin_amdgcn_global_load_lds((const unsigned*)((const char*)(gbase) + (voff)[_i]), (PG8_LAS unsigned*)(lds + (bufoff) + ldsw + _i * 8192), 16, 0, 0); } while (0)
; #define PG8_LDA(dst, b, h) do { _Pragma("unroll") for (int m = 0; m < 4; ++m) _Pragma("unroll") for (int k = 0; k < 2; ++k) dst[m][k] = *(const PG8_LAS bf16x8*)(lds + PG8_SA(b, h) + aoff + m * 2048 + k * 1024); } while (0)
; #define PG8_LDB(dst, b, h) do { _Pragma("unroll") for (int n = 0; n < 2; ++n) _Pragma("unroll") for (int k = 0; k < 2; ++k) dst[n][k] = *(const PG8_LAS bf16x8*)(lds + PG8_SB(b, h) + boff + n * 2048 + k * 1024); } while (0)
; #define PG8_MMA(ai, bj, At, Bt) do { __builtin_amdgcn_s_setprio(1); _Pragma("unroll") for (int m = 0; m < 4; ++m) _Pragma("unroll") for (int n = 0; n < 2; ++n) _Pragma("unroll") for (int k = 0; k < 2; ++k) \
;         acc[ai][bj][m][n] = __builtin_amdgcn_mfma_f32_16x16x32_bf16(Bt[n][k], At[m][k], acc[ai][bj][m][n], 0, 0, 0); __builtin_amdgcn_s_setprio(0); } while (0)
; #define PG8_WAIT_V(n) asm volatile("s_waitcnt vmcnt(" #n ")" ::: "memory")
; #define PG8_WAIT_L(n) asm volatile("s_waitcnt lgkmcnt(" #n ")" ::: "memory")
; #define PG8_BAR __builtin_amdgcn_s_barrier()
; #define PG8_SCHED __builtin_amdgcn_sched_barrier(0)
; template <class Epi, class Sched>
; __device__ __forceinline__ void gemm_phase(PG8_LAS unsigned char* lds, const Gemm g, const Sched& S, const Epi& E) {
;     ...
;             PG8_BAR; PG8_WAIT_L(0); PG8_MMA(1, 0, At, B0); PG8_BAR; PG8_SCHED;
;             PG8_STAGE(PG8_SB(0, 1), b2 + hstep, voffB);
;             PG8_WAIT_V(6); PG8_BAR; PG8_MMA(1, 1, At, B1); PG8_BAR;
;             PG8_LDB(B0, 1, 0); PG8_SCHED; PG8_LDA(At, 1, 0); PG8_STAGE(PG8_SA(0, 1), a2 + hstep, voffA);
;             PG8_WAIT_L(8); PG8_BAR; PG8_WAIT_L(0); PG8_MMA(0, 0, At, B0); PG8_BAR; PG8_SCHED;
;             PG8_LDB(B1, 1, 1); PG8_STAGE(PG8_SB(1, 0), b3, voffB);
;             PG8_BAR; PG8_WAIT_L(0); PG8_MMA(0, 1, At, B1); PG8_BAR;
;             PG8_LDA(At, 1, 1); PG8_STAGE(PG8_SA(1, 0), a3, voffA);
;             PG8_BAR; PG8_WAIT_L(0); PG8_MMA(1, 0, At, B0); PG8_BAR; PG8_SCHED;
	v_mfma_f32_16x16x32_bf16 v[60:63], v[144:147], v[168:171], 0
	v_mfma_f32_16x16x32_bf16 v[56:59], v[160:163], v[168:171], 0
	v_mfma_f32_16x16x32_bf16 v[48:51], v[144:147], v[182:185], 0
	v_mfma_f32_16x16x32_bf16 v[40:43], v[160:163], v[182:185], 0
	v_mfma_f32_16x16x32_bf16 v[32:35], v[144:147], v[194:197], 0
	v_mfma_f32_16x16x32_bf16 v[24:27], v[160:163], v[194:197], 0
	v_mfma_f32_16x16x32_bf16 v[16:19], v[144:147], v[202:205], 0
	v_mfma_f32_16x16x32_bf16 v[8:11], v[160:163], v[202:205], 0
	v_mfma_f32_16x16x32_bf16 v[60:63], v[156:159], v[172:175], v[60:63]
	v_mfma_f32_16x16x32_bf16 v[56:59], v[164:167], v[172:175], v[56:59]
	v_mfma_f32_16x16x32_bf16 v[48:51], v[156:159], v[190:193], v[48:51]
	v_mfma_f32_16x16x32_bf16 v[40:43], v[164:167], v[190:193], v[40:43]
	v_mfma_f32_16x16x32_bf16 v[32:35], v[156:159], v[198:201], v[32:35]
	v_mfma_f32_16x16x32_bf16 v[24:27], v[164:167], v[198:201], v[24:27]
	v_mfma_f32_16x16x32_bf16 v[16:19], v[156:159], v[206:209], v[16:19]
	v_mfma_f32_16x16x32_bf16 v[8:11], v[164:167], v[206:209], v[8:11]
	v_mfma_f32_16x16x32_bf16 v[52:55], v[210:213], v[168:171], 0
	v_mfma_f32_16x16x32_bf16 v[44:47], v[218:221], v[168:171], 0
	v_mfma_f32_16x16x32_bf16 v[36:39], v[210:213], v[182:185], 0
	v_mfma_f32_16x16x32_bf16 v[28:31], v[218:221], v[182:185], 0
	v_mfma_f32_16x16x32_bf16 v[20:23], v[210:213], v[194:197], 0
	v_mfma_f32_16x16x32_bf16 v[12:15], v[218:221], v[194:197], 0
	v_mfma_f32_16x16x32_bf16 v[4:7], v[210:213], v[202:205], 0
	v_mfma_f32_16x16x32_bf16 v[0:3], v[218:221], v[202:205], 0
	v_mfma_f32_16x16x32_bf16 v[52:55], v[214:217], v[172:175], v[52:55]
	v_mfma_f32_16x16x32_bf16 v[44:47], v[222:225], v[172:175], v[44:47]
	v_mfma_f32_16x16x32_bf16 v[36:39], v[214:217], v[190:193], v[36:39]
	v_mfma_f32_16x16x32_bf16 v[28:31], v[222:225], v[190:193], v[28:31]
	v_mfma_f32_16x16x32_bf16 v[20:23], v[214:217], v[198:201], v[20:23]
	v_mfma_f32_16x16x32_bf16 v[12:15], v[222:225], v[198:201], v[12:15]
	v_mfma_f32_16x16x32_bf16 v[4:7], v[214:217], v[206:209], v[4:7]
	v_mfma_f32_16x16x32_bf16 v[0:3], v[222:225], v[206:209], v[0:3]
	s_barrier
	s_add_i32 s48, 0, 0x18000
	v_add_u32_e32 v164, s48, v151
	ds_read_b128 v[144:147], v164
	ds_read_b128 v[156:159], v164 offset:1024
	ds_read_b128 v[160:163], v164 offset:2048
	ds_read_b128 v[164:167], v164 offset:3072
	ds_read_b128 v[168:171], v154 offset:32768
	ds_read_b128 v[172:175], v154 offset:33792
	ds_read_b128 v[182:185], v154 offset:34816
	ds_read_b128 v[190:193], v154 offset:35840
	ds_read_b128 v[194:197], v154 offset:36864
	ds_read_b128 v[198:201], v154 offset:37888
	ds_read_b128 v[202:205], v154 offset:38912
	ds_read_b128 v[206:209], v154 offset:39936
	v_add_u32_e32 v179, 0x1c000, v151
	s_waitcnt lgkmcnt(8)
	ds_read_b128 v[210:213], v179
	ds_read_b128 v[214:217], v179 offset:1024
	ds_read_b128 v[218:221], v179 offset:2048
	ds_read_b128 v[222:225], v179 offset:3072
	s_add_u32 s22, s22, 0x40000
	s_addc_u32 s23, s23, 0
	s_mov_b32 m0, s31
	s_nop 0
	global_load_lds_dwordx4 v128, s[22:23]
	s_nop 1
	s_mov_b32 m0, s34
	s_nop 0
	global_load_lds_dwordx4 v132, s[22:23]
	s_add_i32 s22, 0, 0x1c000
	s_waitcnt vmcnt(8) lgkmcnt(0)
	s_barrier
	v_mfma_f32_16x16x32_bf16 v[124:127], v[144:147], v[168:171], v[124:127]
	v_mfma_f32_16x16x32_bf16 v[120:123], v[160:163], v[168:171], v[120:123]
	v_mfma_f32_16x16x32_bf16 v[112:115], v[144:147], v[182:185], v[112:115]
	v_mfma_f32_16x16x32_bf16 v[104:107], v[160:163], v[182:185], v[104:107]
	v_mfma_f32_16x16x32_bf16 v[96:99], v[144:147], v[194:197], v[96:99]
	v_mfma_f32_16x16x32_bf16 v[88:91], v[160:163], v[194:197], v[88:91]
	v_mfma_f32_16x16x32_bf16 v[80:83], v[144:147], v[202:205], v[80:83]
	v_mfma_f32_16x16x32_bf16 v[72:75], v[160:163], v[202:205], v[72:75]
	v_mfma_f32_16x16x32_bf16 v[124:127], v[156:159], v[172:175], v[124:127]
	v_mfma_f32_16x16x32_bf16 v[120:123], v[164:167], v[172:175], v[120:123]
	v_mfma_f32_16x16x32_bf16 v[112:115], v[156:159], v[190:193], v[112:115]
	v_mfma_f32_16x16x32_bf16 v[104:107], v[164:167], v[190:193], v[104:107]
	v_mfma_f32_16x16x32_bf16 v[96:99], v[156:159], v[198:201], v[96:99]
	v_mfma_f32_16x16x32_bf16 v[88:91], v[164:167], v[198:201], v[88:91]
	v_mfma_f32_16x16x32_bf16 v[80:83], v[156:159], v[206:209], v[80:83]
	v_mfma_f32_16x16x32_bf16 v[72:75], v[164:167], v[206:209], v[72:75]
	v_mfma_f32_16x16x32_bf16 v[116:119], v[210:213], v[168:171], v[116:119]
	v_mfma_f32_16x16x32_bf16 v[108:111], v[218:221], v[168:171], v[108:111]
	v_mfma_f32_16x16x32_bf16 v[100:103], v[210:213], v[182:185], v[100:103]
	v_mfma_f32_16x16x32_bf16 v[92:95], v[218:221], v[182:185], v[92:95]
	v_mfma_f32_16x16x32_bf16 v[84:87], v[210:213], v[194:197], v[84:87]
	v_mfma_f32_16x16x32_bf16 v[76:79], v[218:221], v[194:197], v[76:79]
	v_mfma_f32_16x16x32_bf16 v[68:71], v[210:213], v[202:205], v[68:71]
	v_mfma_f32_16x16x32_bf16 v[64:67], v[218:221], v[202:205], v[64:67]
	v_mfma_f32_16x16x32_bf16 v[116:119], v[214:217], v[172:175], v[116:119]
	v_mfma_f32_16x16x32_bf16 v[108:111], v[222:225], v[172:175], v[108:111]
	v_mfma_f32_16x16x32_bf16 v[100:103], v[214:217], v[190:193], v[100:103]
	v_mfma_f32_16x16x32_bf16 v[92:95], v[222:225], v[190:193], v[92:95]
	v_mfma_f32_16x16x32_bf16 v[84:87], v[214:217], v[198:201], v[84:87]
	v_mfma_f32_16x16x32_bf16 v[76:79], v[222:225], v[198:201], v[76:79]
	v_mfma_f32_16x16x32_bf16 v[68:71], v[214:217], v[206:209], v[68:71]
	v_mfma_f32_16x16x32_bf16 v[64:67], v[222:225], v[206:209], v[64:67]
	s_barrier
; #define PG8_STAGE(bufoff, gbase, voff) do { _Pragma("unroll") for (int _i = 0; _i < 2; ++_i) \
;         __builtin_amdgcn_global_load_lds((const unsigned*)((const char*)(gbase) + (voff)[_i]), (PG8_LAS unsigned*)(lds + (bufoff) + ldsw + _i * 8192), 16, 0, 0); } while (0)
; #define PG8_LDA(dst, b, h) do { _Pragma("unroll") for (int m = 0; m < 4; ++m) _Pragma("unroll") for (int k = 0; k < 2; ++k) dst[m][k] = *(const PG8_LAS bf16x8*)(lds + PG8_SA(b, h) + aoff + m * 2048 + k * 1024); } while (0)
; #define PG8_WAIT_V(n) asm volatile("s_waitcnt vmcnt(" #n ")" ::: "memory")
; template <class Epi, class Sched>
; __device__ __forceinline__ void gemm_phase(PG8_LAS unsigned char* lds, const Gemm g, const Sched& S, const Epi& E) {
;     ...
;         for (int t = 0; t < nt; t += 2) {
;             const bool last = (t == nt - 2);
;             const char* a1 = cA + (size_t)(t + 1) * kstep;
;             const char* a2 = last ? nA : cA + (size_t)(t + 2) * kstep; const char* b2 = last ? nB : cB + (size_t)(t + 2) * kstep;
;             const char* a3 = a2 + kstep; const char* b3 = b2 + kstep;
;             if (last && has_next) S.a_ready(nxt);
;             PG8_LDB(B0, 0, 0); PG8_SCHED; PG8_LDA(At, 0, 0); PG8_STAGE(PG8_SA(1, 1), a1 + hstep, voffA);
;             PG8_WAIT_L(8); PG8_BAR; PG8_WAIT_L(0); PG8_MMA(0, 0, At, B0); PG8_BAR; PG8_SCHED;
;             PG8_LDB(B1, 0, 1); PG8_STAGE(PG8_SB(0, 0), b2, voffB);
;             PG8_BAR; PG8_WAIT_L(0); PG8_MMA(0, 1, At, B1); PG8_BAR;
;             PG8_LDA(At, 0, 1); PG8_STAGE(PG8_SA(0, 0), a2, voffA);
;             PG8_BAR; PG8_WAIT_L(0); PG8_MMA(1, 0, At, B0); PG8_BAR; PG8_SCHED;
;             PG8_STAGE(PG8_SB(0, 1), b2 + hstep, voffB);
;             PG8_WAIT_V(6); PG8_BAR; PG8_MMA(1, 1, At, B1); PG8_BAR;
;             PG8_LDB(B0, 1, 0); PG8_SCHED; PG8_LDA(At, 1, 0); PG8_STAGE(PG8_SA(0, 1), a2 + hstep, voffA);
;             PG8_WAIT_L(8); PG8_BAR; PG8_WAIT_L(0); PG8_MMA(0, 0, At, B0); PG8_BAR; PG8_SCHED;
;             PG8_LDB(B1, 1, 1); PG8_STAGE(PG8_SB(1, 0), b3, voffB);
;             PG8_BAR; PG8_WAIT_L(0); PG8_MMA(0, 1, At, B1); PG8_BAR;
;             PG8_LDA(At, 1, 1); PG8_STAGE(PG8_SA(1, 0), a3, voffA);
;             PG8_BAR; PG8_WAIT_L(0); PG8_MMA(1, 0, At, B0); PG8_BAR; PG8_SCHED;
;             PG8_STAGE(PG8_SB(1, 1), b3 + hstep, voffB);
;             PG8_WAIT_V(6); PG8_BAR; PG8_MMA(1, 1, At, B1); PG8_BAR;
	ds_read_b128 v[168:171], v154 offset:49152
	ds_read_b128 v[172:175], v154 offset:50176
	ds_read_b128 v[182:185], v154 offset:51200
	ds_read_b128 v[190:193], v154 offset:52224
	ds_read_b128 v[194:197], v154 offset:53248
	ds_read_b128 v[198:201], v154 offset:54272
	ds_read_b128 v[202:205], v154 offset:55296
	ds_read_b128 v[206:209], v154 offset:56320
	s_add_i32 s23, s48, s29
	s_mov_b32 m0, s23
	s_nop 0
	global_load_lds_dwordx4 v130, s[98:99]
	s_nop 1
	s_add_i32 m0, s23, 0x2000
	s_nop 0
	global_load_lds_dwordx4 v134, s[98:99]
	s_nop 1
	s_mov_b32 m0, s36
	s_nop 0
	global_load_lds_dwordx4 v128, s[100:101]
	s_nop 1
	s_mov_b32 m0, s37
	s_nop 0
	global_load_lds_dwordx4 v132, s[100:101]
	s_add_u32 s20, s20, 0x40080
	s_addc_u32 s21, s21, 0
	s_add_i32 s22, s22, s29
	s_mov_b32 m0, s22
	s_nop 0
	global_load_lds_dwordx4 v130, s[20:21]
	s_nop 1
	s_add_i32 m0, s22, 0x2000
	s_nop 0
	global_load_lds_dwordx4 v134, s[20:21]
	s_waitcnt vmcnt(8) lgkmcnt(0)
	s_barrier
	v_mfma_f32_16x16x32_bf16 v[60:63], v[144:147], v[168:171], v[60:63]
	v_mfma_f32_16x16x32_bf16 v[56:59], v[160:163], v[168:171], v[56:59]
	v_mfma_f32_16x16x32_bf16 v[48:51], v[144:147], v[182:185], v[48:51]
	v_mfma_f32_16x16x32_bf16 v[40:43], v[160:163], v[182:185], v[40:43]
	v_mfma_f32_16x16x32_bf16 v[32:35], v[144:147], v[194:197], v[32:35]
	v_mfma_f32_16x16x32_bf16 v[24:27], v[160:163], v[194:197], v[24:27]
	v_mfma_f32_16x16x32_bf16 v[16:19], v[144:147], v[202:205], v[16:19]
	v_mfma_f32_16x16x32_bf16 v[8:11], v[160:163], v[202:205], v[8:11]
	v_mfma_f32_16x16x32_bf16 v[60:63], v[156:159], v[172:175], v[60:63]
	v_mfma_f32_16x16x32_bf16 v[56:59], v[164:167], v[172:175], v[56:59]
	v_mfma_f32_16x16x32_bf16 v[48:51], v[156:159], v[190:193], v[48:51]
	v_mfma_f32_16x16x32_bf16 v[40:43], v[164:167], v[190:193], v[40:43]
	v_mfma_f32_16x16x32_bf16 v[32:35], v[156:159], v[198:201], v[32:35]
	v_mfma_f32_16x16x32_bf16 v[24:27], v[164:167], v[198:201], v[24:27]
	v_mfma_f32_16x16x32_bf16 v[16:19], v[156:159], v[206:209], v[16:19]
	v_mfma_f32_16x16x32_bf16 v[8:11], v[164:167], v[206:209], v[8:11]
	v_mfma_f32_16x16x32_bf16 v[52:55], v[210:213], v[168:171], v[52:55]
	v_mfma_f32_16x16x32_bf16 v[44:47], v[218:221], v[168:171], v[44:47]
	v_mfma_f32_16x16x32_bf16 v[36:39], v[210:213], v[182:185], v[36:39]
	v_mfma_f32_16x16x32_bf16 v[28:31], v[218:221], v[182:185], v[28:31]
	v_mfma_f32_16x16x32_bf16 v[20:23], v[210:213], v[194:197], v[20:23]
	v_mfma_f32_16x16x32_bf16 v[12:15], v[218:221], v[194:197], v[12:15]
	v_mfma_f32_16x16x32_bf16 v[4:7], v[210:213], v[202:205], v[4:7]
	v_mfma_f32_16x16x32_bf16 v[0:3], v[218:221], v[202:205], v[0:3]
	v_mfma_f32_16x16x32_bf16 v[52:55], v[214:217], v[172:175], v[52:55]
	v_mfma_f32_16x16x32_bf16 v[44:47], v[222:225], v[172:175], v[44:47]
	v_mfma_f32_16x16x32_bf16 v[36:39], v[214:217], v[190:193], v[36:39]
	v_mfma_f32_16x16x32_bf16 v[28:31], v[222:225], v[190:193], v[28:31]
	v_mfma_f32_16x16x32_bf16 v[20:23], v[214:217], v[198:201], v[20:23]
	v_mfma_f32_16x16x32_bf16 v[12:15], v[222:225], v[198:201], v[12:15]
	v_mfma_f32_16x16x32_bf16 v[4:7], v[214:217], v[206:209], v[4:7]
	v_mfma_f32_16x16x32_bf16 v[0:3], v[222:225], v[206:209], v[0:3]
	s_barrier
	s_add_i32 s47, s47, 2
	s_add_u32 s18, s18, 0x100
	s_addc_u32 s19, s19, 0
	s_add_u32 s45, s45, 0x100
	s_addc_u32 s46, s46, 0
	s_cmp_gt_u32 s47, 13
.LBB0_991:
	ds_read_b128 v[144:147], v153
	ds_read_b128 v[156:159], v153 offset:1024
	ds_read_b128 v[160:163], v153 offset:2048
	ds_read_b128 v[164:167], v153 offset:3072
	s_add_u32 s20, s18, 0xfffc0080
	s_addc_u32 s21, s19, -1
	s_cmp_eq_u32 s47, 12
	s_cselect_b32 s23, s11, s21
	s_cselect_b32 s22, s43, s20
	s_cselect_b32 s21, s9, s46
	s_cselect_b32 s20, s44, s45
	ds_read_b128 v[168:171], v154
	ds_read_b128 v[172:175], v154 offset:1024
	ds_read_b128 v[182:185], v154 offset:2048
	ds_read_b128 v[190:193], v154 offset:3072
	ds_read_b128 v[194:197], v154 offset:4096
	ds_read_b128 v[198:201], v154 offset:5120
	ds_read_b128 v[202:205], v154 offset:6144
	ds_read_b128 v[206:209], v154 offset:7168
	s_waitcnt lgkmcnt(8)
	ds_read_b128 v[210:213], v155
	ds_read_b128 v[214:217], v155 offset:1024
	ds_read_b128 v[218:221], v155 offset:2048
	ds_read_b128 v[222:225], v155 offset:3072
	s_add_i32 m0, s17, 0xc000
	s_nop 0
	global_load_lds_dwordx4 v136, s[18:19]
	s_nop 1
	s_add_i32 m0, s17, 0xe000
	s_nop 0
	global_load_lds_dwordx4 v138, s[18:19]
	s_waitcnt vmcnt(8) lgkmcnt(0)
	s_barrier
	v_mfma_f32_16x16x32_bf16 v[124:127], v[144:147], v[168:171], v[124:127]
	v_mfma_f32_16x16x32_bf16 v[120:123], v[160:163], v[168:171], v[120:123]
	v_mfma_f32_16x16x32_bf16 v[112:115], v[144:147], v[182:185], v[112:115]
	v_mfma_f32_16x16x32_bf16 v[104:107], v[160:163], v[182:185], v[104:107]
	v_mfma_f32_16x16x32_bf16 v[96:99], v[144:147], v[194:197], v[96:99]
	v_mfma_f32_16x16x32_bf16 v[88:91], v[160:163], v[194:197], v[88:91]
	v_mfma_f32_16x16x32_bf16 v[80:83], v[144:147], v[202:205], v[80:83]
	v_mfma_f32_16x16x32_bf16 v[72:75], v[160:163], v[202:205], v[72:75]
	v_mfma_f32_16x16x32_bf16 v[124:127], v[156:159], v[172:175], v[124:127]
	v_mfma_f32_16x16x32_bf16 v[120:123], v[164:167], v[172:175], v[120:123]
	v_mfma_f32_16x16x32_bf16 v[112:115], v[156:159], v[190:193], v[112:115]
	v_mfma_f32_16x16x32_bf16 v[104:107], v[164:167], v[190:193], v[104:107]
	v_mfma_f32_16x16x32_bf16 v[96:99], v[156:159], v[198:201], v[96:99]
	v_mfma_f32_16x16x32_bf16 v[88:91], v[164:167], v[198:201], v[88:91]
	v_mfma_f32_16x16x32_bf16 v[80:83], v[156:159], v[206:209], v[80:83]
	v_mfma_f32_16x16x32_bf16 v[72:75], v[164:167], v[206:209], v[72:75]
	v_mfma_f32_16x16x32_bf16 v[116:119], v[210:213], v[168:171], v[116:119]
	v_mfma_f32_16x16x32_bf16 v[108:111], v[218:221], v[168:171], v[108:111]
	v_mfma_f32_16x16x32_bf16 v[100:103], v[210:213], v[182:185], v[100:103]
	v_mfma_f32_16x16x32_bf16 v[92:95], v[218:221], v[182:185], v[92:95]
	v_mfma_f32_16x16x32_bf16 v[84:87], v[210:213], v[194:197], v[84:87]
	v_mfma_f32_16x16x32_bf16 v[76:79], v[218:221], v[194:197], v[76:79]
	v_mfma_f32_16x16x32_bf16 v[68:71], v[210:213], v[202:205], v[68:71]
	v_mfma_f32_16x16x32_bf16 v[64:67], v[218:221], v[202:205], v[64:67]
	v_mfma_f32_16x16x32_bf16 v[116:119], v[214:217], v[172:175], v[116:119]
	v_mfma_f32_16x16x32_bf16 v[108:111], v[222:225], v[172:175], v[108:111]
	v_mfma_f32_16x16x32_bf16 v[100:103], v[214:217], v[190:193], v[100:103]
	v_mfma_f32_16x16x32_bf16 v[92:95], v[222:225], v[190:193], v[92:95]
	v_mfma_f32_16x16x32_bf16 v[84:87], v[214:217], v[198:201], v[84:87]
	v_mfma_f32_16x16x32_bf16 v[76:79], v[222:225], v[198:201], v[76:79]
	v_mfma_f32_16x16x32_bf16 v[68:71], v[214:217], v[206:209], v[68:71]
	v_mfma_f32_16x16x32_bf16 v[64:67], v[222:225], v[206:209], v[64:67]
	s_barrier
; #define PG8_STAGE(bufoff, gbase, voff) do { _Pragma("unroll") for (int _i = 0; _i < 2; ++_i) \
;         __builtin_amdgcn_global_load_lds((const unsigned*)((const char*)(gbase) + (voff)[_i]), (PG8_LAS unsigned*)(lds + (bufoff) + ldsw + _i * 8192), 16, 0, 0); } while (0)
; #define PG8_LDA(dst, b, h) do { _Pragma("unroll") for (int m = 0; m < 4; ++m) _Pragma("unroll") for (int k = 0; k < 2; ++k) dst[m][k] = *(const PG8_LAS bf16x8*)(lds + PG8_SA(b, h) + aoff + m * 2048 + k * 1024); } while (0)
; #define PG8_LDB(dst, b, h) do { _Pragma("unroll") for (int n = 0; n < 2; ++n) _Pragma("unroll") for (int k = 0; k < 2; ++k) dst[n][k] = *(const PG8_LAS bf16x8*)(lds + PG8_SB(b, h) + boff + n * 2048 + k * 1024); } while (0)
; #define PG8_WAIT_V(n) asm volatile("s_waitcnt vmcnt(" #n ")" ::: "memory")
; #define PG8_WAIT_L(n) asm volatile("s_waitcnt lgkmcnt(" #n ")" ::: "memory")
; #define PG8_BAR __builtin_amdgcn_s_barrier()
; #define PG8_SCHED __builtin_amdgcn_sched_barrier(0)
; template <class Epi, class Sched>
; __device__ __forceinline__ void gemm_phase(PG8_LAS unsigned char* lds, const Gemm g, const Sched& S, const Epi& E) {
;     ...
;             PG8_LDB(B0, 0, 0); PG8_SCHED; PG8_LDA(At, 0, 0); PG8_STAGE(PG8_SA(1, 1), a1 + hstep, voffA);
;             PG8_WAIT_L(8); PG8_BAR; PG8_WAIT_L(0); PG8_MMA(0, 0, At, B0); PG8_BAR; PG8_SCHED;
;             PG8_LDB(B1, 0, 1); PG8_STAGE(PG8_SB(0, 0), b2, voffB);
;             PG8_BAR; PG8_WAIT_L(0); PG8_MMA(0, 1, At, B1); PG8_BAR;
;             PG8_LDA(At, 0, 1); PG8_STAGE(PG8_SA(0, 0), a2, voffA);
;             PG8_BAR; PG8_WAIT_L(0); PG8_MMA(1, 0, At, B0); PG8_BAR; PG8_SCHED;
;             PG8_STAGE(PG8_SB(0, 1), b2 + hstep, voffB);
;             PG8_WAIT_V(6); PG8_BAR; PG8_MMA(1, 1, At, B1); PG8_BAR;
;             PG8_LDB(B0, 1, 0); PG8_SCHED; PG8_LDA(At, 1, 0); PG8_STAGE(PG8_SA(0, 1), a2 + hstep, voffA);
;             PG8_WAIT_L(8); PG8_BAR; PG8_WAIT_L(0); PG8_MMA(0, 0, At, B0); PG8_BAR; PG8_SCHED;
;             PG8_LDB(B1, 1, 1); PG8_STAGE(PG8_SB(1, 0), b3, voffB);
;             PG8_BAR; PG8_WAIT_L(0); PG8_MMA(0, 1, At, B1); PG8_BAR;
;             PG8_LDA(At, 1, 1); PG8_STAGE(PG8_SA(1, 0), a3, voffA);
;             PG8_BAR; PG8_WAIT_L(0); PG8_MMA(1, 0, At, B0); PG8_BAR; PG8_SCHED;
;             PG8_STAGE(PG8_SB(1, 1), b3 + hstep, voffB);
;             PG8_WAIT_V(6); PG8_BAR; PG8_MMA(1, 1, At, B1); PG8_BAR;
	ds_read_b128 v[168:171], v154 offset:16384
	ds_read_b128 v[172:175], v154 offset:17408
	ds_read_b128 v[182:185], v154 offset:18432
	ds_read_b128 v[190:193], v154 offset:19456
	ds_read_b128 v[194:197], v154 offset:20480
	ds_read_b128 v[198:201], v154 offset:21504
	ds_read_b128 v[202:205], v154 offset:22528
	ds_read_b128 v[206:209], v154 offset:23552
	s_add_i32 s48, s39, s29
	s_add_u32 s98, s20, s6
	s_addc_u32 s99, s21, s7
	s_mov_b32 m0, s48
	s_nop 0
	global_load_lds_dwordx4 v130, s[20:21]
	s_nop 1
	s_add_i32 m0, s48, 0x2000
	s_nop 0
	global_load_lds_dwordx4 v134, s[20:21]
	s_nop 1
	s_mov_b32 m0, s17
	s_add_u32 s100, s22, s6
	s_addc_u32 s101, s23, s7
	global_load_lds_dwordx4 v128, s[22:23]
	s_nop 1
	s_mov_b32 m0, s30
	s_nop 0
	global_load_lds_dwordx4 v132, s[22:23]
	s_add_u32 s48, s20, 0x40000
	s_addc_u32 s49, s21, 0
	s_add_i32 s50, s40, s29
	s_mov_b32 m0, s50
	s_nop 0
	global_load_lds_dwordx4 v130, s[48:49]
	s_nop 1
	s_add_i32 m0, s50, 0x2000
	s_nop 0
	global_load_lds_dwordx4 v134, s[48:49]
	s_waitcnt vmcnt(8) lgkmcnt(0)
	s_barrier
	v_mfma_f32_16x16x32_bf16 v[60:63], v[144:147], v[168:171], v[60:63]
	v_mfma_f32_16x16x32_bf16 v[56:59], v[160:163], v[168:171], v[56:59]
	v_mfma_f32_16x16x32_bf16 v[48:51], v[144:147], v[182:185], v[48:51]
	v_mfma_f32_16x16x32_bf16 v[40:43], v[160:163], v[182:185], v[40:43]
	v_mfma_f32_16x16x32_bf16 v[32:35], v[144:147], v[194:197], v[32:35]
	v_mfma_f32_16x16x32_bf16 v[24:27], v[160:163], v[194:197], v[24:27]
	v_mfma_f32_16x16x32_bf16 v[16:19], v[144:147], v[202:205], v[16:19]
	v_mfma_f32_16x16x32_bf16 v[8:11], v[160:163], v[202:205], v[8:11]
	v_mfma_f32_16x16x32_bf16 v[60:63], v[156:159], v[172:175], v[60:63]
	v_mfma_f32_16x16x32_bf16 v[56:59], v[164:167], v[172:175], v[56:59]
	v_mfma_f32_16x16x32_bf16 v[48:51], v[156:159], v[190:193], v[48:51]
	v_mfma_f32_16x16x32_bf16 v[40:43], v[164:167], v[190:193], v[40:43]
	v_mfma_f32_16x16x32_bf16 v[32:35], v[156:159], v[198:201], v[32:35]
	v_mfma_f32_16x16x32_bf16 v[24:27], v[164:167], v[198:201], v[24:27]
	v_mfma_f32_16x16x32_bf16 v[16:19], v[156:159], v[206:209], v[16:19]
	v_mfma_f32_16x16x32_bf16 v[8:11], v[164:167], v[206:209], v[8:11]
	v_mfma_f32_16x16x32_bf16 v[52:55], v[210:213], v[168:171], v[52:55]
	v_mfma_f32_16x16x32_bf16 v[44:47], v[218:221], v[168:171], v[44:47]
	v_mfma_f32_16x16x32_bf16 v[36:39], v[210:213], v[182:185], v[36:39]
	v_mfma_f32_16x16x32_bf16 v[28:31], v[218:221], v[182:185], v[28:31]
	v_mfma_f32_16x16x32_bf16 v[20:23], v[210:213], v[194:197], v[20:23]
	v_mfma_f32_16x16x32_bf16 v[12:15], v[218:221], v[194:197], v[12:15]
	v_mfma_f32_16x16x32_bf16 v[4:7], v[210:213], v[202:205], v[4:7]
	v_mfma_f32_16x16x32_bf16 v[0:3], v[218:221], v[202:205], v[0:3]
	v_mfma_f32_16x16x32_bf16 v[52:55], v[214:217], v[172:175], v[52:55]
	v_mfma_f32_16x16x32_bf16 v[44:47], v[222:225], v[172:175], v[44:47]
	v_mfma_f32_16x16x32_bf16 v[36:39], v[214:217], v[190:193], v[36:39]
	v_mfma_f32_16x16x32_bf16 v[28:31], v[222:225], v[190:193], v[28:31]
	v_mfma_f32_16x16x32_bf16 v[20:23], v[214:217], v[198:201], v[20:23]
	v_mfma_f32_16x16x32_bf16 v[12:15], v[222:225], v[198:201], v[12:15]
	v_mfma_f32_16x16x32_bf16 v[4:7], v[214:217], v[206:209], v[4:7]
	v_mfma_f32_16x16x32_bf16 v[0:3], v[222:225], v[206:209], v[0:3]
	s_barrier
	s_add_i32 s48, 0, 0x18000
	v_add_u32_e32 v164, s48, v151
	ds_read_b128 v[144:147], v164
	ds_read_b128 v[156:159], v164 offset:1024
	ds_read_b128 v[160:163], v164 offset:2048
	ds_read_b128 v[164:167], v164 offset:3072
	ds_read_b128 v[168:171], v154 offset:32768
	ds_read_b128 v[172:175], v154 offset:33792
	ds_read_b128 v[182:185], v154 offset:34816
	ds_read_b128 v[190:193], v154 offset:35840
	ds_read_b128 v[194:197], v154 offset:36864
	ds_read_b128 v[198:201], v154 offset:37888
	ds_read_b128 v[202:205], v154 offset:38912
	ds_read_b128 v[206:209], v154 offset:39936
	v_add_u32_e32 v179, 0x1c000, v151
	s_waitcnt lgkmcnt(8)
	ds_read_b128 v[210:213], v179
	ds_read_b128 v[214:217], v179 offset:1024
	ds_read_b128 v[218:221], v179 offset:2048
	ds_read_b128 v[222:225], v179 offset:3072
	s_add_u32 s22, s22, 0x40000
	s_addc_u32 s23, s23, 0
	s_mov_b32 m0, s31
	s_nop 0
	global_load_lds_dwordx4 v128, s[22:23]
	s_nop 1
	s_mov_b32 m0, s34
	s_nop 0
	global_load_lds_dwordx4 v132, s[22:23]
	s_add_i32 s22, 0, 0x1c000
	s_waitcnt vmcnt(8) lgkmcnt(0)
	s_barrier
	v_mfma_f32_16x16x32_bf16 v[124:127], v[144:147], v[168:171], v[124:127]
	v_mfma_f32_16x16x32_bf16 v[120:123], v[160:163], v[168:171], v[120:123]
	v_mfma_f32_16x16x32_bf16 v[112:115], v[144:147], v[182:185], v[112:115]
	v_mfma_f32_16x16x32_bf16 v[104:107], v[160:163], v[182:185], v[104:107]
	v_mfma_f32_16x16x32_bf16 v[96:99], v[144:147], v[194:197], v[96:99]
	v_mfma_f32_16x16x32_bf16 v[88:91], v[160:163], v[194:197], v[88:91]
	v_mfma_f32_16x16x32_bf16 v[80:83], v[144:147], v[202:205], v[80:83]
	v_mfma_f32_16x16x32_bf16 v[72:75], v[160:163], v[202:205], v[72:75]
	v_mfma_f32_16x16x32_bf16 v[124:127], v[156:159], v[172:175], v[124:127]
	v_mfma_f32_16x16x32_bf16 v[120:123], v[164:167], v[172:175], v[120:123]
	v_mfma_f32_16x16x32_bf16 v[112:115], v[156:159], v[190:193], v[112:115]
	v_mfma_f32_16x16x32_bf16 v[104:107], v[164:167], v[190:193], v[104:107]
	v_mfma_f32_16x16x32_bf16 v[96:99], v[156:159], v[198:201], v[96:99]
	v_mfma_f32_16x16x32_bf16 v[88:91], v[164:167], v[198:201], v[88:91]
	v_mfma_f32_16x16x32_bf16 v[80:83], v[156:159], v[206:209], v[80:83]
	v_mfma_f32_16x16x32_bf16 v[72:75], v[164:167], v[206:209], v[72:75]
	v_mfma_f32_16x16x32_bf16 v[116:119], v[210:213], v[168:171], v[116:119]
	v_mfma_f32_16x16x32_bf16 v[108:111], v[218:221], v[168:171], v[108:111]
	v_mfma_f32_16x16x32_bf16 v[100:103], v[210:213], v[182:185], v[100:103]
	v_mfma_f32_16x16x32_bf16 v[92:95], v[218:221], v[182:185], v[92:95]
	v_mfma_f32_16x16x32_bf16 v[84:87], v[210:213], v[194:197], v[84:87]
	v_mfma_f32_16x16x32_bf16 v[76:79], v[218:221], v[194:197], v[76:79]
	v_mfma_f32_16x16x32_bf16 v[68:71], v[210:213], v[202:205], v[68:71]
	v_mfma_f32_16x16x32_bf16 v[64:67], v[218:221], v[202:205], v[64:67]
	v_mfma_f32_16x16x32_bf16 v[116:119], v[214:217], v[172:175], v[116:119]
	v_mfma_f32_16x16x32_bf16 v[108:111], v[222:225], v[172:175], v[108:111]
	v_mfma_f32_16x16x32_bf16 v[100:103], v[214:217], v[190:193], v[100:103]
	v_mfma_f32_16x16x32_bf16 v[92:95], v[222:225], v[190:193], v[92:95]
	v_mfma_f32_16x16x32_bf16 v[84:87], v[214:217], v[198:201], v[84:87]
	v_mfma_f32_16x16x32_bf16 v[76:79], v[222:225], v[198:201], v[76:79]
	v_mfma_f32_16x16x32_bf16 v[68:71], v[214:217], v[206:209], v[68:71]
	v_mfma_f32_16x16x32_bf16 v[64:67], v[222:225], v[206:209], v[64:67]
	s_barrier
; __device__ __forceinline__ unsigned cvt_pk_bf16(float lo, float hi) { unsigned r; asm volatile("v_cvt_pk_bf16_f32 %0, %1, %2" : "=v"(r) : "v"(lo), "v"(hi)); return r; }
; __device__ __forceinline__ float bf_lo(unsigned u) { return __uint_as_float(u << 16); }
; __device__ __forceinline__ float bf_hi(unsigned u) { return __uint_as_float(u & 0xffff0000u); }
; #define PG8_LDA(dst, b, h) do { _Pragma("unroll") for (int m = 0; m < 4; ++m) _Pragma("unroll") for (int k = 0; k < 2; ++k) dst[m][k] = *(const PG8_LAS bf16x8*)(lds + PG8_SA(b, h) + aoff + m * 2048 + k * 1024); } while (0)
;     __device__ __forceinline__ void operator()(const f32x4 (&acc)[2][2][4][2], const Unit& u, int wr, int wc, int fr, int fq) const {
;     ...
;             for (int m = 0; m < 4; ++m) { const size_t r = (size_t)(row0 + ai * HALF + m * 16); bf16_t* rowp = O + r * ldc + col0; const bf16_t* gp = G + r * ldg + col0;
; #pragma unroll
;                 for (int bj = 0; bj < 2; ++bj) { const u32x4 gw = *(const u32x4*)(gp + bj * HALF);
;                     f32x4 v0 = acc[ai][bj][m][0], v1 = acc[ai][bj][m][1];
;                     v0[0] *= bf_lo(gw.x); v0[1] *= bf_hi(gw.x); v0[2] *= bf_lo(gw.y); v0[3] *= bf_hi(gw.y);
;                     v1[0] *= bf_lo(gw.z); v1[1] *= bf_hi(gw.z); v1[2] *= bf_lo(gw.w); v1[3] *= bf_hi(gw.w);
;                     if (ACCUM) { const u32x4 pw = *(const u32x4*)(rowp + bj * HALF);
;                         v0[0] += bf_lo(pw.x); v0[1] += bf_hi(pw.x); v0[2] += bf_lo(pw.y); v0[3] += bf_hi(pw.y);
;                         v1[0] += bf_lo(pw.z); v1[1] += bf_hi(pw.z); v1[2] += bf_lo(pw.w); v1[3] += bf_hi(pw.w); }
;                     u32x4 w; w.x = cvt_pk_bf16(v0[0], v0[1]); w.y = cvt_pk_bf16(v0[2], v0[3]); w.z = cvt_pk_bf16(v1[0], v1[1]); w.w = cvt_pk_bf16(v1[2], v1[3]);
;                     *(u32x4*)(rowp + bj * HALF) = w; } }
; template <class Epi, class Sched>
; __device__ __forceinline__ void gemm_phase(PG8_LAS unsigned char* lds, const Gemm g, const Sched& S, const Epi& E) {
;     ...
;             PG8_LDA(At, 1, 1); PG8_STAGE(PG8_SA(1, 0), a3, voffA);
;             PG8_BAR; PG8_WAIT_L(0); PG8_MMA(1, 0, At, B0); PG8_BAR; PG8_SCHED;
;             PG8_STAGE(PG8_SB(1, 1), b3 + hstep, voffB);
;             PG8_WAIT_V(6); PG8_BAR; PG8_MMA(1, 1, At, B1); PG8_BAR;
;         }
;         if constexpr (!Epi::AFTER_DRAIN) { E(acc, cur, wr, wc, fr, fq); S.done(cur); }
	ds_read_b128 v[168:171], v154 offset:49152
	ds_read_b128 v[172:175], v154 offset:50176
	ds_read_b128 v[182:185], v154 offset:51200
	ds_read_b128 v[190:193], v154 offset:52224
	ds_read_b128 v[194:197], v154 offset:53248
	ds_read_b128 v[198:201], v154 offset:54272
	ds_read_b128 v[202:205], v154 offset:55296
	ds_read_b128 v[206:209], v154 offset:56320
	s_add_i32 s23, s48, s29
	s_mov_b32 m0, s23
	s_nop 0
	global_load_lds_dwordx4 v130, s[98:99]
	s_nop 1
	s_add_i32 m0, s23, 0x2000
	s_nop 0
	global_load_lds_dwordx4 v134, s[98:99]
	s_nop 1
	s_mov_b32 m0, s36
	s_nop 0
	global_load_lds_dwordx4 v128, s[100:101]
	s_nop 1
	s_mov_b32 m0, s37
	s_nop 0
	global_load_lds_dwordx4 v132, s[100:101]
	s_add_u32 s20, s20, 0x40080
	s_addc_u32 s21, s21, 0
	s_add_i32 s22, s22, s29
	s_mov_b32 m0, s22
	s_nop 0
	global_load_lds_dwordx4 v130, s[20:21]
	s_nop 1
	s_add_i32 m0, s22, 0x2000
	s_nop 0
	global_load_lds_dwordx4 v134, s[20:21]
	s_waitcnt vmcnt(8) lgkmcnt(0)
	s_barrier
	v_mfma_f32_16x16x32_bf16 v[60:63], v[144:147], v[168:171], v[60:63]
	v_mfma_f32_16x16x32_bf16 v[56:59], v[160:163], v[168:171], v[56:59]
	v_mfma_f32_16x16x32_bf16 v[48:51], v[144:147], v[182:185], v[48:51]
	v_mfma_f32_16x16x32_bf16 v[40:43], v[160:163], v[182:185], v[40:43]
	v_mfma_f32_16x16x32_bf16 v[32:35], v[144:147], v[194:197], v[32:35]
	v_mfma_f32_16x16x32_bf16 v[24:27], v[160:163], v[194:197], v[24:27]
	v_mfma_f32_16x16x32_bf16 v[16:19], v[144:147], v[202:205], v[16:19]
	v_mfma_f32_16x16x32_bf16 v[8:11], v[160:163], v[202:205], v[8:11]
	v_mfma_f32_16x16x32_bf16 v[60:63], v[156:159], v[172:175], v[60:63]
	v_mfma_f32_16x16x32_bf16 v[56:59], v[164:167], v[172:175], v[56:59]
	v_mfma_f32_16x16x32_bf16 v[48:51], v[156:159], v[190:193], v[48:51]
	v_mfma_f32_16x16x32_bf16 v[40:43], v[164:167], v[190:193], v[40:43]
	v_mfma_f32_16x16x32_bf16 v[32:35], v[156:159], v[198:201], v[32:35]
	v_mfma_f32_16x16x32_bf16 v[24:27], v[164:167], v[198:201], v[24:27]
	v_mfma_f32_16x16x32_bf16 v[16:19], v[156:159], v[206:209], v[16:19]
	v_mfma_f32_16x16x32_bf16 v[8:11], v[164:167], v[206:209], v[8:11]
	v_mfma_f32_16x16x32_bf16 v[52:55], v[210:213], v[168:171], v[52:55]
	v_mfma_f32_16x16x32_bf16 v[44:47], v[218:221], v[168:171], v[44:47]
	v_mfma_f32_16x16x32_bf16 v[36:39], v[210:213], v[182:185], v[36:39]
	v_mfma_f32_16x16x32_bf16 v[28:31], v[218:221], v[182:185], v[28:31]
	v_mfma_f32_16x16x32_bf16 v[20:23], v[210:213], v[194:197], v[20:23]
	v_mfma_f32_16x16x32_bf16 v[12:15], v[218:221], v[194:197], v[12:15]
	v_mfma_f32_16x16x32_bf16 v[4:7], v[210:213], v[202:205], v[4:7]
	v_mfma_f32_16x16x32_bf16 v[0:3], v[218:221], v[202:205], v[0:3]
	v_mfma_f32_16x16x32_bf16 v[52:55], v[214:217], v[172:175], v[52:55]
	v_mfma_f32_16x16x32_bf16 v[44:47], v[222:225], v[172:175], v[44:47]
	v_mfma_f32_16x16x32_bf16 v[36:39], v[214:217], v[190:193], v[36:39]
	v_mfma_f32_16x16x32_bf16 v[28:31], v[222:225], v[190:193], v[28:31]
	v_mfma_f32_16x16x32_bf16 v[20:23], v[214:217], v[198:201], v[20:23]
	v_mfma_f32_16x16x32_bf16 v[12:15], v[222:225], v[198:201], v[12:15]
	v_mfma_f32_16x16x32_bf16 v[4:7], v[214:217], v[206:209], v[4:7]
	v_mfma_f32_16x16x32_bf16 v[0:3], v[222:225], v[206:209], v[0:3]
	s_barrier
	s_add_i32 s47, s47, 2
	s_add_u32 s18, s18, 0x100
	s_addc_u32 s19, s19, 0
	s_add_u32 s45, s45, 0x100
	s_addc_u32 s46, s46, 0
	s_cmp_gt_u32 s47, 13
	s_cbranch_scc0 .LBB0_991
	v_lshl_or_b32 v144, s42, 8, v152
	v_lshl_add_u32 v146, s16, 8, v150
	v_ashrrev_i32_e32 v145, 31, v144
	v_mov_b64_e32 v[148:149], s[4:5]
	v_lshlrev_b64 v[144:145], 1, v[144:145]
	v_mad_i64_i32 v[156:157], s[18:19], v146, s41, v[148:149]
	v_lshl_add_u64 v[160:161], v[156:157], 0, v[144:145]
	global_load_dwordx4 v[156:159], v[160:161], off offset:3072
	s_and_b64 vcc, exec, s[2:3]
	s_mov_b32 s42, s8
	s_mov_b32 s16, s10
	s_mov_b64 s[20:21], s[14:15]
	s_waitcnt vmcnt(0)
	v_lshlrev_b32_e32 v147, 16, v156
	v_and_b32_e32 v156, 0xffff0000, v156
	v_lshlrev_b32_e32 v162, 16, v157
	v_and_b32_e32 v157, 0xffff0000, v157
	v_lshlrev_b32_e32 v164, 16, v159
	v_and_b32_e32 v159, 0xffff0000, v159
	v_lshlrev_b32_e32 v163, 16, v158
	v_and_b32_e32 v158, 0xffff0000, v158
	v_mul_f32_e32 v124, v124, v147
	v_mul_f32_e32 v125, v125, v156
	v_mul_f32_e32 v126, v126, v162
	v_mul_f32_e32 v127, v127, v157
	v_mul_f32_e32 v123, v123, v159
	v_mul_f32_e32 v147, v120, v163
	v_mul_f32_e32 v156, v121, v158
	v_mul_f32_e32 v157, v122, v164
	v_cvt_pk_bf16_f32 v120, v124, v125
	v_cvt_pk_bf16_f32 v121, v126, v127
	v_cvt_pk_bf16_f32 v122, v147, v156
	v_cvt_pk_bf16_f32 v123, v157, v123
	global_load_dwordx4 v[124:127], v[160:161], off offset:3328
	v_ashrrev_i32_e32 v147, 31, v146
	v_lshlrev_b64 v[158:159], 11, v[146:147]
	v_lshl_add_u64 v[158:159], s[0:1], 0, v[158:159]
	v_or_b32_e32 v156, 16, v146
	v_lshl_add_u64 v[158:159], v[158:159], 0, v[144:145]
	v_mad_i64_i32 v[160:161], s[18:19], v156, s41, v[148:149]
	global_store_dwordx4 v[158:159], v[120:123], off
	v_lshl_add_u64 v[160:161], v[160:161], 0, v[144:145]
	v_ashrrev_i32_e32 v157, 31, v156
	s_waitcnt vmcnt(0)
	v_lshlrev_b32_e32 v120, 16, v124
	v_and_b32_e32 v121, 0xffff0000, v124
	v_lshlrev_b32_e32 v122, 16, v125
	v_and_b32_e32 v123, 0xffff0000, v125
	v_lshlrev_b32_e32 v124, 16, v126
	v_and_b32_e32 v125, 0xffff0000, v126
	v_lshlrev_b32_e32 v126, 16, v127
	v_and_b32_e32 v127, 0xffff0000, v127
	v_mul_f32_e32 v116, v116, v120
	v_mul_f32_e32 v117, v117, v121
	v_mul_f32_e32 v118, v118, v122
	v_mul_f32_e32 v119, v119, v123
	v_mul_f32_e32 v111, v111, v127
	v_mul_f32_e32 v120, v108, v124
	v_mul_f32_e32 v121, v109, v125
	v_mul_f32_e32 v122, v110, v126
	v_cvt_pk_bf16_f32 v108, v116, v117
	v_cvt_pk_bf16_f32 v109, v118, v119
	v_cvt_pk_bf16_f32 v110, v120, v121
	v_cvt_pk_bf16_f32 v111, v122, v111
	global_load_dwordx4 v[116:119], v[160:161], off offset:3072
	s_nop 0
	global_store_dwordx4 v[158:159], v[108:111], off offset:256
	s_waitcnt vmcnt(0)
; __device__ __forceinline__ unsigned cvt_pk_bf16(float lo, float hi) { unsigned r; asm volatile("v_cvt_pk_bf16_f32 %0, %1, %2" : "=v"(r) : "v"(lo), "v"(hi)); return r; }
; __device__ __forceinline__ float bf_lo(unsigned u) { return __uint_as_float(u << 16); }
; __device__ __forceinline__ float bf_hi(unsigned u) { return __uint_as_float(u & 0xffff0000u); }
;     __device__ __forceinline__ void operator()(const f32x4 (&acc)[2][2][4][2], const Unit& u, int wr, int wc, int fr, int fq) const {
;     ...
;             for (int m = 0; m < 4; ++m) { const size_t r = (size_t)(row0 + ai * HALF + m * 16); bf16_t* rowp = O + r * ldc + col0; const bf16_t* gp = G + r * ldg + col0;
; #pragma unroll
;                 for (int bj = 0; bj < 2; ++bj) { const u32x4 gw = *(const u32x4*)(gp + bj * HALF);
;                     f32x4 v0 = acc[ai][bj][m][0], v1 = acc[ai][bj][m][1];
;                     v0[0] *= bf_lo(gw.x); v0[1] *= bf_hi(gw.x); v0[2] *= bf_lo(gw.y); v0[3] *= bf_hi(gw.y);
;                     v1[0] *= bf_lo(gw.z); v1[1] *= bf_hi(gw.z); v1[2] *= bf_lo(gw.w); v1[3] *= bf_hi(gw.w);
;                     if (ACCUM) { const u32x4 pw = *(const u32x4*)(rowp + bj * HALF);
;                         v0[0] += bf_lo(pw.x); v0[1] += bf_hi(pw.x); v0[2] += bf_lo(pw.y); v0[3] += bf_hi(pw.y);
;                         v1[0] += bf_lo(pw.z); v1[1] += bf_hi(pw.z); v1[2] += bf_lo(pw.w); v1[3] += bf_hi(pw.w); }
;                     u32x4 w; w.x = cvt_pk_bf16(v0[0], v0[1]); w.y = cvt_pk_bf16(v0[2], v0[3]); w.z = cvt_pk_bf16(v1[0], v1[1]); w.w = cvt_pk_bf16(v1[2], v1[3]);
;                     *(u32x4*)(rowp + bj * HALF) = w; } }
	s_nop 0
	v_lshlrev_b32_e32 v108, 16, v116
	v_and_b32_e32 v109, 0xffff0000, v116
	v_lshlrev_b32_e32 v110, 16, v117
	v_and_b32_e32 v111, 0xffff0000, v117
	v_lshlrev_b32_e32 v116, 16, v118
	v_and_b32_e32 v117, 0xffff0000, v118
	v_lshlrev_b32_e32 v118, 16, v119
	v_and_b32_e32 v119, 0xffff0000, v119
	v_mul_f32_e32 v108, v112, v108
	v_mul_f32_e32 v109, v113, v109
	v_mul_f32_e32 v110, v114, v110
	v_mul_f32_e32 v111, v115, v111
	v_mul_f32_e32 v107, v107, v119
	v_mul_f32_e32 v112, v104, v116
	v_mul_f32_e32 v113, v105, v117
	v_mul_f32_e32 v114, v106, v118
	v_cvt_pk_bf16_f32 v104, v108, v109
	v_cvt_pk_bf16_f32 v105, v110, v111
	v_cvt_pk_bf16_f32 v106, v112, v113
	v_cvt_pk_bf16_f32 v107, v114, v107
	global_load_dwordx4 v[108:111], v[160:161], off offset:3328
	v_lshlrev_b64 v[116:117], 11, v[156:157]
	v_lshl_add_u64 v[116:117], s[0:1], 0, v[116:117]
	v_or_b32_e32 v112, 32, v146
	v_lshl_add_u64 v[116:117], v[116:117], 0, v[144:145]
	v_mad_i64_i32 v[114:115], s[18:19], v112, s41, v[148:149]
	global_store_dwordx4 v[116:117], v[104:107], off
	v_lshl_add_u64 v[114:115], v[114:115], 0, v[144:145]
	v_ashrrev_i32_e32 v113, 31, v112
	s_waitcnt vmcnt(0)
	v_lshlrev_b32_e32 v104, 16, v108
	v_and_b32_e32 v105, 0xffff0000, v108
	v_lshlrev_b32_e32 v106, 16, v109
	v_and_b32_e32 v107, 0xffff0000, v109
	v_lshlrev_b32_e32 v108, 16, v110
	v_and_b32_e32 v109, 0xffff0000, v110
	v_lshlrev_b32_e32 v110, 16, v111
	v_and_b32_e32 v111, 0xffff0000, v111
	v_mul_f32_e32 v100, v100, v104
	v_mul_f32_e32 v101, v101, v105
	v_mul_f32_e32 v102, v102, v106
	v_mul_f32_e32 v103, v103, v107
	v_mul_f32_e32 v95, v95, v111
	v_mul_f32_e32 v104, v92, v108
	v_mul_f32_e32 v105, v93, v109
	v_mul_f32_e32 v106, v94, v110
	v_cvt_pk_bf16_f32 v92, v100, v101
	v_cvt_pk_bf16_f32 v93, v102, v103
	v_cvt_pk_bf16_f32 v94, v104, v105
	v_cvt_pk_bf16_f32 v95, v106, v95
	global_load_dwordx4 v[100:103], v[114:115], off offset:3072
	s_nop 0
	global_store_dwordx4 v[116:117], v[92:95], off offset:256
	s_waitcnt vmcnt(0)
	s_nop 0
	v_lshlrev_b32_e32 v92, 16, v100
	v_and_b32_e32 v93, 0xffff0000, v100
	v_lshlrev_b32_e32 v94, 16, v101
	v_and_b32_e32 v95, 0xffff0000, v101
	v_lshlrev_b32_e32 v100, 16, v102
	v_and_b32_e32 v101, 0xffff0000, v102
	v_lshlrev_b32_e32 v102, 16, v103
	v_and_b32_e32 v103, 0xffff0000, v103
	v_mul_f32_e32 v92, v96, v92
	v_mul_f32_e32 v93, v97, v93
	v_mul_f32_e32 v94, v98, v94
	v_mul_f32_e32 v95, v99, v95
	v_mul_f32_e32 v91, v91, v103
	v_mul_f32_e32 v96, v88, v100
	v_mul_f32_e32 v97, v89, v101
	v_mul_f32_e32 v98, v90, v102
	v_cvt_pk_bf16_f32 v88, v92, v93
	v_cvt_pk_bf16_f32 v89, v94, v95
	v_cvt_pk_bf16_f32 v90, v96, v97
	v_cvt_pk_bf16_f32 v91, v98, v91
	global_load_dwordx4 v[92:95], v[114:115], off offset:3328
	v_lshlrev_b64 v[100:101], 11, v[112:113]
	v_lshl_add_u64 v[100:101], s[0:1], 0, v[100:101]
	v_or_b32_e32 v96, 48, v146
	v_lshl_add_u64 v[100:101], v[100:101], 0, v[144:145]
	v_mad_i64_i32 v[98:99], s[18:19], v96, s41, v[148:149]
	global_store_dwordx4 v[100:101], v[88:91], off
	v_lshl_add_u64 v[98:99], v[98:99], 0, v[144:145]
	v_ashrrev_i32_e32 v97, 31, v96
	s_waitcnt vmcnt(0)
	v_lshlrev_b32_e32 v88, 16, v92
	v_and_b32_e32 v89, 0xffff0000, v92
	v_lshlrev_b32_e32 v90, 16, v93
	v_and_b32_e32 v91, 0xffff0000, v93
	v_lshlrev_b32_e32 v92, 16, v94
	v_and_b32_e32 v93, 0xffff0000, v94
	v_lshlrev_b32_e32 v94, 16, v95
	v_and_b32_e32 v95, 0xffff0000, v95
	v_mul_f32_e32 v84, v84, v88
	v_mul_f32_e32 v85, v85, v89
	v_mul_f32_e32 v86, v86, v90
	v_mul_f32_e32 v87, v87, v91
	v_mul_f32_e32 v79, v79, v95
	v_mul_f32_e32 v88, v76, v92
	v_mul_f32_e32 v89, v77, v93
	v_mul_f32_e32 v90, v78, v94
	v_cvt_pk_bf16_f32 v76, v84, v85
	v_cvt_pk_bf16_f32 v77, v86, v87
	v_cvt_pk_bf16_f32 v78, v88, v89
	v_cvt_pk_bf16_f32 v79, v90, v79
	global_load_dwordx4 v[84:87], v[98:99], off offset:3072
	s_nop 0
	global_store_dwordx4 v[100:101], v[76:79], off offset:256
	s_waitcnt vmcnt(0)
	s_nop 0
	v_lshlrev_b32_e32 v76, 16, v84
	v_and_b32_e32 v77, 0xffff0000, v84
	v_lshlrev_b32_e32 v78, 16, v85
	v_and_b32_e32 v79, 0xffff0000, v85
	v_lshlrev_b32_e32 v84, 16, v86
	v_and_b32_e32 v85, 0xffff0000, v86
	v_lshlrev_b32_e32 v86, 16, v87
	v_and_b32_e32 v87, 0xffff0000, v87
	v_mul_f32_e32 v76, v80, v76
	v_mul_f32_e32 v77, v81, v77
	v_mul_f32_e32 v78, v82, v78
	v_mul_f32_e32 v79, v83, v79
	v_mul_f32_e32 v75, v75, v87
	v_mul_f32_e32 v80, v72, v84
	v_mul_f32_e32 v81, v73, v85
	v_mul_f32_e32 v82, v74, v86
	v_cvt_pk_bf16_f32 v72, v76, v77
	v_cvt_pk_bf16_f32 v73, v78, v79
	v_cvt_pk_bf16_f32 v74, v80, v81
	v_cvt_pk_bf16_f32 v75, v82, v75
	global_load_dwordx4 v[76:79], v[98:99], off offset:3328
	v_lshlrev_b64 v[84:85], 11, v[96:97]
	v_lshl_add_u64 v[84:85], s[0:1], 0, v[84:85]
	v_add_u32_e32 v80, 0x80, v146
	v_lshl_add_u64 v[84:85], v[84:85], 0, v[144:145]
	v_mad_i64_i32 v[82:83], s[18:19], v80, s41, v[148:149]
	global_store_dwordx4 v[84:85], v[72:75], off
	v_lshl_add_u64 v[82:83], v[82:83], 0, v[144:145]
	v_ashrrev_i32_e32 v81, 31, v80
	s_waitcnt vmcnt(0)
	v_lshlrev_b32_e32 v72, 16, v76
	v_and_b32_e32 v73, 0xffff0000, v76
	v_lshlrev_b32_e32 v74, 16, v77
	v_and_b32_e32 v75, 0xffff0000, v77
	v_lshlrev_b32_e32 v76, 16, v78
	v_and_b32_e32 v77, 0xffff0000, v78
	v_lshlrev_b32_e32 v78, 16, v79
	v_and_b32_e32 v79, 0xffff0000, v79
	v_mul_f32_e32 v68, v68, v72
	v_mul_f32_e32 v69, v69, v73
	v_mul_f32_e32 v70, v70, v74
	v_mul_f32_e32 v71, v71, v75
	v_mul_f32_e32 v67, v67, v79
	v_mul_f32_e32 v72, v64, v76
	v_mul_f32_e32 v73, v65, v77
	v_mul_f32_e32 v74, v66, v78
	v_cvt_pk_bf16_f32 v64, v68, v69
	v_cvt_pk_bf16_f32 v65, v70, v71
	v_cvt_pk_bf16_f32 v66, v72, v73
	v_cvt_pk_bf16_f32 v67, v74, v67
	global_load_dwordx4 v[68:71], v[82:83], off offset:3072
	s_nop 0
	global_store_dwordx4 v[84:85], v[64:67], off offset:256
	s_waitcnt vmcnt(0)
; __device__ __forceinline__ unsigned cvt_pk_bf16(float lo, float hi) { unsigned r; asm volatile("v_cvt_pk_bf16_f32 %0, %1, %2" : "=v"(r) : "v"(lo), "v"(hi)); return r; }
; __device__ __forceinline__ float bf_lo(unsigned u) { return __uint_as_float(u << 16); }
; __device__ __forceinline__ float bf_hi(unsigned u) { return __uint_as_float(u & 0xffff0000u); }
;     __device__ __forceinline__ void operator()(const f32x4 (&acc)[2][2][4][2], const Unit& u, int wr, int wc, int fr, int fq) const {
;     ...
;             for (int m = 0; m < 4; ++m) { const size_t r = (size_t)(row0 + ai * HALF + m * 16); bf16_t* rowp = O + r * ldc + col0; const bf16_t* gp = G + r * ldg + col0;
; #pragma unroll
;                 for (int bj = 0; bj < 2; ++bj) { const u32x4 gw = *(const u32x4*)(gp + bj * HALF);
;                     f32x4 v0 = acc[ai][bj][m][0], v1 = acc[ai][bj][m][1];
;                     v0[0] *= bf_lo(gw.x); v0[1] *= bf_hi(gw.x); v0[2] *= bf_lo(gw.y); v0[3] *= bf_hi(gw.y);
;                     v1[0] *= bf_lo(gw.z); v1[1] *= bf_hi(gw.z); v1[2] *= bf_lo(gw.w); v1[3] *= bf_hi(gw.w);
;                     if (ACCUM) { const u32x4 pw = *(const u32x4*)(rowp + bj * HALF);
;                         v0[0] += bf_lo(pw.x); v0[1] += bf_hi(pw.x); v0[2] += bf_lo(pw.y); v0[3] += bf_hi(pw.y);
;                         v1[0] += bf_lo(pw.z); v1[1] += bf_hi(pw.z); v1[2] += bf_lo(pw.w); v1[3] += bf_hi(pw.w); }
;                     u32x4 w; w.x = cvt_pk_bf16(v0[0], v0[1]); w.y = cvt_pk_bf16(v0[2], v0[3]); w.z = cvt_pk_bf16(v1[0], v1[1]); w.w = cvt_pk_bf16(v1[2], v1[3]);
;                     *(u32x4*)(rowp + bj * HALF) = w; } }
	s_nop 0
	v_lshlrev_b32_e32 v64, 16, v68
	v_and_b32_e32 v65, 0xffff0000, v68
	v_lshlrev_b32_e32 v66, 16, v69
	v_and_b32_e32 v67, 0xffff0000, v69
	v_lshlrev_b32_e32 v68, 16, v70
	v_and_b32_e32 v69, 0xffff0000, v70
	v_lshlrev_b32_e32 v70, 16, v71
	v_and_b32_e32 v71, 0xffff0000, v71
	v_mul_f32_e32 v60, v60, v64
	v_mul_f32_e32 v61, v61, v65
	v_mul_f32_e32 v62, v62, v66
	v_mul_f32_e32 v63, v63, v67
	v_mul_f32_e32 v59, v59, v71
	v_mul_f32_e32 v64, v56, v68
	v_mul_f32_e32 v65, v57, v69
	v_mul_f32_e32 v66, v58, v70
	v_cvt_pk_bf16_f32 v56, v60, v61
	v_cvt_pk_bf16_f32 v57, v62, v63
	v_cvt_pk_bf16_f32 v58, v64, v65
	v_cvt_pk_bf16_f32 v59, v66, v59
	global_load_dwordx4 v[60:63], v[82:83], off offset:3328
	v_lshlrev_b64 v[68:69], 11, v[80:81]
	v_lshl_add_u64 v[68:69], s[0:1], 0, v[68:69]
	v_add_u32_e32 v64, 0x90, v146
	v_lshl_add_u64 v[68:69], v[68:69], 0, v[144:145]
	v_mad_i64_i32 v[66:67], s[18:19], v64, s41, v[148:149]
	global_store_dwordx4 v[68:69], v[56:59], off
	v_lshl_add_u64 v[66:67], v[66:67], 0, v[144:145]
	v_ashrrev_i32_e32 v65, 31, v64
	s_waitcnt vmcnt(0)
	v_lshlrev_b32_e32 v56, 16, v60
	v_and_b32_e32 v57, 0xffff0000, v60
	v_lshlrev_b32_e32 v58, 16, v61
	v_and_b32_e32 v59, 0xffff0000, v61
	v_lshlrev_b32_e32 v60, 16, v62
	v_and_b32_e32 v61, 0xffff0000, v62
	v_lshlrev_b32_e32 v62, 16, v63
	v_and_b32_e32 v63, 0xffff0000, v63
	v_mul_f32_e32 v52, v52, v56
	v_mul_f32_e32 v53, v53, v57
	v_mul_f32_e32 v54, v54, v58
	v_mul_f32_e32 v55, v55, v59
	v_mul_f32_e32 v47, v47, v63
	v_mul_f32_e32 v56, v44, v60
	v_mul_f32_e32 v57, v45, v61
	v_mul_f32_e32 v58, v46, v62
	v_cvt_pk_bf16_f32 v44, v52, v53
	v_cvt_pk_bf16_f32 v45, v54, v55
	v_cvt_pk_bf16_f32 v46, v56, v57
	v_cvt_pk_bf16_f32 v47, v58, v47
	global_load_dwordx4 v[52:55], v[66:67], off offset:3072
	s_nop 0
	global_store_dwordx4 v[68:69], v[44:47], off offset:256
	s_waitcnt vmcnt(0)
	s_nop 0
	v_lshlrev_b32_e32 v44, 16, v52
	v_and_b32_e32 v45, 0xffff0000, v52
	v_lshlrev_b32_e32 v46, 16, v53
	v_and_b32_e32 v47, 0xffff0000, v53
	v_lshlrev_b32_e32 v52, 16, v54
	v_and_b32_e32 v53, 0xffff0000, v54
	v_lshlrev_b32_e32 v54, 16, v55
	v_and_b32_e32 v55, 0xffff0000, v55
	v_mul_f32_e32 v44, v48, v44
	v_mul_f32_e32 v45, v49, v45
	v_mul_f32_e32 v46, v50, v46
	v_mul_f32_e32 v47, v51, v47
	v_mul_f32_e32 v43, v43, v55
	v_mul_f32_e32 v48, v40, v52
	v_mul_f32_e32 v49, v41, v53
	v_mul_f32_e32 v50, v42, v54
	v_cvt_pk_bf16_f32 v40, v44, v45
	v_cvt_pk_bf16_f32 v41, v46, v47
	v_cvt_pk_bf16_f32 v42, v48, v49
	v_cvt_pk_bf16_f32 v43, v50, v43
	global_load_dwordx4 v[44:47], v[66:67], off offset:3328
	v_lshlrev_b64 v[52:53], 11, v[64:65]
	v_lshl_add_u64 v[52:53], s[0:1], 0, v[52:53]
	v_add_u32_e32 v48, 0xa0, v146
	v_lshl_add_u64 v[52:53], v[52:53], 0, v[144:145]
	v_mad_i64_i32 v[50:51], s[18:19], v48, s41, v[148:149]
	global_store_dwordx4 v[52:53], v[40:43], off
	v_lshl_add_u64 v[50:51], v[50:51], 0, v[144:145]
	v_ashrrev_i32_e32 v49, 31, v48
	s_waitcnt vmcnt(0)
	v_lshlrev_b32_e32 v40, 16, v44
	v_and_b32_e32 v41, 0xffff0000, v44
	v_lshlrev_b32_e32 v42, 16, v45
	v_and_b32_e32 v43, 0xffff0000, v45
	v_lshlrev_b32_e32 v44, 16, v46
	v_and_b32_e32 v45, 0xffff0000, v46
	v_lshlrev_b32_e32 v46, 16, v47
	v_and_b32_e32 v47, 0xffff0000, v47
	v_mul_f32_e32 v36, v36, v40
	v_mul_f32_e32 v37, v37, v41
	v_mul_f32_e32 v38, v38, v42
	v_mul_f32_e32 v39, v39, v43
	v_mul_f32_e32 v31, v31, v47
	v_mul_f32_e32 v40, v28, v44
	v_mul_f32_e32 v41, v29, v45
	v_mul_f32_e32 v42, v30, v46
	v_cvt_pk_bf16_f32 v28, v36, v37
	v_cvt_pk_bf16_f32 v29, v38, v39
	v_cvt_pk_bf16_f32 v30, v40, v41
	v_cvt_pk_bf16_f32 v31, v42, v31
	global_load_dwordx4 v[36:39], v[50:51], off offset:3072
	s_nop 0
	global_store_dwordx4 v[52:53], v[28:31], off offset:256
	s_waitcnt vmcnt(0)
; __device__ __forceinline__ unsigned cvt_pk_bf16(float lo, float hi) { unsigned r; asm volatile("v_cvt_pk_bf16_f32 %0, %1, %2" : "=v"(r) : "v"(lo), "v"(hi)); return r; }
; __device__ __forceinline__ float bf_lo(unsigned u) { return __uint_as_float(u << 16); }
; __device__ __forceinline__ float bf_hi(unsigned u) { return __uint_as_float(u & 0xffff0000u); }
; #define PG8_WAIT_V(n) asm volatile("s_waitcnt vmcnt(" #n ")" ::: "memory")
;     __device__ __forceinline__ void operator()(const f32x4 (&acc)[2][2][4][2], const Unit& u, int wr, int wc, int fr, int fq) const {
;     ...
;             for (int m = 0; m < 4; ++m) { const size_t r = (size_t)(row0 + ai * HALF + m * 16); bf16_t* rowp = O + r * ldc + col0; const bf16_t* gp = G + r * ldg + col0;
; #pragma unroll
;                 for (int bj = 0; bj < 2; ++bj) { const u32x4 gw = *(const u32x4*)(gp + bj * HALF);
;                     f32x4 v0 = acc[ai][bj][m][0], v1 = acc[ai][bj][m][1];
;                     v0[0] *= bf_lo(gw.x); v0[1] *= bf_hi(gw.x); v0[2] *= bf_lo(gw.y); v0[3] *= bf_hi(gw.y);
;                     v1[0] *= bf_lo(gw.z); v1[1] *= bf_hi(gw.z); v1[2] *= bf_lo(gw.w); v1[3] *= bf_hi(gw.w);
;                     if (ACCUM) { const u32x4 pw = *(const u32x4*)(rowp + bj * HALF);
;                         v0[0] += bf_lo(pw.x); v0[1] += bf_hi(pw.x); v0[2] += bf_lo(pw.y); v0[3] += bf_hi(pw.y);
;                         v1[0] += bf_lo(pw.z); v1[1] += bf_hi(pw.z); v1[2] += bf_lo(pw.w); v1[3] += bf_hi(pw.w); }
;                     u32x4 w; w.x = cvt_pk_bf16(v0[0], v0[1]); w.y = cvt_pk_bf16(v0[2], v0[3]); w.z = cvt_pk_bf16(v1[0], v1[1]); w.w = cvt_pk_bf16(v1[2], v1[3]);
;                     *(u32x4*)(rowp + bj * HALF) = w; } }
; template <class Epi, class Sched>
; __device__ __forceinline__ void gemm_phase(PG8_LAS unsigned char* lds, const Gemm g, const Sched& S, const Epi& E) {
;     ...
;         if constexpr (!Epi::AFTER_DRAIN) { E(acc, cur, wr, wc, fr, fq); S.done(cur); }
;         if (!has_next) break;
; #pragma unroll
;         for (int a = 0; a < 2; ++a)
; #pragma unroll
;             for (int b = 0; b < 2; ++b)
; #pragma unroll
;                 for (int m = 0; m < 4; ++m)
; #pragma unroll
;                     for (int n = 0; n < 2; ++n) acc[a][b][m][n] = (f32x4){0.f, 0.f, 0.f, 0.f};
;         cur = nxt; cA = nA; cB = nB; ++ui;
;     }
;     PG8_WAIT_V(0);
;     if (wr == 0) PG8_BAR;
;     PG8_BAR;
	s_nop 0
	v_lshlrev_b32_e32 v28, 16, v36
	v_and_b32_e32 v29, 0xffff0000, v36
	v_lshlrev_b32_e32 v30, 16, v37
	v_and_b32_e32 v31, 0xffff0000, v37
	v_lshlrev_b32_e32 v36, 16, v38
	v_and_b32_e32 v37, 0xffff0000, v38
	v_lshlrev_b32_e32 v38, 16, v39
	v_and_b32_e32 v39, 0xffff0000, v39
	v_mul_f32_e32 v28, v32, v28
	v_mul_f32_e32 v29, v33, v29
	v_mul_f32_e32 v30, v34, v30
	v_mul_f32_e32 v31, v35, v31
	v_mul_f32_e32 v27, v27, v39
	v_mul_f32_e32 v32, v24, v36
	v_mul_f32_e32 v33, v25, v37
	v_mul_f32_e32 v34, v26, v38
	v_cvt_pk_bf16_f32 v24, v28, v29
	v_cvt_pk_bf16_f32 v25, v30, v31
	v_cvt_pk_bf16_f32 v26, v32, v33
	v_cvt_pk_bf16_f32 v27, v34, v27
	global_load_dwordx4 v[28:31], v[50:51], off offset:3328
	v_lshlrev_b64 v[36:37], 11, v[48:49]
	v_lshl_add_u64 v[36:37], s[0:1], 0, v[36:37]
	v_add_u32_e32 v32, 0xb0, v146
	v_lshl_add_u64 v[36:37], v[36:37], 0, v[144:145]
	v_mad_i64_i32 v[34:35], s[18:19], v32, s41, v[148:149]
	global_store_dwordx4 v[36:37], v[24:27], off
	v_lshl_add_u64 v[34:35], v[34:35], 0, v[144:145]
	v_ashrrev_i32_e32 v33, 31, v32
	s_mov_b64 s[18:19], s[12:13]
	s_waitcnt vmcnt(0)
	v_lshlrev_b32_e32 v24, 16, v28
	v_and_b32_e32 v25, 0xffff0000, v28
	v_lshlrev_b32_e32 v26, 16, v29
	v_and_b32_e32 v27, 0xffff0000, v29
	v_lshlrev_b32_e32 v28, 16, v30
	v_and_b32_e32 v29, 0xffff0000, v30
	v_lshlrev_b32_e32 v30, 16, v31
	v_and_b32_e32 v31, 0xffff0000, v31
	v_mul_f32_e32 v20, v20, v24
	v_mul_f32_e32 v21, v21, v25
	v_mul_f32_e32 v22, v22, v26
	v_mul_f32_e32 v23, v23, v27
	v_mul_f32_e32 v15, v15, v31
	v_mul_f32_e32 v24, v12, v28
	v_mul_f32_e32 v25, v13, v29
	v_mul_f32_e32 v26, v14, v30
	v_cvt_pk_bf16_f32 v12, v20, v21
	v_cvt_pk_bf16_f32 v13, v22, v23
	v_cvt_pk_bf16_f32 v14, v24, v25
	v_cvt_pk_bf16_f32 v15, v26, v15
	global_load_dwordx4 v[20:23], v[34:35], off offset:3072
	s_nop 0
	global_store_dwordx4 v[36:37], v[12:15], off offset:256
	s_waitcnt vmcnt(0)
	s_nop 0
	v_lshlrev_b32_e32 v12, 16, v20
	v_and_b32_e32 v13, 0xffff0000, v20
	v_lshlrev_b32_e32 v14, 16, v21
	v_and_b32_e32 v15, 0xffff0000, v21
	v_lshlrev_b32_e32 v20, 16, v22
	v_and_b32_e32 v21, 0xffff0000, v22
	v_lshlrev_b32_e32 v22, 16, v23
	v_and_b32_e32 v23, 0xffff0000, v23
	v_mul_f32_e32 v12, v16, v12
	v_mul_f32_e32 v13, v17, v13
	v_mul_f32_e32 v14, v18, v14
	v_mul_f32_e32 v15, v19, v15
	v_mul_f32_e32 v11, v11, v23
	v_mul_f32_e32 v16, v8, v20
	v_mul_f32_e32 v17, v9, v21
	v_mul_f32_e32 v18, v10, v22
	v_cvt_pk_bf16_f32 v8, v12, v13
	v_cvt_pk_bf16_f32 v9, v14, v15
	v_cvt_pk_bf16_f32 v10, v16, v17
	v_cvt_pk_bf16_f32 v11, v18, v11
	global_load_dwordx4 v[12:15], v[34:35], off offset:3328
	v_lshlrev_b64 v[16:17], 11, v[32:33]
	v_lshl_add_u64 v[16:17], s[0:1], 0, v[16:17]
	v_lshl_add_u64 v[16:17], v[16:17], 0, v[144:145]
	global_store_dwordx4 v[16:17], v[8:11], off
	s_waitcnt vmcnt(0)
	s_nop 0
	v_lshlrev_b32_e32 v8, 16, v12
	v_and_b32_e32 v9, 0xffff0000, v12
	v_lshlrev_b32_e32 v10, 16, v13
	v_and_b32_e32 v11, 0xffff0000, v13
	v_lshlrev_b32_e32 v12, 16, v14
	v_and_b32_e32 v13, 0xffff0000, v14
	v_lshlrev_b32_e32 v14, 16, v15
	v_and_b32_e32 v15, 0xffff0000, v15
	v_mul_f32_e32 v3, v3, v15
	v_mul_f32_e32 v4, v4, v8
	v_mul_f32_e32 v5, v5, v9
	v_mul_f32_e32 v6, v6, v10
	v_mul_f32_e32 v7, v7, v11
	v_mul_f32_e32 v8, v0, v12
	v_mul_f32_e32 v9, v1, v13
	v_mul_f32_e32 v10, v2, v14
	v_cvt_pk_bf16_f32 v0, v4, v5
	v_cvt_pk_bf16_f32 v1, v6, v7
	v_cvt_pk_bf16_f32 v2, v8, v9
	v_cvt_pk_bf16_f32 v3, v10, v3
	global_store_dwordx4 v[16:17], v[0:3], off offset:256
	s_cbranch_vccz .LBB0_984
	s_waitcnt vmcnt(0)
	s_cmpk_gt_u32 s25, 0xff
	s_cbranch_scc1 .LBB0_995
	s_barrier

; #define PG8_STAGE(bufoff, gbase, voff) do { _Pragma("unroll") for (int _i = 0; _i < 2; ++_i) \
;         __builtin_amdgcn_global_load_lds((const unsigned*)((const char*)(gbase) + (voff)[_i]), (PG8_LAS unsigned*)(lds + (bufoff) + ldsw + _i * 8192), 16, 0, 0); } while (0)
; #define PG8_WAIT_V(n) asm volatile("s_waitcnt vmcnt(" #n ")" ::: "memory")
; template <class Epi, class Sched>
; __device__ __forceinline__ void gemm_phase(PG8_LAS unsigned char* lds, const Gemm g, const Sched& S, const Epi& E) {
;     ...
;         const bool has_next = S.next(ui + 1, nxt);
;         const char* nA = has_next ? (const char*)g.A + (size_t)nxt.pm * tstep : cA; const char* nB = has_next ? (const char*)g.Bt + (size_t)nxt.pn * tstep : cB;
;         for (int t = 0; t < nt; t += 2) {
;             const bool last = (t == nt - 2);
;             const char* a1 = cA + (size_t)(t + 1) * kstep;
;             const char* a2 = last ? nA : cA + (size_t)(t + 2) * kstep; const char* b2 = last ? nB : cB + (size_t)(t + 2) * kstep;
;             const char* a3 = a2 + kstep; const char* b3 = b2 + kstep;
;             if (last && has_next) S.a_ready(nxt);
;             PG8_LDB(B0, 0, 0); PG8_SCHED; PG8_LDA(At, 0, 0); PG8_STAGE(PG8_SA(1, 1), a1 + hstep, voffA);
;             PG8_WAIT_L(8); PG8_BAR; PG8_WAIT_L(0); PG8_MMA(0, 0, At, B0); PG8_BAR; PG8_SCHED;
;             PG8_LDB(B1, 0, 1); PG8_STAGE(PG8_SB(0, 0), b2, voffB);
;             PG8_BAR; PG8_WAIT_L(0); PG8_MMA(0, 1, At, B1); PG8_BAR;
;             PG8_LDA(At, 0, 1); PG8_STAGE(PG8_SA(0, 0), a2, voffA);
;             PG8_BAR; PG8_WAIT_L(0); PG8_MMA(1, 0, At, B0); PG8_BAR; PG8_SCHED;
;             PG8_STAGE(PG8_SB(0, 1), b2 + hstep, voffB);
;             PG8_WAIT_V(6); PG8_BAR; PG8_MMA(1, 1, At, B1); PG8_BAR;
;             PG8_LDB(B0, 1, 0); PG8_SCHED; PG8_LDA(At, 1, 0); PG8_STAGE(PG8_SA(0, 1), a2 + hstep, voffA);
;             PG8_WAIT_L(8); PG8_BAR; PG8_WAIT_L(0); PG8_MMA(0, 0, At, B0); PG8_BAR; PG8_SCHED;
;             PG8_LDB(B1, 1, 1); PG8_STAGE(PG8_SB(1, 0), b3, voffB);
;             PG8_BAR; PG8_WAIT_L(0); PG8_MMA(0, 1, At, B1); PG8_BAR;
;             PG8_LDA(At, 1, 1); PG8_STAGE(PG8_SA(1, 0), a3, voffA);
;             PG8_BAR; PG8_WAIT_L(0); PG8_MMA(1, 0, At, B0); PG8_BAR; PG8_SCHED;
;             PG8_STAGE(PG8_SB(1, 1), b3 + hstep, voffB);
;             PG8_WAIT_V(6); PG8_BAR; PG8_MMA(1, 1, At, B1); PG8_BAR;
.LBB0_1010:
	s_ashr_i32 s11, s10, 31
	v_cmp_lt_i64_e32 vcc, s[12:13], v[140:141]
	s_lshl_b64 s[12:13], s[10:11], 19
	s_add_u32 s12, s27, s12
	s_addc_u32 s13, s28, s13
	s_and_b64 s[14:15], vcc, exec
	s_cselect_b32 s11, s13, s19
	s_cselect_b32 s43, s12, s18
	s_ashr_i32 s9, s8, 31
	s_lshl_b64 s[14:15], s[8:9], 19
	s_add_u32 s14, s94, s14
	s_addc_u32 s15, s95, s15
	s_and_b64 s[22:23], vcc, exec
	s_cselect_b32 s9, s15, s21
	s_cselect_b32 s44, s14, s20
	s_add_u32 s18, s18, 0x40080
	s_addc_u32 s19, s19, 0
	s_add_u32 s45, s20, 0x100
	s_addc_u32 s46, s21, 0
	s_mov_b32 s47, -2
	ds_read_b128 v[144:147], v153
	ds_read_b128 v[156:159], v153 offset:1024
	ds_read_b128 v[160:163], v153 offset:2048
	ds_read_b128 v[164:167], v153 offset:3072
	s_add_u32 s20, s18, 0xfffc0080
	s_addc_u32 s21, s19, -1
	s_cmp_eq_u32 s47, 12
	s_cselect_b32 s23, s11, s21
	s_cselect_b32 s22, s43, s20
	s_cselect_b32 s21, s9, s46
	s_cselect_b32 s20, s44, s45
	ds_read_b128 v[168:171], v154
	ds_read_b128 v[172:175], v154 offset:1024
	ds_read_b128 v[182:185], v154 offset:2048
	ds_read_b128 v[190:193], v154 offset:3072
	ds_read_b128 v[194:197], v154 offset:4096
	ds_read_b128 v[198:201], v154 offset:5120
	ds_read_b128 v[202:205], v154 offset:6144
	ds_read_b128 v[206:209], v154 offset:7168
	s_waitcnt lgkmcnt(8)
	ds_read_b128 v[210:213], v155
	ds_read_b128 v[214:217], v155 offset:1024
	ds_read_b128 v[218:221], v155 offset:2048
	ds_read_b128 v[222:225], v155 offset:3072
	s_add_i32 m0, s17, 0xc000
	s_nop 0
	global_load_lds_dwordx4 v136, s[18:19]
	s_nop 1
	s_add_i32 m0, s17, 0xe000
	s_nop 0
	global_load_lds_dwordx4 v138, s[18:19]
	s_waitcnt vmcnt(8) lgkmcnt(0)
	s_barrier
	v_mfma_f32_16x16x32_bf16 v[124:127], v[144:147], v[168:171], 0
	v_mfma_f32_16x16x32_bf16 v[120:123], v[160:163], v[168:171], 0
	v_mfma_f32_16x16x32_bf16 v[108:111], v[144:147], v[182:185], 0
	v_mfma_f32_16x16x32_bf16 v[104:107], v[160:163], v[182:185], 0
	v_mfma_f32_16x16x32_bf16 v[92:95], v[144:147], v[194:197], 0
	v_mfma_f32_16x16x32_bf16 v[88:91], v[160:163], v[194:197], 0
	v_mfma_f32_16x16x32_bf16 v[76:79], v[144:147], v[202:205], 0
	v_mfma_f32_16x16x32_bf16 v[72:75], v[160:163], v[202:205], 0
	v_mfma_f32_16x16x32_bf16 v[124:127], v[156:159], v[172:175], v[124:127]
	v_mfma_f32_16x16x32_bf16 v[120:123], v[164:167], v[172:175], v[120:123]
	v_mfma_f32_16x16x32_bf16 v[108:111], v[156:159], v[190:193], v[108:111]
	v_mfma_f32_16x16x32_bf16 v[104:107], v[164:167], v[190:193], v[104:107]
	v_mfma_f32_16x16x32_bf16 v[92:95], v[156:159], v[198:201], v[92:95]
	v_mfma_f32_16x16x32_bf16 v[88:91], v[164:167], v[198:201], v[88:91]
	v_mfma_f32_16x16x32_bf16 v[76:79], v[156:159], v[206:209], v[76:79]
	v_mfma_f32_16x16x32_bf16 v[72:75], v[164:167], v[206:209], v[72:75]
	v_mfma_f32_16x16x32_bf16 v[116:119], v[210:213], v[168:171], 0
	v_mfma_f32_16x16x32_bf16 v[112:115], v[218:221], v[168:171], 0
	v_mfma_f32_16x16x32_bf16 v[100:103], v[210:213], v[182:185], 0
	v_mfma_f32_16x16x32_bf16 v[96:99], v[218:221], v[182:185], 0
	v_mfma_f32_16x16x32_bf16 v[84:87], v[210:213], v[194:197], 0
	v_mfma_f32_16x16x32_bf16 v[80:83], v[218:221], v[194:197], 0
	v_mfma_f32_16x16x32_bf16 v[68:71], v[210:213], v[202:205], 0
	v_mfma_f32_16x16x32_bf16 v[64:67], v[218:221], v[202:205], 0
	v_mfma_f32_16x16x32_bf16 v[116:119], v[214:217], v[172:175], v[116:119]
	v_mfma_f32_16x16x32_bf16 v[112:115], v[222:225], v[172:175], v[112:115]
	v_mfma_f32_16x16x32_bf16 v[100:103], v[214:217], v[190:193], v[100:103]
	v_mfma_f32_16x16x32_bf16 v[96:99], v[222:225], v[190:193], v[96:99]
	v_mfma_f32_16x16x32_bf16 v[84:87], v[214:217], v[198:201], v[84:87]
	v_mfma_f32_16x16x32_bf16 v[80:83], v[222:225], v[198:201], v[80:83]
	v_mfma_f32_16x16x32_bf16 v[68:71], v[214:217], v[206:209], v[68:71]
	v_mfma_f32_16x16x32_bf16 v[64:67], v[222:225], v[206:209], v[64:67]
	s_barrier
	ds_read_b128 v[168:171], v154 offset:16384
	ds_read_b128 v[172:175], v154 offset:17408
	ds_read_b128 v[182:185], v154 offset:18432
	ds_read_b128 v[190:193], v154 offset:19456
	ds_read_b128 v[194:197], v154 offset:20480
	ds_read_b128 v[198:201], v154 offset:21504
	ds_read_b128 v[202:205], v154 offset:22528
	ds_read_b128 v[206:209], v154 offset:23552
	s_add_i32 s48, s39, s29
	s_add_u32 s98, s20, s6
	s_addc_u32 s99, s21, s7
	s_mov_b32 m0, s48
	s_nop 0
	global_load_lds_dwordx4 v130, s[20:21]
	s_nop 1
	s_add_i32 m0, s48, 0x2000
	s_nop 0
	global_load_lds_dwordx4 v134, s[20:21]
	s_nop 1
	s_mov_b32 m0, s17
	s_add_u32 s100, s22, s6
	s_addc_u32 s101, s23, s7
	global_load_lds_dwordx4 v128, s[22:23]
	s_nop 1
	s_mov_b32 m0, s30
	s_nop 0
	global_load_lds_dwordx4 v132, s[22:23]
	s_add_u32 s48, s20, 0x40000
	s_addc_u32 s49, s21, 0
	s_add_i32 s50, s40, s29
	s_mov_b32 m0, s50
	s_nop 0
	global_load_lds_dwordx4 v130, s[48:49]
	s_nop 1
	s_add_i32 m0, s50, 0x2000
	s_nop 0
	global_load_lds_dwordx4 v134, s[48:49]
	s_waitcnt vmcnt(8) lgkmcnt(0)
	s_barrier
; #define PG8_STAGE(bufoff, gbase, voff) do { _Pragma("unroll") for (int _i = 0; _i < 2; ++_i) \
;         __builtin_amdgcn_global_load_lds((const unsigned*)((const char*)(gbase) + (voff)[_i]), (PG8_LAS unsigned*)(lds + (bufoff) + ldsw + _i * 8192), 16, 0, 0); } while (0)
; #define PG8_LDA(dst, b, h) do { _Pragma("unroll") for (int m = 0; m < 4; ++m) _Pragma("unroll") for (int k = 0; k < 2; ++k) dst[m][k] = *(const PG8_LAS bf16x8*)(lds + PG8_SA(b, h) + aoff + m * 2048 + k * 1024); } while (0)
; #define PG8_LDB(dst, b, h) do { _Pragma("unroll") for (int n = 0; n < 2; ++n) _Pragma("unroll") for (int k = 0; k < 2; ++k) dst[n][k] = *(const PG8_LAS bf16x8*)(lds + PG8_SB(b, h) + boff + n * 2048 + k * 1024); } while (0)
; #define PG8_WAIT_V(n) asm volatile("s_waitcnt vmcnt(" #n ")" ::: "memory")
; #define PG8_WAIT_L(n) asm volatile("s_waitcnt lgkmcnt(" #n ")" ::: "memory")
; #define PG8_BAR __builtin_amdgcn_s_barrier()
; #define PG8_SCHED __builtin_amdgcn_sched_barrier(0)
; template <class Epi, class Sched>
; __device__ __forceinline__ void gemm_phase(PG8_LAS unsigned char* lds, const Gemm g, const Sched& S, const Epi& E) {
;     ...
;             PG8_LDB(B0, 0, 0); PG8_SCHED; PG8_LDA(At, 0, 0); PG8_STAGE(PG8_SA(1, 1), a1 + hstep, voffA);
;             PG8_WAIT_L(8); PG8_BAR; PG8_WAIT_L(0); PG8_MMA(0, 0, At, B0); PG8_BAR; PG8_SCHED;
;             PG8_LDB(B1, 0, 1); PG8_STAGE(PG8_SB(0, 0), b2, voffB);
;             PG8_BAR; PG8_WAIT_L(0); PG8_MMA(0, 1, At, B1); PG8_BAR;
;             PG8_LDA(At, 0, 1); PG8_STAGE(PG8_SA(0, 0), a2, voffA);
;             PG8_BAR; PG8_WAIT_L(0); PG8_MMA(1, 0, At, B0); PG8_BAR; PG8_SCHED;
;             PG8_STAGE(PG8_SB(0, 1), b2 + hstep, voffB);
;             PG8_WAIT_V(6); PG8_BAR; PG8_MMA(1, 1, At, B1); PG8_BAR;
;             PG8_LDB(B0, 1, 0); PG8_SCHED; PG8_LDA(At, 1, 0); PG8_STAGE(PG8_SA(0, 1), a2 + hstep, voffA);
;             PG8_WAIT_L(8); PG8_BAR; PG8_WAIT_L(0); PG8_MMA(0, 0, At, B0); PG8_BAR; PG8_SCHED;
;             PG8_LDB(B1, 1, 1); PG8_STAGE(PG8_SB(1, 0), b3, voffB);
;             PG8_BAR; PG8_WAIT_L(0); PG8_MMA(0, 1, At, B1); PG8_BAR;
;             PG8_LDA(At, 1, 1); PG8_STAGE(PG8_SA(1, 0), a3, voffA);
;             PG8_BAR; PG8_WAIT_L(0); PG8_MMA(1, 0, At, B0); PG8_BAR; PG8_SCHED;
;             PG8_STAGE(PG8_SB(1, 1), b3 + hstep, voffB);
;             PG8_WAIT_V(6); PG8_BAR; PG8_MMA(1, 1, At, B1); PG8_BAR;
	v_mfma_f32_16x16x32_bf16 v[60:63], v[144:147], v[168:171], 0
	v_mfma_f32_16x16x32_bf16 v[56:59], v[160:163], v[168:171], 0
	v_mfma_f32_16x16x32_bf16 v[44:47], v[144:147], v[182:185], 0
	v_mfma_f32_16x16x32_bf16 v[40:43], v[160:163], v[182:185], 0
	v_mfma_f32_16x16x32_bf16 v[28:31], v[144:147], v[194:197], 0
	v_mfma_f32_16x16x32_bf16 v[24:27], v[160:163], v[194:197], 0
	v_mfma_f32_16x16x32_bf16 v[12:15], v[144:147], v[202:205], 0
	v_mfma_f32_16x16x32_bf16 v[8:11], v[160:163], v[202:205], 0
	v_mfma_f32_16x16x32_bf16 v[60:63], v[156:159], v[172:175], v[60:63]
	v_mfma_f32_16x16x32_bf16 v[56:59], v[164:167], v[172:175], v[56:59]
	v_mfma_f32_16x16x32_bf16 v[44:47], v[156:159], v[190:193], v[44:47]
	v_mfma_f32_16x16x32_bf16 v[40:43], v[164:167], v[190:193], v[40:43]
	v_mfma_f32_16x16x32_bf16 v[28:31], v[156:159], v[198:201], v[28:31]
	v_mfma_f32_16x16x32_bf16 v[24:27], v[164:167], v[198:201], v[24:27]
	v_mfma_f32_16x16x32_bf16 v[12:15], v[156:159], v[206:209], v[12:15]
	v_mfma_f32_16x16x32_bf16 v[8:11], v[164:167], v[206:209], v[8:11]
	v_mfma_f32_16x16x32_bf16 v[52:55], v[210:213], v[168:171], 0
	v_mfma_f32_16x16x32_bf16 v[48:51], v[218:221], v[168:171], 0
	v_mfma_f32_16x16x32_bf16 v[36:39], v[210:213], v[182:185], 0
	v_mfma_f32_16x16x32_bf16 v[32:35], v[218:221], v[182:185], 0
	v_mfma_f32_16x16x32_bf16 v[20:23], v[210:213], v[194:197], 0
	v_mfma_f32_16x16x32_bf16 v[16:19], v[218:221], v[194:197], 0
	v_mfma_f32_16x16x32_bf16 v[4:7], v[210:213], v[202:205], 0
	v_mfma_f32_16x16x32_bf16 v[0:3], v[218:221], v[202:205], 0
	v_mfma_f32_16x16x32_bf16 v[52:55], v[214:217], v[172:175], v[52:55]
	v_mfma_f32_16x16x32_bf16 v[48:51], v[222:225], v[172:175], v[48:51]
	v_mfma_f32_16x16x32_bf16 v[36:39], v[214:217], v[190:193], v[36:39]
	v_mfma_f32_16x16x32_bf16 v[32:35], v[222:225], v[190:193], v[32:35]
	v_mfma_f32_16x16x32_bf16 v[20:23], v[214:217], v[198:201], v[20:23]
	v_mfma_f32_16x16x32_bf16 v[16:19], v[222:225], v[198:201], v[16:19]
	v_mfma_f32_16x16x32_bf16 v[4:7], v[214:217], v[206:209], v[4:7]
	v_mfma_f32_16x16x32_bf16 v[0:3], v[222:225], v[206:209], v[0:3]
	s_barrier
	s_add_i32 s48, 0, 0x18000
	v_add_u32_e32 v164, s48, v151
	ds_read_b128 v[144:147], v164
	ds_read_b128 v[156:159], v164 offset:1024
	ds_read_b128 v[160:163], v164 offset:2048
	ds_read_b128 v[164:167], v164 offset:3072
	ds_read_b128 v[168:171], v154 offset:32768
	ds_read_b128 v[172:175], v154 offset:33792
	ds_read_b128 v[182:185], v154 offset:34816
	ds_read_b128 v[190:193], v154 offset:35840
	ds_read_b128 v[194:197], v154 offset:36864
	ds_read_b128 v[198:201], v154 offset:37888
	ds_read_b128 v[202:205], v154 offset:38912
	ds_read_b128 v[206:209], v154 offset:39936
	v_add_u32_e32 v179, 0x1c000, v151
	s_waitcnt lgkmcnt(8)
	ds_read_b128 v[210:213], v179
	ds_read_b128 v[214:217], v179 offset:1024
	ds_read_b128 v[218:221], v179 offset:2048
	ds_read_b128 v[222:225], v179 offset:3072
	s_add_u32 s22, s22, 0x40000
	s_addc_u32 s23, s23, 0
	s_mov_b32 m0, s31
	s_nop 0
	global_load_lds_dwordx4 v128, s[22:23]
	s_nop 1
	s_mov_b32 m0, s34
	s_nop 0
	global_load_lds_dwordx4 v132, s[22:23]
	s_add_i32 s22, 0, 0x1c000
	s_waitcnt vmcnt(8) lgkmcnt(0)
	s_barrier
	v_mfma_f32_16x16x32_bf16 v[124:127], v[144:147], v[168:171], v[124:127]
	v_mfma_f32_16x16x32_bf16 v[120:123], v[160:163], v[168:171], v[120:123]
	v_mfma_f32_16x16x32_bf16 v[108:111], v[144:147], v[182:185], v[108:111]
	v_mfma_f32_16x16x32_bf16 v[104:107], v[160:163], v[182:185], v[104:107]
	v_mfma_f32_16x16x32_bf16 v[92:95], v[144:147], v[194:197], v[92:95]
	v_mfma_f32_16x16x32_bf16 v[88:91], v[160:163], v[194:197], v[88:91]
	v_mfma_f32_16x16x32_bf16 v[76:79], v[144:147], v[202:205], v[76:79]
	v_mfma_f32_16x16x32_bf16 v[72:75], v[160:163], v[202:205], v[72:75]
	v_mfma_f32_16x16x32_bf16 v[124:127], v[156:159], v[172:175], v[124:127]
	v_mfma_f32_16x16x32_bf16 v[120:123], v[164:167], v[172:175], v[120:123]
	v_mfma_f32_16x16x32_bf16 v[108:111], v[156:159], v[190:193], v[108:111]
	v_mfma_f32_16x16x32_bf16 v[104:107], v[164:167], v[190:193], v[104:107]
	v_mfma_f32_16x16x32_bf16 v[92:95], v[156:159], v[198:201], v[92:95]
	v_mfma_f32_16x16x32_bf16 v[88:91], v[164:167], v[198:201], v[88:91]
	v_mfma_f32_16x16x32_bf16 v[76:79], v[156:159], v[206:209], v[76:79]
	v_mfma_f32_16x16x32_bf16 v[72:75], v[164:167], v[206:209], v[72:75]
	v_mfma_f32_16x16x32_bf16 v[116:119], v[210:213], v[168:171], v[116:119]
	v_mfma_f32_16x16x32_bf16 v[112:115], v[218:221], v[168:171], v[112:115]
	v_mfma_f32_16x16x32_bf16 v[100:103], v[210:213], v[182:185], v[100:103]
	v_mfma_f32_16x16x32_bf16 v[96:99], v[218:221], v[182:185], v[96:99]
	v_mfma_f32_16x16x32_bf16 v[84:87], v[210:213], v[194:197], v[84:87]
	v_mfma_f32_16x16x32_bf16 v[80:83], v[218:221], v[194:197], v[80:83]
	v_mfma_f32_16x16x32_bf16 v[68:71], v[210:213], v[202:205], v[68:71]
	v_mfma_f32_16x16x32_bf16 v[64:67], v[218:221], v[202:205], v[64:67]
	v_mfma_f32_16x16x32_bf16 v[116:119], v[214:217], v[172:175], v[116:119]
	v_mfma_f32_16x16x32_bf16 v[112:115], v[222:225], v[172:175], v[112:115]
	v_mfma_f32_16x16x32_bf16 v[100:103], v[214:217], v[190:193], v[100:103]
	v_mfma_f32_16x16x32_bf16 v[96:99], v[222:225], v[190:193], v[96:99]
	v_mfma_f32_16x16x32_bf16 v[84:87], v[214:217], v[198:201], v[84:87]
	v_mfma_f32_16x16x32_bf16 v[80:83], v[222:225], v[198:201], v[80:83]
	v_mfma_f32_16x16x32_bf16 v[68:71], v[214:217], v[206:209], v[68:71]
	v_mfma_f32_16x16x32_bf16 v[64:67], v[222:225], v[206:209], v[64:67]
	s_barrier
; #define PG8_STAGE(bufoff, gbase, voff) do { _Pragma("unroll") for (int _i = 0; _i < 2; ++_i) \
;         __builtin_amdgcn_global_load_lds((const unsigned*)((const char*)(gbase) + (voff)[_i]), (PG8_LAS unsigned*)(lds + (bufoff) + ldsw + _i * 8192), 16, 0, 0); } while (0)
; #define PG8_LDA(dst, b, h) do { _Pragma("unroll") for (int m = 0; m < 4; ++m) _Pragma("unroll") for (int k = 0; k < 2; ++k) dst[m][k] = *(const PG8_LAS bf16x8*)(lds + PG8_SA(b, h) + aoff + m * 2048 + k * 1024); } while (0)
; #define PG8_LDB(dst, b, h) do { _Pragma("unroll") for (int n = 0; n < 2; ++n) _Pragma("unroll") for (int k = 0; k < 2; ++k) dst[n][k] = *(const PG8_LAS bf16x8*)(lds + PG8_SB(b, h) + boff + n * 2048 + k * 1024); } while (0)
; #define PG8_WAIT_V(n) asm volatile("s_waitcnt vmcnt(" #n ")" ::: "memory")
; #define PG8_WAIT_L(n) asm volatile("s_waitcnt lgkmcnt(" #n ")" ::: "memory")
; #define PG8_BAR __builtin_amdgcn_s_barrier()
; #define PG8_SCHED __builtin_amdgcn_sched_barrier(0)
; template <class Epi, class Sched>
; __device__ __forceinline__ void gemm_phase(PG8_LAS unsigned char* lds, const Gemm g, const Sched& S, const Epi& E) {
;     ...
;             PG8_LDB(B0, 0, 0); PG8_SCHED; PG8_LDA(At, 0, 0); PG8_STAGE(PG8_SA(1, 1), a1 + hstep, voffA);
;             PG8_WAIT_L(8); PG8_BAR; PG8_WAIT_L(0); PG8_MMA(0, 0, At, B0); PG8_BAR; PG8_SCHED;
;             PG8_LDB(B1, 0, 1); PG8_STAGE(PG8_SB(0, 0), b2, voffB);
;             PG8_BAR; PG8_WAIT_L(0); PG8_MMA(0, 1, At, B1); PG8_BAR;
;             PG8_LDA(At, 0, 1); PG8_STAGE(PG8_SA(0, 0), a2, voffA);
;             PG8_BAR; PG8_WAIT_L(0); PG8_MMA(1, 0, At, B0); PG8_BAR; PG8_SCHED;
;             PG8_STAGE(PG8_SB(0, 1), b2 + hstep, voffB);
;             PG8_WAIT_V(6); PG8_BAR; PG8_MMA(1, 1, At, B1); PG8_BAR;
;             PG8_LDB(B0, 1, 0); PG8_SCHED; PG8_LDA(At, 1, 0); PG8_STAGE(PG8_SA(0, 1), a2 + hstep, voffA);
;             PG8_WAIT_L(8); PG8_BAR; PG8_WAIT_L(0); PG8_MMA(0, 0, At, B0); PG8_BAR; PG8_SCHED;
;             PG8_LDB(B1, 1, 1); PG8_STAGE(PG8_SB(1, 0), b3, voffB);
;             PG8_BAR; PG8_WAIT_L(0); PG8_MMA(0, 1, At, B1); PG8_BAR;
;             PG8_LDA(At, 1, 1); PG8_STAGE(PG8_SA(1, 0), a3, voffA);
;             PG8_BAR; PG8_WAIT_L(0); PG8_MMA(1, 0, At, B0); PG8_BAR; PG8_SCHED;
;             PG8_STAGE(PG8_SB(1, 1), b3 + hstep, voffB);
;             PG8_WAIT_V(6); PG8_BAR; PG8_MMA(1, 1, At, B1); PG8_BAR;
	ds_read_b128 v[168:171], v154 offset:49152
	ds_read_b128 v[172:175], v154 offset:50176
	ds_read_b128 v[182:185], v154 offset:51200
	ds_read_b128 v[190:193], v154 offset:52224
	ds_read_b128 v[194:197], v154 offset:53248
	ds_read_b128 v[198:201], v154 offset:54272
	ds_read_b128 v[202:205], v154 offset:55296
	ds_read_b128 v[206:209], v154 offset:56320
	s_add_i32 s23, s48, s29
	s_mov_b32 m0, s23
	s_nop 0
	global_load_lds_dwordx4 v130, s[98:99]
	s_nop 1
	s_add_i32 m0, s23, 0x2000
	s_nop 0
	global_load_lds_dwordx4 v134, s[98:99]
	s_nop 1
	s_mov_b32 m0, s36
	s_nop 0
	global_load_lds_dwordx4 v128, s[100:101]
	s_nop 1
	s_mov_b32 m0, s37
	s_nop 0
	global_load_lds_dwordx4 v132, s[100:101]
	s_add_u32 s20, s20, 0x40080
	s_addc_u32 s21, s21, 0
	s_add_i32 s22, s22, s29
	s_mov_b32 m0, s22
	s_nop 0
	global_load_lds_dwordx4 v130, s[20:21]
	s_nop 1
	s_add_i32 m0, s22, 0x2000
	s_nop 0
	global_load_lds_dwordx4 v134, s[20:21]
	s_waitcnt vmcnt(8) lgkmcnt(0)
	s_barrier
	v_mfma_f32_16x16x32_bf16 v[60:63], v[144:147], v[168:171], v[60:63]
	v_mfma_f32_16x16x32_bf16 v[56:59], v[160:163], v[168:171], v[56:59]
	v_mfma_f32_16x16x32_bf16 v[44:47], v[144:147], v[182:185], v[44:47]
	v_mfma_f32_16x16x32_bf16 v[40:43], v[160:163], v[182:185], v[40:43]
	v_mfma_f32_16x16x32_bf16 v[28:31], v[144:147], v[194:197], v[28:31]
	v_mfma_f32_16x16x32_bf16 v[24:27], v[160:163], v[194:197], v[24:27]
	v_mfma_f32_16x16x32_bf16 v[12:15], v[144:147], v[202:205], v[12:15]
	v_mfma_f32_16x16x32_bf16 v[8:11], v[160:163], v[202:205], v[8:11]
	v_mfma_f32_16x16x32_bf16 v[60:63], v[156:159], v[172:175], v[60:63]
	v_mfma_f32_16x16x32_bf16 v[56:59], v[164:167], v[172:175], v[56:59]
	v_mfma_f32_16x16x32_bf16 v[44:47], v[156:159], v[190:193], v[44:47]
	v_mfma_f32_16x16x32_bf16 v[40:43], v[164:167], v[190:193], v[40:43]
	v_mfma_f32_16x16x32_bf16 v[28:31], v[156:159], v[198:201], v[28:31]
	v_mfma_f32_16x16x32_bf16 v[24:27], v[164:167], v[198:201], v[24:27]
	v_mfma_f32_16x16x32_bf16 v[12:15], v[156:159], v[206:209], v[12:15]
	v_mfma_f32_16x16x32_bf16 v[8:11], v[164:167], v[206:209], v[8:11]
	v_mfma_f32_16x16x32_bf16 v[52:55], v[210:213], v[168:171], v[52:55]
	v_mfma_f32_16x16x32_bf16 v[48:51], v[218:221], v[168:171], v[48:51]
	v_mfma_f32_16x16x32_bf16 v[36:39], v[210:213], v[182:185], v[36:39]
	v_mfma_f32_16x16x32_bf16 v[32:35], v[218:221], v[182:185], v[32:35]
	v_mfma_f32_16x16x32_bf16 v[20:23], v[210:213], v[194:197], v[20:23]
	v_mfma_f32_16x16x32_bf16 v[16:19], v[218:221], v[194:197], v[16:19]
	v_mfma_f32_16x16x32_bf16 v[4:7], v[210:213], v[202:205], v[4:7]
	v_mfma_f32_16x16x32_bf16 v[0:3], v[218:221], v[202:205], v[0:3]
	v_mfma_f32_16x16x32_bf16 v[52:55], v[214:217], v[172:175], v[52:55]
	v_mfma_f32_16x16x32_bf16 v[48:51], v[222:225], v[172:175], v[48:51]
	v_mfma_f32_16x16x32_bf16 v[36:39], v[214:217], v[190:193], v[36:39]
	v_mfma_f32_16x16x32_bf16 v[32:35], v[222:225], v[190:193], v[32:35]
	v_mfma_f32_16x16x32_bf16 v[20:23], v[214:217], v[198:201], v[20:23]
	v_mfma_f32_16x16x32_bf16 v[16:19], v[222:225], v[198:201], v[16:19]
	v_mfma_f32_16x16x32_bf16 v[4:7], v[214:217], v[206:209], v[4:7]
	v_mfma_f32_16x16x32_bf16 v[0:3], v[222:225], v[206:209], v[0:3]
	s_barrier
	s_add_i32 s47, s47, 2
	s_add_u32 s18, s18, 0x100
	s_addc_u32 s19, s19, 0
	s_add_u32 s45, s45, 0x100
	s_addc_u32 s46, s46, 0
	s_cmp_gt_u32 s47, 13
.LBB0_1011:
	ds_read_b128 v[144:147], v153
	ds_read_b128 v[156:159], v153 offset:1024
	ds_read_b128 v[160:163], v153 offset:2048
	ds_read_b128 v[164:167], v153 offset:3072
	s_add_u32 s20, s18, 0xfffc0080
	s_addc_u32 s21, s19, -1
	s_cmp_eq_u32 s47, 12
	s_cselect_b32 s23, s11, s21
	s_cselect_b32 s22, s43, s20
	s_cselect_b32 s21, s9, s46
	s_cselect_b32 s20, s44, s45
	ds_read_b128 v[168:171], v154
	ds_read_b128 v[172:175], v154 offset:1024
	ds_read_b128 v[182:185], v154 offset:2048
	ds_read_b128 v[190:193], v154 offset:3072
	ds_read_b128 v[194:197], v154 offset:4096
	ds_read_b128 v[198:201], v154 offset:5120
	ds_read_b128 v[202:205], v154 offset:6144
	ds_read_b128 v[206:209], v154 offset:7168
	s_waitcnt lgkmcnt(8)
	ds_read_b128 v[210:213], v155
	ds_read_b128 v[214:217], v155 offset:1024
	ds_read_b128 v[218:221], v155 offset:2048
	ds_read_b128 v[222:225], v155 offset:3072
	s_add_i32 m0, s17, 0xc000
	s_nop 0
	global_load_lds_dwordx4 v136, s[18:19]
	s_nop 1
	s_add_i32 m0, s17, 0xe000
	s_nop 0
	global_load_lds_dwordx4 v138, s[18:19]
	s_waitcnt vmcnt(8) lgkmcnt(0)
	s_barrier
	v_mfma_f32_16x16x32_bf16 v[124:127], v[144:147], v[168:171], v[124:127]
	v_mfma_f32_16x16x32_bf16 v[120:123], v[160:163], v[168:171], v[120:123]
	v_mfma_f32_16x16x32_bf16 v[108:111], v[144:147], v[182:185], v[108:111]
	v_mfma_f32_16x16x32_bf16 v[104:107], v[160:163], v[182:185], v[104:107]
	v_mfma_f32_16x16x32_bf16 v[92:95], v[144:147], v[194:197], v[92:95]
	v_mfma_f32_16x16x32_bf16 v[88:91], v[160:163], v[194:197], v[88:91]
	v_mfma_f32_16x16x32_bf16 v[76:79], v[144:147], v[202:205], v[76:79]
	v_mfma_f32_16x16x32_bf16 v[72:75], v[160:163], v[202:205], v[72:75]
	v_mfma_f32_16x16x32_bf16 v[124:127], v[156:159], v[172:175], v[124:127]
	v_mfma_f32_16x16x32_bf16 v[120:123], v[164:167], v[172:175], v[120:123]
	v_mfma_f32_16x16x32_bf16 v[108:111], v[156:159], v[190:193], v[108:111]
	v_mfma_f32_16x16x32_bf16 v[104:107], v[164:167], v[190:193], v[104:107]
	v_mfma_f32_16x16x32_bf16 v[92:95], v[156:159], v[198:201], v[92:95]
	v_mfma_f32_16x16x32_bf16 v[88:91], v[164:167], v[198:201], v[88:91]
	v_mfma_f32_16x16x32_bf16 v[76:79], v[156:159], v[206:209], v[76:79]
	v_mfma_f32_16x16x32_bf16 v[72:75], v[164:167], v[206:209], v[72:75]
	v_mfma_f32_16x16x32_bf16 v[116:119], v[210:213], v[168:171], v[116:119]
	v_mfma_f32_16x16x32_bf16 v[112:115], v[218:221], v[168:171], v[112:115]
	v_mfma_f32_16x16x32_bf16 v[100:103], v[210:213], v[182:185], v[100:103]
	v_mfma_f32_16x16x32_bf16 v[96:99], v[218:221], v[182:185], v[96:99]
	v_mfma_f32_16x16x32_bf16 v[84:87], v[210:213], v[194:197], v[84:87]
	v_mfma_f32_16x16x32_bf16 v[80:83], v[218:221], v[194:197], v[80:83]
	v_mfma_f32_16x16x32_bf16 v[68:71], v[210:213], v[202:205], v[68:71]
	v_mfma_f32_16x16x32_bf16 v[64:67], v[218:221], v[202:205], v[64:67]
	v_mfma_f32_16x16x32_bf16 v[116:119], v[214:217], v[172:175], v[116:119]
	v_mfma_f32_16x16x32_bf16 v[112:115], v[222:225], v[172:175], v[112:115]
	v_mfma_f32_16x16x32_bf16 v[100:103], v[214:217], v[190:193], v[100:103]
	v_mfma_f32_16x16x32_bf16 v[96:99], v[222:225], v[190:193], v[96:99]
	v_mfma_f32_16x16x32_bf16 v[84:87], v[214:217], v[198:201], v[84:87]
	v_mfma_f32_16x16x32_bf16 v[80:83], v[222:225], v[198:201], v[80:83]
	v_mfma_f32_16x16x32_bf16 v[68:71], v[214:217], v[206:209], v[68:71]
	v_mfma_f32_16x16x32_bf16 v[64:67], v[222:225], v[206:209], v[64:67]
	s_barrier
; #define PG8_STAGE(bufoff, gbase, voff) do { _Pragma("unroll") for (int _i = 0; _i < 2; ++_i) \
;         __builtin_amdgcn_global_load_lds((const unsigned*)((const char*)(gbase) + (voff)[_i]), (PG8_LAS unsigned*)(lds + (bufoff) + ldsw + _i * 8192), 16, 0, 0); } while (0)
; #define PG8_LDA(dst, b, h) do { _Pragma("unroll") for (int m = 0; m < 4; ++m) _Pragma("unroll") for (int k = 0; k < 2; ++k) dst[m][k] = *(const PG8_LAS bf16x8*)(lds + PG8_SA(b, h) + aoff + m * 2048 + k * 1024); } while (0)
; #define PG8_LDB(dst, b, h) do { _Pragma("unroll") for (int n = 0; n < 2; ++n) _Pragma("unroll") for (int k = 0; k < 2; ++k) dst[n][k] = *(const PG8_LAS bf16x8*)(lds + PG8_SB(b, h) + boff + n * 2048 + k * 1024); } while (0)
; #define PG8_WAIT_V(n) asm volatile("s_waitcnt vmcnt(" #n ")" ::: "memory")
; #define PG8_WAIT_L(n) asm volatile("s_waitcnt lgkmcnt(" #n ")" ::: "memory")
; #define PG8_BAR __builtin_amdgcn_s_barrier()
; #define PG8_SCHED __builtin_amdgcn_sched_barrier(0)
; template <class Epi, class Sched>
; __device__ __forceinline__ void gemm_phase(PG8_LAS unsigned char* lds, const Gemm g, const Sched& S, const Epi& E) {
;     ...
;             PG8_LDB(B0, 0, 0); PG8_SCHED; PG8_LDA(At, 0, 0); PG8_STAGE(PG8_SA(1, 1), a1 + hstep, voffA);
;             PG8_WAIT_L(8); PG8_BAR; PG8_WAIT_L(0); PG8_MMA(0, 0, At, B0); PG8_BAR; PG8_SCHED;
;             PG8_LDB(B1, 0, 1); PG8_STAGE(PG8_SB(0, 0), b2, voffB);
;             PG8_BAR; PG8_WAIT_L(0); PG8_MMA(0, 1, At, B1); PG8_BAR;
;             PG8_LDA(At, 0, 1); PG8_STAGE(PG8_SA(0, 0), a2, voffA);
;             PG8_BAR; PG8_WAIT_L(0); PG8_MMA(1, 0, At, B0); PG8_BAR; PG8_SCHED;
;             PG8_STAGE(PG8_SB(0, 1), b2 + hstep, voffB);
;             PG8_WAIT_V(6); PG8_BAR; PG8_MMA(1, 1, At, B1); PG8_BAR;
;             PG8_LDB(B0, 1, 0); PG8_SCHED; PG8_LDA(At, 1, 0); PG8_STAGE(PG8_SA(0, 1), a2 + hstep, voffA);
;             PG8_WAIT_L(8); PG8_BAR; PG8_WAIT_L(0); PG8_MMA(0, 0, At, B0); PG8_BAR; PG8_SCHED;
;             PG8_LDB(B1, 1, 1); PG8_STAGE(PG8_SB(1, 0), b3, voffB);
;             PG8_BAR; PG8_WAIT_L(0); PG8_MMA(0, 1, At, B1); PG8_BAR;
;             PG8_LDA(At, 1, 1); PG8_STAGE(PG8_SA(1, 0), a3, voffA);
;             PG8_BAR; PG8_WAIT_L(0); PG8_MMA(1, 0, At, B0); PG8_BAR; PG8_SCHED;
;             PG8_STAGE(PG8_SB(1, 1), b3 + hstep, voffB);
;             PG8_WAIT_V(6); PG8_BAR; PG8_MMA(1, 1, At, B1); PG8_BAR;
	ds_read_b128 v[168:171], v154 offset:16384
	ds_read_b128 v[172:175], v154 offset:17408
	ds_read_b128 v[182:185], v154 offset:18432
	ds_read_b128 v[190:193], v154 offset:19456
	ds_read_b128 v[194:197], v154 offset:20480
	ds_read_b128 v[198:201], v154 offset:21504
	ds_read_b128 v[202:205], v154 offset:22528
	ds_read_b128 v[206:209], v154 offset:23552
	s_add_i32 s48, s39, s29
	s_add_u32 s98, s20, s6
	s_addc_u32 s99, s21, s7
	s_mov_b32 m0, s48
	s_nop 0
	global_load_lds_dwordx4 v130, s[20:21]
	s_nop 1
	s_add_i32 m0, s48, 0x2000
	s_nop 0
	global_load_lds_dwordx4 v134, s[20:21]
	s_nop 1
	s_mov_b32 m0, s17
	s_add_u32 s100, s22, s6
	s_addc_u32 s101, s23, s7
	global_load_lds_dwordx4 v128, s[22:23]
	s_nop 1
	s_mov_b32 m0, s30
	s_nop 0
	global_load_lds_dwordx4 v132, s[22:23]
	s_add_u32 s48, s20, 0x40000
	s_addc_u32 s49, s21, 0
	s_add_i32 s50, s40, s29
	s_mov_b32 m0, s50
	s_nop 0
	global_load_lds_dwordx4 v130, s[48:49]
	s_nop 1
	s_add_i32 m0, s50, 0x2000
	s_nop 0
	global_load_lds_dwordx4 v134, s[48:49]
	s_waitcnt vmcnt(8) lgkmcnt(0)
	s_barrier
	v_mfma_f32_16x16x32_bf16 v[60:63], v[144:147], v[168:171], v[60:63]
	v_mfma_f32_16x16x32_bf16 v[56:59], v[160:163], v[168:171], v[56:59]
	v_mfma_f32_16x16x32_bf16 v[44:47], v[144:147], v[182:185], v[44:47]
	v_mfma_f32_16x16x32_bf16 v[40:43], v[160:163], v[182:185], v[40:43]
	v_mfma_f32_16x16x32_bf16 v[28:31], v[144:147], v[194:197], v[28:31]
	v_mfma_f32_16x16x32_bf16 v[24:27], v[160:163], v[194:197], v[24:27]
	v_mfma_f32_16x16x32_bf16 v[12:15], v[144:147], v[202:205], v[12:15]
	v_mfma_f32_16x16x32_bf16 v[8:11], v[160:163], v[202:205], v[8:11]
	v_mfma_f32_16x16x32_bf16 v[60:63], v[156:159], v[172:175], v[60:63]
	v_mfma_f32_16x16x32_bf16 v[56:59], v[164:167], v[172:175], v[56:59]
	v_mfma_f32_16x16x32_bf16 v[44:47], v[156:159], v[190:193], v[44:47]
	v_mfma_f32_16x16x32_bf16 v[40:43], v[164:167], v[190:193], v[40:43]
	v_mfma_f32_16x16x32_bf16 v[28:31], v[156:159], v[198:201], v[28:31]
	v_mfma_f32_16x16x32_bf16 v[24:27], v[164:167], v[198:201], v[24:27]
	v_mfma_f32_16x16x32_bf16 v[12:15], v[156:159], v[206:209], v[12:15]
	v_mfma_f32_16x16x32_bf16 v[8:11], v[164:167], v[206:209], v[8:11]
	v_mfma_f32_16x16x32_bf16 v[52:55], v[210:213], v[168:171], v[52:55]
	v_mfma_f32_16x16x32_bf16 v[48:51], v[218:221], v[168:171], v[48:51]
	v_mfma_f32_16x16x32_bf16 v[36:39], v[210:213], v[182:185], v[36:39]
	v_mfma_f32_16x16x32_bf16 v[32:35], v[218:221], v[182:185], v[32:35]
	v_mfma_f32_16x16x32_bf16 v[20:23], v[210:213], v[194:197], v[20:23]
	v_mfma_f32_16x16x32_bf16 v[16:19], v[218:221], v[194:197], v[16:19]
	v_mfma_f32_16x16x32_bf16 v[4:7], v[210:213], v[202:205], v[4:7]
	v_mfma_f32_16x16x32_bf16 v[0:3], v[218:221], v[202:205], v[0:3]
	v_mfma_f32_16x16x32_bf16 v[52:55], v[214:217], v[172:175], v[52:55]
	v_mfma_f32_16x16x32_bf16 v[48:51], v[222:225], v[172:175], v[48:51]
	v_mfma_f32_16x16x32_bf16 v[36:39], v[214:217], v[190:193], v[36:39]
	v_mfma_f32_16x16x32_bf16 v[32:35], v[222:225], v[190:193], v[32:35]
	v_mfma_f32_16x16x32_bf16 v[20:23], v[214:217], v[198:201], v[20:23]
	v_mfma_f32_16x16x32_bf16 v[16:19], v[222:225], v[198:201], v[16:19]
	v_mfma_f32_16x16x32_bf16 v[4:7], v[214:217], v[206:209], v[4:7]
	v_mfma_f32_16x16x32_bf16 v[0:3], v[222:225], v[206:209], v[0:3]
	s_barrier
	s_add_i32 s48, 0, 0x18000
	v_add_u32_e32 v164, s48, v151
	ds_read_b128 v[144:147], v164
	ds_read_b128 v[156:159], v164 offset:1024
	ds_read_b128 v[160:163], v164 offset:2048
	ds_read_b128 v[164:167], v164 offset:3072
	ds_read_b128 v[168:171], v154 offset:32768
	ds_read_b128 v[172:175], v154 offset:33792
	ds_read_b128 v[182:185], v154 offset:34816
	ds_read_b128 v[190:193], v154 offset:35840
	ds_read_b128 v[194:197], v154 offset:36864
	ds_read_b128 v[198:201], v154 offset:37888
	ds_read_b128 v[202:205], v154 offset:38912
	ds_read_b128 v[206:209], v154 offset:39936
	v_add_u32_e32 v179, 0x1c000, v151
	s_waitcnt lgkmcnt(8)
	ds_read_b128 v[210:213], v179
	ds_read_b128 v[214:217], v179 offset:1024
	ds_read_b128 v[218:221], v179 offset:2048
	ds_read_b128 v[222:225], v179 offset:3072
	s_add_u32 s22, s22, 0x40000
	s_addc_u32 s23, s23, 0
	s_mov_b32 m0, s31
	s_nop 0
	global_load_lds_dwordx4 v128, s[22:23]
	s_nop 1
	s_mov_b32 m0, s34
	s_nop 0
	global_load_lds_dwordx4 v132, s[22:23]
	s_add_i32 s22, 0, 0x1c000
	s_waitcnt vmcnt(8) lgkmcnt(0)
	s_barrier
	v_mfma_f32_16x16x32_bf16 v[124:127], v[144:147], v[168:171], v[124:127]
	v_mfma_f32_16x16x32_bf16 v[120:123], v[160:163], v[168:171], v[120:123]
	v_mfma_f32_16x16x32_bf16 v[108:111], v[144:147], v[182:185], v[108:111]
	v_mfma_f32_16x16x32_bf16 v[104:107], v[160:163], v[182:185], v[104:107]
	v_mfma_f32_16x16x32_bf16 v[92:95], v[144:147], v[194:197], v[92:95]
	v_mfma_f32_16x16x32_bf16 v[88:91], v[160:163], v[194:197], v[88:91]
	v_mfma_f32_16x16x32_bf16 v[76:79], v[144:147], v[202:205], v[76:79]
	v_mfma_f32_16x16x32_bf16 v[72:75], v[160:163], v[202:205], v[72:75]
	v_mfma_f32_16x16x32_bf16 v[124:127], v[156:159], v[172:175], v[124:127]
	v_mfma_f32_16x16x32_bf16 v[120:123], v[164:167], v[172:175], v[120:123]
	v_mfma_f32_16x16x32_bf16 v[108:111], v[156:159], v[190:193], v[108:111]
	v_mfma_f32_16x16x32_bf16 v[104:107], v[164:167], v[190:193], v[104:107]
	v_mfma_f32_16x16x32_bf16 v[92:95], v[156:159], v[198:201], v[92:95]
	v_mfma_f32_16x16x32_bf16 v[88:91], v[164:167], v[198:201], v[88:91]
	v_mfma_f32_16x16x32_bf16 v[76:79], v[156:159], v[206:209], v[76:79]
	v_mfma_f32_16x16x32_bf16 v[72:75], v[164:167], v[206:209], v[72:75]
	v_mfma_f32_16x16x32_bf16 v[116:119], v[210:213], v[168:171], v[116:119]
	v_mfma_f32_16x16x32_bf16 v[112:115], v[218:221], v[168:171], v[112:115]
	v_mfma_f32_16x16x32_bf16 v[100:103], v[210:213], v[182:185], v[100:103]
	v_mfma_f32_16x16x32_bf16 v[96:99], v[218:221], v[182:185], v[96:99]
	v_mfma_f32_16x16x32_bf16 v[84:87], v[210:213], v[194:197], v[84:87]
	v_mfma_f32_16x16x32_bf16 v[80:83], v[218:221], v[194:197], v[80:83]
	v_mfma_f32_16x16x32_bf16 v[68:71], v[210:213], v[202:205], v[68:71]
	v_mfma_f32_16x16x32_bf16 v[64:67], v[218:221], v[202:205], v[64:67]
	v_mfma_f32_16x16x32_bf16 v[116:119], v[214:217], v[172:175], v[116:119]
	v_mfma_f32_16x16x32_bf16 v[112:115], v[222:225], v[172:175], v[112:115]
	v_mfma_f32_16x16x32_bf16 v[100:103], v[214:217], v[190:193], v[100:103]
	v_mfma_f32_16x16x32_bf16 v[96:99], v[222:225], v[190:193], v[96:99]
	v_mfma_f32_16x16x32_bf16 v[84:87], v[214:217], v[198:201], v[84:87]
	v_mfma_f32_16x16x32_bf16 v[80:83], v[222:225], v[198:201], v[80:83]
	v_mfma_f32_16x16x32_bf16 v[68:71], v[214:217], v[206:209], v[68:71]
	v_mfma_f32_16x16x32_bf16 v[64:67], v[222:225], v[206:209], v[64:67]
	s_barrier
; #define PG8_WAIT_V(n) asm volatile("s_waitcnt vmcnt(" #n ")" ::: "memory")
;     __device__ __forceinline__ void operator()(const f32x4 (&acc)[2][2][4][2], const Unit& u, int wr, int wc, int fr, int fq) const {
;     ...
;             for (int m = 0; m < 4; ++m) { const size_t r = (size_t)(row0 + ai * HALF + m * 16); bf16_t* rowp = O + r * ldc + col0; const bf16_t* gp = G + r * ldg + col0;
; #pragma unroll
;                 for (int bj = 0; bj < 2; ++bj) { const u32x4 gw = *(const u32x4*)(gp + bj * HALF);
;                     f32x4 v0 = acc[ai][bj][m][0], v1 = acc[ai][bj][m][1];
;                     v0[0] *= bf_lo(gw.x); v0[1] *= bf_hi(gw.x); v0[2] *= bf_lo(gw.y); v0[3] *= bf_hi(gw.y);
;                     v1[0] *= bf_lo(gw.z); v1[1] *= bf_hi(gw.z); v1[2] *= bf_lo(gw.w); v1[3] *= bf_hi(gw.w);
;                     if (ACCUM) { const u32x4 pw = *(const u32x4*)(rowp + bj * HALF);
;                         v0[0] += bf_lo(pw.x); v0[1] += bf_hi(pw.x); v0[2] += bf_lo(pw.y); v0[3] += bf_hi(pw.y);
; template <class Epi, class Sched>
; __device__ __forceinline__ void gemm_phase(PG8_LAS unsigned char* lds, const Gemm g, const Sched& S, const Epi& E) {
;     ...
;             PG8_LDB(B0, 0, 0); PG8_SCHED; PG8_LDA(At, 0, 0); PG8_STAGE(PG8_SA(1, 1), a1 + hstep, voffA);
;             PG8_WAIT_L(8); PG8_BAR; PG8_WAIT_L(0); PG8_MMA(0, 0, At, B0); PG8_BAR; PG8_SCHED;
;             PG8_LDB(B1, 0, 1); PG8_STAGE(PG8_SB(0, 0), b2, voffB);
;             PG8_BAR; PG8_WAIT_L(0); PG8_MMA(0, 1, At, B1); PG8_BAR;
;             PG8_LDA(At, 0, 1); PG8_STAGE(PG8_SA(0, 0), a2, voffA);
;             PG8_BAR; PG8_WAIT_L(0); PG8_MMA(1, 0, At, B0); PG8_BAR; PG8_SCHED;
;             PG8_STAGE(PG8_SB(0, 1), b2 + hstep, voffB);
;             PG8_WAIT_V(6); PG8_BAR; PG8_MMA(1, 1, At, B1); PG8_BAR;
;             PG8_LDB(B0, 1, 0); PG8_SCHED; PG8_LDA(At, 1, 0); PG8_STAGE(PG8_SA(0, 1), a2 + hstep, voffA);
;             PG8_WAIT_L(8); PG8_BAR; PG8_WAIT_L(0); PG8_MMA(0, 0, At, B0); PG8_BAR; PG8_SCHED;
;             PG8_LDB(B1, 1, 1); PG8_STAGE(PG8_SB(1, 0), b3, voffB);
;             PG8_BAR; PG8_WAIT_L(0); PG8_MMA(0, 1, At, B1); PG8_BAR;
;             PG8_LDA(At, 1, 1); PG8_STAGE(PG8_SA(1, 0), a3, voffA);
;             PG8_BAR; PG8_WAIT_L(0); PG8_MMA(1, 0, At, B0); PG8_BAR; PG8_SCHED;
;             PG8_STAGE(PG8_SB(1, 1), b3 + hstep, voffB);
;             PG8_WAIT_V(6); PG8_BAR; PG8_MMA(1, 1, At, B1); PG8_BAR;
	ds_read_b128 v[168:171], v154 offset:49152
	ds_read_b128 v[172:175], v154 offset:50176
	ds_read_b128 v[182:185], v154 offset:51200
	ds_read_b128 v[190:193], v154 offset:52224
	ds_read_b128 v[194:197], v154 offset:53248
	ds_read_b128 v[198:201], v154 offset:54272
	ds_read_b128 v[202:205], v154 offset:55296
	ds_read_b128 v[206:209], v154 offset:56320
	s_add_i32 s23, s48, s29
	s_mov_b32 m0, s23
	s_nop 0
	global_load_lds_dwordx4 v130, s[98:99]
	s_nop 1
	s_add_i32 m0, s23, 0x2000
	s_nop 0
	global_load_lds_dwordx4 v134, s[98:99]
	s_nop 1
	s_mov_b32 m0, s36
	s_nop 0
	global_load_lds_dwordx4 v128, s[100:101]
	s_nop 1
	s_mov_b32 m0, s37
	s_nop 0
	global_load_lds_dwordx4 v132, s[100:101]
	s_add_u32 s20, s20, 0x40080
	s_addc_u32 s21, s21, 0
	s_add_i32 s22, s22, s29
	s_mov_b32 m0, s22
	s_nop 0
	global_load_lds_dwordx4 v130, s[20:21]
	s_nop 1
	s_add_i32 m0, s22, 0x2000
	s_nop 0
	global_load_lds_dwordx4 v134, s[20:21]
	s_waitcnt vmcnt(8) lgkmcnt(0)
	s_barrier
	v_mfma_f32_16x16x32_bf16 v[60:63], v[144:147], v[168:171], v[60:63]
	v_mfma_f32_16x16x32_bf16 v[56:59], v[160:163], v[168:171], v[56:59]
	v_mfma_f32_16x16x32_bf16 v[44:47], v[144:147], v[182:185], v[44:47]
	v_mfma_f32_16x16x32_bf16 v[40:43], v[160:163], v[182:185], v[40:43]
	v_mfma_f32_16x16x32_bf16 v[28:31], v[144:147], v[194:197], v[28:31]
	v_mfma_f32_16x16x32_bf16 v[24:27], v[160:163], v[194:197], v[24:27]
	v_mfma_f32_16x16x32_bf16 v[12:15], v[144:147], v[202:205], v[12:15]
	v_mfma_f32_16x16x32_bf16 v[8:11], v[160:163], v[202:205], v[8:11]
	v_mfma_f32_16x16x32_bf16 v[60:63], v[156:159], v[172:175], v[60:63]
	v_mfma_f32_16x16x32_bf16 v[56:59], v[164:167], v[172:175], v[56:59]
	v_mfma_f32_16x16x32_bf16 v[44:47], v[156:159], v[190:193], v[44:47]
	v_mfma_f32_16x16x32_bf16 v[40:43], v[164:167], v[190:193], v[40:43]
	v_mfma_f32_16x16x32_bf16 v[28:31], v[156:159], v[198:201], v[28:31]
	v_mfma_f32_16x16x32_bf16 v[24:27], v[164:167], v[198:201], v[24:27]
	v_mfma_f32_16x16x32_bf16 v[12:15], v[156:159], v[206:209], v[12:15]
	v_mfma_f32_16x16x32_bf16 v[8:11], v[164:167], v[206:209], v[8:11]
	v_mfma_f32_16x16x32_bf16 v[52:55], v[210:213], v[168:171], v[52:55]
	v_mfma_f32_16x16x32_bf16 v[48:51], v[218:221], v[168:171], v[48:51]
	v_mfma_f32_16x16x32_bf16 v[36:39], v[210:213], v[182:185], v[36:39]
	v_mfma_f32_16x16x32_bf16 v[32:35], v[218:221], v[182:185], v[32:35]
	v_mfma_f32_16x16x32_bf16 v[20:23], v[210:213], v[194:197], v[20:23]
	v_mfma_f32_16x16x32_bf16 v[16:19], v[218:221], v[194:197], v[16:19]
	v_mfma_f32_16x16x32_bf16 v[4:7], v[210:213], v[202:205], v[4:7]
	v_mfma_f32_16x16x32_bf16 v[0:3], v[218:221], v[202:205], v[0:3]
	v_mfma_f32_16x16x32_bf16 v[52:55], v[214:217], v[172:175], v[52:55]
	v_mfma_f32_16x16x32_bf16 v[48:51], v[222:225], v[172:175], v[48:51]
	v_mfma_f32_16x16x32_bf16 v[36:39], v[214:217], v[190:193], v[36:39]
	v_mfma_f32_16x16x32_bf16 v[32:35], v[222:225], v[190:193], v[32:35]
	v_mfma_f32_16x16x32_bf16 v[20:23], v[214:217], v[198:201], v[20:23]
	v_mfma_f32_16x16x32_bf16 v[16:19], v[222:225], v[198:201], v[16:19]
	v_mfma_f32_16x16x32_bf16 v[4:7], v[214:217], v[206:209], v[4:7]
	v_mfma_f32_16x16x32_bf16 v[0:3], v[222:225], v[206:209], v[0:3]
	s_barrier
	s_add_i32 s47, s47, 2
	s_add_u32 s18, s18, 0x100
	s_addc_u32 s19, s19, 0
	s_add_u32 s45, s45, 0x100
	s_addc_u32 s46, s46, 0
	s_cmp_gt_u32 s47, 13
	s_cbranch_scc0 .LBB0_1011
	v_lshl_add_u32 v146, s16, 8, v150
	v_lshl_or_b32 v144, s42, 8, v152
	v_ashrrev_i32_e32 v147, 31, v146
	v_ashrrev_i32_e32 v145, 31, v144
	v_mov_b64_e32 v[148:149], s[4:5]
	v_lshlrev_b64 v[160:161], 11, v[146:147]
	v_lshlrev_b64 v[144:145], 1, v[144:145]
	v_mad_i64_i32 v[156:157], s[18:19], v146, s41, v[148:149]
	v_lshl_add_u64 v[160:161], s[0:1], 0, v[160:161]
	v_lshl_add_u64 v[164:165], v[156:157], 0, v[144:145]
	v_lshl_add_u64 v[166:167], v[160:161], 0, v[144:145]
	global_load_dwordx4 v[156:159], v[164:165], off
	global_load_dwordx4 v[160:163], v[166:167], off
	s_and_b64 vcc, exec, s[2:3]
	s_mov_b32 s42, s8
	s_mov_b32 s16, s10
	s_mov_b64 s[20:21], s[14:15]
	s_waitcnt vmcnt(0)
	v_lshlrev_b32_e32 v147, 16, v156
	v_and_b32_e32 v156, 0xffff0000, v156
	v_lshlrev_b32_e32 v168, 16, v157
	v_and_b32_e32 v157, 0xffff0000, v157
	v_lshlrev_b32_e32 v169, 16, v158
	v_and_b32_e32 v158, 0xffff0000, v158
	v_lshlrev_b32_e32 v170, 16, v159
	v_and_b32_e32 v159, 0xffff0000, v159
	v_lshlrev_b32_e32 v171, 16, v160
	v_and_b32_e32 v160, 0xffff0000, v160
	v_lshlrev_b32_e32 v172, 16, v161
	v_and_b32_e32 v161, 0xffff0000, v161
	v_lshlrev_b32_e32 v173, 16, v162
	v_and_b32_e32 v162, 0xffff0000, v162
	v_lshlrev_b32_e32 v174, 16, v163
	v_and_b32_e32 v163, 0xffff0000, v163
	v_fmac_f32_e32 v171, v124, v147
	v_fmac_f32_e32 v160, v125, v156
	v_fmac_f32_e32 v172, v126, v168
	v_fmac_f32_e32 v161, v127, v157
	v_fmac_f32_e32 v173, v120, v169
	v_fmac_f32_e32 v162, v121, v158
	v_fmac_f32_e32 v174, v122, v170
	v_fmac_f32_e32 v163, v123, v159
	v_cvt_pk_bf16_f32 v120, v171, v160
	v_cvt_pk_bf16_f32 v121, v172, v161
	v_cvt_pk_bf16_f32 v122, v173, v162
	v_cvt_pk_bf16_f32 v123, v174, v163
	global_load_dwordx4 v[124:127], v[164:165], off offset:256
	global_load_dwordx4 v[156:159], v[166:167], off offset:256
	v_or_b32_e32 v160, 16, v146
	global_store_dwordx4 v[166:167], v[120:123], off
	v_mad_i64_i32 v[162:163], s[18:19], v160, s41, v[148:149]
	v_lshl_add_u64 v[162:163], v[162:163], 0, v[144:145]
	s_waitcnt vmcnt(0)
; __device__ __forceinline__ unsigned cvt_pk_bf16(float lo, float hi) { unsigned r; asm volatile("v_cvt_pk_bf16_f32 %0, %1, %2" : "=v"(r) : "v"(lo), "v"(hi)); return r; }
; __device__ __forceinline__ float bf_lo(unsigned u) { return __uint_as_float(u << 16); }
; __device__ __forceinline__ float bf_hi(unsigned u) { return __uint_as_float(u & 0xffff0000u); }
;     __device__ __forceinline__ void operator()(const f32x4 (&acc)[2][2][4][2], const Unit& u, int wr, int wc, int fr, int fq) const {
;     ...
;             for (int m = 0; m < 4; ++m) { const size_t r = (size_t)(row0 + ai * HALF + m * 16); bf16_t* rowp = O + r * ldc + col0; const bf16_t* gp = G + r * ldg + col0;
; #pragma unroll
;                 for (int bj = 0; bj < 2; ++bj) { const u32x4 gw = *(const u32x4*)(gp + bj * HALF);
;                     f32x4 v0 = acc[ai][bj][m][0], v1 = acc[ai][bj][m][1];
;                     v0[0] *= bf_lo(gw.x); v0[1] *= bf_hi(gw.x); v0[2] *= bf_lo(gw.y); v0[3] *= bf_hi(gw.y);
;                     v1[0] *= bf_lo(gw.z); v1[1] *= bf_hi(gw.z); v1[2] *= bf_lo(gw.w); v1[3] *= bf_hi(gw.w);
;                     if (ACCUM) { const u32x4 pw = *(const u32x4*)(rowp + bj * HALF);
;                         v0[0] += bf_lo(pw.x); v0[1] += bf_hi(pw.x); v0[2] += bf_lo(pw.y); v0[3] += bf_hi(pw.y);
;                         v1[0] += bf_lo(pw.z); v1[1] += bf_hi(pw.z); v1[2] += bf_lo(pw.w); v1[3] += bf_hi(pw.w); }
;                     u32x4 w; w.x = cvt_pk_bf16(v0[0], v0[1]); w.y = cvt_pk_bf16(v0[2], v0[3]); w.z = cvt_pk_bf16(v1[0], v1[1]); w.w = cvt_pk_bf16(v1[2], v1[3]);
;                     *(u32x4*)(rowp + bj * HALF) = w; } }
	v_lshlrev_b32_e32 v122, 16, v125
	v_lshlrev_b32_e32 v161, 16, v157
	v_lshlrev_b32_e32 v120, 16, v124
	v_and_b32_e32 v121, 0xffff0000, v124
	v_and_b32_e32 v123, 0xffff0000, v125
	v_lshlrev_b32_e32 v124, 16, v126
	v_and_b32_e32 v125, 0xffff0000, v126
	v_lshlrev_b32_e32 v147, 16, v156
	v_and_b32_e32 v156, 0xffff0000, v156
	v_and_b32_e32 v157, 0xffff0000, v157
	v_lshlrev_b32_e32 v164, 16, v158
	v_and_b32_e32 v158, 0xffff0000, v158
	v_fmac_f32_e32 v161, v118, v122
	v_fmac_f32_e32 v147, v116, v120
	v_fmac_f32_e32 v156, v117, v121
	v_fmac_f32_e32 v157, v119, v123
	v_fmac_f32_e32 v164, v112, v124
	v_fmac_f32_e32 v158, v113, v125
	v_cvt_pk_bf16_f32 v112, v147, v156
	v_cvt_pk_bf16_f32 v113, v161, v157
	v_ashrrev_i32_e32 v161, 31, v160
	v_lshlrev_b64 v[120:121], 11, v[160:161]
	v_lshl_add_u64 v[120:121], s[0:1], 0, v[120:121]
	v_lshlrev_b32_e32 v126, 16, v127
	v_and_b32_e32 v127, 0xffff0000, v127
	v_lshlrev_b32_e32 v165, 16, v159
	v_and_b32_e32 v159, 0xffff0000, v159
	v_lshl_add_u64 v[124:125], v[120:121], 0, v[144:145]
	v_fmac_f32_e32 v165, v114, v126
	v_fmac_f32_e32 v159, v115, v127
	v_cvt_pk_bf16_f32 v114, v164, v158
	v_cvt_pk_bf16_f32 v115, v165, v159
	global_load_dwordx4 v[116:119], v[162:163], off
	global_load_dwordx4 v[120:123], v[124:125], off
	s_waitcnt vmcnt(0)
	v_lshlrev_b32_e32 v126, 16, v120
	global_store_dwordx4 v[166:167], v[112:115], off offset:256
	v_and_b32_e32 v120, 0xffff0000, v120
	v_lshlrev_b32_e32 v127, 16, v121
	v_lshlrev_b32_e32 v112, 16, v116
	v_and_b32_e32 v113, 0xffff0000, v116
	v_lshlrev_b32_e32 v114, 16, v117
	v_and_b32_e32 v115, 0xffff0000, v117
	v_lshlrev_b32_e32 v116, 16, v118
	v_and_b32_e32 v117, 0xffff0000, v118
	v_lshlrev_b32_e32 v118, 16, v119
	v_and_b32_e32 v119, 0xffff0000, v119
	v_and_b32_e32 v121, 0xffff0000, v121
	v_lshlrev_b32_e32 v147, 16, v122
	v_and_b32_e32 v122, 0xffff0000, v122
	v_lshlrev_b32_e32 v156, 16, v123
	v_and_b32_e32 v123, 0xffff0000, v123
	v_fmac_f32_e32 v126, v108, v112
	v_fmac_f32_e32 v120, v109, v113
	v_fmac_f32_e32 v127, v110, v114
	v_fmac_f32_e32 v121, v111, v115
	v_fmac_f32_e32 v147, v104, v116
	v_fmac_f32_e32 v122, v105, v117
	v_fmac_f32_e32 v156, v106, v118
	v_fmac_f32_e32 v123, v107, v119
	v_cvt_pk_bf16_f32 v104, v126, v120
	v_cvt_pk_bf16_f32 v105, v127, v121
	v_cvt_pk_bf16_f32 v106, v147, v122
	v_cvt_pk_bf16_f32 v107, v156, v123
	global_load_dwordx4 v[108:111], v[162:163], off offset:256
	global_load_dwordx4 v[112:115], v[124:125], off offset:256
	v_or_b32_e32 v116, 32, v146
	global_store_dwordx4 v[124:125], v[104:107], off
	v_mad_i64_i32 v[118:119], s[18:19], v116, s41, v[148:149]
	v_lshl_add_u64 v[118:119], v[118:119], 0, v[144:145]
	s_waitcnt vmcnt(0)
	v_lshlrev_b32_e32 v104, 16, v108
	v_lshlrev_b32_e32 v117, 16, v112
	v_and_b32_e32 v105, 0xffff0000, v108
	v_lshlrev_b32_e32 v108, 16, v110
	v_and_b32_e32 v112, 0xffff0000, v112
	v_lshlrev_b32_e32 v121, 16, v114
	v_fmac_f32_e32 v117, v100, v104
	v_fmac_f32_e32 v112, v101, v105
	v_fmac_f32_e32 v121, v96, v108
	v_cvt_pk_bf16_f32 v96, v117, v112
	v_ashrrev_i32_e32 v117, 31, v116
	v_lshlrev_b64 v[104:105], 11, v[116:117]
	v_lshlrev_b32_e32 v106, 16, v109
	v_and_b32_e32 v107, 0xffff0000, v109
	v_and_b32_e32 v109, 0xffff0000, v110
	v_and_b32_e32 v114, 0xffff0000, v114
	v_lshl_add_u64 v[104:105], s[0:1], 0, v[104:105]
	v_lshlrev_b32_e32 v110, 16, v111
	v_and_b32_e32 v111, 0xffff0000, v111
	v_lshlrev_b32_e32 v120, 16, v113
	v_and_b32_e32 v113, 0xffff0000, v113
	v_lshlrev_b32_e32 v122, 16, v115
	v_and_b32_e32 v115, 0xffff0000, v115
	v_fmac_f32_e32 v114, v97, v109
	v_lshl_add_u64 v[108:109], v[104:105], 0, v[144:145]
	v_fmac_f32_e32 v120, v102, v106
	v_fmac_f32_e32 v113, v103, v107
	v_fmac_f32_e32 v122, v98, v110
	v_fmac_f32_e32 v115, v99, v111
	v_cvt_pk_bf16_f32 v97, v120, v113
	v_cvt_pk_bf16_f32 v98, v121, v114
	v_cvt_pk_bf16_f32 v99, v122, v115
	global_load_dwordx4 v[100:103], v[118:119], off
	global_load_dwordx4 v[104:107], v[108:109], off
	s_waitcnt vmcnt(0)
	v_lshlrev_b32_e32 v110, 16, v104
	global_store_dwordx4 v[124:125], v[96:99], off offset:256
	v_and_b32_e32 v104, 0xffff0000, v104
	v_lshlrev_b32_e32 v111, 16, v105
	v_lshlrev_b32_e32 v96, 16, v100
	v_and_b32_e32 v97, 0xffff0000, v100
	v_lshlrev_b32_e32 v98, 16, v101
	v_and_b32_e32 v99, 0xffff0000, v101
	v_lshlrev_b32_e32 v100, 16, v102
	v_and_b32_e32 v101, 0xffff0000, v102
	v_lshlrev_b32_e32 v102, 16, v103
	v_and_b32_e32 v103, 0xffff0000, v103
	v_and_b32_e32 v105, 0xffff0000, v105
	v_lshlrev_b32_e32 v112, 16, v106
	v_and_b32_e32 v106, 0xffff0000, v106
	v_lshlrev_b32_e32 v113, 16, v107
	v_and_b32_e32 v107, 0xffff0000, v107
	v_fmac_f32_e32 v110, v92, v96
	v_fmac_f32_e32 v104, v93, v97
	v_fmac_f32_e32 v111, v94, v98
	v_fmac_f32_e32 v105, v95, v99
	v_fmac_f32_e32 v112, v88, v100
	v_fmac_f32_e32 v106, v89, v101
	v_fmac_f32_e32 v113, v90, v102
	v_fmac_f32_e32 v107, v91, v103
	v_cvt_pk_bf16_f32 v88, v110, v104
	v_cvt_pk_bf16_f32 v89, v111, v105
	v_cvt_pk_bf16_f32 v90, v112, v106
	v_cvt_pk_bf16_f32 v91, v113, v107
	global_load_dwordx4 v[92:95], v[118:119], off offset:256
	global_load_dwordx4 v[96:99], v[108:109], off offset:256
	v_or_b32_e32 v100, 48, v146
	global_store_dwordx4 v[108:109], v[88:91], off
	v_mad_i64_i32 v[102:103], s[18:19], v100, s41, v[148:149]
	v_lshl_add_u64 v[102:103], v[102:103], 0, v[144:145]
	s_waitcnt vmcnt(0)
; __device__ __forceinline__ unsigned cvt_pk_bf16(float lo, float hi) { unsigned r; asm volatile("v_cvt_pk_bf16_f32 %0, %1, %2" : "=v"(r) : "v"(lo), "v"(hi)); return r; }
; __device__ __forceinline__ float bf_lo(unsigned u) { return __uint_as_float(u << 16); }
; __device__ __forceinline__ float bf_hi(unsigned u) { return __uint_as_float(u & 0xffff0000u); }
;     __device__ __forceinline__ void operator()(const f32x4 (&acc)[2][2][4][2], const Unit& u, int wr, int wc, int fr, int fq) const {
;     ...
;             for (int m = 0; m < 4; ++m) { const size_t r = (size_t)(row0 + ai * HALF + m * 16); bf16_t* rowp = O + r * ldc + col0; const bf16_t* gp = G + r * ldg + col0;
; #pragma unroll
;                 for (int bj = 0; bj < 2; ++bj) { const u32x4 gw = *(const u32x4*)(gp + bj * HALF);
;                     f32x4 v0 = acc[ai][bj][m][0], v1 = acc[ai][bj][m][1];
;                     v0[0] *= bf_lo(gw.x); v0[1] *= bf_hi(gw.x); v0[2] *= bf_lo(gw.y); v0[3] *= bf_hi(gw.y);
;                     v1[0] *= bf_lo(gw.z); v1[1] *= bf_hi(gw.z); v1[2] *= bf_lo(gw.w); v1[3] *= bf_hi(gw.w);
;                     if (ACCUM) { const u32x4 pw = *(const u32x4*)(rowp + bj * HALF);
;                         v0[0] += bf_lo(pw.x); v0[1] += bf_hi(pw.x); v0[2] += bf_lo(pw.y); v0[3] += bf_hi(pw.y);
;                         v1[0] += bf_lo(pw.z); v1[1] += bf_hi(pw.z); v1[2] += bf_lo(pw.w); v1[3] += bf_hi(pw.w); }
;                     u32x4 w; w.x = cvt_pk_bf16(v0[0], v0[1]); w.y = cvt_pk_bf16(v0[2], v0[3]); w.z = cvt_pk_bf16(v1[0], v1[1]); w.w = cvt_pk_bf16(v1[2], v1[3]);
;                     *(u32x4*)(rowp + bj * HALF) = w; } }
	v_lshlrev_b32_e32 v88, 16, v92
	v_lshlrev_b32_e32 v101, 16, v96
	v_and_b32_e32 v89, 0xffff0000, v92
	v_lshlrev_b32_e32 v92, 16, v94
	v_and_b32_e32 v96, 0xffff0000, v96
	v_lshlrev_b32_e32 v105, 16, v98
	v_fmac_f32_e32 v101, v84, v88
	v_fmac_f32_e32 v96, v85, v89
	v_fmac_f32_e32 v105, v80, v92
	v_cvt_pk_bf16_f32 v80, v101, v96
	v_ashrrev_i32_e32 v101, 31, v100
	v_lshlrev_b64 v[88:89], 11, v[100:101]
	v_lshlrev_b32_e32 v90, 16, v93
	v_and_b32_e32 v91, 0xffff0000, v93
	v_and_b32_e32 v93, 0xffff0000, v94
	v_and_b32_e32 v98, 0xffff0000, v98
	v_lshl_add_u64 v[88:89], s[0:1], 0, v[88:89]
	v_lshlrev_b32_e32 v94, 16, v95
	v_and_b32_e32 v95, 0xffff0000, v95
	v_lshlrev_b32_e32 v104, 16, v97
	v_and_b32_e32 v97, 0xffff0000, v97
	v_lshlrev_b32_e32 v106, 16, v99
	v_and_b32_e32 v99, 0xffff0000, v99
	v_fmac_f32_e32 v98, v81, v93
	v_lshl_add_u64 v[92:93], v[88:89], 0, v[144:145]
	v_fmac_f32_e32 v104, v86, v90
	v_fmac_f32_e32 v97, v87, v91
	v_fmac_f32_e32 v106, v82, v94
	v_fmac_f32_e32 v99, v83, v95
	v_cvt_pk_bf16_f32 v81, v104, v97
	v_cvt_pk_bf16_f32 v82, v105, v98
	v_cvt_pk_bf16_f32 v83, v106, v99
	global_load_dwordx4 v[84:87], v[102:103], off
	global_load_dwordx4 v[88:91], v[92:93], off
	s_waitcnt vmcnt(0)
	v_lshlrev_b32_e32 v94, 16, v88
	global_store_dwordx4 v[108:109], v[80:83], off offset:256
	v_and_b32_e32 v88, 0xffff0000, v88
	v_lshlrev_b32_e32 v95, 16, v89
	v_lshlrev_b32_e32 v80, 16, v84
	v_and_b32_e32 v81, 0xffff0000, v84
	v_lshlrev_b32_e32 v82, 16, v85
	v_and_b32_e32 v83, 0xffff0000, v85
	v_lshlrev_b32_e32 v84, 16, v86
	v_and_b32_e32 v85, 0xffff0000, v86
	v_lshlrev_b32_e32 v86, 16, v87
	v_and_b32_e32 v87, 0xffff0000, v87
	v_and_b32_e32 v89, 0xffff0000, v89
	v_lshlrev_b32_e32 v96, 16, v90
	v_and_b32_e32 v90, 0xffff0000, v90
	v_lshlrev_b32_e32 v97, 16, v91
	v_and_b32_e32 v91, 0xffff0000, v91
	v_fmac_f32_e32 v94, v76, v80
	v_fmac_f32_e32 v88, v77, v81
	v_fmac_f32_e32 v95, v78, v82
	v_fmac_f32_e32 v89, v79, v83
	v_fmac_f32_e32 v96, v72, v84
	v_fmac_f32_e32 v90, v73, v85
	v_fmac_f32_e32 v97, v74, v86
	v_fmac_f32_e32 v91, v75, v87
	v_cvt_pk_bf16_f32 v72, v94, v88
	v_cvt_pk_bf16_f32 v73, v95, v89
	v_cvt_pk_bf16_f32 v74, v96, v90
	v_cvt_pk_bf16_f32 v75, v97, v91
	global_load_dwordx4 v[76:79], v[102:103], off offset:256
	global_load_dwordx4 v[80:83], v[92:93], off offset:256
	v_add_u32_e32 v84, 0x80, v146
	global_store_dwordx4 v[92:93], v[72:75], off
	v_mad_i64_i32 v[86:87], s[18:19], v84, s41, v[148:149]
	v_lshl_add_u64 v[86:87], v[86:87], 0, v[144:145]
	s_waitcnt vmcnt(0)
	v_lshlrev_b32_e32 v72, 16, v76
	v_lshlrev_b32_e32 v85, 16, v80
	v_and_b32_e32 v73, 0xffff0000, v76
	v_lshlrev_b32_e32 v76, 16, v78
	v_and_b32_e32 v80, 0xffff0000, v80
	v_lshlrev_b32_e32 v89, 16, v82
	v_fmac_f32_e32 v85, v68, v72
	v_fmac_f32_e32 v80, v69, v73
	v_fmac_f32_e32 v89, v64, v76
	v_cvt_pk_bf16_f32 v64, v85, v80
	v_ashrrev_i32_e32 v85, 31, v84
	v_lshlrev_b64 v[72:73], 11, v[84:85]
	v_lshlrev_b32_e32 v74, 16, v77
	v_and_b32_e32 v75, 0xffff0000, v77
	v_and_b32_e32 v77, 0xffff0000, v78
	v_and_b32_e32 v82, 0xffff0000, v82
	v_lshl_add_u64 v[72:73], s[0:1], 0, v[72:73]
	v_lshlrev_b32_e32 v78, 16, v79
	v_and_b32_e32 v79, 0xffff0000, v79
	v_lshlrev_b32_e32 v88, 16, v81
	v_and_b32_e32 v81, 0xffff0000, v81
	v_lshlrev_b32_e32 v90, 16, v83
	v_and_b32_e32 v83, 0xffff0000, v83
	v_fmac_f32_e32 v82, v65, v77
	v_lshl_add_u64 v[76:77], v[72:73], 0, v[144:145]
	v_fmac_f32_e32 v88, v70, v74
	v_fmac_f32_e32 v81, v71, v75
	v_fmac_f32_e32 v90, v66, v78
	v_fmac_f32_e32 v83, v67, v79
	v_cvt_pk_bf16_f32 v65, v88, v81
	v_cvt_pk_bf16_f32 v66, v89, v82
	v_cvt_pk_bf16_f32 v67, v90, v83
	global_load_dwordx4 v[68:71], v[86:87], off
	global_load_dwordx4 v[72:75], v[76:77], off
	s_waitcnt vmcnt(0)
	v_lshlrev_b32_e32 v78, 16, v72
	global_store_dwordx4 v[92:93], v[64:67], off offset:256
	v_and_b32_e32 v72, 0xffff0000, v72
	v_lshlrev_b32_e32 v79, 16, v73
	v_lshlrev_b32_e32 v64, 16, v68
	v_and_b32_e32 v65, 0xffff0000, v68
	v_lshlrev_b32_e32 v66, 16, v69
	v_and_b32_e32 v67, 0xffff0000, v69
	v_lshlrev_b32_e32 v68, 16, v70
	v_and_b32_e32 v69, 0xffff0000, v70
	v_lshlrev_b32_e32 v70, 16, v71
	v_and_b32_e32 v71, 0xffff0000, v71
	v_and_b32_e32 v73, 0xffff0000, v73
	v_lshlrev_b32_e32 v80, 16, v74
	v_and_b32_e32 v74, 0xffff0000, v74
	v_lshlrev_b32_e32 v81, 16, v75
	v_and_b32_e32 v75, 0xffff0000, v75
	v_fmac_f32_e32 v78, v60, v64
	v_fmac_f32_e32 v72, v61, v65
	v_fmac_f32_e32 v79, v62, v66
	v_fmac_f32_e32 v73, v63, v67
	v_fmac_f32_e32 v80, v56, v68
	v_fmac_f32_e32 v74, v57, v69
	v_fmac_f32_e32 v81, v58, v70
	v_fmac_f32_e32 v75, v59, v71
	v_cvt_pk_bf16_f32 v56, v78, v72
	v_cvt_pk_bf16_f32 v57, v79, v73
	v_cvt_pk_bf16_f32 v58, v80, v74
	v_cvt_pk_bf16_f32 v59, v81, v75
	global_load_dwordx4 v[60:63], v[86:87], off offset:256
	global_load_dwordx4 v[64:67], v[76:77], off offset:256
	v_add_u32_e32 v68, 0x90, v146
	global_store_dwordx4 v[76:77], v[56:59], off
	v_mad_i64_i32 v[70:71], s[18:19], v68, s41, v[148:149]
	v_lshl_add_u64 v[70:71], v[70:71], 0, v[144:145]
	s_waitcnt vmcnt(0)
	v_lshlrev_b32_e32 v56, 16, v60
	v_lshlrev_b32_e32 v69, 16, v64
	v_and_b32_e32 v57, 0xffff0000, v60
	v_lshlrev_b32_e32 v60, 16, v62
	v_and_b32_e32 v64, 0xffff0000, v64
	v_lshlrev_b32_e32 v73, 16, v66
	v_fmac_f32_e32 v69, v52, v56
	v_fmac_f32_e32 v64, v53, v57
	v_fmac_f32_e32 v73, v48, v60
	v_cvt_pk_bf16_f32 v48, v69, v64
	v_ashrrev_i32_e32 v69, 31, v68
	v_lshlrev_b64 v[56:57], 11, v[68:69]
	v_lshlrev_b32_e32 v58, 16, v61
	v_and_b32_e32 v59, 0xffff0000, v61
	v_and_b32_e32 v61, 0xffff0000, v62
	v_and_b32_e32 v66, 0xffff0000, v66
	v_lshl_add_u64 v[56:57], s[0:1], 0, v[56:57]
	v_lshlrev_b32_e32 v62, 16, v63
	v_and_b32_e32 v63, 0xffff0000, v63
	v_lshlrev_b32_e32 v72, 16, v65
	v_and_b32_e32 v65, 0xffff0000, v65
	v_lshlrev_b32_e32 v74, 16, v67
	v_and_b32_e32 v67, 0xffff0000, v67
	v_fmac_f32_e32 v66, v49, v61
	v_lshl_add_u64 v[60:61], v[56:57], 0, v[144:145]
	v_fmac_f32_e32 v72, v54, v58
	v_fmac_f32_e32 v65, v55, v59
	v_fmac_f32_e32 v74, v50, v62
	v_fmac_f32_e32 v67, v51, v63
	v_cvt_pk_bf16_f32 v49, v72, v65
	v_cvt_pk_bf16_f32 v50, v73, v66
	v_cvt_pk_bf16_f32 v51, v74, v67
	global_load_dwordx4 v[52:55], v[70:71], off
	global_load_dwordx4 v[56:59], v[60:61], off
	s_waitcnt vmcnt(0)
; __device__ __forceinline__ unsigned cvt_pk_bf16(float lo, float hi) { unsigned r; asm volatile("v_cvt_pk_bf16_f32 %0, %1, %2" : "=v"(r) : "v"(lo), "v"(hi)); return r; }
; __device__ __forceinline__ float bf_lo(unsigned u) { return __uint_as_float(u << 16); }
; __device__ __forceinline__ float bf_hi(unsigned u) { return __uint_as_float(u & 0xffff0000u); }
;     __device__ __forceinline__ void operator()(const f32x4 (&acc)[2][2][4][2], const Unit& u, int wr, int wc, int fr, int fq) const {
;     ...
;             for (int m = 0; m < 4; ++m) { const size_t r = (size_t)(row0 + ai * HALF + m * 16); bf16_t* rowp = O + r * ldc + col0; const bf16_t* gp = G + r * ldg + col0;
; #pragma unroll
;                 for (int bj = 0; bj < 2; ++bj) { const u32x4 gw = *(const u32x4*)(gp + bj * HALF);
;                     f32x4 v0 = acc[ai][bj][m][0], v1 = acc[ai][bj][m][1];
;                     v0[0] *= bf_lo(gw.x); v0[1] *= bf_hi(gw.x); v0[2] *= bf_lo(gw.y); v0[3] *= bf_hi(gw.y);
;                     v1[0] *= bf_lo(gw.z); v1[1] *= bf_hi(gw.z); v1[2] *= bf_lo(gw.w); v1[3] *= bf_hi(gw.w);
;                     if (ACCUM) { const u32x4 pw = *(const u32x4*)(rowp + bj * HALF);
;                         v0[0] += bf_lo(pw.x); v0[1] += bf_hi(pw.x); v0[2] += bf_lo(pw.y); v0[3] += bf_hi(pw.y);
;                         v1[0] += bf_lo(pw.z); v1[1] += bf_hi(pw.z); v1[2] += bf_lo(pw.w); v1[3] += bf_hi(pw.w); }
;                     u32x4 w; w.x = cvt_pk_bf16(v0[0], v0[1]); w.y = cvt_pk_bf16(v0[2], v0[3]); w.z = cvt_pk_bf16(v1[0], v1[1]); w.w = cvt_pk_bf16(v1[2], v1[3]);
;                     *(u32x4*)(rowp + bj * HALF) = w; } }
	v_lshlrev_b32_e32 v62, 16, v56
	global_store_dwordx4 v[76:77], v[48:51], off offset:256
	v_and_b32_e32 v56, 0xffff0000, v56
	v_lshlrev_b32_e32 v63, 16, v57
	v_lshlrev_b32_e32 v48, 16, v52
	v_and_b32_e32 v49, 0xffff0000, v52
	v_lshlrev_b32_e32 v50, 16, v53
	v_and_b32_e32 v51, 0xffff0000, v53
	v_lshlrev_b32_e32 v52, 16, v54
	v_and_b32_e32 v53, 0xffff0000, v54
	v_lshlrev_b32_e32 v54, 16, v55
	v_and_b32_e32 v55, 0xffff0000, v55
	v_and_b32_e32 v57, 0xffff0000, v57
	v_lshlrev_b32_e32 v64, 16, v58
	v_and_b32_e32 v58, 0xffff0000, v58
	v_lshlrev_b32_e32 v65, 16, v59
	v_and_b32_e32 v59, 0xffff0000, v59
	v_fmac_f32_e32 v62, v44, v48
	v_fmac_f32_e32 v56, v45, v49
	v_fmac_f32_e32 v63, v46, v50
	v_fmac_f32_e32 v57, v47, v51
	v_fmac_f32_e32 v64, v40, v52
	v_fmac_f32_e32 v58, v41, v53
	v_fmac_f32_e32 v65, v42, v54
	v_fmac_f32_e32 v59, v43, v55
	v_cvt_pk_bf16_f32 v40, v62, v56
	v_cvt_pk_bf16_f32 v41, v63, v57
	v_cvt_pk_bf16_f32 v42, v64, v58
	v_cvt_pk_bf16_f32 v43, v65, v59
	global_load_dwordx4 v[44:47], v[70:71], off offset:256
	global_load_dwordx4 v[48:51], v[60:61], off offset:256
	v_add_u32_e32 v52, 0xa0, v146
	global_store_dwordx4 v[60:61], v[40:43], off
	v_mad_i64_i32 v[54:55], s[18:19], v52, s41, v[148:149]
	v_lshl_add_u64 v[54:55], v[54:55], 0, v[144:145]
	s_waitcnt vmcnt(0)
	v_lshlrev_b32_e32 v40, 16, v44
	v_lshlrev_b32_e32 v53, 16, v48
	v_and_b32_e32 v41, 0xffff0000, v44
	v_lshlrev_b32_e32 v44, 16, v46
	v_and_b32_e32 v48, 0xffff0000, v48
	v_lshlrev_b32_e32 v57, 16, v50
	v_fmac_f32_e32 v53, v36, v40
	v_fmac_f32_e32 v48, v37, v41
	v_fmac_f32_e32 v57, v32, v44
	v_cvt_pk_bf16_f32 v32, v53, v48
	v_ashrrev_i32_e32 v53, 31, v52
	v_lshlrev_b64 v[40:41], 11, v[52:53]
	v_lshlrev_b32_e32 v42, 16, v45
	v_and_b32_e32 v43, 0xffff0000, v45
	v_and_b32_e32 v45, 0xffff0000, v46
	v_and_b32_e32 v50, 0xffff0000, v50
	v_lshl_add_u64 v[40:41], s[0:1], 0, v[40:41]
	v_lshlrev_b32_e32 v46, 16, v47
	v_and_b32_e32 v47, 0xffff0000, v47
	v_lshlrev_b32_e32 v56, 16, v49
	v_and_b32_e32 v49, 0xffff0000, v49
	v_lshlrev_b32_e32 v58, 16, v51
	v_and_b32_e32 v51, 0xffff0000, v51
	v_fmac_f32_e32 v50, v33, v45
	v_lshl_add_u64 v[44:45], v[40:41], 0, v[144:145]
	v_fmac_f32_e32 v56, v38, v42
	v_fmac_f32_e32 v49, v39, v43
	v_fmac_f32_e32 v58, v34, v46
	v_fmac_f32_e32 v51, v35, v47
	v_cvt_pk_bf16_f32 v33, v56, v49
	v_cvt_pk_bf16_f32 v34, v57, v50
	v_cvt_pk_bf16_f32 v35, v58, v51
	global_load_dwordx4 v[36:39], v[54:55], off
	global_load_dwordx4 v[40:43], v[44:45], off
	s_waitcnt vmcnt(0)
	v_lshlrev_b32_e32 v46, 16, v40
	global_store_dwordx4 v[60:61], v[32:35], off offset:256
	v_and_b32_e32 v40, 0xffff0000, v40
	v_lshlrev_b32_e32 v47, 16, v41
	v_lshlrev_b32_e32 v32, 16, v36
	v_and_b32_e32 v33, 0xffff0000, v36
	v_lshlrev_b32_e32 v34, 16, v37
	v_and_b32_e32 v35, 0xffff0000, v37
	v_lshlrev_b32_e32 v36, 16, v38
	v_and_b32_e32 v37, 0xffff0000, v38
	v_lshlrev_b32_e32 v38, 16, v39
	v_and_b32_e32 v39, 0xffff0000, v39
	v_and_b32_e32 v41, 0xffff0000, v41
	v_lshlrev_b32_e32 v48, 16, v42
	v_and_b32_e32 v42, 0xffff0000, v42
	v_lshlrev_b32_e32 v49, 16, v43
	v_and_b32_e32 v43, 0xffff0000, v43
	v_fmac_f32_e32 v46, v28, v32
	v_fmac_f32_e32 v40, v29, v33
	v_fmac_f32_e32 v47, v30, v34
	v_fmac_f32_e32 v41, v31, v35
	v_fmac_f32_e32 v48, v24, v36
	v_fmac_f32_e32 v42, v25, v37
	v_fmac_f32_e32 v49, v26, v38
	v_fmac_f32_e32 v43, v27, v39
	v_cvt_pk_bf16_f32 v24, v46, v40
	v_cvt_pk_bf16_f32 v25, v47, v41
	v_cvt_pk_bf16_f32 v26, v48, v42
	v_cvt_pk_bf16_f32 v27, v49, v43
	global_load_dwordx4 v[28:31], v[54:55], off offset:256
	global_load_dwordx4 v[32:35], v[44:45], off offset:256
	v_add_u32_e32 v36, 0xb0, v146
	global_store_dwordx4 v[44:45], v[24:27], off
	v_mad_i64_i32 v[38:39], s[18:19], v36, s41, v[148:149]
	v_lshl_add_u64 v[38:39], v[38:39], 0, v[144:145]
	s_mov_b64 s[18:19], s[12:13]
	s_waitcnt vmcnt(0)
; __device__ __forceinline__ unsigned cvt_pk_bf16(float lo, float hi) { unsigned r; asm volatile("v_cvt_pk_bf16_f32 %0, %1, %2" : "=v"(r) : "v"(lo), "v"(hi)); return r; }
; __device__ __forceinline__ float bf_lo(unsigned u) { return __uint_as_float(u << 16); }
; __device__ __forceinline__ float bf_hi(unsigned u) { return __uint_as_float(u & 0xffff0000u); }
; #define PG8_WAIT_V(n) asm volatile("s_waitcnt vmcnt(" #n ")" ::: "memory")
; #define PG8_BAR __builtin_amdgcn_s_barrier()
;     __device__ __forceinline__ void operator()(const f32x4 (&acc)[2][2][4][2], const Unit& u, int wr, int wc, int fr, int fq) const {
;     ...
;             for (int m = 0; m < 4; ++m) { const size_t r = (size_t)(row0 + ai * HALF + m * 16); bf16_t* rowp = O + r * ldc + col0; const bf16_t* gp = G + r * ldg + col0;
; #pragma unroll
;                 for (int bj = 0; bj < 2; ++bj) { const u32x4 gw = *(const u32x4*)(gp + bj * HALF);
;                     f32x4 v0 = acc[ai][bj][m][0], v1 = acc[ai][bj][m][1];
;                     v0[0] *= bf_lo(gw.x); v0[1] *= bf_hi(gw.x); v0[2] *= bf_lo(gw.y); v0[3] *= bf_hi(gw.y);
;                     v1[0] *= bf_lo(gw.z); v1[1] *= bf_hi(gw.z); v1[2] *= bf_lo(gw.w); v1[3] *= bf_hi(gw.w);
;                     if (ACCUM) { const u32x4 pw = *(const u32x4*)(rowp + bj * HALF);
;                         v0[0] += bf_lo(pw.x); v0[1] += bf_hi(pw.x); v0[2] += bf_lo(pw.y); v0[3] += bf_hi(pw.y);
;                         v1[0] += bf_lo(pw.z); v1[1] += bf_hi(pw.z); v1[2] += bf_lo(pw.w); v1[3] += bf_hi(pw.w); }
;                     u32x4 w; w.x = cvt_pk_bf16(v0[0], v0[1]); w.y = cvt_pk_bf16(v0[2], v0[3]); w.z = cvt_pk_bf16(v1[0], v1[1]); w.w = cvt_pk_bf16(v1[2], v1[3]);
;                     *(u32x4*)(rowp + bj * HALF) = w; } }
; template <class Epi, class Sched>
; __device__ __forceinline__ void gemm_phase(PG8_LAS unsigned char* lds, const Gemm g, const Sched& S, const Epi& E) {
;     ...
;         if (!has_next) break;
; #pragma unroll
;         for (int a = 0; a < 2; ++a)
; #pragma unroll
;             for (int b = 0; b < 2; ++b)
; #pragma unroll
;                 for (int m = 0; m < 4; ++m)
; #pragma unroll
;                     for (int n = 0; n < 2; ++n) acc[a][b][m][n] = (f32x4){0.f, 0.f, 0.f, 0.f};
;         cur = nxt; cA = nA; cB = nB; ++ui;
;     }
;     PG8_WAIT_V(0);
;     if (wr == 0) PG8_BAR;
;     PG8_BAR;
	v_lshlrev_b32_e32 v24, 16, v28
	v_lshlrev_b32_e32 v37, 16, v32
	v_and_b32_e32 v25, 0xffff0000, v28
	v_lshlrev_b32_e32 v28, 16, v30
	v_and_b32_e32 v32, 0xffff0000, v32
	v_lshlrev_b32_e32 v41, 16, v34
	v_fmac_f32_e32 v37, v20, v24
	v_fmac_f32_e32 v32, v21, v25
	v_fmac_f32_e32 v41, v16, v28
	v_cvt_pk_bf16_f32 v16, v37, v32
	v_ashrrev_i32_e32 v37, 31, v36
	v_lshlrev_b64 v[24:25], 11, v[36:37]
	v_lshlrev_b32_e32 v26, 16, v29
	v_and_b32_e32 v27, 0xffff0000, v29
	v_and_b32_e32 v29, 0xffff0000, v30
	v_and_b32_e32 v34, 0xffff0000, v34
	v_lshl_add_u64 v[24:25], s[0:1], 0, v[24:25]
	v_lshlrev_b32_e32 v30, 16, v31
	v_and_b32_e32 v31, 0xffff0000, v31
	v_lshlrev_b32_e32 v40, 16, v33
	v_and_b32_e32 v33, 0xffff0000, v33
	v_lshlrev_b32_e32 v42, 16, v35
	v_and_b32_e32 v35, 0xffff0000, v35
	v_fmac_f32_e32 v34, v17, v29
	v_lshl_add_u64 v[28:29], v[24:25], 0, v[144:145]
	v_fmac_f32_e32 v40, v22, v26
	v_fmac_f32_e32 v33, v23, v27
	v_fmac_f32_e32 v42, v18, v30
	v_fmac_f32_e32 v35, v19, v31
	v_cvt_pk_bf16_f32 v17, v40, v33
	v_cvt_pk_bf16_f32 v18, v41, v34
	v_cvt_pk_bf16_f32 v19, v42, v35
	global_load_dwordx4 v[20:23], v[38:39], off
	global_load_dwordx4 v[24:27], v[28:29], off
	s_waitcnt vmcnt(0)
	v_lshlrev_b32_e32 v30, 16, v24
	global_store_dwordx4 v[44:45], v[16:19], off offset:256
	v_and_b32_e32 v24, 0xffff0000, v24
	v_lshlrev_b32_e32 v31, 16, v25
	v_lshlrev_b32_e32 v16, 16, v20
	v_and_b32_e32 v17, 0xffff0000, v20
	v_lshlrev_b32_e32 v18, 16, v21
	v_and_b32_e32 v19, 0xffff0000, v21
	v_lshlrev_b32_e32 v20, 16, v22
	v_and_b32_e32 v21, 0xffff0000, v22
	v_lshlrev_b32_e32 v22, 16, v23
	v_and_b32_e32 v23, 0xffff0000, v23
	v_and_b32_e32 v25, 0xffff0000, v25
	v_lshlrev_b32_e32 v32, 16, v26
	v_and_b32_e32 v26, 0xffff0000, v26
	v_lshlrev_b32_e32 v33, 16, v27
	v_and_b32_e32 v27, 0xffff0000, v27
	v_fmac_f32_e32 v30, v12, v16
	v_fmac_f32_e32 v24, v13, v17
	v_fmac_f32_e32 v31, v14, v18
	v_fmac_f32_e32 v25, v15, v19
	v_fmac_f32_e32 v32, v8, v20
	v_fmac_f32_e32 v26, v9, v21
	v_fmac_f32_e32 v33, v10, v22
	v_fmac_f32_e32 v27, v11, v23
	v_cvt_pk_bf16_f32 v8, v30, v24
	v_cvt_pk_bf16_f32 v9, v31, v25
	v_cvt_pk_bf16_f32 v10, v32, v26
	v_cvt_pk_bf16_f32 v11, v33, v27
	global_load_dwordx4 v[12:15], v[38:39], off offset:256
	global_load_dwordx4 v[16:19], v[28:29], off offset:256
	s_waitcnt vmcnt(0)
	v_lshlrev_b32_e32 v20, 16, v16
	global_store_dwordx4 v[28:29], v[8:11], off
	v_and_b32_e32 v16, 0xffff0000, v16
	v_lshlrev_b32_e32 v21, 16, v17
	v_lshlrev_b32_e32 v8, 16, v12
	v_and_b32_e32 v9, 0xffff0000, v12
	v_lshlrev_b32_e32 v10, 16, v13
	v_and_b32_e32 v11, 0xffff0000, v13
	v_lshlrev_b32_e32 v12, 16, v14
	v_and_b32_e32 v13, 0xffff0000, v14
	v_lshlrev_b32_e32 v14, 16, v15
	v_and_b32_e32 v15, 0xffff0000, v15
	v_and_b32_e32 v17, 0xffff0000, v17
	v_lshlrev_b32_e32 v22, 16, v18
	v_and_b32_e32 v18, 0xffff0000, v18
	v_lshlrev_b32_e32 v23, 16, v19
	v_and_b32_e32 v19, 0xffff0000, v19
	v_fmac_f32_e32 v20, v4, v8
	v_fmac_f32_e32 v16, v5, v9
	v_fmac_f32_e32 v21, v6, v10
	v_fmac_f32_e32 v17, v7, v11
	v_fmac_f32_e32 v22, v0, v12
	v_fmac_f32_e32 v18, v1, v13
	v_fmac_f32_e32 v23, v2, v14
	v_fmac_f32_e32 v19, v3, v15
	v_cvt_pk_bf16_f32 v0, v20, v16
	v_cvt_pk_bf16_f32 v1, v21, v17
	v_cvt_pk_bf16_f32 v2, v22, v18
	v_cvt_pk_bf16_f32 v3, v23, v19
	global_store_dwordx4 v[28:29], v[0:3], off offset:256
	s_cbranch_vccz .LBB0_1004
	s_waitcnt vmcnt(0)
	s_cmpk_gt_u32 s25, 0xff
	s_cbranch_scc1 .LBB0_1015
	s_barrier

; #define PG8_STAGE(bufoff, gbase, voff) do { _Pragma("unroll") for (int _i = 0; _i < 2; ++_i) \
;         __builtin_amdgcn_global_load_lds((const unsigned*)((const char*)(gbase) + (voff)[_i]), (PG8_LAS unsigned*)(lds + (bufoff) + ldsw + _i * 8192), 16, 0, 0); } while (0)
; #define PG8_WAIT_V(n) asm volatile("s_waitcnt vmcnt(" #n ")" ::: "memory")
; template <class Epi, class Sched>
; __device__ __forceinline__ void gemm_phase(PG8_LAS unsigned char* lds, const Gemm g, const Sched& S, const Epi& E) {
;     ...
;         const bool has_next = S.next(ui + 1, nxt);
;         const char* nA = has_next ? (const char*)g.A + (size_t)nxt.pm * tstep : cA; const char* nB = has_next ? (const char*)g.Bt + (size_t)nxt.pn * tstep : cB;
;         for (int t = 0; t < nt; t += 2) {
;             const bool last = (t == nt - 2);
;             const char* a1 = cA + (size_t)(t + 1) * kstep;
;             const char* a2 = last ? nA : cA + (size_t)(t + 2) * kstep; const char* b2 = last ? nB : cB + (size_t)(t + 2) * kstep;
;             const char* a3 = a2 + kstep; const char* b3 = b2 + kstep;
;             if (last && has_next) S.a_ready(nxt);
;             PG8_LDB(B0, 0, 0); PG8_SCHED; PG8_LDA(At, 0, 0); PG8_STAGE(PG8_SA(1, 1), a1 + hstep, voffA);
;             PG8_WAIT_L(8); PG8_BAR; PG8_WAIT_L(0); PG8_MMA(0, 0, At, B0); PG8_BAR; PG8_SCHED;
;             PG8_LDB(B1, 0, 1); PG8_STAGE(PG8_SB(0, 0), b2, voffB);
;             PG8_BAR; PG8_WAIT_L(0); PG8_MMA(0, 1, At, B1); PG8_BAR;
;             PG8_LDA(At, 0, 1); PG8_STAGE(PG8_SA(0, 0), a2, voffA);
;             PG8_BAR; PG8_WAIT_L(0); PG8_MMA(1, 0, At, B0); PG8_BAR; PG8_SCHED;
;             PG8_STAGE(PG8_SB(0, 1), b2 + hstep, voffB);
;             PG8_WAIT_V(6); PG8_BAR; PG8_MMA(1, 1, At, B1); PG8_BAR;
;             PG8_LDB(B0, 1, 0); PG8_SCHED; PG8_LDA(At, 1, 0); PG8_STAGE(PG8_SA(0, 1), a2 + hstep, voffA);
;             PG8_WAIT_L(8); PG8_BAR; PG8_WAIT_L(0); PG8_MMA(0, 0, At, B0); PG8_BAR; PG8_SCHED;
;             PG8_LDB(B1, 1, 1); PG8_STAGE(PG8_SB(1, 0), b3, voffB);
;             PG8_BAR; PG8_WAIT_L(0); PG8_MMA(0, 1, At, B1); PG8_BAR;
;             PG8_LDA(At, 1, 1); PG8_STAGE(PG8_SA(1, 0), a3, voffA);
;             PG8_BAR; PG8_WAIT_L(0); PG8_MMA(1, 0, At, B0); PG8_BAR; PG8_SCHED;
;             PG8_STAGE(PG8_SB(1, 1), b3 + hstep, voffB);
;             PG8_WAIT_V(6); PG8_BAR; PG8_MMA(1, 1, At, B1); PG8_BAR;
.LBB0_1082:
	s_ashr_i32 s17, s16, 31
	v_cmp_lt_i64_e32 vcc, s[18:19], v[140:141]
	s_lshl_b64 s[18:19], s[16:17], 19
	s_add_u32 s18, s35, s18
	s_addc_u32 s19, s36, s19
	s_and_b64 s[20:21], vcc, exec
	s_cselect_b32 s17, s19, s25
	s_cselect_b32 s52, s18, s24
	s_ashr_i32 s15, s14, 31
	s_lshl_b64 s[20:21], s[14:15], 19
	s_add_u32 s20, s72, s20
	s_addc_u32 s21, s73, s21
	s_and_b64 s[28:29], vcc, exec
	s_cselect_b32 s15, s21, s27
	s_cselect_b32 s53, s20, s26
	s_add_u32 s24, s24, 0x40080
	s_addc_u32 s25, s25, 0
	s_add_u32 s54, s26, 0x100
	s_addc_u32 s55, s27, 0
	s_mov_b32 s56, -2
	ds_read_b128 v[152:155], v149
	ds_read_b128 v[156:159], v149 offset:1024
	ds_read_b128 v[160:163], v149 offset:2048
	ds_read_b128 v[164:167], v149 offset:3072
	s_add_u32 s26, s24, 0xfffc0080
	s_addc_u32 s27, s25, -1
	s_cmp_eq_u32 s56, 12
	s_cselect_b32 s29, s17, s27
	s_cselect_b32 s28, s52, s26
	s_cselect_b32 s27, s15, s55
	s_cselect_b32 s26, s53, s54
	ds_read_b128 v[168:171], v150
	ds_read_b128 v[172:175], v150 offset:1024
	ds_read_b128 v[182:185], v150 offset:2048
	ds_read_b128 v[190:193], v150 offset:3072
	ds_read_b128 v[194:197], v150 offset:4096
	ds_read_b128 v[198:201], v150 offset:5120
	ds_read_b128 v[202:205], v150 offset:6144
	ds_read_b128 v[206:209], v150 offset:7168
	s_waitcnt lgkmcnt(8)
	ds_read_b128 v[210:213], v151
	ds_read_b128 v[214:217], v151 offset:1024
	ds_read_b128 v[218:221], v151 offset:2048
	ds_read_b128 v[222:225], v151 offset:3072
	s_add_i32 m0, s23, 0xc000
	s_nop 0
	global_load_lds_dwordx4 v136, s[24:25]
	s_nop 1
	s_add_i32 m0, s23, 0xe000
	s_nop 0
	global_load_lds_dwordx4 v138, s[24:25]
	s_waitcnt vmcnt(8) lgkmcnt(0)
	s_barrier
	v_mfma_f32_16x16x32_bf16 v[124:127], v[152:155], v[168:171], 0
	v_mfma_f32_16x16x32_bf16 v[120:123], v[160:163], v[168:171], 0
	v_mfma_f32_16x16x32_bf16 v[108:111], v[152:155], v[182:185], 0
	v_mfma_f32_16x16x32_bf16 v[104:107], v[160:163], v[182:185], 0
	v_mfma_f32_16x16x32_bf16 v[92:95], v[152:155], v[194:197], 0
	v_mfma_f32_16x16x32_bf16 v[88:91], v[160:163], v[194:197], 0
	v_mfma_f32_16x16x32_bf16 v[76:79], v[152:155], v[202:205], 0
	v_mfma_f32_16x16x32_bf16 v[72:75], v[160:163], v[202:205], 0
	v_mfma_f32_16x16x32_bf16 v[124:127], v[156:159], v[172:175], v[124:127]
	v_mfma_f32_16x16x32_bf16 v[120:123], v[164:167], v[172:175], v[120:123]
	v_mfma_f32_16x16x32_bf16 v[108:111], v[156:159], v[190:193], v[108:111]
	v_mfma_f32_16x16x32_bf16 v[104:107], v[164:167], v[190:193], v[104:107]
	v_mfma_f32_16x16x32_bf16 v[92:95], v[156:159], v[198:201], v[92:95]
	v_mfma_f32_16x16x32_bf16 v[88:91], v[164:167], v[198:201], v[88:91]
	v_mfma_f32_16x16x32_bf16 v[76:79], v[156:159], v[206:209], v[76:79]
	v_mfma_f32_16x16x32_bf16 v[72:75], v[164:167], v[206:209], v[72:75]
	v_mfma_f32_16x16x32_bf16 v[116:119], v[210:213], v[168:171], 0
	v_mfma_f32_16x16x32_bf16 v[112:115], v[218:221], v[168:171], 0
	v_mfma_f32_16x16x32_bf16 v[100:103], v[210:213], v[182:185], 0
	v_mfma_f32_16x16x32_bf16 v[96:99], v[218:221], v[182:185], 0
	v_mfma_f32_16x16x32_bf16 v[84:87], v[210:213], v[194:197], 0
	v_mfma_f32_16x16x32_bf16 v[80:83], v[218:221], v[194:197], 0
	v_mfma_f32_16x16x32_bf16 v[68:71], v[210:213], v[202:205], 0
	v_mfma_f32_16x16x32_bf16 v[64:67], v[218:221], v[202:205], 0
	v_mfma_f32_16x16x32_bf16 v[116:119], v[214:217], v[172:175], v[116:119]
	v_mfma_f32_16x16x32_bf16 v[112:115], v[222:225], v[172:175], v[112:115]
	v_mfma_f32_16x16x32_bf16 v[100:103], v[214:217], v[190:193], v[100:103]
	v_mfma_f32_16x16x32_bf16 v[96:99], v[222:225], v[190:193], v[96:99]
	v_mfma_f32_16x16x32_bf16 v[84:87], v[214:217], v[198:201], v[84:87]
	v_mfma_f32_16x16x32_bf16 v[80:83], v[222:225], v[198:201], v[80:83]
	v_mfma_f32_16x16x32_bf16 v[68:71], v[214:217], v[206:209], v[68:71]
	v_mfma_f32_16x16x32_bf16 v[64:67], v[222:225], v[206:209], v[64:67]
	s_barrier
	ds_read_b128 v[168:171], v150 offset:16384
	ds_read_b128 v[172:175], v150 offset:17408
	ds_read_b128 v[182:185], v150 offset:18432
	ds_read_b128 v[190:193], v150 offset:19456
	ds_read_b128 v[194:197], v150 offset:20480
	ds_read_b128 v[198:201], v150 offset:21504
	ds_read_b128 v[202:205], v150 offset:22528
	ds_read_b128 v[206:209], v150 offset:23552
	s_add_i32 s57, s45, s37
	s_add_u32 s98, s26, s6
	s_addc_u32 s99, s27, s7
	s_mov_b32 m0, s57
	s_nop 0
	global_load_lds_dwordx4 v130, s[26:27]
	s_nop 1
	s_add_i32 m0, s57, 0x2000
	s_nop 0
	global_load_lds_dwordx4 v134, s[26:27]
	s_nop 1
	s_mov_b32 m0, s23
	s_add_u32 s100, s28, s6
	s_addc_u32 s101, s29, s7
	global_load_lds_dwordx4 v128, s[28:29]
	s_nop 1
	s_mov_b32 m0, s38
	s_nop 0
	global_load_lds_dwordx4 v132, s[28:29]
	s_add_u32 s58, s26, 0x40000
	s_addc_u32 s59, s27, 0
	s_add_i32 s57, s46, s37
	s_mov_b32 m0, s57
	s_nop 0
	global_load_lds_dwordx4 v130, s[58:59]
	s_nop 1
	s_add_i32 m0, s57, 0x2000
	s_nop 0
	global_load_lds_dwordx4 v134, s[58:59]
	s_waitcnt vmcnt(8) lgkmcnt(0)
	s_barrier
; #define PG8_STAGE(bufoff, gbase, voff) do { _Pragma("unroll") for (int _i = 0; _i < 2; ++_i) \
;         __builtin_amdgcn_global_load_lds((const unsigned*)((const char*)(gbase) + (voff)[_i]), (PG8_LAS unsigned*)(lds + (bufoff) + ldsw + _i * 8192), 16, 0, 0); } while (0)
; #define PG8_LDA(dst, b, h) do { _Pragma("unroll") for (int m = 0; m < 4; ++m) _Pragma("unroll") for (int k = 0; k < 2; ++k) dst[m][k] = *(const PG8_LAS bf16x8*)(lds + PG8_SA(b, h) + aoff + m * 2048 + k * 1024); } while (0)
; #define PG8_LDB(dst, b, h) do { _Pragma("unroll") for (int n = 0; n < 2; ++n) _Pragma("unroll") for (int k = 0; k < 2; ++k) dst[n][k] = *(const PG8_LAS bf16x8*)(lds + PG8_SB(b, h) + boff + n * 2048 + k * 1024); } while (0)
; #define PG8_WAIT_V(n) asm volatile("s_waitcnt vmcnt(" #n ")" ::: "memory")
; #define PG8_WAIT_L(n) asm volatile("s_waitcnt lgkmcnt(" #n ")" ::: "memory")
; #define PG8_BAR __builtin_amdgcn_s_barrier()
; #define PG8_SCHED __builtin_amdgcn_sched_barrier(0)
; template <class Epi, class Sched>
; __device__ __forceinline__ void gemm_phase(PG8_LAS unsigned char* lds, const Gemm g, const Sched& S, const Epi& E) {
;     ...
;             PG8_LDB(B0, 0, 0); PG8_SCHED; PG8_LDA(At, 0, 0); PG8_STAGE(PG8_SA(1, 1), a1 + hstep, voffA);
;             PG8_WAIT_L(8); PG8_BAR; PG8_WAIT_L(0); PG8_MMA(0, 0, At, B0); PG8_BAR; PG8_SCHED;
;             PG8_LDB(B1, 0, 1); PG8_STAGE(PG8_SB(0, 0), b2, voffB);
;             PG8_BAR; PG8_WAIT_L(0); PG8_MMA(0, 1, At, B1); PG8_BAR;
;             PG8_LDA(At, 0, 1); PG8_STAGE(PG8_SA(0, 0), a2, voffA);
;             PG8_BAR; PG8_WAIT_L(0); PG8_MMA(1, 0, At, B0); PG8_BAR; PG8_SCHED;
;             PG8_STAGE(PG8_SB(0, 1), b2 + hstep, voffB);
;             PG8_WAIT_V(6); PG8_BAR; PG8_MMA(1, 1, At, B1); PG8_BAR;
;             PG8_LDB(B0, 1, 0); PG8_SCHED; PG8_LDA(At, 1, 0); PG8_STAGE(PG8_SA(0, 1), a2 + hstep, voffA);
;             PG8_WAIT_L(8); PG8_BAR; PG8_WAIT_L(0); PG8_MMA(0, 0, At, B0); PG8_BAR; PG8_SCHED;
;             PG8_LDB(B1, 1, 1); PG8_STAGE(PG8_SB(1, 0), b3, voffB);
;             PG8_BAR; PG8_WAIT_L(0); PG8_MMA(0, 1, At, B1); PG8_BAR;
;             PG8_LDA(At, 1, 1); PG8_STAGE(PG8_SA(1, 0), a3, voffA);
;             PG8_BAR; PG8_WAIT_L(0); PG8_MMA(1, 0, At, B0); PG8_BAR; PG8_SCHED;
;             PG8_STAGE(PG8_SB(1, 1), b3 + hstep, voffB);
;             PG8_WAIT_V(6); PG8_BAR; PG8_MMA(1, 1, At, B1); PG8_BAR;
	v_mfma_f32_16x16x32_bf16 v[60:63], v[152:155], v[168:171], 0
	v_mfma_f32_16x16x32_bf16 v[56:59], v[160:163], v[168:171], 0
	v_mfma_f32_16x16x32_bf16 v[48:51], v[152:155], v[182:185], 0
	v_mfma_f32_16x16x32_bf16 v[40:43], v[160:163], v[182:185], 0
	v_mfma_f32_16x16x32_bf16 v[32:35], v[152:155], v[194:197], 0
	v_mfma_f32_16x16x32_bf16 v[24:27], v[160:163], v[194:197], 0
	v_mfma_f32_16x16x32_bf16 v[16:19], v[152:155], v[202:205], 0
	v_mfma_f32_16x16x32_bf16 v[8:11], v[160:163], v[202:205], 0
	v_mfma_f32_16x16x32_bf16 v[60:63], v[156:159], v[172:175], v[60:63]
	v_mfma_f32_16x16x32_bf16 v[56:59], v[164:167], v[172:175], v[56:59]
	v_mfma_f32_16x16x32_bf16 v[48:51], v[156:159], v[190:193], v[48:51]
	v_mfma_f32_16x16x32_bf16 v[40:43], v[164:167], v[190:193], v[40:43]
	v_mfma_f32_16x16x32_bf16 v[32:35], v[156:159], v[198:201], v[32:35]
	v_mfma_f32_16x16x32_bf16 v[24:27], v[164:167], v[198:201], v[24:27]
	v_mfma_f32_16x16x32_bf16 v[16:19], v[156:159], v[206:209], v[16:19]
	v_mfma_f32_16x16x32_bf16 v[8:11], v[164:167], v[206:209], v[8:11]
	v_mfma_f32_16x16x32_bf16 v[52:55], v[210:213], v[168:171], 0
	v_mfma_f32_16x16x32_bf16 v[44:47], v[218:221], v[168:171], 0
	v_mfma_f32_16x16x32_bf16 v[36:39], v[210:213], v[182:185], 0
	v_mfma_f32_16x16x32_bf16 v[28:31], v[218:221], v[182:185], 0
	v_mfma_f32_16x16x32_bf16 v[20:23], v[210:213], v[194:197], 0
	v_mfma_f32_16x16x32_bf16 v[12:15], v[218:221], v[194:197], 0
	v_mfma_f32_16x16x32_bf16 v[4:7], v[210:213], v[202:205], 0
	v_mfma_f32_16x16x32_bf16 v[0:3], v[218:221], v[202:205], 0
	v_mfma_f32_16x16x32_bf16 v[52:55], v[214:217], v[172:175], v[52:55]
	v_mfma_f32_16x16x32_bf16 v[44:47], v[222:225], v[172:175], v[44:47]
	v_mfma_f32_16x16x32_bf16 v[36:39], v[214:217], v[190:193], v[36:39]
	v_mfma_f32_16x16x32_bf16 v[28:31], v[222:225], v[190:193], v[28:31]
	v_mfma_f32_16x16x32_bf16 v[20:23], v[214:217], v[198:201], v[20:23]
	v_mfma_f32_16x16x32_bf16 v[12:15], v[222:225], v[198:201], v[12:15]
	v_mfma_f32_16x16x32_bf16 v[4:7], v[214:217], v[206:209], v[4:7]
	v_mfma_f32_16x16x32_bf16 v[0:3], v[222:225], v[206:209], v[0:3]
	s_barrier
	s_add_i32 s57, 0, 0x18000
	v_add_u32_e32 v164, s57, v147
	ds_read_b128 v[152:155], v164
	ds_read_b128 v[156:159], v164 offset:1024
	ds_read_b128 v[160:163], v164 offset:2048
	ds_read_b128 v[164:167], v164 offset:3072
	ds_read_b128 v[168:171], v150 offset:32768
	ds_read_b128 v[172:175], v150 offset:33792
	ds_read_b128 v[182:185], v150 offset:34816
	ds_read_b128 v[190:193], v150 offset:35840
	ds_read_b128 v[194:197], v150 offset:36864
	ds_read_b128 v[198:201], v150 offset:37888
	ds_read_b128 v[202:205], v150 offset:38912
	ds_read_b128 v[206:209], v150 offset:39936
	v_add_u32_e32 v179, 0x1c000, v147
	s_waitcnt lgkmcnt(8)
	ds_read_b128 v[210:213], v179
	ds_read_b128 v[214:217], v179 offset:1024
	ds_read_b128 v[218:221], v179 offset:2048
	ds_read_b128 v[222:225], v179 offset:3072
	s_add_u32 s28, s28, 0x40000
	s_addc_u32 s29, s29, 0
	s_mov_b32 m0, s39
	s_nop 0
	global_load_lds_dwordx4 v128, s[28:29]
	s_nop 1
	s_mov_b32 m0, s40
	s_nop 0
	global_load_lds_dwordx4 v132, s[28:29]
	s_add_i32 s28, 0, 0x1c000
	s_waitcnt vmcnt(8) lgkmcnt(0)
	s_barrier
	v_mfma_f32_16x16x32_bf16 v[124:127], v[152:155], v[168:171], v[124:127]
	v_mfma_f32_16x16x32_bf16 v[120:123], v[160:163], v[168:171], v[120:123]
	v_mfma_f32_16x16x32_bf16 v[108:111], v[152:155], v[182:185], v[108:111]
	v_mfma_f32_16x16x32_bf16 v[104:107], v[160:163], v[182:185], v[104:107]
	v_mfma_f32_16x16x32_bf16 v[92:95], v[152:155], v[194:197], v[92:95]
	v_mfma_f32_16x16x32_bf16 v[88:91], v[160:163], v[194:197], v[88:91]
	v_mfma_f32_16x16x32_bf16 v[76:79], v[152:155], v[202:205], v[76:79]
	v_mfma_f32_16x16x32_bf16 v[72:75], v[160:163], v[202:205], v[72:75]
	v_mfma_f32_16x16x32_bf16 v[124:127], v[156:159], v[172:175], v[124:127]
	v_mfma_f32_16x16x32_bf16 v[120:123], v[164:167], v[172:175], v[120:123]
	v_mfma_f32_16x16x32_bf16 v[108:111], v[156:159], v[190:193], v[108:111]
	v_mfma_f32_16x16x32_bf16 v[104:107], v[164:167], v[190:193], v[104:107]
	v_mfma_f32_16x16x32_bf16 v[92:95], v[156:159], v[198:201], v[92:95]
	v_mfma_f32_16x16x32_bf16 v[88:91], v[164:167], v[198:201], v[88:91]
	v_mfma_f32_16x16x32_bf16 v[76:79], v[156:159], v[206:209], v[76:79]
	v_mfma_f32_16x16x32_bf16 v[72:75], v[164:167], v[206:209], v[72:75]
	v_mfma_f32_16x16x32_bf16 v[116:119], v[210:213], v[168:171], v[116:119]
	v_mfma_f32_16x16x32_bf16 v[112:115], v[218:221], v[168:171], v[112:115]
	v_mfma_f32_16x16x32_bf16 v[100:103], v[210:213], v[182:185], v[100:103]
	v_mfma_f32_16x16x32_bf16 v[96:99], v[218:221], v[182:185], v[96:99]
	v_mfma_f32_16x16x32_bf16 v[84:87], v[210:213], v[194:197], v[84:87]
	v_mfma_f32_16x16x32_bf16 v[80:83], v[218:221], v[194:197], v[80:83]
	v_mfma_f32_16x16x32_bf16 v[68:71], v[210:213], v[202:205], v[68:71]
	v_mfma_f32_16x16x32_bf16 v[64:67], v[218:221], v[202:205], v[64:67]
	v_mfma_f32_16x16x32_bf16 v[116:119], v[214:217], v[172:175], v[116:119]
	v_mfma_f32_16x16x32_bf16 v[112:115], v[222:225], v[172:175], v[112:115]
	v_mfma_f32_16x16x32_bf16 v[100:103], v[214:217], v[190:193], v[100:103]
	v_mfma_f32_16x16x32_bf16 v[96:99], v[222:225], v[190:193], v[96:99]
	v_mfma_f32_16x16x32_bf16 v[84:87], v[214:217], v[198:201], v[84:87]
	v_mfma_f32_16x16x32_bf16 v[80:83], v[222:225], v[198:201], v[80:83]
	v_mfma_f32_16x16x32_bf16 v[68:71], v[214:217], v[206:209], v[68:71]
	v_mfma_f32_16x16x32_bf16 v[64:67], v[222:225], v[206:209], v[64:67]
	s_barrier
; #define PG8_STAGE(bufoff, gbase, voff) do { _Pragma("unroll") for (int _i = 0; _i < 2; ++_i) \
;         __builtin_amdgcn_global_load_lds((const unsigned*)((const char*)(gbase) + (voff)[_i]), (PG8_LAS unsigned*)(lds + (bufoff) + ldsw + _i * 8192), 16, 0, 0); } while (0)
; #define PG8_LDA(dst, b, h) do { _Pragma("unroll") for (int m = 0; m < 4; ++m) _Pragma("unroll") for (int k = 0; k < 2; ++k) dst[m][k] = *(const PG8_LAS bf16x8*)(lds + PG8_SA(b, h) + aoff + m * 2048 + k * 1024); } while (0)
; #define PG8_LDB(dst, b, h) do { _Pragma("unroll") for (int n = 0; n < 2; ++n) _Pragma("unroll") for (int k = 0; k < 2; ++k) dst[n][k] = *(const PG8_LAS bf16x8*)(lds + PG8_SB(b, h) + boff + n * 2048 + k * 1024); } while (0)
; #define PG8_WAIT_V(n) asm volatile("s_waitcnt vmcnt(" #n ")" ::: "memory")
; #define PG8_WAIT_L(n) asm volatile("s_waitcnt lgkmcnt(" #n ")" ::: "memory")
; #define PG8_BAR __builtin_amdgcn_s_barrier()
; #define PG8_SCHED __builtin_amdgcn_sched_barrier(0)
; template <class Epi, class Sched>
; __device__ __forceinline__ void gemm_phase(PG8_LAS unsigned char* lds, const Gemm g, const Sched& S, const Epi& E) {
;     ...
;             PG8_LDB(B0, 0, 0); PG8_SCHED; PG8_LDA(At, 0, 0); PG8_STAGE(PG8_SA(1, 1), a1 + hstep, voffA);
;             PG8_WAIT_L(8); PG8_BAR; PG8_WAIT_L(0); PG8_MMA(0, 0, At, B0); PG8_BAR; PG8_SCHED;
;             PG8_LDB(B1, 0, 1); PG8_STAGE(PG8_SB(0, 0), b2, voffB);
;             PG8_BAR; PG8_WAIT_L(0); PG8_MMA(0, 1, At, B1); PG8_BAR;
;             PG8_LDA(At, 0, 1); PG8_STAGE(PG8_SA(0, 0), a2, voffA);
;             PG8_BAR; PG8_WAIT_L(0); PG8_MMA(1, 0, At, B0); PG8_BAR; PG8_SCHED;
;             PG8_STAGE(PG8_SB(0, 1), b2 + hstep, voffB);
;             PG8_WAIT_V(6); PG8_BAR; PG8_MMA(1, 1, At, B1); PG8_BAR;
;             PG8_LDB(B0, 1, 0); PG8_SCHED; PG8_LDA(At, 1, 0); PG8_STAGE(PG8_SA(0, 1), a2 + hstep, voffA);
;             PG8_WAIT_L(8); PG8_BAR; PG8_WAIT_L(0); PG8_MMA(0, 0, At, B0); PG8_BAR; PG8_SCHED;
;             PG8_LDB(B1, 1, 1); PG8_STAGE(PG8_SB(1, 0), b3, voffB);
;             PG8_BAR; PG8_WAIT_L(0); PG8_MMA(0, 1, At, B1); PG8_BAR;
;             PG8_LDA(At, 1, 1); PG8_STAGE(PG8_SA(1, 0), a3, voffA);
;             PG8_BAR; PG8_WAIT_L(0); PG8_MMA(1, 0, At, B0); PG8_BAR; PG8_SCHED;
;             PG8_STAGE(PG8_SB(1, 1), b3 + hstep, voffB);
;             PG8_WAIT_V(6); PG8_BAR; PG8_MMA(1, 1, At, B1); PG8_BAR;
	ds_read_b128 v[168:171], v150 offset:49152
	ds_read_b128 v[172:175], v150 offset:50176
	ds_read_b128 v[182:185], v150 offset:51200
	ds_read_b128 v[190:193], v150 offset:52224
	ds_read_b128 v[194:197], v150 offset:53248
	ds_read_b128 v[198:201], v150 offset:54272
	ds_read_b128 v[202:205], v150 offset:55296
	ds_read_b128 v[206:209], v150 offset:56320
	s_add_i32 s29, s57, s37
	s_mov_b32 m0, s29
	s_nop 0
	global_load_lds_dwordx4 v130, s[98:99]
	s_nop 1
	s_add_i32 m0, s29, 0x2000
	s_nop 0
	global_load_lds_dwordx4 v134, s[98:99]
	s_nop 1
	s_mov_b32 m0, s42
	s_nop 0
	global_load_lds_dwordx4 v128, s[100:101]
	s_nop 1
	s_mov_b32 m0, s43
	s_nop 0
	global_load_lds_dwordx4 v132, s[100:101]
	s_add_u32 s26, s26, 0x40080
	s_addc_u32 s27, s27, 0
	s_add_i32 s28, s28, s37
	s_mov_b32 m0, s28
	s_nop 0
	global_load_lds_dwordx4 v130, s[26:27]
	s_nop 1
	s_add_i32 m0, s28, 0x2000
	s_nop 0
	global_load_lds_dwordx4 v134, s[26:27]
	s_waitcnt vmcnt(8) lgkmcnt(0)
	s_barrier
	v_mfma_f32_16x16x32_bf16 v[60:63], v[152:155], v[168:171], v[60:63]
	v_mfma_f32_16x16x32_bf16 v[56:59], v[160:163], v[168:171], v[56:59]
	v_mfma_f32_16x16x32_bf16 v[48:51], v[152:155], v[182:185], v[48:51]
	v_mfma_f32_16x16x32_bf16 v[40:43], v[160:163], v[182:185], v[40:43]
	v_mfma_f32_16x16x32_bf16 v[32:35], v[152:155], v[194:197], v[32:35]
	v_mfma_f32_16x16x32_bf16 v[24:27], v[160:163], v[194:197], v[24:27]
	v_mfma_f32_16x16x32_bf16 v[16:19], v[152:155], v[202:205], v[16:19]
	v_mfma_f32_16x16x32_bf16 v[8:11], v[160:163], v[202:205], v[8:11]
	v_mfma_f32_16x16x32_bf16 v[60:63], v[156:159], v[172:175], v[60:63]
	v_mfma_f32_16x16x32_bf16 v[56:59], v[164:167], v[172:175], v[56:59]
	v_mfma_f32_16x16x32_bf16 v[48:51], v[156:159], v[190:193], v[48:51]
	v_mfma_f32_16x16x32_bf16 v[40:43], v[164:167], v[190:193], v[40:43]
	v_mfma_f32_16x16x32_bf16 v[32:35], v[156:159], v[198:201], v[32:35]
	v_mfma_f32_16x16x32_bf16 v[24:27], v[164:167], v[198:201], v[24:27]
	v_mfma_f32_16x16x32_bf16 v[16:19], v[156:159], v[206:209], v[16:19]
	v_mfma_f32_16x16x32_bf16 v[8:11], v[164:167], v[206:209], v[8:11]
	v_mfma_f32_16x16x32_bf16 v[52:55], v[210:213], v[168:171], v[52:55]
	v_mfma_f32_16x16x32_bf16 v[44:47], v[218:221], v[168:171], v[44:47]
	v_mfma_f32_16x16x32_bf16 v[36:39], v[210:213], v[182:185], v[36:39]
	v_mfma_f32_16x16x32_bf16 v[28:31], v[218:221], v[182:185], v[28:31]
	v_mfma_f32_16x16x32_bf16 v[20:23], v[210:213], v[194:197], v[20:23]
	v_mfma_f32_16x16x32_bf16 v[12:15], v[218:221], v[194:197], v[12:15]
	v_mfma_f32_16x16x32_bf16 v[4:7], v[210:213], v[202:205], v[4:7]
	v_mfma_f32_16x16x32_bf16 v[0:3], v[218:221], v[202:205], v[0:3]
	v_mfma_f32_16x16x32_bf16 v[52:55], v[214:217], v[172:175], v[52:55]
	v_mfma_f32_16x16x32_bf16 v[44:47], v[222:225], v[172:175], v[44:47]
	v_mfma_f32_16x16x32_bf16 v[36:39], v[214:217], v[190:193], v[36:39]
	v_mfma_f32_16x16x32_bf16 v[28:31], v[222:225], v[190:193], v[28:31]
	v_mfma_f32_16x16x32_bf16 v[20:23], v[214:217], v[198:201], v[20:23]
	v_mfma_f32_16x16x32_bf16 v[12:15], v[222:225], v[198:201], v[12:15]
	v_mfma_f32_16x16x32_bf16 v[4:7], v[214:217], v[206:209], v[4:7]
	v_mfma_f32_16x16x32_bf16 v[0:3], v[222:225], v[206:209], v[0:3]
	s_barrier
	s_add_i32 s56, s56, 2
	s_add_u32 s24, s24, 0x100
	s_addc_u32 s25, s25, 0
	s_add_u32 s54, s54, 0x100
	s_addc_u32 s55, s55, 0
	s_cmp_gt_u32 s56, 13
.LBB0_1083:
	ds_read_b128 v[152:155], v149
	ds_read_b128 v[156:159], v149 offset:1024
	ds_read_b128 v[160:163], v149 offset:2048
	ds_read_b128 v[164:167], v149 offset:3072
	s_add_u32 s26, s24, 0xfffc0080
	s_addc_u32 s27, s25, -1
	s_cmp_eq_u32 s56, 12
	s_cselect_b32 s29, s17, s27
	s_cselect_b32 s28, s52, s26
	s_cselect_b32 s27, s15, s55
	s_cselect_b32 s26, s53, s54
	ds_read_b128 v[168:171], v150
	ds_read_b128 v[172:175], v150 offset:1024
	ds_read_b128 v[182:185], v150 offset:2048
	ds_read_b128 v[190:193], v150 offset:3072
	ds_read_b128 v[194:197], v150 offset:4096
	ds_read_b128 v[198:201], v150 offset:5120
	ds_read_b128 v[202:205], v150 offset:6144
	ds_read_b128 v[206:209], v150 offset:7168
	s_waitcnt lgkmcnt(8)
	ds_read_b128 v[210:213], v151
	ds_read_b128 v[214:217], v151 offset:1024
	ds_read_b128 v[218:221], v151 offset:2048
	ds_read_b128 v[222:225], v151 offset:3072
	s_add_i32 m0, s23, 0xc000
	s_nop 0
	global_load_lds_dwordx4 v136, s[24:25]
	s_nop 1
	s_add_i32 m0, s23, 0xe000
	s_nop 0
	global_load_lds_dwordx4 v138, s[24:25]
	s_waitcnt vmcnt(8) lgkmcnt(0)
	s_barrier
	v_mfma_f32_16x16x32_bf16 v[124:127], v[152:155], v[168:171], v[124:127]
	v_mfma_f32_16x16x32_bf16 v[120:123], v[160:163], v[168:171], v[120:123]
	v_mfma_f32_16x16x32_bf16 v[108:111], v[152:155], v[182:185], v[108:111]
	v_mfma_f32_16x16x32_bf16 v[104:107], v[160:163], v[182:185], v[104:107]
	v_mfma_f32_16x16x32_bf16 v[92:95], v[152:155], v[194:197], v[92:95]
	v_mfma_f32_16x16x32_bf16 v[88:91], v[160:163], v[194:197], v[88:91]
	v_mfma_f32_16x16x32_bf16 v[76:79], v[152:155], v[202:205], v[76:79]
	v_mfma_f32_16x16x32_bf16 v[72:75], v[160:163], v[202:205], v[72:75]
	v_mfma_f32_16x16x32_bf16 v[124:127], v[156:159], v[172:175], v[124:127]
	v_mfma_f32_16x16x32_bf16 v[120:123], v[164:167], v[172:175], v[120:123]
	v_mfma_f32_16x16x32_bf16 v[108:111], v[156:159], v[190:193], v[108:111]
	v_mfma_f32_16x16x32_bf16 v[104:107], v[164:167], v[190:193], v[104:107]
	v_mfma_f32_16x16x32_bf16 v[92:95], v[156:159], v[198:201], v[92:95]
	v_mfma_f32_16x16x32_bf16 v[88:91], v[164:167], v[198:201], v[88:91]
	v_mfma_f32_16x16x32_bf16 v[76:79], v[156:159], v[206:209], v[76:79]
	v_mfma_f32_16x16x32_bf16 v[72:75], v[164:167], v[206:209], v[72:75]
	v_mfma_f32_16x16x32_bf16 v[116:119], v[210:213], v[168:171], v[116:119]
	v_mfma_f32_16x16x32_bf16 v[112:115], v[218:221], v[168:171], v[112:115]
	v_mfma_f32_16x16x32_bf16 v[100:103], v[210:213], v[182:185], v[100:103]
	v_mfma_f32_16x16x32_bf16 v[96:99], v[218:221], v[182:185], v[96:99]
	v_mfma_f32_16x16x32_bf16 v[84:87], v[210:213], v[194:197], v[84:87]
	v_mfma_f32_16x16x32_bf16 v[80:83], v[218:221], v[194:197], v[80:83]
	v_mfma_f32_16x16x32_bf16 v[68:71], v[210:213], v[202:205], v[68:71]
	v_mfma_f32_16x16x32_bf16 v[64:67], v[218:221], v[202:205], v[64:67]
	v_mfma_f32_16x16x32_bf16 v[116:119], v[214:217], v[172:175], v[116:119]
	v_mfma_f32_16x16x32_bf16 v[112:115], v[222:225], v[172:175], v[112:115]
	v_mfma_f32_16x16x32_bf16 v[100:103], v[214:217], v[190:193], v[100:103]
	v_mfma_f32_16x16x32_bf16 v[96:99], v[222:225], v[190:193], v[96:99]
	v_mfma_f32_16x16x32_bf16 v[84:87], v[214:217], v[198:201], v[84:87]
	v_mfma_f32_16x16x32_bf16 v[80:83], v[222:225], v[198:201], v[80:83]
	v_mfma_f32_16x16x32_bf16 v[68:71], v[214:217], v[206:209], v[68:71]
	v_mfma_f32_16x16x32_bf16 v[64:67], v[222:225], v[206:209], v[64:67]
	s_barrier
; #define PG8_STAGE(bufoff, gbase, voff) do { _Pragma("unroll") for (int _i = 0; _i < 2; ++_i) \
;         __builtin_amdgcn_global_load_lds((const unsigned*)((const char*)(gbase) + (voff)[_i]), (PG8_LAS unsigned*)(lds + (bufoff) + ldsw + _i * 8192), 16, 0, 0); } while (0)
; #define PG8_LDA(dst, b, h) do { _Pragma("unroll") for (int m = 0; m < 4; ++m) _Pragma("unroll") for (int k = 0; k < 2; ++k) dst[m][k] = *(const PG8_LAS bf16x8*)(lds + PG8_SA(b, h) + aoff + m * 2048 + k * 1024); } while (0)
; #define PG8_LDB(dst, b, h) do { _Pragma("unroll") for (int n = 0; n < 2; ++n) _Pragma("unroll") for (int k = 0; k < 2; ++k) dst[n][k] = *(const PG8_LAS bf16x8*)(lds + PG8_SB(b, h) + boff + n * 2048 + k * 1024); } while (0)
; #define PG8_WAIT_V(n) asm volatile("s_waitcnt vmcnt(" #n ")" ::: "memory")
; #define PG8_WAIT_L(n) asm volatile("s_waitcnt lgkmcnt(" #n ")" ::: "memory")
; #define PG8_BAR __builtin_amdgcn_s_barrier()
; #define PG8_SCHED __builtin_amdgcn_sched_barrier(0)
; template <class Epi, class Sched>
; __device__ __forceinline__ void gemm_phase(PG8_LAS unsigned char* lds, const Gemm g, const Sched& S, const Epi& E) {
;     ...
;             PG8_LDB(B0, 0, 0); PG8_SCHED; PG8_LDA(At, 0, 0); PG8_STAGE(PG8_SA(1, 1), a1 + hstep, voffA);
;             PG8_WAIT_L(8); PG8_BAR; PG8_WAIT_L(0); PG8_MMA(0, 0, At, B0); PG8_BAR; PG8_SCHED;
;             PG8_LDB(B1, 0, 1); PG8_STAGE(PG8_SB(0, 0), b2, voffB);
;             PG8_BAR; PG8_WAIT_L(0); PG8_MMA(0, 1, At, B1); PG8_BAR;
;             PG8_LDA(At, 0, 1); PG8_STAGE(PG8_SA(0, 0), a2, voffA);
;             PG8_BAR; PG8_WAIT_L(0); PG8_MMA(1, 0, At, B0); PG8_BAR; PG8_SCHED;
;             PG8_STAGE(PG8_SB(0, 1), b2 + hstep, voffB);
;             PG8_WAIT_V(6); PG8_BAR; PG8_MMA(1, 1, At, B1); PG8_BAR;
;             PG8_LDB(B0, 1, 0); PG8_SCHED; PG8_LDA(At, 1, 0); PG8_STAGE(PG8_SA(0, 1), a2 + hstep, voffA);
;             PG8_WAIT_L(8); PG8_BAR; PG8_WAIT_L(0); PG8_MMA(0, 0, At, B0); PG8_BAR; PG8_SCHED;
;             PG8_LDB(B1, 1, 1); PG8_STAGE(PG8_SB(1, 0), b3, voffB);
;             PG8_BAR; PG8_WAIT_L(0); PG8_MMA(0, 1, At, B1); PG8_BAR;
;             PG8_LDA(At, 1, 1); PG8_STAGE(PG8_SA(1, 0), a3, voffA);
;             PG8_BAR; PG8_WAIT_L(0); PG8_MMA(1, 0, At, B0); PG8_BAR; PG8_SCHED;
;             PG8_STAGE(PG8_SB(1, 1), b3 + hstep, voffB);
;             PG8_WAIT_V(6); PG8_BAR; PG8_MMA(1, 1, At, B1); PG8_BAR;
	ds_read_b128 v[168:171], v150 offset:16384
	ds_read_b128 v[172:175], v150 offset:17408
	ds_read_b128 v[182:185], v150 offset:18432
	ds_read_b128 v[190:193], v150 offset:19456
	ds_read_b128 v[194:197], v150 offset:20480
	ds_read_b128 v[198:201], v150 offset:21504
	ds_read_b128 v[202:205], v150 offset:22528
	ds_read_b128 v[206:209], v150 offset:23552
	s_add_i32 s57, s45, s37
	s_add_u32 s98, s26, s6
	s_addc_u32 s99, s27, s7
	s_mov_b32 m0, s57
	s_nop 0
	global_load_lds_dwordx4 v130, s[26:27]
	s_nop 1
	s_add_i32 m0, s57, 0x2000
	s_nop 0
	global_load_lds_dwordx4 v134, s[26:27]
	s_nop 1
	s_mov_b32 m0, s23
	s_add_u32 s100, s28, s6
	s_addc_u32 s101, s29, s7
	global_load_lds_dwordx4 v128, s[28:29]
	s_nop 1
	s_mov_b32 m0, s38
	s_nop 0
	global_load_lds_dwordx4 v132, s[28:29]
	s_add_u32 s58, s26, 0x40000
	s_addc_u32 s59, s27, 0
	s_add_i32 s57, s46, s37
	s_mov_b32 m0, s57
	s_nop 0
	global_load_lds_dwordx4 v130, s[58:59]
	s_nop 1
	s_add_i32 m0, s57, 0x2000
	s_nop 0
	global_load_lds_dwordx4 v134, s[58:59]
	s_waitcnt vmcnt(8) lgkmcnt(0)
	s_barrier
	v_mfma_f32_16x16x32_bf16 v[60:63], v[152:155], v[168:171], v[60:63]
	v_mfma_f32_16x16x32_bf16 v[56:59], v[160:163], v[168:171], v[56:59]
	v_mfma_f32_16x16x32_bf16 v[48:51], v[152:155], v[182:185], v[48:51]
	v_mfma_f32_16x16x32_bf16 v[40:43], v[160:163], v[182:185], v[40:43]
	v_mfma_f32_16x16x32_bf16 v[32:35], v[152:155], v[194:197], v[32:35]
	v_mfma_f32_16x16x32_bf16 v[24:27], v[160:163], v[194:197], v[24:27]
	v_mfma_f32_16x16x32_bf16 v[16:19], v[152:155], v[202:205], v[16:19]
	v_mfma_f32_16x16x32_bf16 v[8:11], v[160:163], v[202:205], v[8:11]
	v_mfma_f32_16x16x32_bf16 v[60:63], v[156:159], v[172:175], v[60:63]
	v_mfma_f32_16x16x32_bf16 v[56:59], v[164:167], v[172:175], v[56:59]
	v_mfma_f32_16x16x32_bf16 v[48:51], v[156:159], v[190:193], v[48:51]
	v_mfma_f32_16x16x32_bf16 v[40:43], v[164:167], v[190:193], v[40:43]
	v_mfma_f32_16x16x32_bf16 v[32:35], v[156:159], v[198:201], v[32:35]
	v_mfma_f32_16x16x32_bf16 v[24:27], v[164:167], v[198:201], v[24:27]
	v_mfma_f32_16x16x32_bf16 v[16:19], v[156:159], v[206:209], v[16:19]
	v_mfma_f32_16x16x32_bf16 v[8:11], v[164:167], v[206:209], v[8:11]
	v_mfma_f32_16x16x32_bf16 v[52:55], v[210:213], v[168:171], v[52:55]
	v_mfma_f32_16x16x32_bf16 v[44:47], v[218:221], v[168:171], v[44:47]
	v_mfma_f32_16x16x32_bf16 v[36:39], v[210:213], v[182:185], v[36:39]
	v_mfma_f32_16x16x32_bf16 v[28:31], v[218:221], v[182:185], v[28:31]
	v_mfma_f32_16x16x32_bf16 v[20:23], v[210:213], v[194:197], v[20:23]
	v_mfma_f32_16x16x32_bf16 v[12:15], v[218:221], v[194:197], v[12:15]
	v_mfma_f32_16x16x32_bf16 v[4:7], v[210:213], v[202:205], v[4:7]
	v_mfma_f32_16x16x32_bf16 v[0:3], v[218:221], v[202:205], v[0:3]
	v_mfma_f32_16x16x32_bf16 v[52:55], v[214:217], v[172:175], v[52:55]
	v_mfma_f32_16x16x32_bf16 v[44:47], v[222:225], v[172:175], v[44:47]
	v_mfma_f32_16x16x32_bf16 v[36:39], v[214:217], v[190:193], v[36:39]
	v_mfma_f32_16x16x32_bf16 v[28:31], v[222:225], v[190:193], v[28:31]
	v_mfma_f32_16x16x32_bf16 v[20:23], v[214:217], v[198:201], v[20:23]
	v_mfma_f32_16x16x32_bf16 v[12:15], v[222:225], v[198:201], v[12:15]
	v_mfma_f32_16x16x32_bf16 v[4:7], v[214:217], v[206:209], v[4:7]
	v_mfma_f32_16x16x32_bf16 v[0:3], v[222:225], v[206:209], v[0:3]
	s_barrier
	s_add_i32 s57, 0, 0x18000
	v_add_u32_e32 v164, s57, v147
	ds_read_b128 v[152:155], v164
	ds_read_b128 v[156:159], v164 offset:1024
	ds_read_b128 v[160:163], v164 offset:2048
	ds_read_b128 v[164:167], v164 offset:3072
	ds_read_b128 v[168:171], v150 offset:32768
	ds_read_b128 v[172:175], v150 offset:33792
	ds_read_b128 v[182:185], v150 offset:34816
	ds_read_b128 v[190:193], v150 offset:35840
	ds_read_b128 v[194:197], v150 offset:36864
	ds_read_b128 v[198:201], v150 offset:37888
	ds_read_b128 v[202:205], v150 offset:38912
	ds_read_b128 v[206:209], v150 offset:39936
	v_add_u32_e32 v179, 0x1c000, v147
	s_waitcnt lgkmcnt(8)
	ds_read_b128 v[210:213], v179
	ds_read_b128 v[214:217], v179 offset:1024
	ds_read_b128 v[218:221], v179 offset:2048
	ds_read_b128 v[222:225], v179 offset:3072
	s_add_u32 s28, s28, 0x40000
	s_addc_u32 s29, s29, 0
	s_mov_b32 m0, s39
	s_nop 0
	global_load_lds_dwordx4 v128, s[28:29]
	s_nop 1
	s_mov_b32 m0, s40
	s_nop 0
	global_load_lds_dwordx4 v132, s[28:29]
	s_add_i32 s28, 0, 0x1c000
	s_waitcnt vmcnt(8) lgkmcnt(0)
	s_barrier
	v_mfma_f32_16x16x32_bf16 v[124:127], v[152:155], v[168:171], v[124:127]
	v_mfma_f32_16x16x32_bf16 v[120:123], v[160:163], v[168:171], v[120:123]
	v_mfma_f32_16x16x32_bf16 v[108:111], v[152:155], v[182:185], v[108:111]
	v_mfma_f32_16x16x32_bf16 v[104:107], v[160:163], v[182:185], v[104:107]
	v_mfma_f32_16x16x32_bf16 v[92:95], v[152:155], v[194:197], v[92:95]
	v_mfma_f32_16x16x32_bf16 v[88:91], v[160:163], v[194:197], v[88:91]
	v_mfma_f32_16x16x32_bf16 v[76:79], v[152:155], v[202:205], v[76:79]
	v_mfma_f32_16x16x32_bf16 v[72:75], v[160:163], v[202:205], v[72:75]
	v_mfma_f32_16x16x32_bf16 v[124:127], v[156:159], v[172:175], v[124:127]
	v_mfma_f32_16x16x32_bf16 v[120:123], v[164:167], v[172:175], v[120:123]
	v_mfma_f32_16x16x32_bf16 v[108:111], v[156:159], v[190:193], v[108:111]
	v_mfma_f32_16x16x32_bf16 v[104:107], v[164:167], v[190:193], v[104:107]
	v_mfma_f32_16x16x32_bf16 v[92:95], v[156:159], v[198:201], v[92:95]
	v_mfma_f32_16x16x32_bf16 v[88:91], v[164:167], v[198:201], v[88:91]
	v_mfma_f32_16x16x32_bf16 v[76:79], v[156:159], v[206:209], v[76:79]
	v_mfma_f32_16x16x32_bf16 v[72:75], v[164:167], v[206:209], v[72:75]
	v_mfma_f32_16x16x32_bf16 v[116:119], v[210:213], v[168:171], v[116:119]
	v_mfma_f32_16x16x32_bf16 v[112:115], v[218:221], v[168:171], v[112:115]
	v_mfma_f32_16x16x32_bf16 v[100:103], v[210:213], v[182:185], v[100:103]
	v_mfma_f32_16x16x32_bf16 v[96:99], v[218:221], v[182:185], v[96:99]
	v_mfma_f32_16x16x32_bf16 v[84:87], v[210:213], v[194:197], v[84:87]
	v_mfma_f32_16x16x32_bf16 v[80:83], v[218:221], v[194:197], v[80:83]
	v_mfma_f32_16x16x32_bf16 v[68:71], v[210:213], v[202:205], v[68:71]
	v_mfma_f32_16x16x32_bf16 v[64:67], v[218:221], v[202:205], v[64:67]
	v_mfma_f32_16x16x32_bf16 v[116:119], v[214:217], v[172:175], v[116:119]
	v_mfma_f32_16x16x32_bf16 v[112:115], v[222:225], v[172:175], v[112:115]
	v_mfma_f32_16x16x32_bf16 v[100:103], v[214:217], v[190:193], v[100:103]
	v_mfma_f32_16x16x32_bf16 v[96:99], v[222:225], v[190:193], v[96:99]
	v_mfma_f32_16x16x32_bf16 v[84:87], v[214:217], v[198:201], v[84:87]
	v_mfma_f32_16x16x32_bf16 v[80:83], v[222:225], v[198:201], v[80:83]
	v_mfma_f32_16x16x32_bf16 v[68:71], v[214:217], v[206:209], v[68:71]
	v_mfma_f32_16x16x32_bf16 v[64:67], v[222:225], v[206:209], v[64:67]
	s_barrier
; #define PG8_WAIT_V(n) asm volatile("s_waitcnt vmcnt(" #n ")" ::: "memory")
;     __device__ __forceinline__ void operator()(const f32x4 (&acc)[2][2][4][2], const Unit& u, int wr, int wc, int fr, int fq) const {
;     ...
;             for (int m = 0; m < 4; ++m) { bf16_t* rowp = O + (size_t)(row0 + ai * HALF + m * 16) * ldc + col0;
; #pragma unroll
;                 for (int bj = 0; bj < 2; ++bj) { f32x4 v0 = acc[ai][bj][m][0] + bv[bj][0], v1 = acc[ai][bj][m][1] + bv[bj][1];
;                     if (act == 1) {
; #pragma unroll
;                         for (int j = 0; j < 1; ++j) { v0 = v0 * sigmoid4(v0); v1 = v1 * sigmoid4(v1); } }
;                     else if (act == 2) {
; #pragma unroll
;                         for (int j = 0; j < 1; ++j) { v0 = sigmoid4(v0); v1 = sigmoid4(v1); } }
;                     else if (act == 3) {
; #pragma unroll
;                         for (int j = 0; j < 4; ++j) { v0[j] = flogsig16(v0[j]); v1[j] = flogsig16(v1[j]); } }
; template <class Epi, class Sched>
; __device__ __forceinline__ void gemm_phase(PG8_LAS unsigned char* lds, const Gemm g, const Sched& S, const Epi& E) {
;     ...
;             PG8_LDB(B0, 0, 0); PG8_SCHED; PG8_LDA(At, 0, 0); PG8_STAGE(PG8_SA(1, 1), a1 + hstep, voffA);
;             PG8_WAIT_L(8); PG8_BAR; PG8_WAIT_L(0); PG8_MMA(0, 0, At, B0); PG8_BAR; PG8_SCHED;
;             PG8_LDB(B1, 0, 1); PG8_STAGE(PG8_SB(0, 0), b2, voffB);
;             PG8_BAR; PG8_WAIT_L(0); PG8_MMA(0, 1, At, B1); PG8_BAR;
;             PG8_LDA(At, 0, 1); PG8_STAGE(PG8_SA(0, 0), a2, voffA);
;             PG8_BAR; PG8_WAIT_L(0); PG8_MMA(1, 0, At, B0); PG8_BAR; PG8_SCHED;
;             PG8_STAGE(PG8_SB(0, 1), b2 + hstep, voffB);
;             PG8_WAIT_V(6); PG8_BAR; PG8_MMA(1, 1, At, B1); PG8_BAR;
;             PG8_LDB(B0, 1, 0); PG8_SCHED; PG8_LDA(At, 1, 0); PG8_STAGE(PG8_SA(0, 1), a2 + hstep, voffA);
;             PG8_WAIT_L(8); PG8_BAR; PG8_WAIT_L(0); PG8_MMA(0, 0, At, B0); PG8_BAR; PG8_SCHED;
;             PG8_LDB(B1, 1, 1); PG8_STAGE(PG8_SB(1, 0), b3, voffB);
;             PG8_BAR; PG8_WAIT_L(0); PG8_MMA(0, 1, At, B1); PG8_BAR;
;             PG8_LDA(At, 1, 1); PG8_STAGE(PG8_SA(1, 0), a3, voffA);
;             PG8_BAR; PG8_WAIT_L(0); PG8_MMA(1, 0, At, B0); PG8_BAR; PG8_SCHED;
;             PG8_STAGE(PG8_SB(1, 1), b3 + hstep, voffB);
;             PG8_WAIT_V(6); PG8_BAR; PG8_MMA(1, 1, At, B1); PG8_BAR;
	ds_read_b128 v[168:171], v150 offset:49152
	ds_read_b128 v[172:175], v150 offset:50176
	ds_read_b128 v[182:185], v150 offset:51200
	ds_read_b128 v[190:193], v150 offset:52224
	ds_read_b128 v[194:197], v150 offset:53248
	ds_read_b128 v[198:201], v150 offset:54272
	ds_read_b128 v[202:205], v150 offset:55296
	ds_read_b128 v[206:209], v150 offset:56320
	s_add_i32 s29, s57, s37
	s_mov_b32 m0, s29
	s_nop 0
	global_load_lds_dwordx4 v130, s[98:99]
	s_nop 1
	s_add_i32 m0, s29, 0x2000
	s_nop 0
	global_load_lds_dwordx4 v134, s[98:99]
	s_nop 1
	s_mov_b32 m0, s42
	s_nop 0
	global_load_lds_dwordx4 v128, s[100:101]
	s_nop 1
	s_mov_b32 m0, s43
	s_nop 0
	global_load_lds_dwordx4 v132, s[100:101]
	s_add_u32 s26, s26, 0x40080
	s_addc_u32 s27, s27, 0
	s_add_i32 s28, s28, s37
	s_mov_b32 m0, s28
	s_nop 0
	global_load_lds_dwordx4 v130, s[26:27]
	s_nop 1
	s_add_i32 m0, s28, 0x2000
	s_nop 0
	global_load_lds_dwordx4 v134, s[26:27]
	s_waitcnt vmcnt(8) lgkmcnt(0)
	s_barrier
	v_mfma_f32_16x16x32_bf16 v[60:63], v[152:155], v[168:171], v[60:63]
	v_mfma_f32_16x16x32_bf16 v[56:59], v[160:163], v[168:171], v[56:59]
	v_mfma_f32_16x16x32_bf16 v[48:51], v[152:155], v[182:185], v[48:51]
	v_mfma_f32_16x16x32_bf16 v[40:43], v[160:163], v[182:185], v[40:43]
	v_mfma_f32_16x16x32_bf16 v[32:35], v[152:155], v[194:197], v[32:35]
	v_mfma_f32_16x16x32_bf16 v[24:27], v[160:163], v[194:197], v[24:27]
	v_mfma_f32_16x16x32_bf16 v[16:19], v[152:155], v[202:205], v[16:19]
	v_mfma_f32_16x16x32_bf16 v[8:11], v[160:163], v[202:205], v[8:11]
	v_mfma_f32_16x16x32_bf16 v[60:63], v[156:159], v[172:175], v[60:63]
	v_mfma_f32_16x16x32_bf16 v[56:59], v[164:167], v[172:175], v[56:59]
	v_mfma_f32_16x16x32_bf16 v[48:51], v[156:159], v[190:193], v[48:51]
	v_mfma_f32_16x16x32_bf16 v[40:43], v[164:167], v[190:193], v[40:43]
	v_mfma_f32_16x16x32_bf16 v[32:35], v[156:159], v[198:201], v[32:35]
	v_mfma_f32_16x16x32_bf16 v[24:27], v[164:167], v[198:201], v[24:27]
	v_mfma_f32_16x16x32_bf16 v[16:19], v[156:159], v[206:209], v[16:19]
	v_mfma_f32_16x16x32_bf16 v[8:11], v[164:167], v[206:209], v[8:11]
	v_mfma_f32_16x16x32_bf16 v[52:55], v[210:213], v[168:171], v[52:55]
	v_mfma_f32_16x16x32_bf16 v[44:47], v[218:221], v[168:171], v[44:47]
	v_mfma_f32_16x16x32_bf16 v[36:39], v[210:213], v[182:185], v[36:39]
	v_mfma_f32_16x16x32_bf16 v[28:31], v[218:221], v[182:185], v[28:31]
	v_mfma_f32_16x16x32_bf16 v[20:23], v[210:213], v[194:197], v[20:23]
	v_mfma_f32_16x16x32_bf16 v[12:15], v[218:221], v[194:197], v[12:15]
	v_mfma_f32_16x16x32_bf16 v[4:7], v[210:213], v[202:205], v[4:7]
	v_mfma_f32_16x16x32_bf16 v[0:3], v[218:221], v[202:205], v[0:3]
	v_mfma_f32_16x16x32_bf16 v[52:55], v[214:217], v[172:175], v[52:55]
	v_mfma_f32_16x16x32_bf16 v[44:47], v[222:225], v[172:175], v[44:47]
	v_mfma_f32_16x16x32_bf16 v[36:39], v[214:217], v[190:193], v[36:39]
	v_mfma_f32_16x16x32_bf16 v[28:31], v[222:225], v[190:193], v[28:31]
	v_mfma_f32_16x16x32_bf16 v[20:23], v[214:217], v[198:201], v[20:23]
	v_mfma_f32_16x16x32_bf16 v[12:15], v[222:225], v[198:201], v[12:15]
	v_mfma_f32_16x16x32_bf16 v[4:7], v[214:217], v[206:209], v[4:7]
	v_mfma_f32_16x16x32_bf16 v[0:3], v[222:225], v[206:209], v[0:3]
	s_barrier
	s_add_i32 s56, s56, 2
	s_add_u32 s24, s24, 0x100
	s_addc_u32 s25, s25, 0
	s_add_u32 s54, s54, 0x100
	s_addc_u32 s55, s55, 0
	s_cmp_gt_u32 s56, 13
	s_cbranch_scc0 .LBB0_1083
	v_lshl_add_u32 v152, s22, 8, v146
	v_lshl_or_b32 v144, s51, 8, v148
	v_ashrrev_i32_e32 v153, 31, v152
	v_ashrrev_i32_e32 v145, 31, v144
	v_lshlrev_b64 v[154:155], 11, v[152:153]
	v_lshl_add_u64 v[154:155], s[4:5], 0, v[154:155]
	v_lshlrev_b64 v[156:157], 1, v[144:145]
	v_lshl_add_u64 v[144:145], v[154:155], 0, v[156:157]
	v_pk_add_f32 v[126:127], v[126:127], 0 op_sel_hi:[1,0]
	v_pk_add_f32 v[124:125], v[124:125], 0 op_sel_hi:[1,0]
	v_pk_add_f32 v[154:155], v[122:123], 0 op_sel_hi:[1,0]
	v_pk_add_f32 v[122:123], v[120:121], 0 op_sel_hi:[1,0]
	v_cvt_pk_bf16_f32 v120, v124, v125
	v_cvt_pk_bf16_f32 v121, v126, v127
	v_pk_add_f32 v[116:117], v[116:117], 0 op_sel_hi:[1,0]
	v_cvt_pk_bf16_f32 v122, v122, v123
	v_cvt_pk_bf16_f32 v123, v154, v155
	global_store_dwordx4 v[144:145], v[120:123], off
	v_pk_add_f32 v[118:119], v[118:119], 0 op_sel_hi:[1,0]
	v_pk_add_f32 v[110:111], v[110:111], 0 op_sel_hi:[1,0]
	v_pk_add_f32 v[120:121], v[114:115], 0 op_sel_hi:[1,0]
	v_pk_add_f32 v[114:115], v[112:113], 0 op_sel_hi:[1,0]
	v_cvt_pk_bf16_f32 v112, v116, v117
	v_cvt_pk_bf16_f32 v113, v118, v119
	v_pk_add_f32 v[108:109], v[108:109], 0 op_sel_hi:[1,0]
	v_cvt_pk_bf16_f32 v114, v114, v115
	v_cvt_pk_bf16_f32 v115, v120, v121
	global_store_dwordx4 v[144:145], v[112:115], off offset:256
	v_pk_add_f32 v[100:101], v[100:101], 0 op_sel_hi:[1,0]
	v_pk_add_f32 v[102:103], v[102:103], 0 op_sel_hi:[1,0]
	v_or_b32_e32 v112, 16, v152
	v_ashrrev_i32_e32 v113, 31, v112
	v_lshlrev_b64 v[112:113], 11, v[112:113]
	v_lshl_add_u64 v[112:113], s[4:5], 0, v[112:113]
	v_lshl_add_u64 v[112:113], v[112:113], 0, v[156:157]
	v_pk_add_f32 v[114:115], v[106:107], 0 op_sel_hi:[1,0]
	v_pk_add_f32 v[106:107], v[104:105], 0 op_sel_hi:[1,0]
	v_cvt_pk_bf16_f32 v104, v108, v109
	v_cvt_pk_bf16_f32 v105, v110, v111
	v_pk_add_f32 v[94:95], v[94:95], 0 op_sel_hi:[1,0]
	v_cvt_pk_bf16_f32 v106, v106, v107
	v_cvt_pk_bf16_f32 v107, v114, v115
	global_store_dwordx4 v[112:113], v[104:107], off
	v_pk_add_f32 v[92:93], v[92:93], 0 op_sel_hi:[1,0]
	v_pk_add_f32 v[84:85], v[84:85], 0 op_sel_hi:[1,0]
	v_pk_add_f32 v[104:105], v[98:99], 0 op_sel_hi:[1,0]
	v_pk_add_f32 v[98:99], v[96:97], 0 op_sel_hi:[1,0]
	v_cvt_pk_bf16_f32 v96, v100, v101
	v_cvt_pk_bf16_f32 v97, v102, v103
	v_pk_add_f32 v[86:87], v[86:87], 0 op_sel_hi:[1,0]
; __device__ __forceinline__ unsigned cvt_pk_bf16(float lo, float hi) { unsigned r; asm volatile("v_cvt_pk_bf16_f32 %0, %1, %2" : "=v"(r) : "v"(lo), "v"(hi)); return r; }
; __device__ __forceinline__ float flogsig16(float x) { return (fminf(x, 0.f) - __logf(1.0f + __expf(-fabsf(x)))) * 0.0625f; }
; #define PG8_WAIT_V(n) asm volatile("s_waitcnt vmcnt(" #n ")" ::: "memory")
; #define PG8_BAR __builtin_amdgcn_s_barrier()
;     __device__ __forceinline__ void operator()(const f32x4 (&acc)[2][2][4][2], const Unit& u, int wr, int wc, int fr, int fq) const {
;     ...
;             for (int m = 0; m < 4; ++m) { bf16_t* rowp = O + (size_t)(row0 + ai * HALF + m * 16) * ldc + col0;
; #pragma unroll
;                 for (int bj = 0; bj < 2; ++bj) { f32x4 v0 = acc[ai][bj][m][0] + bv[bj][0], v1 = acc[ai][bj][m][1] + bv[bj][1];
;                     if (act == 1) {
; #pragma unroll
;                         for (int j = 0; j < 1; ++j) { v0 = v0 * sigmoid4(v0); v1 = v1 * sigmoid4(v1); } }
;                     else if (act == 2) {
; #pragma unroll
;                         for (int j = 0; j < 1; ++j) { v0 = sigmoid4(v0); v1 = sigmoid4(v1); } }
;                     else if (act == 3) {
; #pragma unroll
;                         for (int j = 0; j < 4; ++j) { v0[j] = flogsig16(v0[j]); v1[j] = flogsig16(v1[j]); } }
;                     u32x4 w; w.x = cvt_pk_bf16(v0[0], v0[1]); w.y = cvt_pk_bf16(v0[2], v0[3]); w.z = cvt_pk_bf16(v1[0], v1[1]); w.w = cvt_pk_bf16(v1[2], v1[3]);
;                     *(u32x4*)(rowp + bj * HALF) = w; } }
; template <class Epi, class Sched>
; __device__ __forceinline__ void gemm_phase(PG8_LAS unsigned char* lds, const Gemm g, const Sched& S, const Epi& E) {
;     ...
;         if (!has_next) break;
; #pragma unroll
;         for (int a = 0; a < 2; ++a)
; #pragma unroll
;             for (int b = 0; b < 2; ++b)
; #pragma unroll
;                 for (int m = 0; m < 4; ++m)
; #pragma unroll
;                     for (int n = 0; n < 2; ++n) acc[a][b][m][n] = (f32x4){0.f, 0.f, 0.f, 0.f};
;         cur = nxt; cA = nA; cB = nB; ++ui;
;     }
;     PG8_WAIT_V(0);
;     if (wr == 0) PG8_BAR;
;     PG8_BAR;
	v_cvt_pk_bf16_f32 v98, v98, v99
	v_cvt_pk_bf16_f32 v99, v104, v105
	global_store_dwordx4 v[112:113], v[96:99], off offset:256
	v_pk_add_f32 v[78:79], v[78:79], 0 op_sel_hi:[1,0]
	v_pk_add_f32 v[76:77], v[76:77], 0 op_sel_hi:[1,0]
	v_or_b32_e32 v96, 32, v152
	v_ashrrev_i32_e32 v97, 31, v96
	v_lshlrev_b64 v[96:97], 11, v[96:97]
	v_lshl_add_u64 v[96:97], s[4:5], 0, v[96:97]
	v_lshl_add_u64 v[96:97], v[96:97], 0, v[156:157]
	v_pk_add_f32 v[98:99], v[90:91], 0 op_sel_hi:[1,0]
	v_pk_add_f32 v[90:91], v[88:89], 0 op_sel_hi:[1,0]
	v_cvt_pk_bf16_f32 v88, v92, v93
	v_cvt_pk_bf16_f32 v89, v94, v95
	v_pk_add_f32 v[70:71], v[70:71], 0 op_sel_hi:[1,0]
	v_cvt_pk_bf16_f32 v90, v90, v91
	v_cvt_pk_bf16_f32 v91, v98, v99
	global_store_dwordx4 v[96:97], v[88:91], off
	v_pk_add_f32 v[68:69], v[68:69], 0 op_sel_hi:[1,0]
	v_pk_add_f32 v[60:61], v[60:61], 0 op_sel_hi:[1,0]
	v_pk_add_f32 v[88:89], v[82:83], 0 op_sel_hi:[1,0]
	v_pk_add_f32 v[82:83], v[80:81], 0 op_sel_hi:[1,0]
	v_cvt_pk_bf16_f32 v80, v84, v85
	v_cvt_pk_bf16_f32 v81, v86, v87
	v_pk_add_f32 v[62:63], v[62:63], 0 op_sel_hi:[1,0]
	v_cvt_pk_bf16_f32 v82, v82, v83
	v_cvt_pk_bf16_f32 v83, v88, v89
	global_store_dwordx4 v[96:97], v[80:83], off offset:256
	v_pk_add_f32 v[54:55], v[54:55], 0 op_sel_hi:[1,0]
	v_pk_add_f32 v[52:53], v[52:53], 0 op_sel_hi:[1,0]
	v_or_b32_e32 v80, 48, v152
	v_ashrrev_i32_e32 v81, 31, v80
	v_lshlrev_b64 v[80:81], 11, v[80:81]
	v_lshl_add_u64 v[80:81], s[4:5], 0, v[80:81]
	v_lshl_add_u64 v[80:81], v[80:81], 0, v[156:157]
	v_pk_add_f32 v[82:83], v[74:75], 0 op_sel_hi:[1,0]
	v_pk_add_f32 v[74:75], v[72:73], 0 op_sel_hi:[1,0]
	v_cvt_pk_bf16_f32 v72, v76, v77
	v_cvt_pk_bf16_f32 v73, v78, v79
	v_pk_add_f32 v[48:49], v[48:49], 0 op_sel_hi:[1,0]
	v_cvt_pk_bf16_f32 v74, v74, v75
	v_cvt_pk_bf16_f32 v75, v82, v83
	global_store_dwordx4 v[80:81], v[72:75], off
	v_pk_add_f32 v[38:39], v[38:39], 0 op_sel_hi:[1,0]
	v_pk_add_f32 v[36:37], v[36:37], 0 op_sel_hi:[1,0]
	v_pk_add_f32 v[72:73], v[66:67], 0 op_sel_hi:[1,0]
	v_pk_add_f32 v[66:67], v[64:65], 0 op_sel_hi:[1,0]
	v_cvt_pk_bf16_f32 v64, v68, v69
	v_cvt_pk_bf16_f32 v65, v70, v71
	v_pk_add_f32 v[32:33], v[32:33], 0 op_sel_hi:[1,0]
	v_cvt_pk_bf16_f32 v66, v66, v67
	v_cvt_pk_bf16_f32 v67, v72, v73
	global_store_dwordx4 v[80:81], v[64:67], off offset:256
	v_pk_add_f32 v[22:23], v[22:23], 0 op_sel_hi:[1,0]
	v_pk_add_f32 v[20:21], v[20:21], 0 op_sel_hi:[1,0]
	v_pk_add_f32 v[66:67], v[58:59], 0 op_sel_hi:[1,0]
	v_pk_add_f32 v[58:59], v[56:57], 0 op_sel_hi:[1,0]
	v_cvt_pk_bf16_f32 v56, v60, v61
	v_add_co_u32_e32 v60, vcc, s47, v144
	v_cvt_pk_bf16_f32 v57, v62, v63
	v_cvt_pk_bf16_f32 v58, v58, v59
	v_cvt_pk_bf16_f32 v59, v66, v67
	v_lshl_add_u64 v[64:65], v[144:145], 0, s[0:1]
	s_nop 0
	v_addc_co_u32_e32 v61, vcc, 0, v145, vcc
	global_store_dwordx4 v[60:61], v[56:59], off
	v_pk_add_f32 v[16:17], v[16:17], 0 op_sel_hi:[1,0]
	s_mov_b32 s51, s14
	v_pk_add_f32 v[56:57], v[46:47], 0 op_sel_hi:[1,0]
	v_pk_add_f32 v[46:47], v[44:45], 0 op_sel_hi:[1,0]
	v_cvt_pk_bf16_f32 v44, v52, v53
	v_cvt_pk_bf16_f32 v45, v54, v55
	s_mov_b32 s22, s16
	v_cvt_pk_bf16_f32 v46, v46, v47
	v_cvt_pk_bf16_f32 v47, v56, v57
	global_store_dwordx4 v[64:65], v[44:47], off offset:256
	s_mov_b64 s[26:27], s[20:21]
	s_mov_b64 s[24:25], s[18:19]
	v_pk_add_f32 v[46:47], v[50:51], 0 op_sel_hi:[1,0]
	v_pk_add_f32 v[50:51], v[42:43], 0 op_sel_hi:[1,0]
	v_pk_add_f32 v[42:43], v[40:41], 0 op_sel_hi:[1,0]
	v_cvt_pk_bf16_f32 v40, v48, v49
	v_cvt_pk_bf16_f32 v41, v46, v47
	v_add_co_u32_e32 v46, vcc, s48, v144
	v_cvt_pk_bf16_f32 v42, v42, v43
	v_cvt_pk_bf16_f32 v43, v50, v51
	v_lshl_add_u64 v[44:45], v[144:145], 0, s[8:9]
	s_nop 0
	v_addc_co_u32_e32 v47, vcc, 0, v145, vcc
	global_store_dwordx4 v[46:47], v[40:43], off
	v_pk_add_f32 v[6:7], v[6:7], 0 op_sel_hi:[1,0]
	v_pk_add_f32 v[4:5], v[4:5], 0 op_sel_hi:[1,0]
	v_pk_add_f32 v[40:41], v[30:31], 0 op_sel_hi:[1,0]
	v_pk_add_f32 v[30:31], v[28:29], 0 op_sel_hi:[1,0]
	v_cvt_pk_bf16_f32 v28, v36, v37
	v_cvt_pk_bf16_f32 v29, v38, v39
	s_nop 0
	v_cvt_pk_bf16_f32 v30, v30, v31
	v_cvt_pk_bf16_f32 v31, v40, v41
	global_store_dwordx4 v[44:45], v[28:31], off offset:256
	s_nop 1
	v_pk_add_f32 v[30:31], v[34:35], 0 op_sel_hi:[1,0]
	v_pk_add_f32 v[34:35], v[26:27], 0 op_sel_hi:[1,0]
	v_pk_add_f32 v[26:27], v[24:25], 0 op_sel_hi:[1,0]
	v_cvt_pk_bf16_f32 v24, v32, v33
	v_cvt_pk_bf16_f32 v25, v30, v31
	v_add_co_u32_e32 v30, vcc, s49, v144
	v_cvt_pk_bf16_f32 v26, v26, v27
	v_cvt_pk_bf16_f32 v27, v34, v35
	v_lshl_add_u64 v[28:29], v[144:145], 0, s[10:11]
	s_nop 0
	v_addc_co_u32_e32 v31, vcc, 0, v145, vcc
	global_store_dwordx4 v[30:31], v[24:27], off
	s_nop 1
	v_pk_add_f32 v[24:25], v[14:15], 0 op_sel_hi:[1,0]
	v_pk_add_f32 v[14:15], v[12:13], 0 op_sel_hi:[1,0]
	v_cvt_pk_bf16_f32 v12, v20, v21
	v_cvt_pk_bf16_f32 v13, v22, v23
	s_nop 0
	v_cvt_pk_bf16_f32 v14, v14, v15
	v_cvt_pk_bf16_f32 v15, v24, v25
	global_store_dwordx4 v[28:29], v[12:15], off offset:256
	s_nop 1
	v_pk_add_f32 v[14:15], v[18:19], 0 op_sel_hi:[1,0]
	v_pk_add_f32 v[18:19], v[10:11], 0 op_sel_hi:[1,0]
	v_pk_add_f32 v[10:11], v[8:9], 0 op_sel_hi:[1,0]
	v_cvt_pk_bf16_f32 v8, v16, v17
	v_cvt_pk_bf16_f32 v9, v14, v15
	v_add_co_u32_e32 v14, vcc, s50, v144
	v_lshl_add_u64 v[12:13], v[144:145], 0, s[12:13]
	s_nop 0
	v_addc_co_u32_e32 v15, vcc, 0, v145, vcc
	v_cvt_pk_bf16_f32 v10, v10, v11
	v_cvt_pk_bf16_f32 v11, v18, v19
	global_store_dwordx4 v[14:15], v[8:11], off
	s_and_b64 vcc, exec, s[2:3]
	s_nop 0
	v_pk_add_f32 v[8:9], v[2:3], 0 op_sel_hi:[1,0]
	v_pk_add_f32 v[2:3], v[0:1], 0 op_sel_hi:[1,0]
	v_cvt_pk_bf16_f32 v0, v4, v5
	v_cvt_pk_bf16_f32 v1, v6, v7
	s_nop 0
	v_cvt_pk_bf16_f32 v2, v2, v3
	v_cvt_pk_bf16_f32 v3, v8, v9
	global_store_dwordx4 v[12:13], v[0:3], off offset:256
	s_cbranch_vccz .LBB0_1076
	s_waitcnt vmcnt(0)
	s_cmpk_gt_u32 s31, 0xff
	s_cbranch_scc1 .LBB0_1087
	s_barrier

; #define PG8_STAGE(bufoff, gbase, voff) do { _Pragma("unroll") for (int _i = 0; _i < 2; ++_i) \
;         __builtin_amdgcn_global_load_lds((const unsigned*)((const char*)(gbase) + (voff)[_i]), (PG8_LAS unsigned*)(lds + (bufoff) + ldsw + _i * 8192), 16, 0, 0); } while (0)
; #define PG8_WAIT_V(n) asm volatile("s_waitcnt vmcnt(" #n ")" ::: "memory")
; template <class Epi, class Sched>
; __device__ __forceinline__ void gemm_phase(PG8_LAS unsigned char* lds, const Gemm g, const Sched& S, const Epi& E) {
;     ...
;         const bool has_next = S.next(ui + 1, nxt);
;         const char* nA = has_next ? (const char*)g.A + (size_t)nxt.pm * tstep : cA; const char* nB = has_next ? (const char*)g.Bt + (size_t)nxt.pn * tstep : cB;
;         for (int t = 0; t < nt; t += 2) {
;             const bool last = (t == nt - 2);
;             const char* a1 = cA + (size_t)(t + 1) * kstep;
;             const char* a2 = last ? nA : cA + (size_t)(t + 2) * kstep; const char* b2 = last ? nB : cB + (size_t)(t + 2) * kstep;
;             const char* a3 = a2 + kstep; const char* b3 = b2 + kstep;
;             if (last && has_next) S.a_ready(nxt);
;             PG8_LDB(B0, 0, 0); PG8_SCHED; PG8_LDA(At, 0, 0); PG8_STAGE(PG8_SA(1, 1), a1 + hstep, voffA);
;             PG8_WAIT_L(8); PG8_BAR; PG8_WAIT_L(0); PG8_MMA(0, 0, At, B0); PG8_BAR; PG8_SCHED;
;             PG8_LDB(B1, 0, 1); PG8_STAGE(PG8_SB(0, 0), b2, voffB);
;             PG8_BAR; PG8_WAIT_L(0); PG8_MMA(0, 1, At, B1); PG8_BAR;
;             PG8_LDA(At, 0, 1); PG8_STAGE(PG8_SA(0, 0), a2, voffA);
;             PG8_BAR; PG8_WAIT_L(0); PG8_MMA(1, 0, At, B0); PG8_BAR; PG8_SCHED;
;             PG8_STAGE(PG8_SB(0, 1), b2 + hstep, voffB);
;             PG8_WAIT_V(6); PG8_BAR; PG8_MMA(1, 1, At, B1); PG8_BAR;
;             PG8_LDB(B0, 1, 0); PG8_SCHED; PG8_LDA(At, 1, 0); PG8_STAGE(PG8_SA(0, 1), a2 + hstep, voffA);
;             PG8_WAIT_L(8); PG8_BAR; PG8_WAIT_L(0); PG8_MMA(0, 0, At, B0); PG8_BAR; PG8_SCHED;
;             PG8_LDB(B1, 1, 1); PG8_STAGE(PG8_SB(1, 0), b3, voffB);
;             PG8_BAR; PG8_WAIT_L(0); PG8_MMA(0, 1, At, B1); PG8_BAR;
;             PG8_LDA(At, 1, 1); PG8_STAGE(PG8_SA(1, 0), a3, voffA);
;             PG8_BAR; PG8_WAIT_L(0); PG8_MMA(1, 0, At, B0); PG8_BAR; PG8_SCHED;
;             PG8_STAGE(PG8_SB(1, 1), b3 + hstep, voffB);
;             PG8_WAIT_V(6); PG8_BAR; PG8_MMA(1, 1, At, B1); PG8_BAR;
.LBB0_1201:
	s_ashr_i32 s9, s8, 31
	v_cmp_lt_i64_e32 vcc, s[10:11], v[140:141]
	s_lshl_b64 s[10:11], s[8:9], 19
	s_add_u32 s10, s24, s10
	s_addc_u32 s11, s25, s11
	s_and_b64 s[12:13], vcc, exec
	s_cselect_b32 s9, s11, s17
	s_cselect_b32 s42, s10, s16
	s_ashr_i32 s7, s6, 31
	s_lshl_b64 s[12:13], s[6:7], 19
	s_add_u32 s12, s84, s12
	s_addc_u32 s13, s85, s13
	s_and_b64 s[20:21], vcc, exec
	s_cselect_b32 s7, s13, s19
	s_cselect_b32 s43, s12, s18
	s_add_u32 s16, s16, 0x40080
	s_addc_u32 s17, s17, 0
	s_add_u32 s44, s18, 0x100
	s_addc_u32 s45, s19, 0
	s_mov_b32 s46, -2
	ds_read_b128 v[144:147], v151
	ds_read_b128 v[154:157], v151 offset:1024
	ds_read_b128 v[158:161], v151 offset:2048
	ds_read_b128 v[162:165], v151 offset:3072
	s_add_u32 s18, s16, 0xfffc0080
	s_addc_u32 s19, s17, -1
	s_cmp_eq_u32 s46, 12
	s_cselect_b32 s21, s9, s19
	s_cselect_b32 s20, s42, s18
	s_cselect_b32 s19, s7, s45
	s_cselect_b32 s18, s43, s44
	ds_read_b128 v[166:169], v152
	ds_read_b128 v[170:173], v152 offset:1024
	ds_read_b128 v[182:185], v152 offset:2048
	ds_read_b128 v[190:193], v152 offset:3072
	ds_read_b128 v[194:197], v152 offset:4096
	ds_read_b128 v[198:201], v152 offset:5120
	ds_read_b128 v[202:205], v152 offset:6144
	ds_read_b128 v[206:209], v152 offset:7168
	s_waitcnt lgkmcnt(8)
	ds_read_b128 v[210:213], v153
	ds_read_b128 v[214:217], v153 offset:1024
	ds_read_b128 v[218:221], v153 offset:2048
	ds_read_b128 v[222:225], v153 offset:3072
	s_add_i32 m0, s15, 0xc000
	s_nop 0
	global_load_lds_dwordx4 v136, s[16:17]
	s_nop 1
	s_add_i32 m0, s15, 0xe000
	s_nop 0
	global_load_lds_dwordx4 v138, s[16:17]
	s_waitcnt vmcnt(8) lgkmcnt(0)
	s_barrier
	v_mfma_f32_16x16x32_bf16 v[124:127], v[144:147], v[166:169], 0
	v_mfma_f32_16x16x32_bf16 v[120:123], v[158:161], v[166:169], 0
	v_mfma_f32_16x16x32_bf16 v[108:111], v[144:147], v[182:185], 0
	v_mfma_f32_16x16x32_bf16 v[104:107], v[158:161], v[182:185], 0
	v_mfma_f32_16x16x32_bf16 v[92:95], v[144:147], v[194:197], 0
	v_mfma_f32_16x16x32_bf16 v[88:91], v[158:161], v[194:197], 0
	v_mfma_f32_16x16x32_bf16 v[76:79], v[144:147], v[202:205], 0
	v_mfma_f32_16x16x32_bf16 v[72:75], v[158:161], v[202:205], 0
	v_mfma_f32_16x16x32_bf16 v[124:127], v[154:157], v[170:173], v[124:127]
	v_mfma_f32_16x16x32_bf16 v[120:123], v[162:165], v[170:173], v[120:123]
	v_mfma_f32_16x16x32_bf16 v[108:111], v[154:157], v[190:193], v[108:111]
	v_mfma_f32_16x16x32_bf16 v[104:107], v[162:165], v[190:193], v[104:107]
	v_mfma_f32_16x16x32_bf16 v[92:95], v[154:157], v[198:201], v[92:95]
	v_mfma_f32_16x16x32_bf16 v[88:91], v[162:165], v[198:201], v[88:91]
	v_mfma_f32_16x16x32_bf16 v[76:79], v[154:157], v[206:209], v[76:79]
	v_mfma_f32_16x16x32_bf16 v[72:75], v[162:165], v[206:209], v[72:75]
	v_mfma_f32_16x16x32_bf16 v[116:119], v[210:213], v[166:169], 0
	v_mfma_f32_16x16x32_bf16 v[112:115], v[218:221], v[166:169], 0
	v_mfma_f32_16x16x32_bf16 v[100:103], v[210:213], v[182:185], 0
	v_mfma_f32_16x16x32_bf16 v[96:99], v[218:221], v[182:185], 0
	v_mfma_f32_16x16x32_bf16 v[84:87], v[210:213], v[194:197], 0
	v_mfma_f32_16x16x32_bf16 v[80:83], v[218:221], v[194:197], 0
	v_mfma_f32_16x16x32_bf16 v[68:71], v[210:213], v[202:205], 0
	v_mfma_f32_16x16x32_bf16 v[64:67], v[218:221], v[202:205], 0
	v_mfma_f32_16x16x32_bf16 v[116:119], v[214:217], v[170:173], v[116:119]
	v_mfma_f32_16x16x32_bf16 v[112:115], v[222:225], v[170:173], v[112:115]
	v_mfma_f32_16x16x32_bf16 v[100:103], v[214:217], v[190:193], v[100:103]
	v_mfma_f32_16x16x32_bf16 v[96:99], v[222:225], v[190:193], v[96:99]
	v_mfma_f32_16x16x32_bf16 v[84:87], v[214:217], v[198:201], v[84:87]
	v_mfma_f32_16x16x32_bf16 v[80:83], v[222:225], v[198:201], v[80:83]
	v_mfma_f32_16x16x32_bf16 v[68:71], v[214:217], v[206:209], v[68:71]
	v_mfma_f32_16x16x32_bf16 v[64:67], v[222:225], v[206:209], v[64:67]
	s_barrier
	ds_read_b128 v[166:169], v152 offset:16384
	ds_read_b128 v[170:173], v152 offset:17408
	ds_read_b128 v[182:185], v152 offset:18432
	ds_read_b128 v[190:193], v152 offset:19456
	ds_read_b128 v[194:197], v152 offset:20480
	ds_read_b128 v[198:201], v152 offset:21504
	ds_read_b128 v[202:205], v152 offset:22528
	ds_read_b128 v[206:209], v152 offset:23552
	s_add_i32 s47, s38, s26
	s_add_u32 s98, s18, s4
	s_addc_u32 s99, s19, s5
	s_mov_b32 m0, s47
	s_nop 0
	global_load_lds_dwordx4 v132, s[18:19]
	s_nop 1
	s_add_i32 m0, s47, 0x2000
	s_nop 0
	global_load_lds_dwordx4 v128, s[18:19]
	s_nop 1
	s_mov_b32 m0, s15
	s_add_u32 s100, s20, s4
	s_addc_u32 s101, s21, s5
	global_load_lds_dwordx4 v134, s[20:21]
	s_nop 1
	s_mov_b32 m0, s29
	s_nop 0
	global_load_lds_dwordx4 v130, s[20:21]
	s_add_u32 s48, s18, 0x40000
	s_addc_u32 s49, s19, 0
	s_add_i32 s47, s39, s26
	s_mov_b32 m0, s47
	s_nop 0
	global_load_lds_dwordx4 v132, s[48:49]
	s_nop 1
	s_add_i32 m0, s47, 0x2000
	s_nop 0
	global_load_lds_dwordx4 v128, s[48:49]
	s_waitcnt vmcnt(8) lgkmcnt(0)
	s_barrier
; #define PG8_STAGE(bufoff, gbase, voff) do { _Pragma("unroll") for (int _i = 0; _i < 2; ++_i) \
;         __builtin_amdgcn_global_load_lds((const unsigned*)((const char*)(gbase) + (voff)[_i]), (PG8_LAS unsigned*)(lds + (bufoff) + ldsw + _i * 8192), 16, 0, 0); } while (0)
; #define PG8_LDA(dst, b, h) do { _Pragma("unroll") for (int m = 0; m < 4; ++m) _Pragma("unroll") for (int k = 0; k < 2; ++k) dst[m][k] = *(const PG8_LAS bf16x8*)(lds + PG8_SA(b, h) + aoff + m * 2048 + k * 1024); } while (0)
; #define PG8_LDB(dst, b, h) do { _Pragma("unroll") for (int n = 0; n < 2; ++n) _Pragma("unroll") for (int k = 0; k < 2; ++k) dst[n][k] = *(const PG8_LAS bf16x8*)(lds + PG8_SB(b, h) + boff + n * 2048 + k * 1024); } while (0)
; #define PG8_WAIT_V(n) asm volatile("s_waitcnt vmcnt(" #n ")" ::: "memory")
; #define PG8_WAIT_L(n) asm volatile("s_waitcnt lgkmcnt(" #n ")" ::: "memory")
; #define PG8_BAR __builtin_amdgcn_s_barrier()
; #define PG8_SCHED __builtin_amdgcn_sched_barrier(0)
; template <class Epi, class Sched>
; __device__ __forceinline__ void gemm_phase(PG8_LAS unsigned char* lds, const Gemm g, const Sched& S, const Epi& E) {
;     ...
;             PG8_LDB(B0, 0, 0); PG8_SCHED; PG8_LDA(At, 0, 0); PG8_STAGE(PG8_SA(1, 1), a1 + hstep, voffA);
;             PG8_WAIT_L(8); PG8_BAR; PG8_WAIT_L(0); PG8_MMA(0, 0, At, B0); PG8_BAR; PG8_SCHED;
;             PG8_LDB(B1, 0, 1); PG8_STAGE(PG8_SB(0, 0), b2, voffB);
;             PG8_BAR; PG8_WAIT_L(0); PG8_MMA(0, 1, At, B1); PG8_BAR;
;             PG8_LDA(At, 0, 1); PG8_STAGE(PG8_SA(0, 0), a2, voffA);
;             PG8_BAR; PG8_WAIT_L(0); PG8_MMA(1, 0, At, B0); PG8_BAR; PG8_SCHED;
;             PG8_STAGE(PG8_SB(0, 1), b2 + hstep, voffB);
;             PG8_WAIT_V(6); PG8_BAR; PG8_MMA(1, 1, At, B1); PG8_BAR;
;             PG8_LDB(B0, 1, 0); PG8_SCHED; PG8_LDA(At, 1, 0); PG8_STAGE(PG8_SA(0, 1), a2 + hstep, voffA);
;             PG8_WAIT_L(8); PG8_BAR; PG8_WAIT_L(0); PG8_MMA(0, 0, At, B0); PG8_BAR; PG8_SCHED;
;             PG8_LDB(B1, 1, 1); PG8_STAGE(PG8_SB(1, 0), b3, voffB);
;             PG8_BAR; PG8_WAIT_L(0); PG8_MMA(0, 1, At, B1); PG8_BAR;
;             PG8_LDA(At, 1, 1); PG8_STAGE(PG8_SA(1, 0), a3, voffA);
;             PG8_BAR; PG8_WAIT_L(0); PG8_MMA(1, 0, At, B0); PG8_BAR; PG8_SCHED;
;             PG8_STAGE(PG8_SB(1, 1), b3 + hstep, voffB);
;             PG8_WAIT_V(6); PG8_BAR; PG8_MMA(1, 1, At, B1); PG8_BAR;
	v_mfma_f32_16x16x32_bf16 v[60:63], v[144:147], v[166:169], 0
	v_mfma_f32_16x16x32_bf16 v[56:59], v[158:161], v[166:169], 0
	v_mfma_f32_16x16x32_bf16 v[44:47], v[144:147], v[182:185], 0
	v_mfma_f32_16x16x32_bf16 v[40:43], v[158:161], v[182:185], 0
	v_mfma_f32_16x16x32_bf16 v[28:31], v[144:147], v[194:197], 0
	v_mfma_f32_16x16x32_bf16 v[24:27], v[158:161], v[194:197], 0
	v_mfma_f32_16x16x32_bf16 v[12:15], v[144:147], v[202:205], 0
	v_mfma_f32_16x16x32_bf16 v[8:11], v[158:161], v[202:205], 0
	v_mfma_f32_16x16x32_bf16 v[60:63], v[154:157], v[170:173], v[60:63]
	v_mfma_f32_16x16x32_bf16 v[56:59], v[162:165], v[170:173], v[56:59]
	v_mfma_f32_16x16x32_bf16 v[44:47], v[154:157], v[190:193], v[44:47]
	v_mfma_f32_16x16x32_bf16 v[40:43], v[162:165], v[190:193], v[40:43]
	v_mfma_f32_16x16x32_bf16 v[28:31], v[154:157], v[198:201], v[28:31]
	v_mfma_f32_16x16x32_bf16 v[24:27], v[162:165], v[198:201], v[24:27]
	v_mfma_f32_16x16x32_bf16 v[12:15], v[154:157], v[206:209], v[12:15]
	v_mfma_f32_16x16x32_bf16 v[8:11], v[162:165], v[206:209], v[8:11]
	v_mfma_f32_16x16x32_bf16 v[52:55], v[210:213], v[166:169], 0
	v_mfma_f32_16x16x32_bf16 v[48:51], v[218:221], v[166:169], 0
	v_mfma_f32_16x16x32_bf16 v[36:39], v[210:213], v[182:185], 0
	v_mfma_f32_16x16x32_bf16 v[32:35], v[218:221], v[182:185], 0
	v_mfma_f32_16x16x32_bf16 v[20:23], v[210:213], v[194:197], 0
	v_mfma_f32_16x16x32_bf16 v[16:19], v[218:221], v[194:197], 0
	v_mfma_f32_16x16x32_bf16 v[4:7], v[210:213], v[202:205], 0
	v_mfma_f32_16x16x32_bf16 v[0:3], v[218:221], v[202:205], 0
	v_mfma_f32_16x16x32_bf16 v[52:55], v[214:217], v[170:173], v[52:55]
	v_mfma_f32_16x16x32_bf16 v[48:51], v[222:225], v[170:173], v[48:51]
	v_mfma_f32_16x16x32_bf16 v[36:39], v[214:217], v[190:193], v[36:39]
	v_mfma_f32_16x16x32_bf16 v[32:35], v[222:225], v[190:193], v[32:35]
	v_mfma_f32_16x16x32_bf16 v[20:23], v[214:217], v[198:201], v[20:23]
	v_mfma_f32_16x16x32_bf16 v[16:19], v[222:225], v[198:201], v[16:19]
	v_mfma_f32_16x16x32_bf16 v[4:7], v[214:217], v[206:209], v[4:7]
	v_mfma_f32_16x16x32_bf16 v[0:3], v[222:225], v[206:209], v[0:3]
	s_barrier
	s_add_i32 s47, 0, 0x18000
	v_add_u32_e32 v162, s47, v149
	ds_read_b128 v[144:147], v162
	ds_read_b128 v[154:157], v162 offset:1024
	ds_read_b128 v[158:161], v162 offset:2048
	ds_read_b128 v[162:165], v162 offset:3072
	ds_read_b128 v[166:169], v152 offset:32768
	ds_read_b128 v[170:173], v152 offset:33792
	ds_read_b128 v[182:185], v152 offset:34816
	ds_read_b128 v[190:193], v152 offset:35840
	ds_read_b128 v[194:197], v152 offset:36864
	ds_read_b128 v[198:201], v152 offset:37888
	ds_read_b128 v[202:205], v152 offset:38912
	ds_read_b128 v[206:209], v152 offset:39936
	v_add_u32_e32 v179, 0x1c000, v149
	s_waitcnt lgkmcnt(8)
	ds_read_b128 v[210:213], v179
	ds_read_b128 v[214:217], v179 offset:1024
	ds_read_b128 v[218:221], v179 offset:2048
	ds_read_b128 v[222:225], v179 offset:3072
	s_add_u32 s20, s20, 0x40000
	s_addc_u32 s21, s21, 0
	s_mov_b32 m0, s30
	s_nop 0
	global_load_lds_dwordx4 v134, s[20:21]
	s_nop 1
	s_mov_b32 m0, s31
	s_nop 0
	global_load_lds_dwordx4 v130, s[20:21]
	s_add_i32 s20, 0, 0x1c000
	s_waitcnt vmcnt(8) lgkmcnt(0)
	s_barrier
	v_mfma_f32_16x16x32_bf16 v[124:127], v[144:147], v[166:169], v[124:127]
	v_mfma_f32_16x16x32_bf16 v[120:123], v[158:161], v[166:169], v[120:123]
	v_mfma_f32_16x16x32_bf16 v[108:111], v[144:147], v[182:185], v[108:111]
	v_mfma_f32_16x16x32_bf16 v[104:107], v[158:161], v[182:185], v[104:107]
	v_mfma_f32_16x16x32_bf16 v[92:95], v[144:147], v[194:197], v[92:95]
	v_mfma_f32_16x16x32_bf16 v[88:91], v[158:161], v[194:197], v[88:91]
	v_mfma_f32_16x16x32_bf16 v[76:79], v[144:147], v[202:205], v[76:79]
	v_mfma_f32_16x16x32_bf16 v[72:75], v[158:161], v[202:205], v[72:75]
	v_mfma_f32_16x16x32_bf16 v[124:127], v[154:157], v[170:173], v[124:127]
	v_mfma_f32_16x16x32_bf16 v[120:123], v[162:165], v[170:173], v[120:123]
	v_mfma_f32_16x16x32_bf16 v[108:111], v[154:157], v[190:193], v[108:111]
	v_mfma_f32_16x16x32_bf16 v[104:107], v[162:165], v[190:193], v[104:107]
	v_mfma_f32_16x16x32_bf16 v[92:95], v[154:157], v[198:201], v[92:95]
	v_mfma_f32_16x16x32_bf16 v[88:91], v[162:165], v[198:201], v[88:91]
	v_mfma_f32_16x16x32_bf16 v[76:79], v[154:157], v[206:209], v[76:79]
	v_mfma_f32_16x16x32_bf16 v[72:75], v[162:165], v[206:209], v[72:75]
	v_mfma_f32_16x16x32_bf16 v[116:119], v[210:213], v[166:169], v[116:119]
	v_mfma_f32_16x16x32_bf16 v[112:115], v[218:221], v[166:169], v[112:115]
	v_mfma_f32_16x16x32_bf16 v[100:103], v[210:213], v[182:185], v[100:103]
	v_mfma_f32_16x16x32_bf16 v[96:99], v[218:221], v[182:185], v[96:99]
	v_mfma_f32_16x16x32_bf16 v[84:87], v[210:213], v[194:197], v[84:87]
	v_mfma_f32_16x16x32_bf16 v[80:83], v[218:221], v[194:197], v[80:83]
	v_mfma_f32_16x16x32_bf16 v[68:71], v[210:213], v[202:205], v[68:71]
	v_mfma_f32_16x16x32_bf16 v[64:67], v[218:221], v[202:205], v[64:67]
	v_mfma_f32_16x16x32_bf16 v[116:119], v[214:217], v[170:173], v[116:119]
	v_mfma_f32_16x16x32_bf16 v[112:115], v[222:225], v[170:173], v[112:115]
	v_mfma_f32_16x16x32_bf16 v[100:103], v[214:217], v[190:193], v[100:103]
	v_mfma_f32_16x16x32_bf16 v[96:99], v[222:225], v[190:193], v[96:99]
	v_mfma_f32_16x16x32_bf16 v[84:87], v[214:217], v[198:201], v[84:87]
	v_mfma_f32_16x16x32_bf16 v[80:83], v[222:225], v[198:201], v[80:83]
	v_mfma_f32_16x16x32_bf16 v[68:71], v[214:217], v[206:209], v[68:71]
	v_mfma_f32_16x16x32_bf16 v[64:67], v[222:225], v[206:209], v[64:67]
	s_barrier
; #define PG8_STAGE(bufoff, gbase, voff) do { _Pragma("unroll") for (int _i = 0; _i < 2; ++_i) \
;         __builtin_amdgcn_global_load_lds((const unsigned*)((const char*)(gbase) + (voff)[_i]), (PG8_LAS unsigned*)(lds + (bufoff) + ldsw + _i * 8192), 16, 0, 0); } while (0)
; #define PG8_LDA(dst, b, h) do { _Pragma("unroll") for (int m = 0; m < 4; ++m) _Pragma("unroll") for (int k = 0; k < 2; ++k) dst[m][k] = *(const PG8_LAS bf16x8*)(lds + PG8_SA(b, h) + aoff + m * 2048 + k * 1024); } while (0)
; #define PG8_LDB(dst, b, h) do { _Pragma("unroll") for (int n = 0; n < 2; ++n) _Pragma("unroll") for (int k = 0; k < 2; ++k) dst[n][k] = *(const PG8_LAS bf16x8*)(lds + PG8_SB(b, h) + boff + n * 2048 + k * 1024); } while (0)
; #define PG8_WAIT_V(n) asm volatile("s_waitcnt vmcnt(" #n ")" ::: "memory")
; #define PG8_WAIT_L(n) asm volatile("s_waitcnt lgkmcnt(" #n ")" ::: "memory")
; #define PG8_BAR __builtin_amdgcn_s_barrier()
; #define PG8_SCHED __builtin_amdgcn_sched_barrier(0)
; template <class Epi, class Sched>
; __device__ __forceinline__ void gemm_phase(PG8_LAS unsigned char* lds, const Gemm g, const Sched& S, const Epi& E) {
;     ...
;             PG8_LDB(B0, 0, 0); PG8_SCHED; PG8_LDA(At, 0, 0); PG8_STAGE(PG8_SA(1, 1), a1 + hstep, voffA);
;             PG8_WAIT_L(8); PG8_BAR; PG8_WAIT_L(0); PG8_MMA(0, 0, At, B0); PG8_BAR; PG8_SCHED;
;             PG8_LDB(B1, 0, 1); PG8_STAGE(PG8_SB(0, 0), b2, voffB);
;             PG8_BAR; PG8_WAIT_L(0); PG8_MMA(0, 1, At, B1); PG8_BAR;
;             PG8_LDA(At, 0, 1); PG8_STAGE(PG8_SA(0, 0), a2, voffA);
;             PG8_BAR; PG8_WAIT_L(0); PG8_MMA(1, 0, At, B0); PG8_BAR; PG8_SCHED;
;             PG8_STAGE(PG8_SB(0, 1), b2 + hstep, voffB);
;             PG8_WAIT_V(6); PG8_BAR; PG8_MMA(1, 1, At, B1); PG8_BAR;
;             PG8_LDB(B0, 1, 0); PG8_SCHED; PG8_LDA(At, 1, 0); PG8_STAGE(PG8_SA(0, 1), a2 + hstep, voffA);
;             PG8_WAIT_L(8); PG8_BAR; PG8_WAIT_L(0); PG8_MMA(0, 0, At, B0); PG8_BAR; PG8_SCHED;
;             PG8_LDB(B1, 1, 1); PG8_STAGE(PG8_SB(1, 0), b3, voffB);
;             PG8_BAR; PG8_WAIT_L(0); PG8_MMA(0, 1, At, B1); PG8_BAR;
;             PG8_LDA(At, 1, 1); PG8_STAGE(PG8_SA(1, 0), a3, voffA);
;             PG8_BAR; PG8_WAIT_L(0); PG8_MMA(1, 0, At, B0); PG8_BAR; PG8_SCHED;
;             PG8_STAGE(PG8_SB(1, 1), b3 + hstep, voffB);
;             PG8_WAIT_V(6); PG8_BAR; PG8_MMA(1, 1, At, B1); PG8_BAR;
	ds_read_b128 v[166:169], v152 offset:49152
	ds_read_b128 v[170:173], v152 offset:50176
	ds_read_b128 v[182:185], v152 offset:51200
	ds_read_b128 v[190:193], v152 offset:52224
	ds_read_b128 v[194:197], v152 offset:53248
	ds_read_b128 v[198:201], v152 offset:54272
	ds_read_b128 v[202:205], v152 offset:55296
	ds_read_b128 v[206:209], v152 offset:56320
	s_add_i32 s21, s47, s26
	s_mov_b32 m0, s21
	s_nop 0
	global_load_lds_dwordx4 v132, s[98:99]
	s_nop 1
	s_add_i32 m0, s21, 0x2000
	s_nop 0
	global_load_lds_dwordx4 v128, s[98:99]
	s_nop 1
	s_mov_b32 m0, s35
	s_nop 0
	global_load_lds_dwordx4 v134, s[100:101]
	s_nop 1
	s_mov_b32 m0, s36
	s_nop 0
	global_load_lds_dwordx4 v130, s[100:101]
	s_add_u32 s18, s18, 0x40080
	s_addc_u32 s19, s19, 0
	s_add_i32 s20, s20, s26
	s_mov_b32 m0, s20
	s_nop 0
	global_load_lds_dwordx4 v132, s[18:19]
	s_nop 1
	s_add_i32 m0, s20, 0x2000
	s_nop 0
	global_load_lds_dwordx4 v128, s[18:19]
	s_waitcnt vmcnt(8) lgkmcnt(0)
	s_barrier
	v_mfma_f32_16x16x32_bf16 v[60:63], v[144:147], v[166:169], v[60:63]
	v_mfma_f32_16x16x32_bf16 v[56:59], v[158:161], v[166:169], v[56:59]
	v_mfma_f32_16x16x32_bf16 v[44:47], v[144:147], v[182:185], v[44:47]
	v_mfma_f32_16x16x32_bf16 v[40:43], v[158:161], v[182:185], v[40:43]
	v_mfma_f32_16x16x32_bf16 v[28:31], v[144:147], v[194:197], v[28:31]
	v_mfma_f32_16x16x32_bf16 v[24:27], v[158:161], v[194:197], v[24:27]
	v_mfma_f32_16x16x32_bf16 v[12:15], v[144:147], v[202:205], v[12:15]
	v_mfma_f32_16x16x32_bf16 v[8:11], v[158:161], v[202:205], v[8:11]
	v_mfma_f32_16x16x32_bf16 v[60:63], v[154:157], v[170:173], v[60:63]
	v_mfma_f32_16x16x32_bf16 v[56:59], v[162:165], v[170:173], v[56:59]
	v_mfma_f32_16x16x32_bf16 v[44:47], v[154:157], v[190:193], v[44:47]
	v_mfma_f32_16x16x32_bf16 v[40:43], v[162:165], v[190:193], v[40:43]
	v_mfma_f32_16x16x32_bf16 v[28:31], v[154:157], v[198:201], v[28:31]
	v_mfma_f32_16x16x32_bf16 v[24:27], v[162:165], v[198:201], v[24:27]
	v_mfma_f32_16x16x32_bf16 v[12:15], v[154:157], v[206:209], v[12:15]
	v_mfma_f32_16x16x32_bf16 v[8:11], v[162:165], v[206:209], v[8:11]
	v_mfma_f32_16x16x32_bf16 v[52:55], v[210:213], v[166:169], v[52:55]
	v_mfma_f32_16x16x32_bf16 v[48:51], v[218:221], v[166:169], v[48:51]
	v_mfma_f32_16x16x32_bf16 v[36:39], v[210:213], v[182:185], v[36:39]
	v_mfma_f32_16x16x32_bf16 v[32:35], v[218:221], v[182:185], v[32:35]
	v_mfma_f32_16x16x32_bf16 v[20:23], v[210:213], v[194:197], v[20:23]
	v_mfma_f32_16x16x32_bf16 v[16:19], v[218:221], v[194:197], v[16:19]
	v_mfma_f32_16x16x32_bf16 v[4:7], v[210:213], v[202:205], v[4:7]
	v_mfma_f32_16x16x32_bf16 v[0:3], v[218:221], v[202:205], v[0:3]
	v_mfma_f32_16x16x32_bf16 v[52:55], v[214:217], v[170:173], v[52:55]
	v_mfma_f32_16x16x32_bf16 v[48:51], v[222:225], v[170:173], v[48:51]
	v_mfma_f32_16x16x32_bf16 v[36:39], v[214:217], v[190:193], v[36:39]
	v_mfma_f32_16x16x32_bf16 v[32:35], v[222:225], v[190:193], v[32:35]
	v_mfma_f32_16x16x32_bf16 v[20:23], v[214:217], v[198:201], v[20:23]
	v_mfma_f32_16x16x32_bf16 v[16:19], v[222:225], v[198:201], v[16:19]
	v_mfma_f32_16x16x32_bf16 v[4:7], v[214:217], v[206:209], v[4:7]
	v_mfma_f32_16x16x32_bf16 v[0:3], v[222:225], v[206:209], v[0:3]
	s_barrier
	s_add_i32 s46, s46, 2
	s_add_u32 s16, s16, 0x100
	s_addc_u32 s17, s17, 0
	s_add_u32 s44, s44, 0x100
	s_addc_u32 s45, s45, 0
	s_cmp_gt_u32 s46, 13
.LBB0_1202:
	ds_read_b128 v[144:147], v151
	ds_read_b128 v[154:157], v151 offset:1024
	ds_read_b128 v[158:161], v151 offset:2048
	ds_read_b128 v[162:165], v151 offset:3072
	s_add_u32 s18, s16, 0xfffc0080
	s_addc_u32 s19, s17, -1
	s_cmp_eq_u32 s46, 12
	s_cselect_b32 s21, s9, s19
	s_cselect_b32 s20, s42, s18
	s_cselect_b32 s19, s7, s45
	s_cselect_b32 s18, s43, s44
	ds_read_b128 v[166:169], v152
	ds_read_b128 v[170:173], v152 offset:1024
	ds_read_b128 v[182:185], v152 offset:2048
	ds_read_b128 v[190:193], v152 offset:3072
	ds_read_b128 v[194:197], v152 offset:4096
	ds_read_b128 v[198:201], v152 offset:5120
	ds_read_b128 v[202:205], v152 offset:6144
	ds_read_b128 v[206:209], v152 offset:7168
	s_waitcnt lgkmcnt(8)
	ds_read_b128 v[210:213], v153
	ds_read_b128 v[214:217], v153 offset:1024
	ds_read_b128 v[218:221], v153 offset:2048
	ds_read_b128 v[222:225], v153 offset:3072
	s_add_i32 m0, s15, 0xc000
	s_nop 0
	global_load_lds_dwordx4 v136, s[16:17]
	s_nop 1
	s_add_i32 m0, s15, 0xe000
	s_nop 0
	global_load_lds_dwordx4 v138, s[16:17]
	s_waitcnt vmcnt(8) lgkmcnt(0)
	s_barrier
	v_mfma_f32_16x16x32_bf16 v[124:127], v[144:147], v[166:169], v[124:127]
	v_mfma_f32_16x16x32_bf16 v[120:123], v[158:161], v[166:169], v[120:123]
	v_mfma_f32_16x16x32_bf16 v[108:111], v[144:147], v[182:185], v[108:111]
	v_mfma_f32_16x16x32_bf16 v[104:107], v[158:161], v[182:185], v[104:107]
	v_mfma_f32_16x16x32_bf16 v[92:95], v[144:147], v[194:197], v[92:95]
	v_mfma_f32_16x16x32_bf16 v[88:91], v[158:161], v[194:197], v[88:91]
	v_mfma_f32_16x16x32_bf16 v[76:79], v[144:147], v[202:205], v[76:79]
	v_mfma_f32_16x16x32_bf16 v[72:75], v[158:161], v[202:205], v[72:75]
	v_mfma_f32_16x16x32_bf16 v[124:127], v[154:157], v[170:173], v[124:127]
	v_mfma_f32_16x16x32_bf16 v[120:123], v[162:165], v[170:173], v[120:123]
	v_mfma_f32_16x16x32_bf16 v[108:111], v[154:157], v[190:193], v[108:111]
	v_mfma_f32_16x16x32_bf16 v[104:107], v[162:165], v[190:193], v[104:107]
	v_mfma_f32_16x16x32_bf16 v[92:95], v[154:157], v[198:201], v[92:95]
	v_mfma_f32_16x16x32_bf16 v[88:91], v[162:165], v[198:201], v[88:91]
	v_mfma_f32_16x16x32_bf16 v[76:79], v[154:157], v[206:209], v[76:79]
	v_mfma_f32_16x16x32_bf16 v[72:75], v[162:165], v[206:209], v[72:75]
	v_mfma_f32_16x16x32_bf16 v[116:119], v[210:213], v[166:169], v[116:119]
	v_mfma_f32_16x16x32_bf16 v[112:115], v[218:221], v[166:169], v[112:115]
	v_mfma_f32_16x16x32_bf16 v[100:103], v[210:213], v[182:185], v[100:103]
	v_mfma_f32_16x16x32_bf16 v[96:99], v[218:221], v[182:185], v[96:99]
	v_mfma_f32_16x16x32_bf16 v[84:87], v[210:213], v[194:197], v[84:87]
	v_mfma_f32_16x16x32_bf16 v[80:83], v[218:221], v[194:197], v[80:83]
	v_mfma_f32_16x16x32_bf16 v[68:71], v[210:213], v[202:205], v[68:71]
	v_mfma_f32_16x16x32_bf16 v[64:67], v[218:221], v[202:205], v[64:67]
	v_mfma_f32_16x16x32_bf16 v[116:119], v[214:217], v[170:173], v[116:119]
	v_mfma_f32_16x16x32_bf16 v[112:115], v[222:225], v[170:173], v[112:115]
	v_mfma_f32_16x16x32_bf16 v[100:103], v[214:217], v[190:193], v[100:103]
	v_mfma_f32_16x16x32_bf16 v[96:99], v[222:225], v[190:193], v[96:99]
	v_mfma_f32_16x16x32_bf16 v[84:87], v[214:217], v[198:201], v[84:87]
	v_mfma_f32_16x16x32_bf16 v[80:83], v[222:225], v[198:201], v[80:83]
	v_mfma_f32_16x16x32_bf16 v[68:71], v[214:217], v[206:209], v[68:71]
	v_mfma_f32_16x16x32_bf16 v[64:67], v[222:225], v[206:209], v[64:67]
	s_barrier
; #define PG8_STAGE(bufoff, gbase, voff) do { _Pragma("unroll") for (int _i = 0; _i < 2; ++_i) \
;         __builtin_amdgcn_global_load_lds((const unsigned*)((const char*)(gbase) + (voff)[_i]), (PG8_LAS unsigned*)(lds + (bufoff) + ldsw + _i * 8192), 16, 0, 0); } while (0)
; #define PG8_LDA(dst, b, h) do { _Pragma("unroll") for (int m = 0; m < 4; ++m) _Pragma("unroll") for (int k = 0; k < 2; ++k) dst[m][k] = *(const PG8_LAS bf16x8*)(lds + PG8_SA(b, h) + aoff + m * 2048 + k * 1024); } while (0)
; #define PG8_LDB(dst, b, h) do { _Pragma("unroll") for (int n = 0; n < 2; ++n) _Pragma("unroll") for (int k = 0; k < 2; ++k) dst[n][k] = *(const PG8_LAS bf16x8*)(lds + PG8_SB(b, h) + boff + n * 2048 + k * 1024); } while (0)
; #define PG8_WAIT_V(n) asm volatile("s_waitcnt vmcnt(" #n ")" ::: "memory")
; #define PG8_WAIT_L(n) asm volatile("s_waitcnt lgkmcnt(" #n ")" ::: "memory")
; #define PG8_BAR __builtin_amdgcn_s_barrier()
; #define PG8_SCHED __builtin_amdgcn_sched_barrier(0)
; template <class Epi, class Sched>
; __device__ __forceinline__ void gemm_phase(PG8_LAS unsigned char* lds, const Gemm g, const Sched& S, const Epi& E) {
;     ...
;             PG8_LDB(B0, 0, 0); PG8_SCHED; PG8_LDA(At, 0, 0); PG8_STAGE(PG8_SA(1, 1), a1 + hstep, voffA);
;             PG8_WAIT_L(8); PG8_BAR; PG8_WAIT_L(0); PG8_MMA(0, 0, At, B0); PG8_BAR; PG8_SCHED;
;             PG8_LDB(B1, 0, 1); PG8_STAGE(PG8_SB(0, 0), b2, voffB);
;             PG8_BAR; PG8_WAIT_L(0); PG8_MMA(0, 1, At, B1); PG8_BAR;
;             PG8_LDA(At, 0, 1); PG8_STAGE(PG8_SA(0, 0), a2, voffA);
;             PG8_BAR; PG8_WAIT_L(0); PG8_MMA(1, 0, At, B0); PG8_BAR; PG8_SCHED;
;             PG8_STAGE(PG8_SB(0, 1), b2 + hstep, voffB);
;             PG8_WAIT_V(6); PG8_BAR; PG8_MMA(1, 1, At, B1); PG8_BAR;
;             PG8_LDB(B0, 1, 0); PG8_SCHED; PG8_LDA(At, 1, 0); PG8_STAGE(PG8_SA(0, 1), a2 + hstep, voffA);
;             PG8_WAIT_L(8); PG8_BAR; PG8_WAIT_L(0); PG8_MMA(0, 0, At, B0); PG8_BAR; PG8_SCHED;
;             PG8_LDB(B1, 1, 1); PG8_STAGE(PG8_SB(1, 0), b3, voffB);
;             PG8_BAR; PG8_WAIT_L(0); PG8_MMA(0, 1, At, B1); PG8_BAR;
;             PG8_LDA(At, 1, 1); PG8_STAGE(PG8_SA(1, 0), a3, voffA);
;             PG8_BAR; PG8_WAIT_L(0); PG8_MMA(1, 0, At, B0); PG8_BAR; PG8_SCHED;
;             PG8_STAGE(PG8_SB(1, 1), b3 + hstep, voffB);
;             PG8_WAIT_V(6); PG8_BAR; PG8_MMA(1, 1, At, B1); PG8_BAR;
	ds_read_b128 v[166:169], v152 offset:16384
	ds_read_b128 v[170:173], v152 offset:17408
	ds_read_b128 v[182:185], v152 offset:18432
	ds_read_b128 v[190:193], v152 offset:19456
	ds_read_b128 v[194:197], v152 offset:20480
	ds_read_b128 v[198:201], v152 offset:21504
	ds_read_b128 v[202:205], v152 offset:22528
	ds_read_b128 v[206:209], v152 offset:23552
	s_add_i32 s47, s38, s26
	s_add_u32 s98, s18, s4
	s_addc_u32 s99, s19, s5
	s_mov_b32 m0, s47
	s_nop 0
	global_load_lds_dwordx4 v132, s[18:19]
	s_nop 1
	s_add_i32 m0, s47, 0x2000
	s_nop 0
	global_load_lds_dwordx4 v128, s[18:19]
	s_nop 1
	s_mov_b32 m0, s15
	s_add_u32 s100, s20, s4
	s_addc_u32 s101, s21, s5
	global_load_lds_dwordx4 v134, s[20:21]
	s_nop 1
	s_mov_b32 m0, s29
	s_nop 0
	global_load_lds_dwordx4 v130, s[20:21]
	s_add_u32 s48, s18, 0x40000
	s_addc_u32 s49, s19, 0
	s_add_i32 s47, s39, s26
	s_mov_b32 m0, s47
	s_nop 0
	global_load_lds_dwordx4 v132, s[48:49]
	s_nop 1
	s_add_i32 m0, s47, 0x2000
	s_nop 0
	global_load_lds_dwordx4 v128, s[48:49]
	s_waitcnt vmcnt(8) lgkmcnt(0)
	s_barrier
	v_mfma_f32_16x16x32_bf16 v[60:63], v[144:147], v[166:169], v[60:63]
	v_mfma_f32_16x16x32_bf16 v[56:59], v[158:161], v[166:169], v[56:59]
	v_mfma_f32_16x16x32_bf16 v[44:47], v[144:147], v[182:185], v[44:47]
	v_mfma_f32_16x16x32_bf16 v[40:43], v[158:161], v[182:185], v[40:43]
	v_mfma_f32_16x16x32_bf16 v[28:31], v[144:147], v[194:197], v[28:31]
	v_mfma_f32_16x16x32_bf16 v[24:27], v[158:161], v[194:197], v[24:27]
	v_mfma_f32_16x16x32_bf16 v[12:15], v[144:147], v[202:205], v[12:15]
	v_mfma_f32_16x16x32_bf16 v[8:11], v[158:161], v[202:205], v[8:11]
	v_mfma_f32_16x16x32_bf16 v[60:63], v[154:157], v[170:173], v[60:63]
	v_mfma_f32_16x16x32_bf16 v[56:59], v[162:165], v[170:173], v[56:59]
	v_mfma_f32_16x16x32_bf16 v[44:47], v[154:157], v[190:193], v[44:47]
	v_mfma_f32_16x16x32_bf16 v[40:43], v[162:165], v[190:193], v[40:43]
	v_mfma_f32_16x16x32_bf16 v[28:31], v[154:157], v[198:201], v[28:31]
	v_mfma_f32_16x16x32_bf16 v[24:27], v[162:165], v[198:201], v[24:27]
	v_mfma_f32_16x16x32_bf16 v[12:15], v[154:157], v[206:209], v[12:15]
	v_mfma_f32_16x16x32_bf16 v[8:11], v[162:165], v[206:209], v[8:11]
	v_mfma_f32_16x16x32_bf16 v[52:55], v[210:213], v[166:169], v[52:55]
	v_mfma_f32_16x16x32_bf16 v[48:51], v[218:221], v[166:169], v[48:51]
	v_mfma_f32_16x16x32_bf16 v[36:39], v[210:213], v[182:185], v[36:39]
	v_mfma_f32_16x16x32_bf16 v[32:35], v[218:221], v[182:185], v[32:35]
	v_mfma_f32_16x16x32_bf16 v[20:23], v[210:213], v[194:197], v[20:23]
	v_mfma_f32_16x16x32_bf16 v[16:19], v[218:221], v[194:197], v[16:19]
	v_mfma_f32_16x16x32_bf16 v[4:7], v[210:213], v[202:205], v[4:7]
	v_mfma_f32_16x16x32_bf16 v[0:3], v[218:221], v[202:205], v[0:3]
	v_mfma_f32_16x16x32_bf16 v[52:55], v[214:217], v[170:173], v[52:55]
	v_mfma_f32_16x16x32_bf16 v[48:51], v[222:225], v[170:173], v[48:51]
	v_mfma_f32_16x16x32_bf16 v[36:39], v[214:217], v[190:193], v[36:39]
	v_mfma_f32_16x16x32_bf16 v[32:35], v[222:225], v[190:193], v[32:35]
	v_mfma_f32_16x16x32_bf16 v[20:23], v[214:217], v[198:201], v[20:23]
	v_mfma_f32_16x16x32_bf16 v[16:19], v[222:225], v[198:201], v[16:19]
	v_mfma_f32_16x16x32_bf16 v[4:7], v[214:217], v[206:209], v[4:7]
	v_mfma_f32_16x16x32_bf16 v[0:3], v[222:225], v[206:209], v[0:3]
	s_barrier
	s_add_i32 s47, 0, 0x18000
	v_add_u32_e32 v162, s47, v149
	ds_read_b128 v[144:147], v162
	ds_read_b128 v[154:157], v162 offset:1024
	ds_read_b128 v[158:161], v162 offset:2048
	ds_read_b128 v[162:165], v162 offset:3072
	ds_read_b128 v[166:169], v152 offset:32768
	ds_read_b128 v[170:173], v152 offset:33792
	ds_read_b128 v[182:185], v152 offset:34816
	ds_read_b128 v[190:193], v152 offset:35840
	ds_read_b128 v[194:197], v152 offset:36864
	ds_read_b128 v[198:201], v152 offset:37888
	ds_read_b128 v[202:205], v152 offset:38912
	ds_read_b128 v[206:209], v152 offset:39936
	v_add_u32_e32 v179, 0x1c000, v149
	s_waitcnt lgkmcnt(8)
	ds_read_b128 v[210:213], v179
	ds_read_b128 v[214:217], v179 offset:1024
	ds_read_b128 v[218:221], v179 offset:2048
	ds_read_b128 v[222:225], v179 offset:3072
	s_add_u32 s20, s20, 0x40000
	s_addc_u32 s21, s21, 0
	s_mov_b32 m0, s30
	s_nop 0
	global_load_lds_dwordx4 v134, s[20:21]
	s_nop 1
	s_mov_b32 m0, s31
	s_nop 0
	global_load_lds_dwordx4 v130, s[20:21]
	s_add_i32 s20, 0, 0x1c000
	s_waitcnt vmcnt(8) lgkmcnt(0)
	s_barrier
	v_mfma_f32_16x16x32_bf16 v[124:127], v[144:147], v[166:169], v[124:127]
	v_mfma_f32_16x16x32_bf16 v[120:123], v[158:161], v[166:169], v[120:123]
	v_mfma_f32_16x16x32_bf16 v[108:111], v[144:147], v[182:185], v[108:111]
	v_mfma_f32_16x16x32_bf16 v[104:107], v[158:161], v[182:185], v[104:107]
	v_mfma_f32_16x16x32_bf16 v[92:95], v[144:147], v[194:197], v[92:95]
	v_mfma_f32_16x16x32_bf16 v[88:91], v[158:161], v[194:197], v[88:91]
	v_mfma_f32_16x16x32_bf16 v[76:79], v[144:147], v[202:205], v[76:79]
	v_mfma_f32_16x16x32_bf16 v[72:75], v[158:161], v[202:205], v[72:75]
	v_mfma_f32_16x16x32_bf16 v[124:127], v[154:157], v[170:173], v[124:127]
	v_mfma_f32_16x16x32_bf16 v[120:123], v[162:165], v[170:173], v[120:123]
	v_mfma_f32_16x16x32_bf16 v[108:111], v[154:157], v[190:193], v[108:111]
	v_mfma_f32_16x16x32_bf16 v[104:107], v[162:165], v[190:193], v[104:107]
	v_mfma_f32_16x16x32_bf16 v[92:95], v[154:157], v[198:201], v[92:95]
	v_mfma_f32_16x16x32_bf16 v[88:91], v[162:165], v[198:201], v[88:91]
	v_mfma_f32_16x16x32_bf16 v[76:79], v[154:157], v[206:209], v[76:79]
	v_mfma_f32_16x16x32_bf16 v[72:75], v[162:165], v[206:209], v[72:75]
	v_mfma_f32_16x16x32_bf16 v[116:119], v[210:213], v[166:169], v[116:119]
	v_mfma_f32_16x16x32_bf16 v[112:115], v[218:221], v[166:169], v[112:115]
	v_mfma_f32_16x16x32_bf16 v[100:103], v[210:213], v[182:185], v[100:103]
	v_mfma_f32_16x16x32_bf16 v[96:99], v[218:221], v[182:185], v[96:99]
	v_mfma_f32_16x16x32_bf16 v[84:87], v[210:213], v[194:197], v[84:87]
	v_mfma_f32_16x16x32_bf16 v[80:83], v[218:221], v[194:197], v[80:83]
	v_mfma_f32_16x16x32_bf16 v[68:71], v[210:213], v[202:205], v[68:71]
	v_mfma_f32_16x16x32_bf16 v[64:67], v[218:221], v[202:205], v[64:67]
	v_mfma_f32_16x16x32_bf16 v[116:119], v[214:217], v[170:173], v[116:119]
	v_mfma_f32_16x16x32_bf16 v[112:115], v[222:225], v[170:173], v[112:115]
	v_mfma_f32_16x16x32_bf16 v[100:103], v[214:217], v[190:193], v[100:103]
	v_mfma_f32_16x16x32_bf16 v[96:99], v[222:225], v[190:193], v[96:99]
	v_mfma_f32_16x16x32_bf16 v[84:87], v[214:217], v[198:201], v[84:87]
	v_mfma_f32_16x16x32_bf16 v[80:83], v[222:225], v[198:201], v[80:83]
	v_mfma_f32_16x16x32_bf16 v[68:71], v[214:217], v[206:209], v[68:71]
	v_mfma_f32_16x16x32_bf16 v[64:67], v[222:225], v[206:209], v[64:67]
	s_barrier
; #define PG8_STAGE(bufoff, gbase, voff) do { _Pragma("unroll") for (int _i = 0; _i < 2; ++_i) \
;         __builtin_amdgcn_global_load_lds((const unsigned*)((const char*)(gbase) + (voff)[_i]), (PG8_LAS unsigned*)(lds + (bufoff) + ldsw + _i * 8192), 16, 0, 0); } while (0)
; #define PG8_LDA(dst, b, h) do { _Pragma("unroll") for (int m = 0; m < 4; ++m) _Pragma("unroll") for (int k = 0; k < 2; ++k) dst[m][k] = *(const PG8_LAS bf16x8*)(lds + PG8_SA(b, h) + aoff + m * 2048 + k * 1024); } while (0)
; #define PG8_WAIT_V(n) asm volatile("s_waitcnt vmcnt(" #n ")" ::: "memory")
; #define PG8_BAR __builtin_amdgcn_s_barrier()
; __device__ __forceinline__ f32x4 sigmoid4(f32x4 x) {
;     f32x4 d;
; #pragma unroll
;     for (int j = 0; j < 4; ++j) d[j] = 1.0f + __expf(-fmaxf(x[j], -20.0f));
;     const float p01 = d[0] * d[1], p23 = d[2] * d[3], r = __builtin_amdgcn_rcpf(p01 * p23), r01 = r * p23, r23 = r * p01;
;     return (f32x4){r01 * d[1], r01 * d[0], r23 * d[3], r23 * d[2]};
; }
; template <class Epi, class Sched>
; __device__ __forceinline__ void gemm_phase(PG8_LAS unsigned char* lds, const Gemm g, const Sched& S, const Epi& E) {
;     ...
;             PG8_LDB(B0, 0, 0); PG8_SCHED; PG8_LDA(At, 0, 0); PG8_STAGE(PG8_SA(1, 1), a1 + hstep, voffA);
;             PG8_WAIT_L(8); PG8_BAR; PG8_WAIT_L(0); PG8_MMA(0, 0, At, B0); PG8_BAR; PG8_SCHED;
;             PG8_LDB(B1, 0, 1); PG8_STAGE(PG8_SB(0, 0), b2, voffB);
;             PG8_BAR; PG8_WAIT_L(0); PG8_MMA(0, 1, At, B1); PG8_BAR;
;             PG8_LDA(At, 0, 1); PG8_STAGE(PG8_SA(0, 0), a2, voffA);
;             PG8_BAR; PG8_WAIT_L(0); PG8_MMA(1, 0, At, B0); PG8_BAR; PG8_SCHED;
;             PG8_STAGE(PG8_SB(0, 1), b2 + hstep, voffB);
;             PG8_WAIT_V(6); PG8_BAR; PG8_MMA(1, 1, At, B1); PG8_BAR;
;             PG8_LDB(B0, 1, 0); PG8_SCHED; PG8_LDA(At, 1, 0); PG8_STAGE(PG8_SA(0, 1), a2 + hstep, voffA);
;             PG8_WAIT_L(8); PG8_BAR; PG8_WAIT_L(0); PG8_MMA(0, 0, At, B0); PG8_BAR; PG8_SCHED;
;             PG8_LDB(B1, 1, 1); PG8_STAGE(PG8_SB(1, 0), b3, voffB);
;             PG8_BAR; PG8_WAIT_L(0); PG8_MMA(0, 1, At, B1); PG8_BAR;
;             PG8_LDA(At, 1, 1); PG8_STAGE(PG8_SA(1, 0), a3, voffA);
;             PG8_BAR; PG8_WAIT_L(0); PG8_MMA(1, 0, At, B0); PG8_BAR; PG8_SCHED;
;             PG8_STAGE(PG8_SB(1, 1), b3 + hstep, voffB);
;             PG8_WAIT_V(6); PG8_BAR; PG8_MMA(1, 1, At, B1); PG8_BAR;
	ds_read_b128 v[166:169], v152 offset:49152
	ds_read_b128 v[170:173], v152 offset:50176
	ds_read_b128 v[182:185], v152 offset:51200
	ds_read_b128 v[190:193], v152 offset:52224
	ds_read_b128 v[194:197], v152 offset:53248
	ds_read_b128 v[198:201], v152 offset:54272
	ds_read_b128 v[202:205], v152 offset:55296
	ds_read_b128 v[206:209], v152 offset:56320
	s_add_i32 s21, s47, s26
	s_mov_b32 m0, s21
	s_nop 0
	global_load_lds_dwordx4 v132, s[98:99]
	s_nop 1
	s_add_i32 m0, s21, 0x2000
	s_nop 0
	global_load_lds_dwordx4 v128, s[98:99]
	s_nop 1
	s_mov_b32 m0, s35
	s_nop 0
	global_load_lds_dwordx4 v134, s[100:101]
	s_nop 1
	s_mov_b32 m0, s36
	s_nop 0
	global_load_lds_dwordx4 v130, s[100:101]
	s_add_u32 s18, s18, 0x40080
	s_addc_u32 s19, s19, 0
	s_add_i32 s20, s20, s26
	s_mov_b32 m0, s20
	s_nop 0
	global_load_lds_dwordx4 v132, s[18:19]
	s_nop 1
	s_add_i32 m0, s20, 0x2000
	s_nop 0
	global_load_lds_dwordx4 v128, s[18:19]
	s_waitcnt vmcnt(8) lgkmcnt(0)
	s_barrier
	v_mfma_f32_16x16x32_bf16 v[60:63], v[144:147], v[166:169], v[60:63]
	v_mfma_f32_16x16x32_bf16 v[56:59], v[158:161], v[166:169], v[56:59]
	v_mfma_f32_16x16x32_bf16 v[44:47], v[144:147], v[182:185], v[44:47]
	v_mfma_f32_16x16x32_bf16 v[40:43], v[158:161], v[182:185], v[40:43]
	v_mfma_f32_16x16x32_bf16 v[28:31], v[144:147], v[194:197], v[28:31]
	v_mfma_f32_16x16x32_bf16 v[24:27], v[158:161], v[194:197], v[24:27]
	v_mfma_f32_16x16x32_bf16 v[12:15], v[144:147], v[202:205], v[12:15]
	v_mfma_f32_16x16x32_bf16 v[8:11], v[158:161], v[202:205], v[8:11]
	v_mfma_f32_16x16x32_bf16 v[60:63], v[154:157], v[170:173], v[60:63]
	v_mfma_f32_16x16x32_bf16 v[56:59], v[162:165], v[170:173], v[56:59]
	v_mfma_f32_16x16x32_bf16 v[44:47], v[154:157], v[190:193], v[44:47]
	v_mfma_f32_16x16x32_bf16 v[40:43], v[162:165], v[190:193], v[40:43]
	v_mfma_f32_16x16x32_bf16 v[28:31], v[154:157], v[198:201], v[28:31]
	v_mfma_f32_16x16x32_bf16 v[24:27], v[162:165], v[198:201], v[24:27]
	v_mfma_f32_16x16x32_bf16 v[12:15], v[154:157], v[206:209], v[12:15]
	v_mfma_f32_16x16x32_bf16 v[8:11], v[162:165], v[206:209], v[8:11]
	v_mfma_f32_16x16x32_bf16 v[52:55], v[210:213], v[166:169], v[52:55]
	v_mfma_f32_16x16x32_bf16 v[48:51], v[218:221], v[166:169], v[48:51]
	v_mfma_f32_16x16x32_bf16 v[36:39], v[210:213], v[182:185], v[36:39]
	v_mfma_f32_16x16x32_bf16 v[32:35], v[218:221], v[182:185], v[32:35]
	v_mfma_f32_16x16x32_bf16 v[20:23], v[210:213], v[194:197], v[20:23]
	v_mfma_f32_16x16x32_bf16 v[16:19], v[218:221], v[194:197], v[16:19]
	v_mfma_f32_16x16x32_bf16 v[4:7], v[210:213], v[202:205], v[4:7]
	v_mfma_f32_16x16x32_bf16 v[0:3], v[218:221], v[202:205], v[0:3]
	v_mfma_f32_16x16x32_bf16 v[52:55], v[214:217], v[170:173], v[52:55]
	v_mfma_f32_16x16x32_bf16 v[48:51], v[222:225], v[170:173], v[48:51]
	v_mfma_f32_16x16x32_bf16 v[36:39], v[214:217], v[190:193], v[36:39]
	v_mfma_f32_16x16x32_bf16 v[32:35], v[222:225], v[190:193], v[32:35]
	v_mfma_f32_16x16x32_bf16 v[20:23], v[214:217], v[198:201], v[20:23]
	v_mfma_f32_16x16x32_bf16 v[16:19], v[222:225], v[198:201], v[16:19]
	v_mfma_f32_16x16x32_bf16 v[4:7], v[214:217], v[206:209], v[4:7]
	v_mfma_f32_16x16x32_bf16 v[0:3], v[222:225], v[206:209], v[0:3]
	s_barrier
	s_add_i32 s46, s46, 2
	s_add_u32 s16, s16, 0x100
	s_addc_u32 s17, s17, 0
	s_add_u32 s44, s44, 0x100
	s_addc_u32 s45, s45, 0
	s_cmp_gt_u32 s46, 13
	s_cbranch_scc0 .LBB0_1202
	v_max_f32_e32 v144, 0xc1a00000, v124
	v_mul_f32_e32 v144, 0xbfb8aa3b, v144
	v_exp_f32_e32 v157, v144
	v_max_f32_e32 v144, 0xc1a00000, v125
	v_mul_f32_e32 v144, 0xbfb8aa3b, v144
	v_exp_f32_e32 v156, v144
	v_max_f32_e32 v144, 0xc1a00000, v126
	v_mul_f32_e32 v144, 0xbfb8aa3b, v144
	v_exp_f32_e32 v159, v144
	v_max_f32_e32 v144, 0xc1a00000, v127
	v_mul_f32_e32 v144, 0xbfb8aa3b, v144
	v_exp_f32_e32 v158, v144
	v_pk_add_f32 v[156:157], v[156:157], 1.0 op_sel_hi:[1,0]
	v_lshl_or_b32 v146, s41, 7, v150
	v_mov_b32_e32 v160, v157
	v_pk_add_f32 v[158:159], v[158:159], 1.0 op_sel_hi:[1,0]
	v_mov_b32_e32 v162, v156
	v_mov_b32_e32 v161, v159
	v_mov_b32_e32 v163, v158
	v_pk_mul_f32 v[160:161], v[160:161], v[162:163]
	v_lshl_add_u32 v154, s14, 8, v148
	v_mul_f32_e32 v155, v160, v161
	v_rcp_f32_e32 v155, v155
	v_ashrrev_i32_e32 v147, 31, v146
	v_mov_b64_e32 v[144:145], s[0:1]
	v_mad_i64_i32 v[162:163], s[16:17], v154, s40, v[144:145]
	v_mul_f32_e32 v164, v161, v155
	v_mul_f32_e32 v160, v160, v155
	v_max_f32_e32 v155, 0xc1a00000, v120
	v_mul_f32_e32 v155, 0xbfb8aa3b, v155
	v_pk_mul_f32 v[158:159], v[158:159], v[160:161] op_sel_hi:[1,0]
	v_exp_f32_e32 v161, v155
	v_max_f32_e32 v155, 0xc1a00000, v121
	v_mul_f32_e32 v155, 0xbfb8aa3b, v155
	v_exp_f32_e32 v160, v155
	v_max_f32_e32 v155, 0xc1a00000, v122
	v_mul_f32_e32 v155, 0xbfb8aa3b, v155
	v_exp_f32_e32 v167, v155
	v_max_f32_e32 v155, 0xc1a00000, v123
	v_mul_f32_e32 v155, 0xbfb8aa3b, v155
	v_exp_f32_e32 v166, v155
	v_pk_mul_f32 v[156:157], v[156:157], v[164:165] op_sel_hi:[1,0]
	v_pk_mul_f32 v[126:127], v[126:127], v[158:159]
	v_pk_mul_f32 v[124:125], v[124:125], v[156:157]
	v_pk_add_f32 v[156:157], v[160:161], 1.0 op_sel_hi:[1,0]
	v_pk_add_f32 v[160:161], v[166:167], 1.0 op_sel_hi:[1,0]
	v_mov_b32_e32 v164, v157
	v_mov_b32_e32 v165, v161
	v_mov_b32_e32 v166, v156
	v_mov_b32_e32 v167, v160
	v_pk_mul_f32 v[164:165], v[164:165], v[166:167]
	v_pk_mul_f32 v[118:119], v[126:127], v[118:119]
	v_mul_f32_e32 v155, v164, v165
	v_rcp_f32_e32 v155, v155
	v_pk_mul_f32 v[116:117], v[124:125], v[116:117]
	v_lshlrev_b64 v[146:147], 1, v[146:147]
	v_lshl_add_u64 v[162:163], v[162:163], 0, v[146:147]
	v_mul_f32_e32 v124, v165, v155
	v_mul_f32_e32 v126, v164, v155
	v_pk_mul_f32 v[126:127], v[160:161], v[126:127] op_sel_hi:[1,0]
; __device__ __forceinline__ unsigned cvt_pk_bf16(float lo, float hi) { unsigned r; asm volatile("v_cvt_pk_bf16_f32 %0, %1, %2" : "=v"(r) : "v"(lo), "v"(hi)); return r; }
; __device__ __forceinline__ f32x4 sigmoid4(f32x4 x) {
;     f32x4 d;
; #pragma unroll
;     for (int j = 0; j < 4; ++j) d[j] = 1.0f + __expf(-fmaxf(x[j], -20.0f));
;     const float p01 = d[0] * d[1], p23 = d[2] * d[3], r = __builtin_amdgcn_rcpf(p01 * p23), r01 = r * p23, r23 = r * p01;
;     return (f32x4){r01 * d[1], r01 * d[0], r23 * d[3], r23 * d[2]};
; }
;     __device__ __forceinline__ void operator()(const f32x4 (&acc)[2][2][4][2], const Unit& u, int wr, int wc, int fr, int fq) const {
;     ...
;             for (int m = 0; m < 4; ++m) { bf16_t* rowp = O + (size_t)(row0 + ai * HALF + m * 16) * ldc + col0;
;                 f32x4 v0, v1;
; #pragma unroll
;                 for (int j = 0; j < 1; ++j) { v0 = acc[ai][0][m][0] * sigmoid4(acc[ai][0][m][0]) * acc[ai][1][m][0]; v1 = acc[ai][0][m][1] * sigmoid4(acc[ai][0][m][1]) * acc[ai][1][m][1]; }
;                 u32x4 w; w.x = cvt_pk_bf16(v0[0], v0[1]); w.y = cvt_pk_bf16(v0[2], v0[3]); w.z = cvt_pk_bf16(v1[0], v1[1]); w.w = cvt_pk_bf16(v1[2], v1[3]);
;                 *(u32x4*)rowp = w; }
	v_pk_mul_f32 v[124:125], v[156:157], v[124:125] op_sel_hi:[1,0]
	v_pk_mul_f32 v[122:123], v[122:123], v[126:127]
	v_pk_mul_f32 v[120:121], v[120:121], v[124:125]
	v_pk_mul_f32 v[122:123], v[122:123], v[114:115]
	v_pk_mul_f32 v[114:115], v[120:121], v[112:113]
	v_cvt_pk_bf16_f32 v112, v116, v117
	v_cvt_pk_bf16_f32 v113, v118, v119
	v_max_f32_e32 v116, 0xc1a00000, v108
	v_max_f32_e32 v118, 0xc1a00000, v110
	v_mul_f32_e32 v116, 0xbfb8aa3b, v116
	v_mul_f32_e32 v118, 0xbfb8aa3b, v118
	v_exp_f32_e32 v117, v116
	v_exp_f32_e32 v119, v118
	v_max_f32_e32 v116, 0xc1a00000, v109
	v_max_f32_e32 v118, 0xc1a00000, v111
	v_mul_f32_e32 v116, 0xbfb8aa3b, v116
	v_mul_f32_e32 v118, 0xbfb8aa3b, v118
	v_exp_f32_e32 v116, v116
	v_exp_f32_e32 v118, v118
	v_cvt_pk_bf16_f32 v114, v114, v115
	v_cvt_pk_bf16_f32 v115, v122, v123
	global_store_dwordx4 v[162:163], v[112:115], off
	v_or_b32_e32 v120, 16, v154
	s_and_b64 vcc, exec, s[2:3]
	v_pk_add_f32 v[112:113], v[116:117], 1.0 op_sel_hi:[1,0]
	v_pk_add_f32 v[114:115], v[118:119], 1.0 op_sel_hi:[1,0]
	v_mov_b32_e32 v116, v113
	v_mov_b32_e32 v117, v115
	v_mov_b32_e32 v118, v112
	v_mov_b32_e32 v119, v114
	v_pk_mul_f32 v[116:117], v[116:117], v[118:119]
	s_mov_b32 s41, s6
	v_mul_f32_e32 v118, v116, v117
	v_rcp_f32_e32 v121, v118
	v_mad_i64_i32 v[118:119], s[16:17], v120, s40, v[144:145]
	v_lshl_add_u64 v[118:119], v[118:119], 0, v[146:147]
	v_mul_f32_e32 v116, v116, v121
	v_mul_f32_e32 v120, v117, v121
	v_pk_mul_f32 v[114:115], v[114:115], v[116:117] op_sel_hi:[1,0]
	v_max_f32_e32 v116, 0xc1a00000, v104
	v_max_f32_e32 v121, 0xc1a00000, v106
	v_mul_f32_e32 v116, 0xbfb8aa3b, v116
	v_mul_f32_e32 v121, 0xbfb8aa3b, v121
	v_exp_f32_e32 v117, v116
	v_exp_f32_e32 v123, v121
	v_max_f32_e32 v116, 0xc1a00000, v105
	v_max_f32_e32 v121, 0xc1a00000, v107
	v_mul_f32_e32 v116, 0xbfb8aa3b, v116
	v_mul_f32_e32 v121, 0xbfb8aa3b, v121
	v_exp_f32_e32 v116, v116
	v_exp_f32_e32 v122, v121
	v_pk_mul_f32 v[112:113], v[112:113], v[120:121] op_sel_hi:[1,0]
	v_pk_mul_f32 v[110:111], v[110:111], v[114:115]
	v_pk_mul_f32 v[108:109], v[108:109], v[112:113]
	v_pk_add_f32 v[112:113], v[116:117], 1.0 op_sel_hi:[1,0]
	v_pk_add_f32 v[116:117], v[122:123], 1.0 op_sel_hi:[1,0]
	v_mov_b32_e32 v120, v113
	v_mov_b32_e32 v121, v117
	v_mov_b32_e32 v122, v112
	v_mov_b32_e32 v123, v116
	v_pk_mul_f32 v[120:121], v[120:121], v[122:123]
	v_pk_mul_f32 v[102:103], v[110:111], v[102:103]
	v_mul_f32_e32 v122, v120, v121
	v_rcp_f32_e32 v122, v122
	v_pk_mul_f32 v[100:101], v[108:109], v[100:101]
	s_mov_b32 s14, s8
	s_mov_b64 s[18:19], s[12:13]
	v_mul_f32_e32 v108, v121, v122
	v_mul_f32_e32 v110, v120, v122
	v_pk_mul_f32 v[110:111], v[116:117], v[110:111] op_sel_hi:[1,0]
	v_pk_mul_f32 v[108:109], v[112:113], v[108:109] op_sel_hi:[1,0]
	v_pk_mul_f32 v[106:107], v[106:107], v[110:111]
	v_pk_mul_f32 v[104:105], v[104:105], v[108:109]
	v_pk_mul_f32 v[106:107], v[106:107], v[98:99]
	v_pk_mul_f32 v[98:99], v[104:105], v[96:97]
	v_cvt_pk_bf16_f32 v96, v100, v101
	v_cvt_pk_bf16_f32 v97, v102, v103
	v_max_f32_e32 v100, 0xc1a00000, v92
	v_max_f32_e32 v102, 0xc1a00000, v94
	v_mul_f32_e32 v100, 0xbfb8aa3b, v100
	v_mul_f32_e32 v102, 0xbfb8aa3b, v102
	v_exp_f32_e32 v101, v100
	v_exp_f32_e32 v103, v102
	v_max_f32_e32 v100, 0xc1a00000, v93
	v_max_f32_e32 v102, 0xc1a00000, v95
	v_mul_f32_e32 v100, 0xbfb8aa3b, v100
	v_mul_f32_e32 v102, 0xbfb8aa3b, v102
	v_exp_f32_e32 v100, v100
	v_exp_f32_e32 v102, v102
	v_cvt_pk_bf16_f32 v98, v98, v99
	v_cvt_pk_bf16_f32 v99, v106, v107
	global_store_dwordx4 v[118:119], v[96:99], off
	v_or_b32_e32 v104, 32, v154
	s_nop 0
	v_pk_add_f32 v[96:97], v[100:101], 1.0 op_sel_hi:[1,0]
	v_pk_add_f32 v[98:99], v[102:103], 1.0 op_sel_hi:[1,0]
	v_mov_b32_e32 v100, v97
	v_mov_b32_e32 v101, v99
	v_mov_b32_e32 v102, v96
	v_mov_b32_e32 v103, v98
	v_pk_mul_f32 v[100:101], v[100:101], v[102:103]
	s_nop 0
	v_mul_f32_e32 v102, v100, v101
	v_rcp_f32_e32 v105, v102
	v_mad_i64_i32 v[102:103], s[16:17], v104, s40, v[144:145]
	v_lshl_add_u64 v[102:103], v[102:103], 0, v[146:147]
	v_mul_f32_e32 v100, v100, v105
	v_mul_f32_e32 v104, v101, v105
	v_pk_mul_f32 v[98:99], v[98:99], v[100:101] op_sel_hi:[1,0]
	v_max_f32_e32 v100, 0xc1a00000, v88
	v_max_f32_e32 v105, 0xc1a00000, v90
	v_mul_f32_e32 v100, 0xbfb8aa3b, v100
	v_mul_f32_e32 v105, 0xbfb8aa3b, v105
	v_exp_f32_e32 v101, v100
	v_exp_f32_e32 v107, v105
	v_max_f32_e32 v100, 0xc1a00000, v89
	v_max_f32_e32 v105, 0xc1a00000, v91
	v_mul_f32_e32 v100, 0xbfb8aa3b, v100
	v_mul_f32_e32 v105, 0xbfb8aa3b, v105
	v_exp_f32_e32 v100, v100
	v_exp_f32_e32 v106, v105
	v_pk_mul_f32 v[96:97], v[96:97], v[104:105] op_sel_hi:[1,0]
	v_pk_mul_f32 v[94:95], v[94:95], v[98:99]
	v_pk_mul_f32 v[92:93], v[92:93], v[96:97]
	v_pk_add_f32 v[96:97], v[100:101], 1.0 op_sel_hi:[1,0]
	v_pk_add_f32 v[100:101], v[106:107], 1.0 op_sel_hi:[1,0]
	v_mov_b32_e32 v104, v97
	v_mov_b32_e32 v105, v101
	v_mov_b32_e32 v106, v96
	v_mov_b32_e32 v107, v100
	v_pk_mul_f32 v[104:105], v[104:105], v[106:107]
	v_pk_mul_f32 v[86:87], v[94:95], v[86:87]
	v_mul_f32_e32 v106, v104, v105
	v_rcp_f32_e32 v106, v106
	v_pk_mul_f32 v[84:85], v[92:93], v[84:85]
	v_mul_f32_e32 v92, v105, v106
	v_mul_f32_e32 v94, v104, v106
	v_pk_mul_f32 v[94:95], v[100:101], v[94:95] op_sel_hi:[1,0]
	v_pk_mul_f32 v[92:93], v[96:97], v[92:93] op_sel_hi:[1,0]
	v_pk_mul_f32 v[90:91], v[90:91], v[94:95]
	v_pk_mul_f32 v[88:89], v[88:89], v[92:93]
	v_pk_mul_f32 v[90:91], v[90:91], v[82:83]
	v_pk_mul_f32 v[82:83], v[88:89], v[80:81]
	v_cvt_pk_bf16_f32 v80, v84, v85
	v_cvt_pk_bf16_f32 v81, v86, v87
	v_max_f32_e32 v84, 0xc1a00000, v76
	v_max_f32_e32 v86, 0xc1a00000, v78
	v_mul_f32_e32 v84, 0xbfb8aa3b, v84
	v_mul_f32_e32 v86, 0xbfb8aa3b, v86
; __device__ __forceinline__ unsigned cvt_pk_bf16(float lo, float hi) { unsigned r; asm volatile("v_cvt_pk_bf16_f32 %0, %1, %2" : "=v"(r) : "v"(lo), "v"(hi)); return r; }
;     __device__ __forceinline__ void operator()(const f32x4 (&acc)[2][2][4][2], const Unit& u, int wr, int wc, int fr, int fq) const {
;         const int row0 = u.pm * BM + wr * 64 + fr, col0 = u.pn * HALF + wc * 32 + 8 * fq;
; #pragma unroll
;         for (int ai = 0; ai < 2; ++ai)
; #pragma unroll
;             for (int m = 0; m < 4; ++m) { bf16_t* rowp = O + (size_t)(row0 + ai * HALF + m * 16) * ldc + col0;
;                 f32x4 v0, v1;
; #pragma unroll
;                 for (int j = 0; j < 1; ++j) { v0 = acc[ai][0][m][0] * sigmoid4(acc[ai][0][m][0]) * acc[ai][1][m][0]; v1 = acc[ai][0][m][1] * sigmoid4(acc[ai][0][m][1]) * acc[ai][1][m][1]; }
;                 u32x4 w; w.x = cvt_pk_bf16(v0[0], v0[1]); w.y = cvt_pk_bf16(v0[2], v0[3]); w.z = cvt_pk_bf16(v1[0], v1[1]); w.w = cvt_pk_bf16(v1[2], v1[3]);
;                 *(u32x4*)rowp = w; }
	v_exp_f32_e32 v85, v84
	v_exp_f32_e32 v87, v86
	v_max_f32_e32 v84, 0xc1a00000, v77
	v_max_f32_e32 v86, 0xc1a00000, v79
	v_mul_f32_e32 v84, 0xbfb8aa3b, v84
	v_mul_f32_e32 v86, 0xbfb8aa3b, v86
	v_exp_f32_e32 v84, v84
	v_exp_f32_e32 v86, v86
	v_cvt_pk_bf16_f32 v82, v82, v83
	v_cvt_pk_bf16_f32 v83, v90, v91
	global_store_dwordx4 v[102:103], v[80:83], off
	v_or_b32_e32 v88, 48, v154
	s_nop 0
	v_pk_add_f32 v[80:81], v[84:85], 1.0 op_sel_hi:[1,0]
	v_pk_add_f32 v[82:83], v[86:87], 1.0 op_sel_hi:[1,0]
	v_mov_b32_e32 v84, v81
	v_mov_b32_e32 v85, v83
	v_mov_b32_e32 v86, v80
	v_mov_b32_e32 v87, v82
	v_pk_mul_f32 v[84:85], v[84:85], v[86:87]
	s_nop 0
	v_mul_f32_e32 v86, v84, v85
	v_rcp_f32_e32 v89, v86
	v_mad_i64_i32 v[86:87], s[16:17], v88, s40, v[144:145]
	v_lshl_add_u64 v[86:87], v[86:87], 0, v[146:147]
	v_mul_f32_e32 v84, v84, v89
	v_mul_f32_e32 v88, v85, v89
	v_pk_mul_f32 v[82:83], v[82:83], v[84:85] op_sel_hi:[1,0]
	v_max_f32_e32 v84, 0xc1a00000, v72
	v_max_f32_e32 v89, 0xc1a00000, v74
	v_mul_f32_e32 v84, 0xbfb8aa3b, v84
	v_mul_f32_e32 v89, 0xbfb8aa3b, v89
	v_exp_f32_e32 v85, v84
	v_exp_f32_e32 v91, v89
	v_max_f32_e32 v84, 0xc1a00000, v73
	v_max_f32_e32 v89, 0xc1a00000, v75
	v_mul_f32_e32 v84, 0xbfb8aa3b, v84
	v_mul_f32_e32 v89, 0xbfb8aa3b, v89
	v_exp_f32_e32 v84, v84
	v_exp_f32_e32 v90, v89
	v_pk_mul_f32 v[80:81], v[80:81], v[88:89] op_sel_hi:[1,0]
	v_pk_mul_f32 v[78:79], v[78:79], v[82:83]
	v_pk_mul_f32 v[76:77], v[76:77], v[80:81]
	v_pk_add_f32 v[80:81], v[84:85], 1.0 op_sel_hi:[1,0]
	v_pk_add_f32 v[84:85], v[90:91], 1.0 op_sel_hi:[1,0]
	v_mov_b32_e32 v88, v81
	v_mov_b32_e32 v89, v85
	v_mov_b32_e32 v90, v80
	v_mov_b32_e32 v91, v84
	v_pk_mul_f32 v[88:89], v[88:89], v[90:91]
	v_pk_mul_f32 v[70:71], v[78:79], v[70:71]
	v_mul_f32_e32 v90, v88, v89
	v_rcp_f32_e32 v90, v90
	v_pk_mul_f32 v[68:69], v[76:77], v[68:69]
	v_mul_f32_e32 v76, v89, v90
	v_mul_f32_e32 v78, v88, v90
	v_pk_mul_f32 v[78:79], v[84:85], v[78:79] op_sel_hi:[1,0]
	v_pk_mul_f32 v[76:77], v[80:81], v[76:77] op_sel_hi:[1,0]
	v_pk_mul_f32 v[74:75], v[74:75], v[78:79]
	v_pk_mul_f32 v[72:73], v[72:73], v[76:77]
	v_pk_mul_f32 v[74:75], v[74:75], v[66:67]
	v_pk_mul_f32 v[66:67], v[72:73], v[64:65]
	v_cvt_pk_bf16_f32 v64, v68, v69
	v_cvt_pk_bf16_f32 v65, v70, v71
	v_max_f32_e32 v68, 0xc1a00000, v60
	v_max_f32_e32 v70, 0xc1a00000, v62
	v_mul_f32_e32 v68, 0xbfb8aa3b, v68
	v_mul_f32_e32 v70, 0xbfb8aa3b, v70
	v_exp_f32_e32 v69, v68
	v_exp_f32_e32 v71, v70
	v_max_f32_e32 v68, 0xc1a00000, v61
	v_max_f32_e32 v70, 0xc1a00000, v63
	v_mul_f32_e32 v68, 0xbfb8aa3b, v68
	v_mul_f32_e32 v70, 0xbfb8aa3b, v70
	v_exp_f32_e32 v68, v68
	v_exp_f32_e32 v70, v70
	v_cvt_pk_bf16_f32 v66, v66, v67
	v_cvt_pk_bf16_f32 v67, v74, v75
	global_store_dwordx4 v[86:87], v[64:67], off
	v_add_u32_e32 v72, 0x80, v154
	s_nop 0
	v_pk_add_f32 v[64:65], v[68:69], 1.0 op_sel_hi:[1,0]
	v_pk_add_f32 v[66:67], v[70:71], 1.0 op_sel_hi:[1,0]
	v_mov_b32_e32 v68, v65
	v_mov_b32_e32 v69, v67
	v_mov_b32_e32 v70, v64
	v_mov_b32_e32 v71, v66
	v_pk_mul_f32 v[68:69], v[68:69], v[70:71]
	s_nop 0
	v_mul_f32_e32 v70, v68, v69
	v_rcp_f32_e32 v73, v70
	v_mad_i64_i32 v[70:71], s[16:17], v72, s40, v[144:145]
	v_lshl_add_u64 v[70:71], v[70:71], 0, v[146:147]
	v_mul_f32_e32 v68, v68, v73
	v_mul_f32_e32 v72, v69, v73
	v_pk_mul_f32 v[66:67], v[66:67], v[68:69] op_sel_hi:[1,0]
	v_max_f32_e32 v68, 0xc1a00000, v56
	v_max_f32_e32 v73, 0xc1a00000, v58
	v_mul_f32_e32 v68, 0xbfb8aa3b, v68
	v_mul_f32_e32 v73, 0xbfb8aa3b, v73
	v_exp_f32_e32 v69, v68
	v_exp_f32_e32 v75, v73
	v_max_f32_e32 v68, 0xc1a00000, v57
	v_max_f32_e32 v73, 0xc1a00000, v59
	v_mul_f32_e32 v68, 0xbfb8aa3b, v68
	v_mul_f32_e32 v73, 0xbfb8aa3b, v73
	v_exp_f32_e32 v68, v68
	v_exp_f32_e32 v74, v73
	v_pk_mul_f32 v[64:65], v[64:65], v[72:73] op_sel_hi:[1,0]
	v_pk_mul_f32 v[62:63], v[62:63], v[66:67]
	v_pk_mul_f32 v[60:61], v[60:61], v[64:65]
	v_pk_add_f32 v[64:65], v[68:69], 1.0 op_sel_hi:[1,0]
	v_pk_add_f32 v[68:69], v[74:75], 1.0 op_sel_hi:[1,0]
	v_mov_b32_e32 v72, v65
	v_mov_b32_e32 v73, v69
	v_mov_b32_e32 v74, v64
	v_mov_b32_e32 v75, v68
	v_pk_mul_f32 v[72:73], v[72:73], v[74:75]
	v_pk_mul_f32 v[54:55], v[62:63], v[54:55]
	v_mul_f32_e32 v74, v72, v73
	v_rcp_f32_e32 v74, v74
	v_pk_mul_f32 v[52:53], v[60:61], v[52:53]
	v_mul_f32_e32 v60, v73, v74
	v_mul_f32_e32 v62, v72, v74
	v_pk_mul_f32 v[62:63], v[68:69], v[62:63] op_sel_hi:[1,0]
	v_pk_mul_f32 v[60:61], v[64:65], v[60:61] op_sel_hi:[1,0]
	v_pk_mul_f32 v[58:59], v[58:59], v[62:63]
	v_pk_mul_f32 v[56:57], v[56:57], v[60:61]
	v_pk_mul_f32 v[58:59], v[58:59], v[50:51]
	v_pk_mul_f32 v[50:51], v[56:57], v[48:49]
	v_cvt_pk_bf16_f32 v48, v52, v53
	v_cvt_pk_bf16_f32 v49, v54, v55
	v_max_f32_e32 v52, 0xc1a00000, v44
	v_max_f32_e32 v54, 0xc1a00000, v46
	v_mul_f32_e32 v52, 0xbfb8aa3b, v52
	v_mul_f32_e32 v54, 0xbfb8aa3b, v54
	v_exp_f32_e32 v53, v52
	v_exp_f32_e32 v55, v54
	v_max_f32_e32 v52, 0xc1a00000, v45
	v_max_f32_e32 v54, 0xc1a00000, v47
	v_mul_f32_e32 v52, 0xbfb8aa3b, v52
	v_mul_f32_e32 v54, 0xbfb8aa3b, v54
	v_exp_f32_e32 v52, v52
	v_exp_f32_e32 v54, v54
	v_cvt_pk_bf16_f32 v50, v50, v51
	v_cvt_pk_bf16_f32 v51, v58, v59
	global_store_dwordx4 v[70:71], v[48:51], off
	v_add_u32_e32 v56, 0x90, v154
	s_nop 0
	v_pk_add_f32 v[48:49], v[52:53], 1.0 op_sel_hi:[1,0]
	v_pk_add_f32 v[50:51], v[54:55], 1.0 op_sel_hi:[1,0]
	v_mov_b32_e32 v52, v49
	v_mov_b32_e32 v53, v51
	v_mov_b32_e32 v54, v48
	v_mov_b32_e32 v55, v50
	v_pk_mul_f32 v[52:53], v[52:53], v[54:55]
	s_nop 0
	v_mul_f32_e32 v54, v52, v53
	v_rcp_f32_e32 v57, v54
	v_mad_i64_i32 v[54:55], s[16:17], v56, s40, v[144:145]
	v_lshl_add_u64 v[54:55], v[54:55], 0, v[146:147]
	v_mul_f32_e32 v52, v52, v57
; __device__ __forceinline__ unsigned cvt_pk_bf16(float lo, float hi) { unsigned r; asm volatile("v_cvt_pk_bf16_f32 %0, %1, %2" : "=v"(r) : "v"(lo), "v"(hi)); return r; }
; #define PG8_WAIT_V(n) asm volatile("s_waitcnt vmcnt(" #n ")" ::: "memory")
; #define PG8_BAR __builtin_amdgcn_s_barrier()
;     __device__ __forceinline__ void operator()(const f32x4 (&acc)[2][2][4][2], const Unit& u, int wr, int wc, int fr, int fq) const {
;         const int row0 = u.pm * BM + wr * 64 + fr, col0 = u.pn * HALF + wc * 32 + 8 * fq;
; #pragma unroll
;         for (int ai = 0; ai < 2; ++ai)
; #pragma unroll
;             for (int m = 0; m < 4; ++m) { bf16_t* rowp = O + (size_t)(row0 + ai * HALF + m * 16) * ldc + col0;
;                 f32x4 v0, v1;
; #pragma unroll
;                 for (int j = 0; j < 1; ++j) { v0 = acc[ai][0][m][0] * sigmoid4(acc[ai][0][m][0]) * acc[ai][1][m][0]; v1 = acc[ai][0][m][1] * sigmoid4(acc[ai][0][m][1]) * acc[ai][1][m][1]; }
;                 u32x4 w; w.x = cvt_pk_bf16(v0[0], v0[1]); w.y = cvt_pk_bf16(v0[2], v0[3]); w.z = cvt_pk_bf16(v1[0], v1[1]); w.w = cvt_pk_bf16(v1[2], v1[3]);
;                 *(u32x4*)rowp = w; }
; template <class Epi, class Sched>
; __device__ __forceinline__ void gemm_phase(PG8_LAS unsigned char* lds, const Gemm g, const Sched& S, const Epi& E) {
;     ...
;         if (!has_next) break;
; #pragma unroll
;         for (int a = 0; a < 2; ++a)
; #pragma unroll
;             for (int b = 0; b < 2; ++b)
; #pragma unroll
;                 for (int m = 0; m < 4; ++m)
; #pragma unroll
;                     for (int n = 0; n < 2; ++n) acc[a][b][m][n] = (f32x4){0.f, 0.f, 0.f, 0.f};
;         cur = nxt; cA = nA; cB = nB; ++ui;
;     }
;     PG8_WAIT_V(0);
;     if (wr == 0) PG8_BAR;
;     PG8_BAR;
	v_mul_f32_e32 v56, v53, v57
	v_pk_mul_f32 v[50:51], v[50:51], v[52:53] op_sel_hi:[1,0]
	v_max_f32_e32 v52, 0xc1a00000, v40
	v_max_f32_e32 v57, 0xc1a00000, v42
	v_mul_f32_e32 v52, 0xbfb8aa3b, v52
	v_mul_f32_e32 v57, 0xbfb8aa3b, v57
	v_exp_f32_e32 v53, v52
	v_exp_f32_e32 v59, v57
	v_max_f32_e32 v52, 0xc1a00000, v41
	v_max_f32_e32 v57, 0xc1a00000, v43
	v_mul_f32_e32 v52, 0xbfb8aa3b, v52
	v_mul_f32_e32 v57, 0xbfb8aa3b, v57
	v_exp_f32_e32 v52, v52
	v_exp_f32_e32 v58, v57
	v_pk_mul_f32 v[48:49], v[48:49], v[56:57] op_sel_hi:[1,0]
	v_pk_mul_f32 v[46:47], v[46:47], v[50:51]
	v_pk_mul_f32 v[44:45], v[44:45], v[48:49]
	v_pk_add_f32 v[48:49], v[52:53], 1.0 op_sel_hi:[1,0]
	v_pk_add_f32 v[52:53], v[58:59], 1.0 op_sel_hi:[1,0]
	v_mov_b32_e32 v56, v49
	v_mov_b32_e32 v57, v53
	v_mov_b32_e32 v58, v48
	v_mov_b32_e32 v59, v52
	v_pk_mul_f32 v[56:57], v[56:57], v[58:59]
	v_pk_mul_f32 v[38:39], v[46:47], v[38:39]
	v_mul_f32_e32 v58, v56, v57
	v_rcp_f32_e32 v58, v58
	v_pk_mul_f32 v[36:37], v[44:45], v[36:37]
	v_mul_f32_e32 v44, v57, v58
	v_mul_f32_e32 v46, v56, v58
	v_pk_mul_f32 v[46:47], v[52:53], v[46:47] op_sel_hi:[1,0]
	v_pk_mul_f32 v[44:45], v[48:49], v[44:45] op_sel_hi:[1,0]
	v_pk_mul_f32 v[42:43], v[42:43], v[46:47]
	v_pk_mul_f32 v[40:41], v[40:41], v[44:45]
	v_pk_mul_f32 v[42:43], v[42:43], v[34:35]
	v_pk_mul_f32 v[34:35], v[40:41], v[32:33]
	v_cvt_pk_bf16_f32 v32, v36, v37
	v_cvt_pk_bf16_f32 v33, v38, v39
	v_max_f32_e32 v36, 0xc1a00000, v28
	v_max_f32_e32 v38, 0xc1a00000, v30
	v_mul_f32_e32 v36, 0xbfb8aa3b, v36
	v_mul_f32_e32 v38, 0xbfb8aa3b, v38
	v_exp_f32_e32 v37, v36
	v_exp_f32_e32 v39, v38
	v_max_f32_e32 v36, 0xc1a00000, v29
	v_max_f32_e32 v38, 0xc1a00000, v31
	v_mul_f32_e32 v36, 0xbfb8aa3b, v36
	v_mul_f32_e32 v38, 0xbfb8aa3b, v38
	v_exp_f32_e32 v36, v36
	v_exp_f32_e32 v38, v38
	v_cvt_pk_bf16_f32 v34, v34, v35
	v_cvt_pk_bf16_f32 v35, v42, v43
	global_store_dwordx4 v[54:55], v[32:35], off
	v_add_u32_e32 v40, 0xa0, v154
	s_nop 0
	v_pk_add_f32 v[32:33], v[36:37], 1.0 op_sel_hi:[1,0]
	v_pk_add_f32 v[34:35], v[38:39], 1.0 op_sel_hi:[1,0]
	v_mov_b32_e32 v36, v33
	v_mov_b32_e32 v37, v35
	v_mov_b32_e32 v38, v32
	v_mov_b32_e32 v39, v34
	v_pk_mul_f32 v[36:37], v[36:37], v[38:39]
	s_nop 0
	v_mul_f32_e32 v38, v36, v37
	v_rcp_f32_e32 v41, v38
	v_mad_i64_i32 v[38:39], s[16:17], v40, s40, v[144:145]
	v_lshl_add_u64 v[38:39], v[38:39], 0, v[146:147]
	v_mul_f32_e32 v36, v36, v41
	v_mul_f32_e32 v40, v37, v41
	v_pk_mul_f32 v[34:35], v[34:35], v[36:37] op_sel_hi:[1,0]
	v_max_f32_e32 v36, 0xc1a00000, v24
	v_max_f32_e32 v41, 0xc1a00000, v26
	v_mul_f32_e32 v36, 0xbfb8aa3b, v36
	v_mul_f32_e32 v41, 0xbfb8aa3b, v41
	v_exp_f32_e32 v37, v36
	v_exp_f32_e32 v43, v41
	v_max_f32_e32 v36, 0xc1a00000, v25
	v_max_f32_e32 v41, 0xc1a00000, v27
	v_mul_f32_e32 v36, 0xbfb8aa3b, v36
	v_mul_f32_e32 v41, 0xbfb8aa3b, v41
	v_exp_f32_e32 v36, v36
	v_exp_f32_e32 v42, v41
	v_pk_mul_f32 v[32:33], v[32:33], v[40:41] op_sel_hi:[1,0]
	v_pk_mul_f32 v[30:31], v[30:31], v[34:35]
	v_pk_mul_f32 v[28:29], v[28:29], v[32:33]
	v_pk_add_f32 v[32:33], v[36:37], 1.0 op_sel_hi:[1,0]
	v_pk_add_f32 v[36:37], v[42:43], 1.0 op_sel_hi:[1,0]
	v_mov_b32_e32 v40, v33
	v_mov_b32_e32 v41, v37
	v_mov_b32_e32 v42, v32
	v_mov_b32_e32 v43, v36
	v_pk_mul_f32 v[40:41], v[40:41], v[42:43]
	v_pk_mul_f32 v[22:23], v[30:31], v[22:23]
	v_mul_f32_e32 v42, v40, v41
	v_rcp_f32_e32 v42, v42
	v_pk_mul_f32 v[20:21], v[28:29], v[20:21]
	v_mul_f32_e32 v28, v41, v42
	v_mul_f32_e32 v30, v40, v42
	v_pk_mul_f32 v[30:31], v[36:37], v[30:31] op_sel_hi:[1,0]
	v_pk_mul_f32 v[28:29], v[32:33], v[28:29] op_sel_hi:[1,0]
	v_pk_mul_f32 v[26:27], v[26:27], v[30:31]
	v_pk_mul_f32 v[24:25], v[24:25], v[28:29]
	v_pk_mul_f32 v[26:27], v[26:27], v[18:19]
	v_pk_mul_f32 v[18:19], v[24:25], v[16:17]
	v_cvt_pk_bf16_f32 v16, v20, v21
	v_cvt_pk_bf16_f32 v17, v22, v23
	v_max_f32_e32 v20, 0xc1a00000, v12
	v_max_f32_e32 v22, 0xc1a00000, v14
	v_mul_f32_e32 v20, 0xbfb8aa3b, v20
	v_mul_f32_e32 v22, 0xbfb8aa3b, v22
	v_exp_f32_e32 v21, v20
	v_exp_f32_e32 v23, v22
	v_max_f32_e32 v20, 0xc1a00000, v13
	v_max_f32_e32 v22, 0xc1a00000, v15
	v_mul_f32_e32 v20, 0xbfb8aa3b, v20
	v_mul_f32_e32 v22, 0xbfb8aa3b, v22
	v_exp_f32_e32 v20, v20
	v_exp_f32_e32 v22, v22
	v_cvt_pk_bf16_f32 v18, v18, v19
	v_cvt_pk_bf16_f32 v19, v26, v27
	global_store_dwordx4 v[38:39], v[16:19], off
	v_add_u32_e32 v24, 0xb0, v154
	s_nop 0
	v_pk_add_f32 v[16:17], v[20:21], 1.0 op_sel_hi:[1,0]
	v_pk_add_f32 v[18:19], v[22:23], 1.0 op_sel_hi:[1,0]
	v_mov_b32_e32 v20, v17
	v_mov_b32_e32 v21, v19
	v_mov_b32_e32 v22, v16
	v_mov_b32_e32 v23, v18
	v_pk_mul_f32 v[20:21], v[20:21], v[22:23]
	s_nop 0
	v_mul_f32_e32 v22, v20, v21
	v_rcp_f32_e32 v25, v22
	v_mad_i64_i32 v[22:23], s[16:17], v24, s40, v[144:145]
	v_lshl_add_u64 v[22:23], v[22:23], 0, v[146:147]
	v_mul_f32_e32 v20, v20, v25
	v_mul_f32_e32 v24, v21, v25
	v_pk_mul_f32 v[18:19], v[18:19], v[20:21] op_sel_hi:[1,0]
	v_max_f32_e32 v20, 0xc1a00000, v8
	v_max_f32_e32 v25, 0xc1a00000, v10
	v_mul_f32_e32 v20, 0xbfb8aa3b, v20
	v_mul_f32_e32 v25, 0xbfb8aa3b, v25
	v_exp_f32_e32 v21, v20
	v_exp_f32_e32 v27, v25
	v_max_f32_e32 v20, 0xc1a00000, v9
	v_max_f32_e32 v25, 0xc1a00000, v11
	v_mul_f32_e32 v20, 0xbfb8aa3b, v20
	v_mul_f32_e32 v25, 0xbfb8aa3b, v25
	v_exp_f32_e32 v20, v20
	v_exp_f32_e32 v26, v25
	v_pk_mul_f32 v[16:17], v[16:17], v[24:25] op_sel_hi:[1,0]
	v_pk_mul_f32 v[14:15], v[14:15], v[18:19]
	v_pk_mul_f32 v[12:13], v[12:13], v[16:17]
	v_pk_add_f32 v[16:17], v[20:21], 1.0 op_sel_hi:[1,0]
	v_pk_add_f32 v[20:21], v[26:27], 1.0 op_sel_hi:[1,0]
	v_mov_b32_e32 v24, v17
	v_mov_b32_e32 v25, v21
	v_mov_b32_e32 v26, v16
	v_mov_b32_e32 v27, v20
	v_pk_mul_f32 v[24:25], v[24:25], v[26:27]
	v_pk_mul_f32 v[6:7], v[14:15], v[6:7]
	v_mul_f32_e32 v26, v24, v25
	v_rcp_f32_e32 v26, v26
	v_pk_mul_f32 v[4:5], v[12:13], v[4:5]
	s_mov_b64 s[16:17], s[10:11]
	v_mul_f32_e32 v12, v25, v26
	v_mul_f32_e32 v14, v24, v26
	v_pk_mul_f32 v[14:15], v[20:21], v[14:15] op_sel_hi:[1,0]
	v_pk_mul_f32 v[12:13], v[16:17], v[12:13] op_sel_hi:[1,0]
	v_pk_mul_f32 v[10:11], v[10:11], v[14:15]
	v_pk_mul_f32 v[8:9], v[8:9], v[12:13]
	v_pk_mul_f32 v[10:11], v[10:11], v[2:3]
	v_pk_mul_f32 v[2:3], v[8:9], v[0:1]
	v_cvt_pk_bf16_f32 v0, v4, v5
	v_cvt_pk_bf16_f32 v1, v6, v7
	s_nop 0
	v_cvt_pk_bf16_f32 v2, v2, v3
	v_cvt_pk_bf16_f32 v3, v10, v11
	global_store_dwordx4 v[22:23], v[0:3], off
	s_cbranch_vccz .LBB0_1199
	s_waitcnt vmcnt(0)
	s_cmpk_gt_u32 s23, 0xff
	s_cbranch_scc1 .LBB0_1206
	s_barrier

; #define PG8_STAGE(bufoff, gbase, voff) do { _Pragma("unroll") for (int _i = 0; _i < 2; ++_i) \
;         __builtin_amdgcn_global_load_lds((const unsigned*)((const char*)(gbase) + (voff)[_i]), (PG8_LAS unsigned*)(lds + (bufoff) + ldsw + _i * 8192), 16, 0, 0); } while (0)
; #define PG8_LDA(dst, b, h) do { _Pragma("unroll") for (int m = 0; m < 4; ++m) _Pragma("unroll") for (int k = 0; k < 2; ++k) dst[m][k] = *(const PG8_LAS bf16x8*)(lds + PG8_SA(b, h) + aoff + m * 2048 + k * 1024); } while (0)
; #define PG8_WAIT_V(n) asm volatile("s_waitcnt vmcnt(" #n ")" ::: "memory")
; template <class Epi, class Sched>
; __device__ __forceinline__ void gemm_phase(PG8_LAS unsigned char* lds, const Gemm g, const Sched& S, const Epi& E) {
;     ...
;         for (int t = 0; t < nt; t += 2) {
;             const bool last = (t == nt - 2);
;             const char* a1 = cA + (size_t)(t + 1) * kstep;
;             const char* a2 = last ? nA : cA + (size_t)(t + 2) * kstep; const char* b2 = last ? nB : cB + (size_t)(t + 2) * kstep;
;             const char* a3 = a2 + kstep; const char* b3 = b2 + kstep;
;             if (last && has_next) S.a_ready(nxt);
;             PG8_LDB(B0, 0, 0); PG8_SCHED; PG8_LDA(At, 0, 0); PG8_STAGE(PG8_SA(1, 1), a1 + hstep, voffA);
;             PG8_WAIT_L(8); PG8_BAR; PG8_WAIT_L(0); PG8_MMA(0, 0, At, B0); PG8_BAR; PG8_SCHED;
;             PG8_LDB(B1, 0, 1); PG8_STAGE(PG8_SB(0, 0), b2, voffB);
;             PG8_BAR; PG8_WAIT_L(0); PG8_MMA(0, 1, At, B1); PG8_BAR;
;             PG8_LDA(At, 0, 1); PG8_STAGE(PG8_SA(0, 0), a2, voffA);
;             PG8_BAR; PG8_WAIT_L(0); PG8_MMA(1, 0, At, B0); PG8_BAR; PG8_SCHED;
;             PG8_STAGE(PG8_SB(0, 1), b2 + hstep, voffB);
;             PG8_WAIT_V(6); PG8_BAR; PG8_MMA(1, 1, At, B1); PG8_BAR;
;             PG8_LDB(B0, 1, 0); PG8_SCHED; PG8_LDA(At, 1, 0); PG8_STAGE(PG8_SA(0, 1), a2 + hstep, voffA);
;             PG8_WAIT_L(8); PG8_BAR; PG8_WAIT_L(0); PG8_MMA(0, 0, At, B0); PG8_BAR; PG8_SCHED;
;             PG8_LDB(B1, 1, 1); PG8_STAGE(PG8_SB(1, 0), b3, voffB);
;             PG8_BAR; PG8_WAIT_L(0); PG8_MMA(0, 1, At, B1); PG8_BAR;
;             PG8_LDA(At, 1, 1); PG8_STAGE(PG8_SA(1, 0), a3, voffA);
;             PG8_BAR; PG8_WAIT_L(0); PG8_MMA(1, 0, At, B0); PG8_BAR; PG8_SCHED;
;             PG8_STAGE(PG8_SB(1, 1), b3 + hstep, voffB);
;             PG8_WAIT_V(6); PG8_BAR; PG8_MMA(1, 1, At, B1); PG8_BAR;
.LBB0_1277:
	s_add_u32 s52, s20, 0x100
	s_addc_u32 s53, s21, 0
	s_mov_b32 s54, -2
	ds_read_b128 v[152:155], v149
	ds_read_b128 v[156:159], v149 offset:1024
	ds_read_b128 v[160:163], v149 offset:2048
	ds_read_b128 v[164:167], v149 offset:3072
	s_add_u32 s20, s18, 0x100
	s_addc_u32 s21, s19, 0
	s_cmp_eq_u32 s54, 40
	s_cselect_b32 s25, s1, s21
	s_cselect_b32 s24, s0, s20
	s_cselect_b32 s23, s5, s53
	s_cselect_b32 s22, s4, s52
	ds_read_b128 v[168:171], v150
	ds_read_b128 v[172:175], v150 offset:1024
	ds_read_b128 v[182:185], v150 offset:2048
	ds_read_b128 v[190:193], v150 offset:3072
	ds_read_b128 v[194:197], v150 offset:4096
	ds_read_b128 v[198:201], v150 offset:5120
	ds_read_b128 v[202:205], v150 offset:6144
	ds_read_b128 v[206:209], v150 offset:7168
	s_waitcnt lgkmcnt(8)
	ds_read_b128 v[210:213], v151
	ds_read_b128 v[214:217], v151 offset:1024
	ds_read_b128 v[218:221], v151 offset:2048
	ds_read_b128 v[222:225], v151 offset:3072
	s_add_i32 m0, s34, 0xc000
	s_nop 0
	global_load_lds_dwordx4 v136, s[18:19]
	s_nop 1
	s_add_i32 m0, s34, 0xe000
	s_nop 0
	global_load_lds_dwordx4 v138, s[18:19]
	s_waitcnt vmcnt(8) lgkmcnt(0)
	s_barrier
	v_mfma_f32_16x16x32_bf16 v[124:127], v[152:155], v[168:171], 0
	v_mfma_f32_16x16x32_bf16 v[120:123], v[160:163], v[168:171], 0
	v_mfma_f32_16x16x32_bf16 v[108:111], v[152:155], v[182:185], 0
	v_mfma_f32_16x16x32_bf16 v[104:107], v[160:163], v[182:185], 0
	v_mfma_f32_16x16x32_bf16 v[92:95], v[152:155], v[194:197], 0
	v_mfma_f32_16x16x32_bf16 v[88:91], v[160:163], v[194:197], 0
	v_mfma_f32_16x16x32_bf16 v[76:79], v[152:155], v[202:205], 0
	v_mfma_f32_16x16x32_bf16 v[72:75], v[160:163], v[202:205], 0
	v_mfma_f32_16x16x32_bf16 v[124:127], v[156:159], v[172:175], v[124:127]
	v_mfma_f32_16x16x32_bf16 v[120:123], v[164:167], v[172:175], v[120:123]
	v_mfma_f32_16x16x32_bf16 v[108:111], v[156:159], v[190:193], v[108:111]
	v_mfma_f32_16x16x32_bf16 v[104:107], v[164:167], v[190:193], v[104:107]
	v_mfma_f32_16x16x32_bf16 v[92:95], v[156:159], v[198:201], v[92:95]
	v_mfma_f32_16x16x32_bf16 v[88:91], v[164:167], v[198:201], v[88:91]
	v_mfma_f32_16x16x32_bf16 v[76:79], v[156:159], v[206:209], v[76:79]
	v_mfma_f32_16x16x32_bf16 v[72:75], v[164:167], v[206:209], v[72:75]
	v_mfma_f32_16x16x32_bf16 v[116:119], v[210:213], v[168:171], 0
	v_mfma_f32_16x16x32_bf16 v[112:115], v[218:221], v[168:171], 0
	v_mfma_f32_16x16x32_bf16 v[100:103], v[210:213], v[182:185], 0
	v_mfma_f32_16x16x32_bf16 v[96:99], v[218:221], v[182:185], 0
	v_mfma_f32_16x16x32_bf16 v[84:87], v[210:213], v[194:197], 0
	v_mfma_f32_16x16x32_bf16 v[80:83], v[218:221], v[194:197], 0
	v_mfma_f32_16x16x32_bf16 v[68:71], v[210:213], v[202:205], 0
	v_mfma_f32_16x16x32_bf16 v[64:67], v[218:221], v[202:205], 0
	v_mfma_f32_16x16x32_bf16 v[116:119], v[214:217], v[172:175], v[116:119]
	v_mfma_f32_16x16x32_bf16 v[112:115], v[222:225], v[172:175], v[112:115]
	v_mfma_f32_16x16x32_bf16 v[100:103], v[214:217], v[190:193], v[100:103]
	v_mfma_f32_16x16x32_bf16 v[96:99], v[222:225], v[190:193], v[96:99]
	v_mfma_f32_16x16x32_bf16 v[84:87], v[214:217], v[198:201], v[84:87]
	v_mfma_f32_16x16x32_bf16 v[80:83], v[222:225], v[198:201], v[80:83]
	v_mfma_f32_16x16x32_bf16 v[68:71], v[214:217], v[206:209], v[68:71]
	v_mfma_f32_16x16x32_bf16 v[64:67], v[222:225], v[206:209], v[64:67]
	s_barrier
	ds_read_b128 v[168:171], v150 offset:16384
	ds_read_b128 v[172:175], v150 offset:17408
	ds_read_b128 v[182:185], v150 offset:18432
	ds_read_b128 v[190:193], v150 offset:19456
	ds_read_b128 v[194:197], v150 offset:20480
	ds_read_b128 v[198:201], v150 offset:21504
	ds_read_b128 v[202:205], v150 offset:22528
	ds_read_b128 v[206:209], v150 offset:23552
	s_add_i32 s18, s42, s31
	s_add_u32 s98, s22, s8
	s_addc_u32 s99, s23, s9
	s_mov_b32 m0, s18
	s_nop 0
	global_load_lds_dwordx4 v130, s[22:23]
	s_nop 1
	s_add_i32 m0, s18, 0x2000
	s_nop 0
	global_load_lds_dwordx4 v134, s[22:23]
	s_nop 1
	s_mov_b32 m0, s34
	s_add_u32 s100, s24, s8
	s_addc_u32 s101, s25, s9
	global_load_lds_dwordx4 v128, s[24:25]
	s_nop 1
	s_mov_b32 m0, s35
	s_nop 0
	global_load_lds_dwordx4 v132, s[24:25]
	s_add_u32 s18, s22, 0xb0000
	s_addc_u32 s19, s23, 0
	s_add_i32 s55, s43, s31
	s_mov_b32 m0, s55
	s_nop 0
	global_load_lds_dwordx4 v130, s[18:19]
	s_nop 1
	s_add_i32 m0, s55, 0x2000
	s_nop 0
	global_load_lds_dwordx4 v134, s[18:19]
	s_waitcnt vmcnt(8) lgkmcnt(0)
	s_barrier
	v_mfma_f32_16x16x32_bf16 v[60:63], v[152:155], v[168:171], 0
	v_mfma_f32_16x16x32_bf16 v[56:59], v[160:163], v[168:171], 0
	v_mfma_f32_16x16x32_bf16 v[48:51], v[152:155], v[182:185], 0
	v_mfma_f32_16x16x32_bf16 v[40:43], v[160:163], v[182:185], 0
	v_mfma_f32_16x16x32_bf16 v[32:35], v[152:155], v[194:197], 0
	v_mfma_f32_16x16x32_bf16 v[24:27], v[160:163], v[194:197], 0
	v_mfma_f32_16x16x32_bf16 v[16:19], v[152:155], v[202:205], 0
	v_mfma_f32_16x16x32_bf16 v[8:11], v[160:163], v[202:205], 0
	v_mfma_f32_16x16x32_bf16 v[60:63], v[156:159], v[172:175], v[60:63]
	v_mfma_f32_16x16x32_bf16 v[56:59], v[164:167], v[172:175], v[56:59]
	v_mfma_f32_16x16x32_bf16 v[48:51], v[156:159], v[190:193], v[48:51]
	v_mfma_f32_16x16x32_bf16 v[40:43], v[164:167], v[190:193], v[40:43]
	v_mfma_f32_16x16x32_bf16 v[32:35], v[156:159], v[198:201], v[32:35]
	v_mfma_f32_16x16x32_bf16 v[24:27], v[164:167], v[198:201], v[24:27]
	v_mfma_f32_16x16x32_bf16 v[16:19], v[156:159], v[206:209], v[16:19]
	v_mfma_f32_16x16x32_bf16 v[8:11], v[164:167], v[206:209], v[8:11]
	v_mfma_f32_16x16x32_bf16 v[52:55], v[210:213], v[168:171], 0
	v_mfma_f32_16x16x32_bf16 v[44:47], v[218:221], v[168:171], 0
	v_mfma_f32_16x16x32_bf16 v[36:39], v[210:213], v[182:185], 0
	v_mfma_f32_16x16x32_bf16 v[28:31], v[218:221], v[182:185], 0
	v_mfma_f32_16x16x32_bf16 v[20:23], v[210:213], v[194:197], 0
	v_mfma_f32_16x16x32_bf16 v[12:15], v[218:221], v[194:197], 0
	v_mfma_f32_16x16x32_bf16 v[4:7], v[210:213], v[202:205], 0
	v_mfma_f32_16x16x32_bf16 v[0:3], v[218:221], v[202:205], 0
	v_mfma_f32_16x16x32_bf16 v[52:55], v[214:217], v[172:175], v[52:55]
	v_mfma_f32_16x16x32_bf16 v[44:47], v[222:225], v[172:175], v[44:47]
	v_mfma_f32_16x16x32_bf16 v[36:39], v[214:217], v[190:193], v[36:39]
	v_mfma_f32_16x16x32_bf16 v[28:31], v[222:225], v[190:193], v[28:31]
	v_mfma_f32_16x16x32_bf16 v[20:23], v[214:217], v[198:201], v[20:23]
	v_mfma_f32_16x16x32_bf16 v[12:15], v[222:225], v[198:201], v[12:15]
	v_mfma_f32_16x16x32_bf16 v[4:7], v[214:217], v[206:209], v[4:7]
	v_mfma_f32_16x16x32_bf16 v[0:3], v[222:225], v[206:209], v[0:3]
	s_barrier
; #define PG8_STAGE(bufoff, gbase, voff) do { _Pragma("unroll") for (int _i = 0; _i < 2; ++_i) \
;         __builtin_amdgcn_global_load_lds((const unsigned*)((const char*)(gbase) + (voff)[_i]), (PG8_LAS unsigned*)(lds + (bufoff) + ldsw + _i * 8192), 16, 0, 0); } while (0)
; #define PG8_LDA(dst, b, h) do { _Pragma("unroll") for (int m = 0; m < 4; ++m) _Pragma("unroll") for (int k = 0; k < 2; ++k) dst[m][k] = *(const PG8_LAS bf16x8*)(lds + PG8_SA(b, h) + aoff + m * 2048 + k * 1024); } while (0)
; #define PG8_LDB(dst, b, h) do { _Pragma("unroll") for (int n = 0; n < 2; ++n) _Pragma("unroll") for (int k = 0; k < 2; ++k) dst[n][k] = *(const PG8_LAS bf16x8*)(lds + PG8_SB(b, h) + boff + n * 2048 + k * 1024); } while (0)
; #define PG8_MMA(ai, bj, At, Bt) do { __builtin_amdgcn_s_setprio(1); _Pragma("unroll") for (int m = 0; m < 4; ++m) _Pragma("unroll") for (int n = 0; n < 2; ++n) _Pragma("unroll") for (int k = 0; k < 2; ++k) \
;         acc[ai][bj][m][n] = __builtin_amdgcn_mfma_f32_16x16x32_bf16(Bt[n][k], At[m][k], acc[ai][bj][m][n], 0, 0, 0); __builtin_amdgcn_s_setprio(0); } while (0)
; #define PG8_WAIT_V(n) asm volatile("s_waitcnt vmcnt(" #n ")" ::: "memory")
; #define PG8_WAIT_L(n) asm volatile("s_waitcnt lgkmcnt(" #n ")" ::: "memory")
; #define PG8_BAR __builtin_amdgcn_s_barrier()
; #define PG8_SCHED __builtin_amdgcn_sched_barrier(0)
; template <class Epi, class Sched>
; __device__ __forceinline__ void gemm_phase(PG8_LAS unsigned char* lds, const Gemm g, const Sched& S, const Epi& E) {
;     ...
;             PG8_LDB(B0, 1, 0); PG8_SCHED; PG8_LDA(At, 1, 0); PG8_STAGE(PG8_SA(0, 1), a2 + hstep, voffA);
;             PG8_WAIT_L(8); PG8_BAR; PG8_WAIT_L(0); PG8_MMA(0, 0, At, B0); PG8_BAR; PG8_SCHED;
;             PG8_LDB(B1, 1, 1); PG8_STAGE(PG8_SB(1, 0), b3, voffB);
;             PG8_BAR; PG8_WAIT_L(0); PG8_MMA(0, 1, At, B1); PG8_BAR;
;             PG8_LDA(At, 1, 1); PG8_STAGE(PG8_SA(1, 0), a3, voffA);
;             PG8_BAR; PG8_WAIT_L(0); PG8_MMA(1, 0, At, B0); PG8_BAR; PG8_SCHED;
;             PG8_STAGE(PG8_SB(1, 1), b3 + hstep, voffB);
;             PG8_WAIT_V(6); PG8_BAR; PG8_MMA(1, 1, At, B1); PG8_BAR;
	s_add_i32 s55, 0, 0x18000
	v_add_u32_e32 v164, s55, v147
	ds_read_b128 v[152:155], v164
	ds_read_b128 v[156:159], v164 offset:1024
	ds_read_b128 v[160:163], v164 offset:2048
	ds_read_b128 v[164:167], v164 offset:3072
	ds_read_b128 v[168:171], v150 offset:32768
	ds_read_b128 v[172:175], v150 offset:33792
	ds_read_b128 v[182:185], v150 offset:34816
	ds_read_b128 v[190:193], v150 offset:35840
	ds_read_b128 v[194:197], v150 offset:36864
	ds_read_b128 v[198:201], v150 offset:37888
	ds_read_b128 v[202:205], v150 offset:38912
	ds_read_b128 v[206:209], v150 offset:39936
	v_add_u32_e32 v179, 0x1c000, v147
	s_waitcnt lgkmcnt(8)
	ds_read_b128 v[210:213], v179
	ds_read_b128 v[214:217], v179 offset:1024
	ds_read_b128 v[218:221], v179 offset:2048
	ds_read_b128 v[222:225], v179 offset:3072
	s_add_u32 s18, s24, 0xb0000
	s_addc_u32 s19, s25, 0
	s_mov_b32 m0, s36
	s_nop 0
	global_load_lds_dwordx4 v128, s[18:19]
	s_nop 1
	s_mov_b32 m0, s37
	s_nop 0
	global_load_lds_dwordx4 v132, s[18:19]
	s_add_i32 s24, 0, 0x1c000
	s_waitcnt vmcnt(8) lgkmcnt(0)
	s_barrier
	v_mfma_f32_16x16x32_bf16 v[124:127], v[152:155], v[168:171], v[124:127]
	v_mfma_f32_16x16x32_bf16 v[120:123], v[160:163], v[168:171], v[120:123]
	v_mfma_f32_16x16x32_bf16 v[108:111], v[152:155], v[182:185], v[108:111]
	v_mfma_f32_16x16x32_bf16 v[104:107], v[160:163], v[182:185], v[104:107]
	v_mfma_f32_16x16x32_bf16 v[92:95], v[152:155], v[194:197], v[92:95]
	v_mfma_f32_16x16x32_bf16 v[88:91], v[160:163], v[194:197], v[88:91]
	v_mfma_f32_16x16x32_bf16 v[76:79], v[152:155], v[202:205], v[76:79]
	v_mfma_f32_16x16x32_bf16 v[72:75], v[160:163], v[202:205], v[72:75]
	v_mfma_f32_16x16x32_bf16 v[124:127], v[156:159], v[172:175], v[124:127]
	v_mfma_f32_16x16x32_bf16 v[120:123], v[164:167], v[172:175], v[120:123]
	v_mfma_f32_16x16x32_bf16 v[108:111], v[156:159], v[190:193], v[108:111]
	v_mfma_f32_16x16x32_bf16 v[104:107], v[164:167], v[190:193], v[104:107]
	v_mfma_f32_16x16x32_bf16 v[92:95], v[156:159], v[198:201], v[92:95]
	v_mfma_f32_16x16x32_bf16 v[88:91], v[164:167], v[198:201], v[88:91]
	v_mfma_f32_16x16x32_bf16 v[76:79], v[156:159], v[206:209], v[76:79]
	v_mfma_f32_16x16x32_bf16 v[72:75], v[164:167], v[206:209], v[72:75]
	v_mfma_f32_16x16x32_bf16 v[116:119], v[210:213], v[168:171], v[116:119]
	v_mfma_f32_16x16x32_bf16 v[112:115], v[218:221], v[168:171], v[112:115]
	v_mfma_f32_16x16x32_bf16 v[100:103], v[210:213], v[182:185], v[100:103]
	v_mfma_f32_16x16x32_bf16 v[96:99], v[218:221], v[182:185], v[96:99]
	v_mfma_f32_16x16x32_bf16 v[84:87], v[210:213], v[194:197], v[84:87]
	v_mfma_f32_16x16x32_bf16 v[80:83], v[218:221], v[194:197], v[80:83]
	v_mfma_f32_16x16x32_bf16 v[68:71], v[210:213], v[202:205], v[68:71]
	v_mfma_f32_16x16x32_bf16 v[64:67], v[218:221], v[202:205], v[64:67]
	v_mfma_f32_16x16x32_bf16 v[116:119], v[214:217], v[172:175], v[116:119]
	v_mfma_f32_16x16x32_bf16 v[112:115], v[222:225], v[172:175], v[112:115]
	v_mfma_f32_16x16x32_bf16 v[100:103], v[214:217], v[190:193], v[100:103]
	v_mfma_f32_16x16x32_bf16 v[96:99], v[222:225], v[190:193], v[96:99]
	v_mfma_f32_16x16x32_bf16 v[84:87], v[214:217], v[198:201], v[84:87]
	v_mfma_f32_16x16x32_bf16 v[80:83], v[222:225], v[198:201], v[80:83]
	v_mfma_f32_16x16x32_bf16 v[68:71], v[214:217], v[206:209], v[68:71]
	v_mfma_f32_16x16x32_bf16 v[64:67], v[222:225], v[206:209], v[64:67]
	s_barrier
	ds_read_b128 v[168:171], v150 offset:49152
	ds_read_b128 v[172:175], v150 offset:50176
	ds_read_b128 v[182:185], v150 offset:51200
	ds_read_b128 v[190:193], v150 offset:52224
	ds_read_b128 v[194:197], v150 offset:53248
	ds_read_b128 v[198:201], v150 offset:54272
	ds_read_b128 v[202:205], v150 offset:55296
	ds_read_b128 v[206:209], v150 offset:56320
	s_add_i32 s18, s55, s31
	s_mov_b32 m0, s18
	s_nop 0
	global_load_lds_dwordx4 v130, s[98:99]
	s_nop 1
	s_add_i32 m0, s18, 0x2000
	s_nop 0
	global_load_lds_dwordx4 v134, s[98:99]
	s_nop 1
	s_mov_b32 m0, s39
	s_nop 0
	global_load_lds_dwordx4 v128, s[100:101]
	s_nop 1
	s_mov_b32 m0, s40
	s_nop 0
	global_load_lds_dwordx4 v132, s[100:101]
	s_add_u32 s18, s22, 0xb0080
	s_addc_u32 s19, s23, 0
	s_add_i32 s22, s24, s31
	s_mov_b32 m0, s22
	s_nop 0
	global_load_lds_dwordx4 v130, s[18:19]
	s_nop 1
	s_add_i32 m0, s22, 0x2000
	s_nop 0
	global_load_lds_dwordx4 v134, s[18:19]
	s_waitcnt vmcnt(8) lgkmcnt(0)
	s_barrier
	v_mfma_f32_16x16x32_bf16 v[60:63], v[152:155], v[168:171], v[60:63]
	v_mfma_f32_16x16x32_bf16 v[56:59], v[160:163], v[168:171], v[56:59]
	v_mfma_f32_16x16x32_bf16 v[48:51], v[152:155], v[182:185], v[48:51]
	v_mfma_f32_16x16x32_bf16 v[40:43], v[160:163], v[182:185], v[40:43]
	v_mfma_f32_16x16x32_bf16 v[32:35], v[152:155], v[194:197], v[32:35]
	v_mfma_f32_16x16x32_bf16 v[24:27], v[160:163], v[194:197], v[24:27]
	v_mfma_f32_16x16x32_bf16 v[16:19], v[152:155], v[202:205], v[16:19]
	v_mfma_f32_16x16x32_bf16 v[8:11], v[160:163], v[202:205], v[8:11]
	v_mfma_f32_16x16x32_bf16 v[60:63], v[156:159], v[172:175], v[60:63]
	v_mfma_f32_16x16x32_bf16 v[56:59], v[164:167], v[172:175], v[56:59]
	v_mfma_f32_16x16x32_bf16 v[48:51], v[156:159], v[190:193], v[48:51]
	v_mfma_f32_16x16x32_bf16 v[40:43], v[164:167], v[190:193], v[40:43]
	v_mfma_f32_16x16x32_bf16 v[32:35], v[156:159], v[198:201], v[32:35]
	v_mfma_f32_16x16x32_bf16 v[24:27], v[164:167], v[198:201], v[24:27]
	v_mfma_f32_16x16x32_bf16 v[16:19], v[156:159], v[206:209], v[16:19]
	v_mfma_f32_16x16x32_bf16 v[8:11], v[164:167], v[206:209], v[8:11]
	v_mfma_f32_16x16x32_bf16 v[52:55], v[210:213], v[168:171], v[52:55]
	v_mfma_f32_16x16x32_bf16 v[44:47], v[218:221], v[168:171], v[44:47]
	v_mfma_f32_16x16x32_bf16 v[36:39], v[210:213], v[182:185], v[36:39]
	v_mfma_f32_16x16x32_bf16 v[28:31], v[218:221], v[182:185], v[28:31]
	v_mfma_f32_16x16x32_bf16 v[20:23], v[210:213], v[194:197], v[20:23]
	v_mfma_f32_16x16x32_bf16 v[12:15], v[218:221], v[194:197], v[12:15]
	v_mfma_f32_16x16x32_bf16 v[4:7], v[210:213], v[202:205], v[4:7]
	v_mfma_f32_16x16x32_bf16 v[0:3], v[218:221], v[202:205], v[0:3]
	v_mfma_f32_16x16x32_bf16 v[52:55], v[214:217], v[172:175], v[52:55]
	v_mfma_f32_16x16x32_bf16 v[44:47], v[222:225], v[172:175], v[44:47]
	v_mfma_f32_16x16x32_bf16 v[36:39], v[214:217], v[190:193], v[36:39]
	v_mfma_f32_16x16x32_bf16 v[28:31], v[222:225], v[190:193], v[28:31]
	v_mfma_f32_16x16x32_bf16 v[20:23], v[214:217], v[198:201], v[20:23]
	v_mfma_f32_16x16x32_bf16 v[12:15], v[222:225], v[198:201], v[12:15]
	v_mfma_f32_16x16x32_bf16 v[4:7], v[214:217], v[206:209], v[4:7]
	v_mfma_f32_16x16x32_bf16 v[0:3], v[222:225], v[206:209], v[0:3]
	s_barrier
	s_add_i32 s54, s54, 2
	s_add_u32 s52, s52, 0x100
	s_addc_u32 s53, s53, 0
	s_cmp_gt_u32 s54, 41
	s_mov_b64 s[18:19], s[20:21]
; #define PG8_STAGE(bufoff, gbase, voff) do { _Pragma("unroll") for (int _i = 0; _i < 2; ++_i) \
;         __builtin_amdgcn_global_load_lds((const unsigned*)((const char*)(gbase) + (voff)[_i]), (PG8_LAS unsigned*)(lds + (bufoff) + ldsw + _i * 8192), 16, 0, 0); } while (0)
; #define PG8_LDA(dst, b, h) do { _Pragma("unroll") for (int m = 0; m < 4; ++m) _Pragma("unroll") for (int k = 0; k < 2; ++k) dst[m][k] = *(const PG8_LAS bf16x8*)(lds + PG8_SA(b, h) + aoff + m * 2048 + k * 1024); } while (0)
; #define PG8_WAIT_V(n) asm volatile("s_waitcnt vmcnt(" #n ")" ::: "memory")
; template <class Epi, class Sched>
; __device__ __forceinline__ void gemm_phase(PG8_LAS unsigned char* lds, const Gemm g, const Sched& S, const Epi& E) {
;     ...
;         for (int t = 0; t < nt; t += 2) {
;             const bool last = (t == nt - 2);
;             const char* a1 = cA + (size_t)(t + 1) * kstep;
;             const char* a2 = last ? nA : cA + (size_t)(t + 2) * kstep; const char* b2 = last ? nB : cB + (size_t)(t + 2) * kstep;
;             const char* a3 = a2 + kstep; const char* b3 = b2 + kstep;
;             if (last && has_next) S.a_ready(nxt);
;             PG8_LDB(B0, 0, 0); PG8_SCHED; PG8_LDA(At, 0, 0); PG8_STAGE(PG8_SA(1, 1), a1 + hstep, voffA);
;             PG8_WAIT_L(8); PG8_BAR; PG8_WAIT_L(0); PG8_MMA(0, 0, At, B0); PG8_BAR; PG8_SCHED;
;             PG8_LDB(B1, 0, 1); PG8_STAGE(PG8_SB(0, 0), b2, voffB);
;             PG8_BAR; PG8_WAIT_L(0); PG8_MMA(0, 1, At, B1); PG8_BAR;
;             PG8_LDA(At, 0, 1); PG8_STAGE(PG8_SA(0, 0), a2, voffA);
;             PG8_BAR; PG8_WAIT_L(0); PG8_MMA(1, 0, At, B0); PG8_BAR; PG8_SCHED;
;             PG8_STAGE(PG8_SB(0, 1), b2 + hstep, voffB);
;             PG8_WAIT_V(6); PG8_BAR; PG8_MMA(1, 1, At, B1); PG8_BAR;
;             PG8_LDB(B0, 1, 0); PG8_SCHED; PG8_LDA(At, 1, 0); PG8_STAGE(PG8_SA(0, 1), a2 + hstep, voffA);
;             PG8_WAIT_L(8); PG8_BAR; PG8_WAIT_L(0); PG8_MMA(0, 0, At, B0); PG8_BAR; PG8_SCHED;
;             PG8_LDB(B1, 1, 1); PG8_STAGE(PG8_SB(1, 0), b3, voffB);
;             PG8_BAR; PG8_WAIT_L(0); PG8_MMA(0, 1, At, B1); PG8_BAR;
;             PG8_LDA(At, 1, 1); PG8_STAGE(PG8_SA(1, 0), a3, voffA);
;             PG8_BAR; PG8_WAIT_L(0); PG8_MMA(1, 0, At, B0); PG8_BAR; PG8_SCHED;
;             PG8_STAGE(PG8_SB(1, 1), b3 + hstep, voffB);
;             PG8_WAIT_V(6); PG8_BAR; PG8_MMA(1, 1, At, B1); PG8_BAR;
.LBB0_1278:
	ds_read_b128 v[152:155], v149
	ds_read_b128 v[156:159], v149 offset:1024
	ds_read_b128 v[160:163], v149 offset:2048
	ds_read_b128 v[164:167], v149 offset:3072
	s_add_u32 s20, s18, 0x100
	s_addc_u32 s21, s19, 0
	s_cmp_eq_u32 s54, 40
	s_cselect_b32 s25, s1, s21
	s_cselect_b32 s24, s0, s20
	s_cselect_b32 s23, s5, s53
	s_cselect_b32 s22, s4, s52
	ds_read_b128 v[168:171], v150
	ds_read_b128 v[172:175], v150 offset:1024
	ds_read_b128 v[182:185], v150 offset:2048
	ds_read_b128 v[190:193], v150 offset:3072
	ds_read_b128 v[194:197], v150 offset:4096
	ds_read_b128 v[198:201], v150 offset:5120
	ds_read_b128 v[202:205], v150 offset:6144
	ds_read_b128 v[206:209], v150 offset:7168
	s_waitcnt lgkmcnt(8)
	ds_read_b128 v[210:213], v151
	ds_read_b128 v[214:217], v151 offset:1024
	ds_read_b128 v[218:221], v151 offset:2048
	ds_read_b128 v[222:225], v151 offset:3072
	s_add_i32 m0, s34, 0xc000
	s_nop 0
	global_load_lds_dwordx4 v136, s[18:19]
	s_nop 1
	s_add_i32 m0, s34, 0xe000
	s_nop 0
	global_load_lds_dwordx4 v138, s[18:19]
	s_waitcnt vmcnt(8) lgkmcnt(0)
	s_barrier
	v_mfma_f32_16x16x32_bf16 v[124:127], v[152:155], v[168:171], v[124:127]
	v_mfma_f32_16x16x32_bf16 v[120:123], v[160:163], v[168:171], v[120:123]
	v_mfma_f32_16x16x32_bf16 v[108:111], v[152:155], v[182:185], v[108:111]
	v_mfma_f32_16x16x32_bf16 v[104:107], v[160:163], v[182:185], v[104:107]
	v_mfma_f32_16x16x32_bf16 v[92:95], v[152:155], v[194:197], v[92:95]
	v_mfma_f32_16x16x32_bf16 v[88:91], v[160:163], v[194:197], v[88:91]
	v_mfma_f32_16x16x32_bf16 v[76:79], v[152:155], v[202:205], v[76:79]
	v_mfma_f32_16x16x32_bf16 v[72:75], v[160:163], v[202:205], v[72:75]
	v_mfma_f32_16x16x32_bf16 v[124:127], v[156:159], v[172:175], v[124:127]
	v_mfma_f32_16x16x32_bf16 v[120:123], v[164:167], v[172:175], v[120:123]
	v_mfma_f32_16x16x32_bf16 v[108:111], v[156:159], v[190:193], v[108:111]
	v_mfma_f32_16x16x32_bf16 v[104:107], v[164:167], v[190:193], v[104:107]
	v_mfma_f32_16x16x32_bf16 v[92:95], v[156:159], v[198:201], v[92:95]
	v_mfma_f32_16x16x32_bf16 v[88:91], v[164:167], v[198:201], v[88:91]
	v_mfma_f32_16x16x32_bf16 v[76:79], v[156:159], v[206:209], v[76:79]
	v_mfma_f32_16x16x32_bf16 v[72:75], v[164:167], v[206:209], v[72:75]
	v_mfma_f32_16x16x32_bf16 v[116:119], v[210:213], v[168:171], v[116:119]
	v_mfma_f32_16x16x32_bf16 v[112:115], v[218:221], v[168:171], v[112:115]
	v_mfma_f32_16x16x32_bf16 v[100:103], v[210:213], v[182:185], v[100:103]
	v_mfma_f32_16x16x32_bf16 v[96:99], v[218:221], v[182:185], v[96:99]
	v_mfma_f32_16x16x32_bf16 v[84:87], v[210:213], v[194:197], v[84:87]
	v_mfma_f32_16x16x32_bf16 v[80:83], v[218:221], v[194:197], v[80:83]
	v_mfma_f32_16x16x32_bf16 v[68:71], v[210:213], v[202:205], v[68:71]
	v_mfma_f32_16x16x32_bf16 v[64:67], v[218:221], v[202:205], v[64:67]
	v_mfma_f32_16x16x32_bf16 v[116:119], v[214:217], v[172:175], v[116:119]
	v_mfma_f32_16x16x32_bf16 v[112:115], v[222:225], v[172:175], v[112:115]
	v_mfma_f32_16x16x32_bf16 v[100:103], v[214:217], v[190:193], v[100:103]
	v_mfma_f32_16x16x32_bf16 v[96:99], v[222:225], v[190:193], v[96:99]
	v_mfma_f32_16x16x32_bf16 v[84:87], v[214:217], v[198:201], v[84:87]
	v_mfma_f32_16x16x32_bf16 v[80:83], v[222:225], v[198:201], v[80:83]
	v_mfma_f32_16x16x32_bf16 v[68:71], v[214:217], v[206:209], v[68:71]
	v_mfma_f32_16x16x32_bf16 v[64:67], v[222:225], v[206:209], v[64:67]
	s_barrier
	ds_read_b128 v[168:171], v150 offset:16384
	ds_read_b128 v[172:175], v150 offset:17408
	ds_read_b128 v[182:185], v150 offset:18432
	ds_read_b128 v[190:193], v150 offset:19456
	ds_read_b128 v[194:197], v150 offset:20480
	ds_read_b128 v[198:201], v150 offset:21504
	ds_read_b128 v[202:205], v150 offset:22528
	ds_read_b128 v[206:209], v150 offset:23552
	s_add_i32 s18, s42, s31
	s_add_u32 s98, s22, s8
	s_addc_u32 s99, s23, s9
	s_mov_b32 m0, s18
	s_nop 0
	global_load_lds_dwordx4 v130, s[22:23]
	s_nop 1
	s_add_i32 m0, s18, 0x2000
	s_nop 0
	global_load_lds_dwordx4 v134, s[22:23]
	s_nop 1
	s_mov_b32 m0, s34
	s_add_u32 s100, s24, s8
	s_addc_u32 s101, s25, s9
	global_load_lds_dwordx4 v128, s[24:25]
	s_nop 1
	s_mov_b32 m0, s35
	s_nop 0
	global_load_lds_dwordx4 v132, s[24:25]
	s_add_u32 s18, s22, 0xb0000
	s_addc_u32 s19, s23, 0
	s_add_i32 s55, s43, s31
	s_mov_b32 m0, s55
	s_nop 0
	global_load_lds_dwordx4 v130, s[18:19]
	s_nop 1
	s_add_i32 m0, s55, 0x2000
	s_nop 0
	global_load_lds_dwordx4 v134, s[18:19]
	s_waitcnt vmcnt(8) lgkmcnt(0)
	s_barrier
	v_mfma_f32_16x16x32_bf16 v[60:63], v[152:155], v[168:171], v[60:63]
	v_mfma_f32_16x16x32_bf16 v[56:59], v[160:163], v[168:171], v[56:59]
	v_mfma_f32_16x16x32_bf16 v[48:51], v[152:155], v[182:185], v[48:51]
	v_mfma_f32_16x16x32_bf16 v[40:43], v[160:163], v[182:185], v[40:43]
	v_mfma_f32_16x16x32_bf16 v[32:35], v[152:155], v[194:197], v[32:35]
	v_mfma_f32_16x16x32_bf16 v[24:27], v[160:163], v[194:197], v[24:27]
	v_mfma_f32_16x16x32_bf16 v[16:19], v[152:155], v[202:205], v[16:19]
	v_mfma_f32_16x16x32_bf16 v[8:11], v[160:163], v[202:205], v[8:11]
	v_mfma_f32_16x16x32_bf16 v[60:63], v[156:159], v[172:175], v[60:63]
	v_mfma_f32_16x16x32_bf16 v[56:59], v[164:167], v[172:175], v[56:59]
	v_mfma_f32_16x16x32_bf16 v[48:51], v[156:159], v[190:193], v[48:51]
	v_mfma_f32_16x16x32_bf16 v[40:43], v[164:167], v[190:193], v[40:43]
	v_mfma_f32_16x16x32_bf16 v[32:35], v[156:159], v[198:201], v[32:35]
	v_mfma_f32_16x16x32_bf16 v[24:27], v[164:167], v[198:201], v[24:27]
	v_mfma_f32_16x16x32_bf16 v[16:19], v[156:159], v[206:209], v[16:19]
	v_mfma_f32_16x16x32_bf16 v[8:11], v[164:167], v[206:209], v[8:11]
	v_mfma_f32_16x16x32_bf16 v[52:55], v[210:213], v[168:171], v[52:55]
	v_mfma_f32_16x16x32_bf16 v[44:47], v[218:221], v[168:171], v[44:47]
	v_mfma_f32_16x16x32_bf16 v[36:39], v[210:213], v[182:185], v[36:39]
	v_mfma_f32_16x16x32_bf16 v[28:31], v[218:221], v[182:185], v[28:31]
	v_mfma_f32_16x16x32_bf16 v[20:23], v[210:213], v[194:197], v[20:23]
	v_mfma_f32_16x16x32_bf16 v[12:15], v[218:221], v[194:197], v[12:15]
	v_mfma_f32_16x16x32_bf16 v[4:7], v[210:213], v[202:205], v[4:7]
	v_mfma_f32_16x16x32_bf16 v[0:3], v[218:221], v[202:205], v[0:3]
	v_mfma_f32_16x16x32_bf16 v[52:55], v[214:217], v[172:175], v[52:55]
	v_mfma_f32_16x16x32_bf16 v[44:47], v[222:225], v[172:175], v[44:47]
	v_mfma_f32_16x16x32_bf16 v[36:39], v[214:217], v[190:193], v[36:39]
	v_mfma_f32_16x16x32_bf16 v[28:31], v[222:225], v[190:193], v[28:31]
	v_mfma_f32_16x16x32_bf16 v[20:23], v[214:217], v[198:201], v[20:23]
	v_mfma_f32_16x16x32_bf16 v[12:15], v[222:225], v[198:201], v[12:15]
	v_mfma_f32_16x16x32_bf16 v[4:7], v[214:217], v[206:209], v[4:7]
	v_mfma_f32_16x16x32_bf16 v[0:3], v[222:225], v[206:209], v[0:3]
	s_barrier
; #define PG8_STAGE(bufoff, gbase, voff) do { _Pragma("unroll") for (int _i = 0; _i < 2; ++_i) \
;         __builtin_amdgcn_global_load_lds((const unsigned*)((const char*)(gbase) + (voff)[_i]), (PG8_LAS unsigned*)(lds + (bufoff) + ldsw + _i * 8192), 16, 0, 0); } while (0)
; #define PG8_LDA(dst, b, h) do { _Pragma("unroll") for (int m = 0; m < 4; ++m) _Pragma("unroll") for (int k = 0; k < 2; ++k) dst[m][k] = *(const PG8_LAS bf16x8*)(lds + PG8_SA(b, h) + aoff + m * 2048 + k * 1024); } while (0)
; #define PG8_LDB(dst, b, h) do { _Pragma("unroll") for (int n = 0; n < 2; ++n) _Pragma("unroll") for (int k = 0; k < 2; ++k) dst[n][k] = *(const PG8_LAS bf16x8*)(lds + PG8_SB(b, h) + boff + n * 2048 + k * 1024); } while (0)
; #define PG8_MMA(ai, bj, At, Bt) do { __builtin_amdgcn_s_setprio(1); _Pragma("unroll") for (int m = 0; m < 4; ++m) _Pragma("unroll") for (int n = 0; n < 2; ++n) _Pragma("unroll") for (int k = 0; k < 2; ++k) \
;         acc[ai][bj][m][n] = __builtin_amdgcn_mfma_f32_16x16x32_bf16(Bt[n][k], At[m][k], acc[ai][bj][m][n], 0, 0, 0); __builtin_amdgcn_s_setprio(0); } while (0)
; #define PG8_WAIT_V(n) asm volatile("s_waitcnt vmcnt(" #n ")" ::: "memory")
; #define PG8_WAIT_L(n) asm volatile("s_waitcnt lgkmcnt(" #n ")" ::: "memory")
; #define PG8_BAR __builtin_amdgcn_s_barrier()
; #define PG8_SCHED __builtin_amdgcn_sched_barrier(0)
; template <class Epi, class Sched>
; __device__ __forceinline__ void gemm_phase(PG8_LAS unsigned char* lds, const Gemm g, const Sched& S, const Epi& E) {
;     ...
;             PG8_LDB(B0, 1, 0); PG8_SCHED; PG8_LDA(At, 1, 0); PG8_STAGE(PG8_SA(0, 1), a2 + hstep, voffA);
;             PG8_WAIT_L(8); PG8_BAR; PG8_WAIT_L(0); PG8_MMA(0, 0, At, B0); PG8_BAR; PG8_SCHED;
;             PG8_LDB(B1, 1, 1); PG8_STAGE(PG8_SB(1, 0), b3, voffB);
;             PG8_BAR; PG8_WAIT_L(0); PG8_MMA(0, 1, At, B1); PG8_BAR;
;             PG8_LDA(At, 1, 1); PG8_STAGE(PG8_SA(1, 0), a3, voffA);
;             PG8_BAR; PG8_WAIT_L(0); PG8_MMA(1, 0, At, B0); PG8_BAR; PG8_SCHED;
;             PG8_STAGE(PG8_SB(1, 1), b3 + hstep, voffB);
;             PG8_WAIT_V(6); PG8_BAR; PG8_MMA(1, 1, At, B1); PG8_BAR;
	s_add_i32 s55, 0, 0x18000
	v_add_u32_e32 v164, s55, v147
	ds_read_b128 v[152:155], v164
	ds_read_b128 v[156:159], v164 offset:1024
	ds_read_b128 v[160:163], v164 offset:2048
	ds_read_b128 v[164:167], v164 offset:3072
	ds_read_b128 v[168:171], v150 offset:32768
	ds_read_b128 v[172:175], v150 offset:33792
	ds_read_b128 v[182:185], v150 offset:34816
	ds_read_b128 v[190:193], v150 offset:35840
	ds_read_b128 v[194:197], v150 offset:36864
	ds_read_b128 v[198:201], v150 offset:37888
	ds_read_b128 v[202:205], v150 offset:38912
	ds_read_b128 v[206:209], v150 offset:39936
	v_add_u32_e32 v179, 0x1c000, v147
	s_waitcnt lgkmcnt(8)
	ds_read_b128 v[210:213], v179
	ds_read_b128 v[214:217], v179 offset:1024
	ds_read_b128 v[218:221], v179 offset:2048
	ds_read_b128 v[222:225], v179 offset:3072
	s_add_u32 s18, s24, 0xb0000
	s_addc_u32 s19, s25, 0
	s_mov_b32 m0, s36
	s_nop 0
	global_load_lds_dwordx4 v128, s[18:19]
	s_nop 1
	s_mov_b32 m0, s37
	s_nop 0
	global_load_lds_dwordx4 v132, s[18:19]
	s_add_i32 s24, 0, 0x1c000
	s_waitcnt vmcnt(8) lgkmcnt(0)
	s_barrier
	v_mfma_f32_16x16x32_bf16 v[124:127], v[152:155], v[168:171], v[124:127]
	v_mfma_f32_16x16x32_bf16 v[120:123], v[160:163], v[168:171], v[120:123]
	v_mfma_f32_16x16x32_bf16 v[108:111], v[152:155], v[182:185], v[108:111]
	v_mfma_f32_16x16x32_bf16 v[104:107], v[160:163], v[182:185], v[104:107]
	v_mfma_f32_16x16x32_bf16 v[92:95], v[152:155], v[194:197], v[92:95]
	v_mfma_f32_16x16x32_bf16 v[88:91], v[160:163], v[194:197], v[88:91]
	v_mfma_f32_16x16x32_bf16 v[76:79], v[152:155], v[202:205], v[76:79]
	v_mfma_f32_16x16x32_bf16 v[72:75], v[160:163], v[202:205], v[72:75]
	v_mfma_f32_16x16x32_bf16 v[124:127], v[156:159], v[172:175], v[124:127]
	v_mfma_f32_16x16x32_bf16 v[120:123], v[164:167], v[172:175], v[120:123]
	v_mfma_f32_16x16x32_bf16 v[108:111], v[156:159], v[190:193], v[108:111]
	v_mfma_f32_16x16x32_bf16 v[104:107], v[164:167], v[190:193], v[104:107]
	v_mfma_f32_16x16x32_bf16 v[92:95], v[156:159], v[198:201], v[92:95]
	v_mfma_f32_16x16x32_bf16 v[88:91], v[164:167], v[198:201], v[88:91]
	v_mfma_f32_16x16x32_bf16 v[76:79], v[156:159], v[206:209], v[76:79]
	v_mfma_f32_16x16x32_bf16 v[72:75], v[164:167], v[206:209], v[72:75]
	v_mfma_f32_16x16x32_bf16 v[116:119], v[210:213], v[168:171], v[116:119]
	v_mfma_f32_16x16x32_bf16 v[112:115], v[218:221], v[168:171], v[112:115]
	v_mfma_f32_16x16x32_bf16 v[100:103], v[210:213], v[182:185], v[100:103]
	v_mfma_f32_16x16x32_bf16 v[96:99], v[218:221], v[182:185], v[96:99]
	v_mfma_f32_16x16x32_bf16 v[84:87], v[210:213], v[194:197], v[84:87]
	v_mfma_f32_16x16x32_bf16 v[80:83], v[218:221], v[194:197], v[80:83]
	v_mfma_f32_16x16x32_bf16 v[68:71], v[210:213], v[202:205], v[68:71]
	v_mfma_f32_16x16x32_bf16 v[64:67], v[218:221], v[202:205], v[64:67]
	v_mfma_f32_16x16x32_bf16 v[116:119], v[214:217], v[172:175], v[116:119]
	v_mfma_f32_16x16x32_bf16 v[112:115], v[222:225], v[172:175], v[112:115]
	v_mfma_f32_16x16x32_bf16 v[100:103], v[214:217], v[190:193], v[100:103]
	v_mfma_f32_16x16x32_bf16 v[96:99], v[222:225], v[190:193], v[96:99]
	v_mfma_f32_16x16x32_bf16 v[84:87], v[214:217], v[198:201], v[84:87]
	v_mfma_f32_16x16x32_bf16 v[80:83], v[222:225], v[198:201], v[80:83]
	v_mfma_f32_16x16x32_bf16 v[68:71], v[214:217], v[206:209], v[68:71]
	v_mfma_f32_16x16x32_bf16 v[64:67], v[222:225], v[206:209], v[64:67]
	s_barrier
	ds_read_b128 v[168:171], v150 offset:49152
	ds_read_b128 v[172:175], v150 offset:50176
	ds_read_b128 v[182:185], v150 offset:51200
	ds_read_b128 v[190:193], v150 offset:52224
	ds_read_b128 v[194:197], v150 offset:53248
	ds_read_b128 v[198:201], v150 offset:54272
	ds_read_b128 v[202:205], v150 offset:55296
	ds_read_b128 v[206:209], v150 offset:56320
	s_add_i32 s18, s55, s31
	s_mov_b32 m0, s18
	s_nop 0
	global_load_lds_dwordx4 v130, s[98:99]
	s_nop 1
	s_add_i32 m0, s18, 0x2000
	s_nop 0
	global_load_lds_dwordx4 v134, s[98:99]
	s_nop 1
	s_mov_b32 m0, s39
	s_nop 0
	global_load_lds_dwordx4 v128, s[100:101]
	s_nop 1
	s_mov_b32 m0, s40
	s_nop 0
	global_load_lds_dwordx4 v132, s[100:101]
	s_add_u32 s18, s22, 0xb0080
	s_addc_u32 s19, s23, 0
	s_add_i32 s22, s24, s31
	s_mov_b32 m0, s22
	s_nop 0
	global_load_lds_dwordx4 v130, s[18:19]
	s_nop 1
	s_add_i32 m0, s22, 0x2000
	s_nop 0
	global_load_lds_dwordx4 v134, s[18:19]
	s_waitcnt vmcnt(8) lgkmcnt(0)
	s_barrier
	v_mfma_f32_16x16x32_bf16 v[60:63], v[152:155], v[168:171], v[60:63]
	v_mfma_f32_16x16x32_bf16 v[56:59], v[160:163], v[168:171], v[56:59]
	v_mfma_f32_16x16x32_bf16 v[48:51], v[152:155], v[182:185], v[48:51]
	v_mfma_f32_16x16x32_bf16 v[40:43], v[160:163], v[182:185], v[40:43]
	v_mfma_f32_16x16x32_bf16 v[32:35], v[152:155], v[194:197], v[32:35]
	v_mfma_f32_16x16x32_bf16 v[24:27], v[160:163], v[194:197], v[24:27]
	v_mfma_f32_16x16x32_bf16 v[16:19], v[152:155], v[202:205], v[16:19]
	v_mfma_f32_16x16x32_bf16 v[8:11], v[160:163], v[202:205], v[8:11]
	v_mfma_f32_16x16x32_bf16 v[60:63], v[156:159], v[172:175], v[60:63]
	v_mfma_f32_16x16x32_bf16 v[56:59], v[164:167], v[172:175], v[56:59]
	v_mfma_f32_16x16x32_bf16 v[48:51], v[156:159], v[190:193], v[48:51]
	v_mfma_f32_16x16x32_bf16 v[40:43], v[164:167], v[190:193], v[40:43]
	v_mfma_f32_16x16x32_bf16 v[32:35], v[156:159], v[198:201], v[32:35]
	v_mfma_f32_16x16x32_bf16 v[24:27], v[164:167], v[198:201], v[24:27]
	v_mfma_f32_16x16x32_bf16 v[16:19], v[156:159], v[206:209], v[16:19]
	v_mfma_f32_16x16x32_bf16 v[8:11], v[164:167], v[206:209], v[8:11]
	v_mfma_f32_16x16x32_bf16 v[52:55], v[210:213], v[168:171], v[52:55]
	v_mfma_f32_16x16x32_bf16 v[44:47], v[218:221], v[168:171], v[44:47]
	v_mfma_f32_16x16x32_bf16 v[36:39], v[210:213], v[182:185], v[36:39]
	v_mfma_f32_16x16x32_bf16 v[28:31], v[218:221], v[182:185], v[28:31]
	v_mfma_f32_16x16x32_bf16 v[20:23], v[210:213], v[194:197], v[20:23]
	v_mfma_f32_16x16x32_bf16 v[12:15], v[218:221], v[194:197], v[12:15]
	v_mfma_f32_16x16x32_bf16 v[4:7], v[210:213], v[202:205], v[4:7]
	v_mfma_f32_16x16x32_bf16 v[0:3], v[218:221], v[202:205], v[0:3]
	v_mfma_f32_16x16x32_bf16 v[52:55], v[214:217], v[172:175], v[52:55]
	v_mfma_f32_16x16x32_bf16 v[44:47], v[222:225], v[172:175], v[44:47]
	v_mfma_f32_16x16x32_bf16 v[36:39], v[214:217], v[190:193], v[36:39]
	v_mfma_f32_16x16x32_bf16 v[28:31], v[222:225], v[190:193], v[28:31]
	v_mfma_f32_16x16x32_bf16 v[20:23], v[214:217], v[198:201], v[20:23]
	v_mfma_f32_16x16x32_bf16 v[12:15], v[222:225], v[198:201], v[12:15]
	v_mfma_f32_16x16x32_bf16 v[4:7], v[214:217], v[206:209], v[4:7]
	v_mfma_f32_16x16x32_bf16 v[0:3], v[222:225], v[206:209], v[0:3]
	s_barrier
; __device__ __forceinline__ unsigned cvt_pk_bf16(float lo, float hi) { unsigned r; asm volatile("v_cvt_pk_bf16_f32 %0, %1, %2" : "=v"(r) : "v"(lo), "v"(hi)); return r; }
; __device__ __forceinline__ float flogsig16(float x) { return (fminf(x, 0.f) - __logf(1.0f + __expf(-fabsf(x)))) * 0.0625f; }
;     __device__ __forceinline__ void operator()(const f32x4 (&acc)[2][2][4][2], const Unit& u, int wr, int wc, int fr, int fq) const {
;     ...
;         const int row0 = u.pm * BM + wr * 64 + fr, col0 = u.pn * BM + wc * 32 + 8 * fq, bcol0 = wc * 32 + 8 * fq;
;         f32x4 bv[2][2];
; #pragma unroll
;         for (int bj = 0; bj < 2; ++bj)
; #pragma unroll
;             for (int n = 0; n < 2; ++n) bv[bj][n] = bias ? *(const f32x4*)(bias + bcol0 + bj * HALF + 4 * n) : (f32x4){0.f, 0.f, 0.f, 0.f};
; #pragma unroll
;         for (int ai = 0; ai < 2; ++ai)
; #pragma unroll
;             for (int m = 0; m < 4; ++m) { bf16_t* rowp = O + (size_t)(row0 + ai * HALF + m * 16) * ldc + col0;
; #pragma unroll
;                 for (int bj = 0; bj < 2; ++bj) { f32x4 v0 = acc[ai][bj][m][0] + bv[bj][0], v1 = acc[ai][bj][m][1] + bv[bj][1];
;                     if (act == 1) {
; #pragma unroll
;                         for (int j = 0; j < 1; ++j) { v0 = v0 * sigmoid4(v0); v1 = v1 * sigmoid4(v1); } }
;                     else if (act == 2) {
; #pragma unroll
;                         for (int j = 0; j < 1; ++j) { v0 = sigmoid4(v0); v1 = sigmoid4(v1); } }
;                     else if (act == 3) {
; #pragma unroll
;                         for (int j = 0; j < 4; ++j) { v0[j] = flogsig16(v0[j]); v1[j] = flogsig16(v1[j]); } }
;                     u32x4 w; w.x = cvt_pk_bf16(v0[0], v0[1]); w.y = cvt_pk_bf16(v0[2], v0[3]); w.z = cvt_pk_bf16(v1[0], v1[1]); w.w = cvt_pk_bf16(v1[2], v1[3]);
;                     *(u32x4*)(rowp + bj * HALF) = w; } }
; template <class Epi, class Sched>
; __device__ __forceinline__ void gemm_phase(PG8_LAS unsigned char* lds, const Gemm g, const Sched& S, const Epi& E) {
;     ...
;         for (int t = 0; t < nt; t += 2) {
	s_add_i32 s54, s54, 2
	s_add_u32 s52, s52, 0x100
	s_addc_u32 s53, s53, 0
	s_cmp_gt_u32 s54, 41
	s_mov_b64 s[18:19], s[20:21]
	s_cbranch_scc0 .LBB0_1278
	v_lshl_add_u32 v152, s50, 8, v146
	v_lshl_or_b32 v144, s51, 8, v148
	v_ashrrev_i32_e32 v153, 31, v152
	v_ashrrev_i32_e32 v145, 31, v144
	v_lshlrev_b64 v[154:155], 11, v[152:153]
	v_lshl_add_u64 v[154:155], s[6:7], 0, v[154:155]
	v_lshlrev_b64 v[156:157], 1, v[144:145]
	v_lshl_add_u64 v[144:145], v[154:155], 0, v[156:157]
	v_pk_add_f32 v[126:127], v[126:127], 0 op_sel_hi:[1,0]
	v_pk_add_f32 v[124:125], v[124:125], 0 op_sel_hi:[1,0]
	v_pk_add_f32 v[154:155], v[122:123], 0 op_sel_hi:[1,0]
	v_pk_add_f32 v[122:123], v[120:121], 0 op_sel_hi:[1,0]
	v_cvt_pk_bf16_f32 v120, v124, v125
	v_cvt_pk_bf16_f32 v121, v126, v127
	v_pk_add_f32 v[116:117], v[116:117], 0 op_sel_hi:[1,0]
	v_cvt_pk_bf16_f32 v122, v122, v123
	v_cvt_pk_bf16_f32 v123, v154, v155
	global_store_dwordx4 v[144:145], v[120:123], off
	v_pk_add_f32 v[118:119], v[118:119], 0 op_sel_hi:[1,0]
	v_pk_add_f32 v[110:111], v[110:111], 0 op_sel_hi:[1,0]
	v_pk_add_f32 v[120:121], v[114:115], 0 op_sel_hi:[1,0]
	v_pk_add_f32 v[114:115], v[112:113], 0 op_sel_hi:[1,0]
	v_cvt_pk_bf16_f32 v112, v116, v117
	v_cvt_pk_bf16_f32 v113, v118, v119
	v_pk_add_f32 v[108:109], v[108:109], 0 op_sel_hi:[1,0]
	v_cvt_pk_bf16_f32 v114, v114, v115
	v_cvt_pk_bf16_f32 v115, v120, v121
	global_store_dwordx4 v[144:145], v[112:115], off offset:256
	v_pk_add_f32 v[100:101], v[100:101], 0 op_sel_hi:[1,0]
	v_pk_add_f32 v[102:103], v[102:103], 0 op_sel_hi:[1,0]
	v_or_b32_e32 v112, 16, v152
	v_ashrrev_i32_e32 v113, 31, v112
	v_lshlrev_b64 v[112:113], 11, v[112:113]
	v_lshl_add_u64 v[112:113], s[6:7], 0, v[112:113]
	v_lshl_add_u64 v[112:113], v[112:113], 0, v[156:157]
	v_pk_add_f32 v[114:115], v[106:107], 0 op_sel_hi:[1,0]
	v_pk_add_f32 v[106:107], v[104:105], 0 op_sel_hi:[1,0]
	v_cvt_pk_bf16_f32 v104, v108, v109
	v_cvt_pk_bf16_f32 v105, v110, v111
	v_pk_add_f32 v[94:95], v[94:95], 0 op_sel_hi:[1,0]
	v_cvt_pk_bf16_f32 v106, v106, v107
	v_cvt_pk_bf16_f32 v107, v114, v115
	global_store_dwordx4 v[112:113], v[104:107], off
	v_pk_add_f32 v[92:93], v[92:93], 0 op_sel_hi:[1,0]
	v_pk_add_f32 v[84:85], v[84:85], 0 op_sel_hi:[1,0]
	v_pk_add_f32 v[104:105], v[98:99], 0 op_sel_hi:[1,0]
	v_pk_add_f32 v[98:99], v[96:97], 0 op_sel_hi:[1,0]
	v_cvt_pk_bf16_f32 v96, v100, v101
	v_cvt_pk_bf16_f32 v97, v102, v103
	v_pk_add_f32 v[86:87], v[86:87], 0 op_sel_hi:[1,0]
	v_cvt_pk_bf16_f32 v98, v98, v99
	v_cvt_pk_bf16_f32 v99, v104, v105
	global_store_dwordx4 v[112:113], v[96:99], off offset:256
	v_pk_add_f32 v[78:79], v[78:79], 0 op_sel_hi:[1,0]
	v_pk_add_f32 v[76:77], v[76:77], 0 op_sel_hi:[1,0]
	v_or_b32_e32 v96, 32, v152
	v_ashrrev_i32_e32 v97, 31, v96
	v_lshlrev_b64 v[96:97], 11, v[96:97]
	v_lshl_add_u64 v[96:97], s[6:7], 0, v[96:97]
	v_lshl_add_u64 v[96:97], v[96:97], 0, v[156:157]
	v_pk_add_f32 v[98:99], v[90:91], 0 op_sel_hi:[1,0]
	v_pk_add_f32 v[90:91], v[88:89], 0 op_sel_hi:[1,0]
	v_cvt_pk_bf16_f32 v88, v92, v93
	v_cvt_pk_bf16_f32 v89, v94, v95
	v_pk_add_f32 v[70:71], v[70:71], 0 op_sel_hi:[1,0]
	v_cvt_pk_bf16_f32 v90, v90, v91
	v_cvt_pk_bf16_f32 v91, v98, v99
	global_store_dwordx4 v[96:97], v[88:91], off
	v_pk_add_f32 v[68:69], v[68:69], 0 op_sel_hi:[1,0]
	v_pk_add_f32 v[60:61], v[60:61], 0 op_sel_hi:[1,0]
	v_pk_add_f32 v[88:89], v[82:83], 0 op_sel_hi:[1,0]
	v_pk_add_f32 v[82:83], v[80:81], 0 op_sel_hi:[1,0]
	v_cvt_pk_bf16_f32 v80, v84, v85
	v_cvt_pk_bf16_f32 v81, v86, v87
	v_pk_add_f32 v[62:63], v[62:63], 0 op_sel_hi:[1,0]
	v_cvt_pk_bf16_f32 v82, v82, v83
	v_cvt_pk_bf16_f32 v83, v88, v89
	global_store_dwordx4 v[96:97], v[80:83], off offset:256
	v_pk_add_f32 v[54:55], v[54:55], 0 op_sel_hi:[1,0]
	v_pk_add_f32 v[52:53], v[52:53], 0 op_sel_hi:[1,0]
	v_or_b32_e32 v80, 48, v152
	v_ashrrev_i32_e32 v81, 31, v80
	v_lshlrev_b64 v[80:81], 11, v[80:81]
	v_lshl_add_u64 v[80:81], s[6:7], 0, v[80:81]
	v_lshl_add_u64 v[80:81], v[80:81], 0, v[156:157]
	v_pk_add_f32 v[82:83], v[74:75], 0 op_sel_hi:[1,0]
	v_pk_add_f32 v[74:75], v[72:73], 0 op_sel_hi:[1,0]
	v_cvt_pk_bf16_f32 v72, v76, v77
	v_cvt_pk_bf16_f32 v73, v78, v79
; __device__ __forceinline__ unsigned cvt_pk_bf16(float lo, float hi) { unsigned r; asm volatile("v_cvt_pk_bf16_f32 %0, %1, %2" : "=v"(r) : "v"(lo), "v"(hi)); return r; }
; __device__ __forceinline__ float flogsig16(float x) { return (fminf(x, 0.f) - __logf(1.0f + __expf(-fabsf(x)))) * 0.0625f; }
; #define PG8_WAIT_V(n) asm volatile("s_waitcnt vmcnt(" #n ")" ::: "memory")
; #define PG8_BAR __builtin_amdgcn_s_barrier()
;     __device__ __forceinline__ void operator()(const f32x4 (&acc)[2][2][4][2], const Unit& u, int wr, int wc, int fr, int fq) const {
;     ...
;             for (int m = 0; m < 4; ++m) { bf16_t* rowp = O + (size_t)(row0 + ai * HALF + m * 16) * ldc + col0;
; #pragma unroll
;                 for (int bj = 0; bj < 2; ++bj) { f32x4 v0 = acc[ai][bj][m][0] + bv[bj][0], v1 = acc[ai][bj][m][1] + bv[bj][1];
;                     if (act == 1) {
; #pragma unroll
;                         for (int j = 0; j < 1; ++j) { v0 = v0 * sigmoid4(v0); v1 = v1 * sigmoid4(v1); } }
;                     else if (act == 2) {
; #pragma unroll
;                         for (int j = 0; j < 1; ++j) { v0 = sigmoid4(v0); v1 = sigmoid4(v1); } }
;                     else if (act == 3) {
; #pragma unroll
;                         for (int j = 0; j < 4; ++j) { v0[j] = flogsig16(v0[j]); v1[j] = flogsig16(v1[j]); } }
;                     u32x4 w; w.x = cvt_pk_bf16(v0[0], v0[1]); w.y = cvt_pk_bf16(v0[2], v0[3]); w.z = cvt_pk_bf16(v1[0], v1[1]); w.w = cvt_pk_bf16(v1[2], v1[3]);
;                     *(u32x4*)(rowp + bj * HALF) = w; } }
; template <class Epi, class Sched>
; __device__ __forceinline__ void gemm_phase(PG8_LAS unsigned char* lds, const Gemm g, const Sched& S, const Epi& E) {
;     ...
;         if constexpr (!Epi::AFTER_DRAIN) { E(acc, cur, wr, wc, fr, fq); S.done(cur); }
;         if (!has_next) break;
; #pragma unroll
;         for (int a = 0; a < 2; ++a)
; #pragma unroll
;             for (int b = 0; b < 2; ++b)
; #pragma unroll
;                 for (int m = 0; m < 4; ++m)
; #pragma unroll
;                     for (int n = 0; n < 2; ++n) acc[a][b][m][n] = (f32x4){0.f, 0.f, 0.f, 0.f};
;         cur = nxt; cA = nA; cB = nB; ++ui;
;     }
;     PG8_WAIT_V(0);
;     if (wr == 0) PG8_BAR;
;     PG8_BAR;
	v_pk_add_f32 v[48:49], v[48:49], 0 op_sel_hi:[1,0]
	v_cvt_pk_bf16_f32 v74, v74, v75
	v_cvt_pk_bf16_f32 v75, v82, v83
	global_store_dwordx4 v[80:81], v[72:75], off
	v_pk_add_f32 v[38:39], v[38:39], 0 op_sel_hi:[1,0]
	v_pk_add_f32 v[36:37], v[36:37], 0 op_sel_hi:[1,0]
	v_pk_add_f32 v[72:73], v[66:67], 0 op_sel_hi:[1,0]
	v_pk_add_f32 v[66:67], v[64:65], 0 op_sel_hi:[1,0]
	v_cvt_pk_bf16_f32 v64, v68, v69
	v_cvt_pk_bf16_f32 v65, v70, v71
	v_pk_add_f32 v[32:33], v[32:33], 0 op_sel_hi:[1,0]
	v_cvt_pk_bf16_f32 v66, v66, v67
	v_cvt_pk_bf16_f32 v67, v72, v73
	global_store_dwordx4 v[80:81], v[64:67], off offset:256
	v_pk_add_f32 v[22:23], v[22:23], 0 op_sel_hi:[1,0]
	v_pk_add_f32 v[20:21], v[20:21], 0 op_sel_hi:[1,0]
	v_pk_add_f32 v[66:67], v[58:59], 0 op_sel_hi:[1,0]
	v_pk_add_f32 v[58:59], v[56:57], 0 op_sel_hi:[1,0]
	v_cvt_pk_bf16_f32 v56, v60, v61
	v_add_co_u32_e32 v60, vcc, s44, v144
	v_cvt_pk_bf16_f32 v57, v62, v63
	v_cvt_pk_bf16_f32 v58, v58, v59
	v_cvt_pk_bf16_f32 v59, v66, v67
	v_lshl_add_u64 v[64:65], v[144:145], 0, s[10:11]
	s_nop 0
	v_addc_co_u32_e32 v61, vcc, 0, v145, vcc
	global_store_dwordx4 v[60:61], v[56:59], off
	v_pk_add_f32 v[16:17], v[16:17], 0 op_sel_hi:[1,0]
	s_mov_b32 s51, s48
	v_pk_add_f32 v[56:57], v[46:47], 0 op_sel_hi:[1,0]
	v_pk_add_f32 v[46:47], v[44:45], 0 op_sel_hi:[1,0]
	v_cvt_pk_bf16_f32 v44, v52, v53
	v_cvt_pk_bf16_f32 v45, v54, v55
	s_mov_b32 s50, s49
	v_cvt_pk_bf16_f32 v46, v46, v47
	v_cvt_pk_bf16_f32 v47, v56, v57
	global_store_dwordx4 v[64:65], v[44:47], off offset:256
	s_mov_b64 s[20:21], s[4:5]
	s_mov_b64 s[18:19], s[0:1]
	v_pk_add_f32 v[46:47], v[50:51], 0 op_sel_hi:[1,0]
	v_pk_add_f32 v[50:51], v[42:43], 0 op_sel_hi:[1,0]
	v_pk_add_f32 v[42:43], v[40:41], 0 op_sel_hi:[1,0]
	v_cvt_pk_bf16_f32 v40, v48, v49
	v_cvt_pk_bf16_f32 v41, v46, v47
	v_add_co_u32_e32 v46, vcc, s45, v144
	v_cvt_pk_bf16_f32 v42, v42, v43
	v_cvt_pk_bf16_f32 v43, v50, v51
	v_lshl_add_u64 v[44:45], v[144:145], 0, s[12:13]
	s_nop 0
	v_addc_co_u32_e32 v47, vcc, 0, v145, vcc
	global_store_dwordx4 v[46:47], v[40:43], off
	v_pk_add_f32 v[6:7], v[6:7], 0 op_sel_hi:[1,0]
	v_pk_add_f32 v[4:5], v[4:5], 0 op_sel_hi:[1,0]
	v_pk_add_f32 v[40:41], v[30:31], 0 op_sel_hi:[1,0]
	v_pk_add_f32 v[30:31], v[28:29], 0 op_sel_hi:[1,0]
	v_cvt_pk_bf16_f32 v28, v36, v37
	v_cvt_pk_bf16_f32 v29, v38, v39
	s_nop 0
	v_cvt_pk_bf16_f32 v30, v30, v31
	v_cvt_pk_bf16_f32 v31, v40, v41
	global_store_dwordx4 v[44:45], v[28:31], off offset:256
	s_nop 1
	v_pk_add_f32 v[30:31], v[34:35], 0 op_sel_hi:[1,0]
	v_pk_add_f32 v[34:35], v[26:27], 0 op_sel_hi:[1,0]
	v_pk_add_f32 v[26:27], v[24:25], 0 op_sel_hi:[1,0]
	v_cvt_pk_bf16_f32 v24, v32, v33
	v_cvt_pk_bf16_f32 v25, v30, v31
	v_add_co_u32_e32 v30, vcc, s46, v144
	v_cvt_pk_bf16_f32 v26, v26, v27
	v_cvt_pk_bf16_f32 v27, v34, v35
	v_lshl_add_u64 v[28:29], v[144:145], 0, s[14:15]
	s_nop 0
	v_addc_co_u32_e32 v31, vcc, 0, v145, vcc
	global_store_dwordx4 v[30:31], v[24:27], off
	s_nop 1
	v_pk_add_f32 v[24:25], v[14:15], 0 op_sel_hi:[1,0]
	v_pk_add_f32 v[14:15], v[12:13], 0 op_sel_hi:[1,0]
	v_cvt_pk_bf16_f32 v12, v20, v21
	v_cvt_pk_bf16_f32 v13, v22, v23
	s_nop 0
	v_cvt_pk_bf16_f32 v14, v14, v15
	v_cvt_pk_bf16_f32 v15, v24, v25
	global_store_dwordx4 v[28:29], v[12:15], off offset:256
	s_nop 1
	v_pk_add_f32 v[14:15], v[18:19], 0 op_sel_hi:[1,0]
	v_pk_add_f32 v[18:19], v[10:11], 0 op_sel_hi:[1,0]
	v_pk_add_f32 v[10:11], v[8:9], 0 op_sel_hi:[1,0]
	v_cvt_pk_bf16_f32 v8, v16, v17
	v_cvt_pk_bf16_f32 v9, v14, v15
	v_add_co_u32_e32 v14, vcc, s47, v144
	v_lshl_add_u64 v[12:13], v[144:145], 0, s[16:17]
	s_nop 0
	v_addc_co_u32_e32 v15, vcc, 0, v145, vcc
	v_cvt_pk_bf16_f32 v10, v10, v11
	v_cvt_pk_bf16_f32 v11, v18, v19
	global_store_dwordx4 v[14:15], v[8:11], off
	s_and_b64 vcc, exec, s[2:3]
	s_nop 0
	v_pk_add_f32 v[8:9], v[2:3], 0 op_sel_hi:[1,0]
	v_pk_add_f32 v[2:3], v[0:1], 0 op_sel_hi:[1,0]
	v_cvt_pk_bf16_f32 v0, v4, v5
	v_cvt_pk_bf16_f32 v1, v6, v7
	s_nop 0
	v_cvt_pk_bf16_f32 v2, v2, v3
	v_cvt_pk_bf16_f32 v3, v8, v9
	global_store_dwordx4 v[12:13], v[0:3], off offset:256
	s_cbranch_vccz .LBB0_1267
	s_waitcnt vmcnt(0)
	s_cmpk_gt_u32 s27, 0xff
	s_cbranch_scc1 .LBB0_1282
	s_barrier
